# A/B: all per-phase s_setprio flips in the GEMM K loops deleted, one static s_setprio 1 for waves 4-7 for the whole kernel; on top of v37
# speedup vs baseline: 1.0093x; 1.0093x over previous
; DI unsigned char* wsp() { return (unsigned char*)inp(25); }
; #define LAS __attribute__((address_space(3)))
; #define G_WS (wsp())
; __global__ void __launch_bounds__(512, 2) mega(Params p) {
;   cg::grid_group grid = cg::this_grid();
;   const int nb = gridDim.x, bid = blockIdx.x, t = threadIdx.x;
;   if (wsp() == nullptr) grid.sync();
;   volatile LAS unsigned* xst = (volatile LAS unsigned*)(smem + SMEM_MAIN);
;   if (t < 4) xst[t] = 0u;
;   __syncthreads();
;   const XcdBarrier xbar = xcd_barrier_post((unsigned*)(G_WS + OFF_BAR), xst);
_Z4mega6Params:
	s_mov_b64 s[70:71], s[0:1]
	s_load_dwordx2 s[0:1], s[70:71], 0xd0
	s_load_dword s33, s[70:71], 0xd8
	v_and_b32_e32 v224, 0x3ff, v0
	s_nop 0
	v_readfirstlane_b32 s100, v224
	s_nop 0
	s_cmpk_lt_u32 s100, 0x100
	s_cbranch_scc1 .Lprio_all
	s_setprio 1
.Lprio_all:
	v_writelane_b32 v252, s2, 0
	s_add_u32 s2, s70, 0xd0
	s_waitcnt lgkmcnt(0)
	v_writelane_b32 v252, s0, 1
	s_addc_u32 s3, s71, 0
	s_nop 0
	v_writelane_b32 v252, s1, 2
	s_mov_b32 s0, 25
	s_ashr_i32 s1, s0, 31
	s_lshl_b64 s[0:1], s[0:1], 3
	s_add_u32 s0, s70, s0
	s_addc_u32 s1, s71, s1
	s_load_dwordx2 s[4:5], s[0:1], 0x0
	s_movk_i32 s0, 0x3ff
	s_waitcnt lgkmcnt(0)
	v_writelane_b32 v255, s4, 60
	v_writelane_b32 v255, s5, 61
	s_cmp_lg_u64 s[4:5], 0
	s_cbranch_scc0 .LBB0_129
	v_cmp_gt_u32_e32 vcc, 4, v224
	s_and_saveexec_b64 s[0:1], vcc

; #define LDA8(dst, b, h) _Pragma("unroll") for (int m = 0; m < 4; ++m) _Pragma("unroll") for (int k = 0; k < 2; ++k) \
;     dst[m][k] = *(const bf16x8*)((const char*)SA8(b, h) + lds_byte8(wr * 64 + m * 16 + fr, k * 32 + fq * 8))
; #define LDB8(dst, b, h) _Pragma("unroll") for (int n = 0; n < 2; ++n) _Pragma("unroll") for (int k = 0; k < 2; ++k) \
;     dst[n][k] = *(const bf16x8*)((const char*)SB8(b, h) + lds_byte8(wc * 32 + n * 16 + fr, k * 32 + fq * 8))
; #define WAIT_L8(n) asm volatile("s_waitcnt lgkmcnt(" #n ")" ::: "memory")
; #define BAR8 __builtin_amdgcn_s_barrier()
; #define SCHED8 __builtin_amdgcn_sched_barrier(0)
;     ...
;     LDB8(B0, 0, 0); SCHED8; LDA8(At, 0, 0); STAGE8(SA8(1, 1), A, lda, brow + 128, tt + 1);
;     WAIT_L8(8); BAR8; WAIT_L8(0); MMA8(0, 0, At, B0); BAR8; SCHED8;
;     LDB8(B1, 0, 1); STAGE8(SB8(0, 0), Bt, K, bcol, tt + 2);
;     BAR8; WAIT_L8(0); MMA8(0, 1, At, B1); BAR8;
;     LDA8(At, 0, 1); STAGE8(SA8(0, 0), A, lda, brow, tt + 2);
;     BAR8; WAIT_L8(0); MMA8(1, 0, At, B0); BAR8; SCHED8;
;     STAGE8(SB8(0, 1), Bt, K, bcol + 128, tt + 2);
.LBB0_192:
	ds_read_b128 v[174:177], v173
	ds_read_b128 v[178:181], v173 offset:1024
	ds_read_b128 v[182:185], v173 offset:2048
	ds_read_b128 v[186:189], v173 offset:3072
	v_lshl_add_u64 v[222:223], v[140:141], 0, s[12:13]
	v_readfirstlane_b32 s15, v172
	v_lshl_add_u64 v[226:227], v[222:223], 0, s[34:35]
	s_mov_b32 m0, s15
	ds_read_b128 v[190:193], v156
	ds_read_b128 v[194:197], v156 offset:1024
	ds_read_b128 v[198:201], v154
	ds_read_b128 v[202:205], v154 offset:1024
	ds_read_b128 v[206:209], v153
	ds_read_b128 v[210:213], v153 offset:1024
	ds_read_b128 v[214:217], v152
	ds_read_b128 v[218:221], v152 offset:1024
	global_load_lds_dwordx4 v[226:227], off
	v_lshl_add_u64 v[226:227], v[138:139], 0, s[12:13]
	v_readfirstlane_b32 s15, v171
	v_lshl_add_u64 v[228:229], v[226:227], 0, s[34:35]
	s_mov_b32 m0, s15
	s_nop 0
	global_load_lds_dwordx4 v[228:229], off
	s_waitcnt lgkmcnt(8)
	s_barrier
	s_waitcnt lgkmcnt(0)
	s_waitcnt lgkmcnt(0)
	v_mfma_f32_16x16x32_f16 v[128:131], v[190:193], v[174:177], v[128:131]
	v_mfma_f32_16x16x32_f16 v[124:127], v[190:193], v[182:185], v[124:127]
	v_mfma_f32_16x16x32_f16 v[120:123], v[198:201], v[174:177], v[120:123]
	v_mfma_f32_16x16x32_f16 v[116:119], v[198:201], v[182:185], v[116:119]
	v_mfma_f32_16x16x32_f16 v[112:115], v[206:209], v[174:177], v[112:115]
	v_mfma_f32_16x16x32_f16 v[108:111], v[206:209], v[182:185], v[108:111]
	v_mfma_f32_16x16x32_f16 v[104:107], v[214:217], v[174:177], v[104:107]
	v_mfma_f32_16x16x32_f16 v[100:103], v[214:217], v[182:185], v[100:103]
	v_mfma_f32_16x16x32_f16 v[128:131], v[194:197], v[178:181], v[128:131]
	v_mfma_f32_16x16x32_f16 v[124:127], v[194:197], v[186:189], v[124:127]
	v_mfma_f32_16x16x32_f16 v[120:123], v[202:205], v[178:181], v[120:123]
	v_mfma_f32_16x16x32_f16 v[116:119], v[202:205], v[186:189], v[116:119]
	v_mfma_f32_16x16x32_f16 v[112:115], v[210:213], v[178:181], v[112:115]
	v_mfma_f32_16x16x32_f16 v[108:111], v[210:213], v[186:189], v[108:111]
	v_mfma_f32_16x16x32_f16 v[104:107], v[218:221], v[178:181], v[104:107]
	v_mfma_f32_16x16x32_f16 v[100:103], v[218:221], v[186:189], v[100:103]
	s_barrier
	v_lshl_add_u64 v[228:229], v[142:143], 0, s[12:13]
	v_readfirstlane_b32 s15, v151
	v_lshl_add_u64 v[236:237], v[228:229], 0, s[60:61]
	s_mov_b32 m0, s15
	ds_read_b128 v[238:241], v169
	ds_read_b128 v[242:245], v169 offset:1024
	ds_read_b128 v[246:249], v169 offset:2048
	ds_read_b128 v[230:233], v169 offset:3072
	global_load_lds_dwordx4 v[236:237], off
	v_lshl_add_u64 v[236:237], v[144:145], 0, s[12:13]
	v_readfirstlane_b32 s15, v157
	v_lshl_add_u64 v[250:251], v[236:237], 0, s[60:61]
	s_mov_b32 m0, s15
	s_nop 0
	global_load_lds_dwordx4 v[250:251], off
	s_barrier
	s_waitcnt lgkmcnt(0)
	s_waitcnt lgkmcnt(0)
	v_mfma_f32_16x16x32_f16 v[96:99], v[190:193], v[238:241], v[96:99]
	v_mfma_f32_16x16x32_f16 v[92:95], v[190:193], v[246:249], v[92:95]
	v_mfma_f32_16x16x32_f16 v[88:91], v[198:201], v[238:241], v[88:91]
	v_mfma_f32_16x16x32_f16 v[84:87], v[198:201], v[246:249], v[84:87]
	v_mfma_f32_16x16x32_f16 v[80:83], v[206:209], v[238:241], v[80:83]
	v_mfma_f32_16x16x32_f16 v[76:79], v[206:209], v[246:249], v[76:79]
	v_mfma_f32_16x16x32_f16 v[72:75], v[214:217], v[238:241], v[72:75]
	v_mfma_f32_16x16x32_f16 v[68:71], v[214:217], v[246:249], v[68:71]
	v_mfma_f32_16x16x32_f16 v[96:99], v[194:197], v[242:245], v[96:99]
	v_mfma_f32_16x16x32_f16 v[92:95], v[194:197], v[230:233], v[92:95]
	v_mfma_f32_16x16x32_f16 v[88:91], v[202:205], v[242:245], v[88:91]
	v_mfma_f32_16x16x32_f16 v[84:87], v[202:205], v[230:233], v[84:87]
	v_mfma_f32_16x16x32_f16 v[80:83], v[210:213], v[242:245], v[80:83]
	v_mfma_f32_16x16x32_f16 v[76:79], v[210:213], v[230:233], v[76:79]
	v_mfma_f32_16x16x32_f16 v[72:75], v[218:221], v[242:245], v[72:75]
	v_mfma_f32_16x16x32_f16 v[68:71], v[218:221], v[230:233], v[68:71]
	v_readfirstlane_b32 s15, v150
	v_lshl_add_u64 v[250:251], v[222:223], 0, s[10:11]
	s_mov_b32 m0, s15
	v_readfirstlane_b32 s15, v155
	s_barrier
	ds_read_b128 v[190:193], v156 offset:16384
	ds_read_b128 v[194:197], v156 offset:17408
	ds_read_b128 v[198:201], v154 offset:16384
	ds_read_b128 v[202:205], v154 offset:17408
	ds_read_b128 v[206:209], v153 offset:16384
	ds_read_b128 v[210:213], v153 offset:17408
	ds_read_b128 v[214:217], v152 offset:16384
	ds_read_b128 v[218:221], v152 offset:17408
	global_load_lds_dwordx4 v[250:251], off
	v_lshl_add_u64 v[250:251], v[226:227], 0, s[10:11]
	s_mov_b32 m0, s15
	s_nop 0
	global_load_lds_dwordx4 v[250:251], off
	s_barrier
	s_waitcnt lgkmcnt(0)
	s_waitcnt lgkmcnt(0)
	v_mfma_f32_16x16x32_f16 v[64:67], v[190:193], v[174:177], v[64:67]
	v_mfma_f32_16x16x32_f16 v[60:63], v[190:193], v[182:185], v[60:63]
	v_mfma_f32_16x16x32_f16 v[56:59], v[198:201], v[174:177], v[56:59]
	v_mfma_f32_16x16x32_f16 v[52:55], v[198:201], v[182:185], v[52:55]
	v_mfma_f32_16x16x32_f16 v[48:51], v[206:209], v[174:177], v[48:51]
	v_mfma_f32_16x16x32_f16 v[44:47], v[206:209], v[182:185], v[44:47]
	v_mfma_f32_16x16x32_f16 v[40:43], v[214:217], v[174:177], v[40:43]
	v_mfma_f32_16x16x32_f16 v[36:39], v[214:217], v[182:185], v[36:39]
	v_mfma_f32_16x16x32_f16 v[64:67], v[194:197], v[178:181], v[64:67]
	v_mfma_f32_16x16x32_f16 v[60:63], v[194:197], v[186:189], v[60:63]
	v_mfma_f32_16x16x32_f16 v[56:59], v[202:205], v[178:181], v[56:59]
	v_mfma_f32_16x16x32_f16 v[52:55], v[202:205], v[186:189], v[52:55]
	v_mfma_f32_16x16x32_f16 v[48:51], v[210:213], v[178:181], v[48:51]
	v_mfma_f32_16x16x32_f16 v[44:47], v[210:213], v[186:189], v[44:47]
	v_mfma_f32_16x16x32_f16 v[40:43], v[218:221], v[178:181], v[40:43]
	v_mfma_f32_16x16x32_f16 v[36:39], v[218:221], v[186:189], v[36:39]
	s_barrier
; #define LDA8(dst, b, h) _Pragma("unroll") for (int m = 0; m < 4; ++m) _Pragma("unroll") for (int k = 0; k < 2; ++k) \
;     dst[m][k] = *(const bf16x8*)((const char*)SA8(b, h) + lds_byte8(wr * 64 + m * 16 + fr, k * 32 + fq * 8))
; #define LDB8(dst, b, h) _Pragma("unroll") for (int n = 0; n < 2; ++n) _Pragma("unroll") for (int k = 0; k < 2; ++k) \
;     dst[n][k] = *(const bf16x8*)((const char*)SB8(b, h) + lds_byte8(wc * 32 + n * 16 + fr, k * 32 + fq * 8))
; #define WAIT_V8(n) asm volatile("s_waitcnt vmcnt(" #n ")" ::: "memory")
; #define WAIT_L8(n) asm volatile("s_waitcnt lgkmcnt(" #n ")" ::: "memory")
; #define BAR8 __builtin_amdgcn_s_barrier()
; #define SCHED8 __builtin_amdgcn_sched_barrier(0)
;     ...
;     STAGE8(SB8(0, 1), Bt, K, bcol + 128, tt + 2);
;     WAIT_V8(6); BAR8; MMA8(1, 1, At, B1); BAR8;
;     LDB8(B0, 1, 0); SCHED8; LDA8(At, 1, 0); STAGE8(SA8(0, 1), A, lda, brow + 128, tt + 2);
;     WAIT_L8(8); BAR8; WAIT_L8(0); MMA8(0, 0, At, B0); BAR8; SCHED8;
;     LDB8(B1, 1, 1); STAGE8(SB8(1, 0), Bt, K, bcol, tt + 3);
;     BAR8; WAIT_L8(0); MMA8(0, 1, At, B1); BAR8;
;     LDA8(At, 1, 1); STAGE8(SA8(1, 0), A, lda, brow, tt + 3);
	v_readfirstlane_b32 s15, v160
	v_lshl_add_u64 v[174:175], v[228:229], 0, s[62:63]
	s_mov_b32 m0, s15
	v_readfirstlane_b32 s15, v161
	global_load_lds_dwordx4 v[174:175], off
	v_lshl_add_u64 v[174:175], v[236:237], 0, s[62:63]
	s_mov_b32 m0, s15
	s_nop 0
	global_load_lds_dwordx4 v[174:175], off
	s_waitcnt vmcnt(6)
	s_barrier
	v_mfma_f32_16x16x32_f16 v[32:35], v[190:193], v[238:241], v[32:35]
	v_mfma_f32_16x16x32_f16 v[28:31], v[190:193], v[246:249], v[28:31]
	v_mfma_f32_16x16x32_f16 v[24:27], v[198:201], v[238:241], v[24:27]
	v_mfma_f32_16x16x32_f16 v[20:23], v[198:201], v[246:249], v[20:23]
	v_mfma_f32_16x16x32_f16 v[16:19], v[206:209], v[238:241], v[16:19]
	v_mfma_f32_16x16x32_f16 v[12:15], v[206:209], v[246:249], v[12:15]
	v_mfma_f32_16x16x32_f16 v[8:11], v[214:217], v[238:241], v[8:11]
	v_mfma_f32_16x16x32_f16 v[4:7], v[214:217], v[246:249], v[4:7]
	v_mfma_f32_16x16x32_f16 v[32:35], v[194:197], v[242:245], v[32:35]
	v_mfma_f32_16x16x32_f16 v[28:31], v[194:197], v[230:233], v[28:31]
	v_mfma_f32_16x16x32_f16 v[24:27], v[202:205], v[242:245], v[24:27]
	v_mfma_f32_16x16x32_f16 v[20:23], v[202:205], v[230:233], v[20:23]
	v_mfma_f32_16x16x32_f16 v[16:19], v[210:213], v[242:245], v[16:19]
	v_mfma_f32_16x16x32_f16 v[12:15], v[210:213], v[230:233], v[12:15]
	v_mfma_f32_16x16x32_f16 v[8:11], v[218:221], v[242:245], v[8:11]
	v_mfma_f32_16x16x32_f16 v[4:7], v[218:221], v[230:233], v[4:7]
	s_barrier
	ds_read_b128 v[174:177], v159
	ds_read_b128 v[178:181], v159 offset:1024
	ds_read_b128 v[182:185], v159 offset:2048
	ds_read_b128 v[186:189], v159 offset:3072
	v_readfirstlane_b32 s15, v162
	v_lshl_add_u64 v[230:231], v[222:223], 0, s[18:19]
	s_mov_b32 m0, s15
	v_readfirstlane_b32 s15, v163
	ds_read_b128 v[190:193], v156 offset:32768
	ds_read_b128 v[194:197], v156 offset:33792
	ds_read_b128 v[198:201], v154 offset:32768
	ds_read_b128 v[202:205], v154 offset:33792
	ds_read_b128 v[206:209], v153 offset:32768
	ds_read_b128 v[210:213], v153 offset:33792
	ds_read_b128 v[214:217], v152 offset:32768
	ds_read_b128 v[218:221], v152 offset:33792
	global_load_lds_dwordx4 v[230:231], off
	v_lshl_add_u64 v[230:231], v[226:227], 0, s[18:19]
	s_mov_b32 m0, s15
	s_nop 0
	global_load_lds_dwordx4 v[230:231], off
	s_waitcnt lgkmcnt(8)
	s_barrier
	s_waitcnt lgkmcnt(0)
	s_waitcnt lgkmcnt(0)
	v_mfma_f32_16x16x32_f16 v[128:131], v[190:193], v[174:177], v[128:131]
	v_mfma_f32_16x16x32_f16 v[124:127], v[190:193], v[182:185], v[124:127]
	v_mfma_f32_16x16x32_f16 v[120:123], v[198:201], v[174:177], v[120:123]
	v_mfma_f32_16x16x32_f16 v[116:119], v[198:201], v[182:185], v[116:119]
	v_mfma_f32_16x16x32_f16 v[112:115], v[206:209], v[174:177], v[112:115]
	v_mfma_f32_16x16x32_f16 v[108:111], v[206:209], v[182:185], v[108:111]
	v_mfma_f32_16x16x32_f16 v[104:107], v[214:217], v[174:177], v[104:107]
	v_mfma_f32_16x16x32_f16 v[100:103], v[214:217], v[182:185], v[100:103]
	v_mfma_f32_16x16x32_f16 v[128:131], v[194:197], v[178:181], v[128:131]
	v_mfma_f32_16x16x32_f16 v[124:127], v[194:197], v[186:189], v[124:127]
	v_mfma_f32_16x16x32_f16 v[120:123], v[202:205], v[178:181], v[120:123]
	v_mfma_f32_16x16x32_f16 v[116:119], v[202:205], v[186:189], v[116:119]
	v_mfma_f32_16x16x32_f16 v[112:115], v[210:213], v[178:181], v[112:115]
	v_mfma_f32_16x16x32_f16 v[108:111], v[210:213], v[186:189], v[108:111]
	v_mfma_f32_16x16x32_f16 v[104:107], v[218:221], v[178:181], v[104:107]
	v_mfma_f32_16x16x32_f16 v[100:103], v[218:221], v[186:189], v[100:103]
	s_barrier
	v_readfirstlane_b32 s15, v164
	v_lshl_add_u64 v[250:251], v[228:229], 0, s[64:65]
	s_mov_b32 m0, s15
	v_readfirstlane_b32 s15, v165
	ds_read_b128 v[230:233], v158
	ds_read_b128 v[238:241], v158 offset:1024
	ds_read_b128 v[242:245], v158 offset:2048
	ds_read_b128 v[246:249], v158 offset:3072
	global_load_lds_dwordx4 v[250:251], off
	v_lshl_add_u64 v[250:251], v[236:237], 0, s[64:65]
	s_mov_b32 m0, s15
	s_nop 0
	global_load_lds_dwordx4 v[250:251], off
	s_barrier
	s_waitcnt lgkmcnt(0)
	s_waitcnt lgkmcnt(0)
	v_mfma_f32_16x16x32_f16 v[96:99], v[190:193], v[230:233], v[96:99]
	v_mfma_f32_16x16x32_f16 v[92:95], v[190:193], v[242:245], v[92:95]
	v_mfma_f32_16x16x32_f16 v[88:91], v[198:201], v[230:233], v[88:91]
	v_mfma_f32_16x16x32_f16 v[84:87], v[198:201], v[242:245], v[84:87]
	v_mfma_f32_16x16x32_f16 v[80:83], v[206:209], v[230:233], v[80:83]
	v_mfma_f32_16x16x32_f16 v[76:79], v[206:209], v[242:245], v[76:79]
	v_mfma_f32_16x16x32_f16 v[72:75], v[214:217], v[230:233], v[72:75]
	v_mfma_f32_16x16x32_f16 v[68:71], v[214:217], v[242:245], v[68:71]
	v_mfma_f32_16x16x32_f16 v[96:99], v[194:197], v[238:241], v[96:99]
	v_mfma_f32_16x16x32_f16 v[92:95], v[194:197], v[246:249], v[92:95]
	v_mfma_f32_16x16x32_f16 v[88:91], v[202:205], v[238:241], v[88:91]
	v_mfma_f32_16x16x32_f16 v[84:87], v[202:205], v[246:249], v[84:87]
	v_mfma_f32_16x16x32_f16 v[80:83], v[210:213], v[238:241], v[80:83]
	v_mfma_f32_16x16x32_f16 v[76:79], v[210:213], v[246:249], v[76:79]
	v_mfma_f32_16x16x32_f16 v[72:75], v[218:221], v[238:241], v[72:75]
	v_mfma_f32_16x16x32_f16 v[68:71], v[218:221], v[246:249], v[68:71]
	v_readfirstlane_b32 s15, v166
	v_lshl_add_u64 v[222:223], v[222:223], 0, s[22:23]
	s_mov_b32 m0, s15
	v_readfirstlane_b32 s15, v167
	s_barrier
	ds_read_b128 v[190:193], v156 offset:49152
	ds_read_b128 v[194:197], v156 offset:50176
	ds_read_b128 v[198:201], v154 offset:49152
	ds_read_b128 v[202:205], v154 offset:50176
	ds_read_b128 v[206:209], v153 offset:49152
	ds_read_b128 v[210:213], v153 offset:50176
	ds_read_b128 v[214:217], v152 offset:49152
	ds_read_b128 v[218:221], v152 offset:50176
	global_load_lds_dwordx4 v[222:223], off
	v_lshl_add_u64 v[222:223], v[226:227], 0, s[22:23]
	s_mov_b32 m0, s15
	s_nop 0
	global_load_lds_dwordx4 v[222:223], off
	s_barrier
; #define LDA8(dst, b, h) _Pragma("unroll") for (int m = 0; m < 4; ++m) _Pragma("unroll") for (int k = 0; k < 2; ++k) \
;     dst[m][k] = *(const bf16x8*)((const char*)SA8(b, h) + lds_byte8(wr * 64 + m * 16 + fr, k * 32 + fq * 8))
; #define LDB8(dst, b, h) _Pragma("unroll") for (int n = 0; n < 2; ++n) _Pragma("unroll") for (int k = 0; k < 2; ++k) \
;     dst[n][k] = *(const bf16x8*)((const char*)SB8(b, h) + lds_byte8(wc * 32 + n * 16 + fr, k * 32 + fq * 8))
; #define WAIT_V8(n) asm volatile("s_waitcnt vmcnt(" #n ")" ::: "memory")
; #define WAIT_L8(n) asm volatile("s_waitcnt lgkmcnt(" #n ")" ::: "memory")
; #define BAR8 __builtin_amdgcn_s_barrier()
; #define SCHED8 __builtin_amdgcn_sched_barrier(0)
;     ...
;     BAR8; WAIT_L8(0); MMA8(1, 0, At, B0); BAR8; SCHED8;
;     STAGE8(SB8(1, 1), Bt, K, bcol + 128, tt + 3);
;     WAIT_V8(6); BAR8; MMA8(1, 1, At, B1); BAR8;
;   }
;   { LDB8(B0, 0, 0); LDA8(At, 0, 0); STAGE8(SA8(1, 1), A, lda, brow + 128, nt - 1);
;     BAR8; WAIT_L8(0); MMA8(0, 0, At, B0); BAR8;
;     LDB8(B1, 0, 1); BAR8; WAIT_L8(0); MMA8(0, 1, At, B1); BAR8;
	s_waitcnt lgkmcnt(0)
	s_waitcnt lgkmcnt(0)
	v_mfma_f32_16x16x32_f16 v[64:67], v[190:193], v[174:177], v[64:67]
	v_mfma_f32_16x16x32_f16 v[60:63], v[190:193], v[182:185], v[60:63]
	v_mfma_f32_16x16x32_f16 v[56:59], v[198:201], v[174:177], v[56:59]
	v_mfma_f32_16x16x32_f16 v[52:55], v[198:201], v[182:185], v[52:55]
	v_mfma_f32_16x16x32_f16 v[48:51], v[206:209], v[174:177], v[48:51]
	v_mfma_f32_16x16x32_f16 v[44:47], v[206:209], v[182:185], v[44:47]
	v_mfma_f32_16x16x32_f16 v[40:43], v[214:217], v[174:177], v[40:43]
	v_mfma_f32_16x16x32_f16 v[36:39], v[214:217], v[182:185], v[36:39]
	v_mfma_f32_16x16x32_f16 v[64:67], v[194:197], v[178:181], v[64:67]
	v_mfma_f32_16x16x32_f16 v[60:63], v[194:197], v[186:189], v[60:63]
	v_mfma_f32_16x16x32_f16 v[56:59], v[202:205], v[178:181], v[56:59]
	v_mfma_f32_16x16x32_f16 v[52:55], v[202:205], v[186:189], v[52:55]
	v_mfma_f32_16x16x32_f16 v[48:51], v[210:213], v[178:181], v[48:51]
	v_mfma_f32_16x16x32_f16 v[44:47], v[210:213], v[186:189], v[44:47]
	v_mfma_f32_16x16x32_f16 v[40:43], v[218:221], v[178:181], v[40:43]
	v_mfma_f32_16x16x32_f16 v[36:39], v[218:221], v[186:189], v[36:39]
	s_barrier
	v_readfirstlane_b32 s15, v168
	v_lshl_add_u64 v[174:175], v[228:229], 0, s[66:67]
	s_mov_b32 m0, s15
	v_readfirstlane_b32 s15, v170
	global_load_lds_dwordx4 v[174:175], off
	v_lshl_add_u64 v[174:175], v[236:237], 0, s[66:67]
	s_mov_b32 m0, s15
	s_nop 0
	global_load_lds_dwordx4 v[174:175], off
	s_waitcnt vmcnt(6)
	s_barrier
	v_mfma_f32_16x16x32_f16 v[32:35], v[190:193], v[230:233], v[32:35]
	v_mfma_f32_16x16x32_f16 v[28:31], v[190:193], v[242:245], v[28:31]
	v_mfma_f32_16x16x32_f16 v[24:27], v[198:201], v[230:233], v[24:27]
	v_mfma_f32_16x16x32_f16 v[20:23], v[198:201], v[242:245], v[20:23]
	v_mfma_f32_16x16x32_f16 v[16:19], v[206:209], v[230:233], v[16:19]
	v_mfma_f32_16x16x32_f16 v[12:15], v[206:209], v[242:245], v[12:15]
	v_mfma_f32_16x16x32_f16 v[8:11], v[214:217], v[230:233], v[8:11]
	v_mfma_f32_16x16x32_f16 v[4:7], v[214:217], v[242:245], v[4:7]
	v_mfma_f32_16x16x32_f16 v[32:35], v[194:197], v[238:241], v[32:35]
	v_mfma_f32_16x16x32_f16 v[28:31], v[194:197], v[246:249], v[28:31]
	v_mfma_f32_16x16x32_f16 v[24:27], v[202:205], v[238:241], v[24:27]
	v_mfma_f32_16x16x32_f16 v[20:23], v[202:205], v[246:249], v[20:23]
	v_mfma_f32_16x16x32_f16 v[16:19], v[210:213], v[238:241], v[16:19]
	v_mfma_f32_16x16x32_f16 v[12:15], v[210:213], v[246:249], v[12:15]
	v_mfma_f32_16x16x32_f16 v[8:11], v[218:221], v[238:241], v[8:11]
	v_mfma_f32_16x16x32_f16 v[4:7], v[218:221], v[246:249], v[4:7]
	s_add_i32 s14, s14, 2
	s_add_u32 s12, s12, 0x100
	s_addc_u32 s13, s13, 0
	s_cmp_lt_u32 s14, 12
	s_barrier
	s_cbranch_scc1 .LBB0_192
	s_add_u32 s4, s4, 0x40780
	s_addc_u32 s5, s5, 0
	v_lshl_add_u64 v[132:133], s[4:5], 0, v[132:133]
	v_readfirstlane_b32 s12, v172
	v_lshl_add_u64 v[0:1], v[0:1], 1, v[132:133]
	s_mov_b32 m0, s12
	ds_read_b128 v[138:141], v173
	ds_read_b128 v[142:145], v173 offset:1024
	ds_read_b128 v[160:163], v173 offset:2048
	ds_read_b128 v[164:167], v173 offset:3072
	ds_read_b128 v[174:177], v156
	ds_read_b128 v[178:181], v156 offset:1024
	ds_read_b128 v[182:185], v154
	ds_read_b128 v[186:189], v154 offset:1024
	ds_read_b128 v[190:193], v153
	ds_read_b128 v[194:197], v153 offset:1024
	ds_read_b128 v[198:201], v152
	ds_read_b128 v[202:205], v152 offset:1024
	global_load_lds_dwordx4 v[0:1], off
	v_lshl_add_u64 v[0:1], s[4:5], 0, v[136:137]
	v_readfirstlane_b32 s4, v171
	v_lshl_add_u64 v[0:1], v[134:135], 1, v[0:1]
	s_mov_b32 m0, s4
	s_nop 0
	global_load_lds_dwordx4 v[0:1], off
	s_barrier
	s_waitcnt lgkmcnt(0)
	s_waitcnt lgkmcnt(0)
	v_mfma_f32_16x16x32_f16 v[128:131], v[174:177], v[138:141], v[128:131]
	v_mfma_f32_16x16x32_f16 v[124:127], v[174:177], v[160:163], v[124:127]
	v_mfma_f32_16x16x32_f16 v[120:123], v[182:185], v[138:141], v[120:123]
	v_mfma_f32_16x16x32_f16 v[112:115], v[190:193], v[138:141], v[112:115]
	v_mfma_f32_16x16x32_f16 v[128:131], v[178:181], v[142:145], v[128:131]
	v_mfma_f32_16x16x32_f16 v[124:127], v[178:181], v[164:167], v[124:127]
	v_mfma_f32_16x16x32_f16 v[120:123], v[186:189], v[142:145], v[120:123]
	v_mfma_f32_16x16x32_f16 v[116:119], v[182:185], v[160:163], v[116:119]
	v_mfma_f32_16x16x32_f16 v[112:115], v[194:197], v[142:145], v[112:115]
	v_mfma_f32_16x16x32_f16 v[108:111], v[190:193], v[160:163], v[108:111]
	v_mfma_f32_16x16x32_f16 v[104:107], v[198:201], v[138:141], v[104:107]
	v_mfma_f32_16x16x32_f16 v[100:103], v[198:201], v[160:163], v[100:103]
	v_mfma_f32_16x16x32_f16 v[132:135], v[186:189], v[164:167], v[116:119]
	v_mfma_f32_16x16x32_f16 v[170:173], v[194:197], v[164:167], v[108:111]
	v_mfma_f32_16x16x32_f16 v[206:209], v[202:205], v[142:145], v[104:107]
	v_mfma_f32_16x16x32_f16 v[210:213], v[202:205], v[164:167], v[100:103]
	s_barrier
	s_nop 1
	ds_read_b128 v[100:103], v169
	ds_read_b128 v[104:107], v169 offset:1024
	ds_read_b128 v[108:111], v169 offset:2048
	ds_read_b128 v[116:119], v169 offset:3072
	s_barrier
	s_waitcnt lgkmcnt(0)
	s_waitcnt lgkmcnt(0)
	v_mfma_f32_16x16x32_f16 v[80:83], v[190:193], v[100:103], v[80:83]
	v_mfma_f32_16x16x32_f16 v[76:79], v[190:193], v[108:111], v[76:79]
	v_mfma_f32_16x16x32_f16 v[72:75], v[198:201], v[100:103], v[72:75]
	v_mfma_f32_16x16x32_f16 v[68:71], v[198:201], v[108:111], v[68:71]
	v_mfma_f32_16x16x32_f16 v[96:99], v[174:177], v[100:103], v[96:99]
	v_mfma_f32_16x16x32_f16 v[92:95], v[174:177], v[108:111], v[92:95]
	v_mfma_f32_16x16x32_f16 v[88:91], v[182:185], v[100:103], v[88:91]
	v_mfma_f32_16x16x32_f16 v[84:87], v[182:185], v[108:111], v[84:87]
	v_mfma_f32_16x16x32_f16 v[80:83], v[194:197], v[104:107], v[80:83]
	v_mfma_f32_16x16x32_f16 v[76:79], v[194:197], v[116:119], v[76:79]
	v_mfma_f32_16x16x32_f16 v[72:75], v[202:205], v[104:107], v[72:75]
	v_mfma_f32_16x16x32_f16 v[68:71], v[202:205], v[116:119], v[68:71]
	v_mfma_f32_16x16x32_f16 v[214:217], v[178:181], v[104:107], v[96:99]
	v_mfma_f32_16x16x32_f16 v[174:177], v[178:181], v[116:119], v[92:95]
	v_mfma_f32_16x16x32_f16 v[178:181], v[186:189], v[104:107], v[88:91]
	v_mfma_f32_16x16x32_f16 v[182:185], v[186:189], v[116:119], v[84:87]
	s_barrier
; #define LDA8(dst, b, h) _Pragma("unroll") for (int m = 0; m < 4; ++m) _Pragma("unroll") for (int k = 0; k < 2; ++k) \
;     dst[m][k] = *(const bf16x8*)((const char*)SA8(b, h) + lds_byte8(wr * 64 + m * 16 + fr, k * 32 + fq * 8))
; #define LDB8(dst, b, h) _Pragma("unroll") for (int n = 0; n < 2; ++n) _Pragma("unroll") for (int k = 0; k < 2; ++k) \
;     dst[n][k] = *(const bf16x8*)((const char*)SB8(b, h) + lds_byte8(wc * 32 + n * 16 + fr, k * 32 + fq * 8))
; #define WAIT_V8(n) asm volatile("s_waitcnt vmcnt(" #n ")" ::: "memory")
; #define WAIT_L8(n) asm volatile("s_waitcnt lgkmcnt(" #n ")" ::: "memory")
; #define BAR8 __builtin_amdgcn_s_barrier()
;     ...
;     LDA8(At, 0, 1); WAIT_V8(4); BAR8; WAIT_L8(0); MMA8(1, 0, At, B0); MMA8(1, 1, At, B1); BAR8; }
;   { LDB8(B0, 1, 0); LDA8(At, 1, 0); WAIT_V8(2); BAR8; WAIT_L8(0); MMA8(0, 0, At, B0); BAR8;
	s_nop 0
	ds_read_b128 v[84:87], v156 offset:16384
	ds_read_b128 v[88:91], v156 offset:17408
	ds_read_b128 v[92:95], v154 offset:16384
	ds_read_b128 v[96:99], v154 offset:17408
	ds_read_b128 v[186:189], v153 offset:16384
	ds_read_b128 v[190:193], v153 offset:17408
	ds_read_b128 v[194:197], v152 offset:16384
	ds_read_b128 v[198:201], v152 offset:17408
	s_waitcnt vmcnt(4)
	s_barrier
	s_waitcnt lgkmcnt(0)
	s_waitcnt lgkmcnt(0)
	v_mfma_f32_16x16x32_f16 v[64:67], v[84:87], v[138:141], v[64:67]
	v_mfma_f32_16x16x32_f16 v[60:63], v[84:87], v[160:163], v[60:63]
	v_mfma_f32_16x16x32_f16 v[56:59], v[92:95], v[138:141], v[56:59]
	v_mfma_f32_16x16x32_f16 v[52:55], v[92:95], v[160:163], v[52:55]
	v_mfma_f32_16x16x32_f16 v[48:51], v[186:189], v[138:141], v[48:51]
	v_mfma_f32_16x16x32_f16 v[44:47], v[186:189], v[160:163], v[44:47]
	v_mfma_f32_16x16x32_f16 v[64:67], v[88:91], v[142:145], v[64:67]
	v_mfma_f32_16x16x32_f16 v[60:63], v[88:91], v[164:167], v[60:63]
	v_mfma_f32_16x16x32_f16 v[56:59], v[96:99], v[142:145], v[56:59]
	v_mfma_f32_16x16x32_f16 v[52:55], v[96:99], v[164:167], v[52:55]
	v_mfma_f32_16x16x32_f16 v[48:51], v[190:193], v[142:145], v[48:51]
	v_mfma_f32_16x16x32_f16 v[44:47], v[190:193], v[164:167], v[44:47]
	v_mfma_f32_16x16x32_f16 v[40:43], v[194:197], v[138:141], v[40:43]
	v_mfma_f32_16x16x32_f16 v[36:39], v[194:197], v[160:163], v[36:39]
	v_mfma_f32_16x16x32_f16 v[136:139], v[198:201], v[142:145], v[40:43]
	v_mfma_f32_16x16x32_f16 v[140:143], v[198:201], v[164:167], v[36:39]
	v_mfma_f32_16x16x32_f16 v[32:35], v[84:87], v[100:103], v[32:35]
	v_mfma_f32_16x16x32_f16 v[28:31], v[84:87], v[108:111], v[28:31]
	v_mfma_f32_16x16x32_f16 v[24:27], v[92:95], v[100:103], v[24:27]
	v_mfma_f32_16x16x32_f16 v[20:23], v[92:95], v[108:111], v[20:23]
	v_mfma_f32_16x16x32_f16 v[16:19], v[186:189], v[100:103], v[16:19]
	v_mfma_f32_16x16x32_f16 v[12:15], v[186:189], v[108:111], v[12:15]
	v_mfma_f32_16x16x32_f16 v[8:11], v[194:197], v[100:103], v[8:11]
	v_mfma_f32_16x16x32_f16 v[4:7], v[194:197], v[108:111], v[4:7]
	v_mfma_f32_16x16x32_f16 v[160:163], v[88:91], v[104:107], v[32:35]
	v_mfma_f32_16x16x32_f16 v[164:167], v[88:91], v[116:119], v[28:31]
	v_mfma_f32_16x16x32_f16 v[202:205], v[96:99], v[104:107], v[24:27]
	v_mfma_f32_16x16x32_f16 v[218:221], v[96:99], v[116:119], v[20:23]
	v_mfma_f32_16x16x32_f16 v[230:233], v[190:193], v[104:107], v[16:19]
	v_mfma_f32_16x16x32_f16 v[186:189], v[190:193], v[116:119], v[12:15]
	v_mfma_f32_16x16x32_f16 v[190:193], v[198:201], v[104:107], v[8:11]
	v_mfma_f32_16x16x32_f16 v[194:197], v[198:201], v[116:119], v[4:7]
	s_barrier
	s_nop 0
	ds_read_b128 v[4:7], v159
	ds_read_b128 v[8:11], v159 offset:1024
	ds_read_b128 v[198:201], v159 offset:2048
	ds_read_b128 v[238:241], v159 offset:3072
	ds_read_b128 v[16:19], v156 offset:32768
	ds_read_b128 v[20:23], v156 offset:33792
	ds_read_b128 v[24:27], v154 offset:32768
	ds_read_b128 v[32:35], v154 offset:33792
	ds_read_b128 v[36:39], v153 offset:32768
	ds_read_b128 v[40:43], v153 offset:33792
	ds_read_b128 v[242:245], v152 offset:32768
	ds_read_b128 v[246:249], v152 offset:33792
	s_waitcnt vmcnt(2)
	s_barrier
	s_waitcnt lgkmcnt(0)
	s_waitcnt lgkmcnt(0)
	v_mfma_f32_16x16x32_f16 v[12:15], v[16:19], v[4:7], v[128:131]
	v_mfma_f32_16x16x32_f16 v[104:107], v[20:23], v[8:11], v[12:15]
	v_mfma_f32_16x16x32_f16 v[12:15], v[16:19], v[198:201], v[124:127]
	v_mfma_f32_16x16x32_f16 v[116:119], v[20:23], v[238:241], v[12:15]
	v_mfma_f32_16x16x32_f16 v[12:15], v[24:27], v[4:7], v[120:123]
	v_mfma_f32_16x16x32_f16 v[100:103], v[32:35], v[8:11], v[12:15]
	v_mfma_f32_16x16x32_f16 v[12:15], v[24:27], v[198:201], v[132:135]
	v_mfma_f32_16x16x32_f16 v[108:111], v[32:35], v[238:241], v[12:15]
	v_mfma_f32_16x16x32_f16 v[12:15], v[36:39], v[4:7], v[112:115]
	v_mfma_f32_16x16x32_f16 v[92:95], v[40:43], v[8:11], v[12:15]
	v_mfma_f32_16x16x32_f16 v[12:15], v[36:39], v[198:201], v[170:173]
	v_mfma_f32_16x16x32_f16 v[96:99], v[40:43], v[238:241], v[12:15]
	v_mfma_f32_16x16x32_f16 v[12:15], v[242:245], v[4:7], v[206:209]
	v_mfma_f32_16x16x32_f16 v[84:87], v[246:249], v[8:11], v[12:15]
	v_mfma_f32_16x16x32_f16 v[12:15], v[242:245], v[198:201], v[210:213]
	v_mfma_f32_16x16x32_f16 v[88:91], v[246:249], v[238:241], v[12:15]
	s_barrier
; #define LDA8(dst, b, h) _Pragma("unroll") for (int m = 0; m < 4; ++m) _Pragma("unroll") for (int k = 0; k < 2; ++k) \
;     dst[m][k] = *(const bf16x8*)((const char*)SA8(b, h) + lds_byte8(wr * 64 + m * 16 + fr, k * 32 + fq * 8))
; #define LDB8(dst, b, h) _Pragma("unroll") for (int n = 0; n < 2; ++n) _Pragma("unroll") for (int k = 0; k < 2; ++k) \
;     dst[n][k] = *(const bf16x8*)((const char*)SB8(b, h) + lds_byte8(wc * 32 + n * 16 + fr, k * 32 + fq * 8))
; #define WAIT_V8(n) asm volatile("s_waitcnt vmcnt(" #n ")" ::: "memory")
; #define WAIT_L8(n) asm volatile("s_waitcnt lgkmcnt(" #n ")" ::: "memory")
; #define BAR8 __builtin_amdgcn_s_barrier()
;     ...
;     LDB8(B1, 1, 1); WAIT_V8(0); BAR8; WAIT_L8(0); MMA8(0, 1, At, B1); BAR8;
;     LDA8(At, 1, 1); BAR8; WAIT_L8(0); MMA8(1, 0, At, B0); MMA8(1, 1, At, B1); BAR8; }
;   if (wr == 0) BAR8;
;   __syncthreads();
	ds_read_b128 v[132:135], v158
	ds_read_b128 v[168:171], v158 offset:1024
	ds_read_b128 v[206:209], v158 offset:2048
	ds_read_b128 v[210:213], v158 offset:3072
	s_waitcnt vmcnt(0)
	s_barrier
	s_waitcnt lgkmcnt(0)
	s_waitcnt lgkmcnt(0)
	v_mfma_f32_16x16x32_f16 v[12:15], v[16:19], v[132:135], v[214:217]
	v_mfma_f32_16x16x32_f16 v[16:19], v[16:19], v[206:209], v[174:177]
	v_mfma_f32_16x16x32_f16 v[12:15], v[20:23], v[168:171], v[12:15]
	v_mfma_f32_16x16x32_f16 v[28:31], v[20:23], v[210:213], v[16:19]
	v_mfma_f32_16x16x32_f16 v[16:19], v[24:27], v[132:135], v[178:181]
	v_mfma_f32_16x16x32_f16 v[20:23], v[24:27], v[206:209], v[182:185]
	v_mfma_f32_16x16x32_f16 v[16:19], v[32:35], v[168:171], v[16:19]
	v_mfma_f32_16x16x32_f16 v[32:35], v[32:35], v[210:213], v[20:23]
	v_mfma_f32_16x16x32_f16 v[20:23], v[36:39], v[132:135], v[80:83]
	v_mfma_f32_16x16x32_f16 v[24:27], v[36:39], v[206:209], v[76:79]
	v_mfma_f32_16x16x32_f16 v[20:23], v[40:43], v[168:171], v[20:23]
	v_mfma_f32_16x16x32_f16 v[36:39], v[40:43], v[210:213], v[24:27]
	v_mfma_f32_16x16x32_f16 v[24:27], v[242:245], v[132:135], v[72:75]
	v_mfma_f32_16x16x32_f16 v[40:43], v[242:245], v[206:209], v[68:71]
	v_mfma_f32_16x16x32_f16 v[24:27], v[246:249], v[168:171], v[24:27]
	v_mfma_f32_16x16x32_f16 v[40:43], v[246:249], v[210:213], v[40:43]
	s_barrier
	ds_read_b128 v[68:71], v156 offset:49152
	ds_read_b128 v[72:75], v156 offset:50176
	ds_read_b128 v[156:159], v154 offset:49152
	ds_read_b128 v[172:175], v154 offset:50176
	ds_read_b128 v[176:179], v153 offset:49152
	ds_read_b128 v[180:183], v153 offset:50176
	ds_read_b128 v[214:217], v152 offset:49152
	ds_read_b128 v[150:153], v152 offset:50176
	s_barrier
	s_waitcnt lgkmcnt(0)
	s_waitcnt lgkmcnt(0)
	v_mfma_f32_16x16x32_f16 v[64:67], v[68:71], v[4:7], v[64:67]
	v_mfma_f32_16x16x32_f16 v[56:59], v[156:159], v[4:7], v[56:59]
	v_mfma_f32_16x16x32_f16 v[48:51], v[176:179], v[4:7], v[48:51]
	v_mfma_f32_16x16x32_f16 v[4:7], v[214:217], v[4:7], v[136:139]
	v_mfma_f32_16x16x32_f16 v[128:131], v[72:75], v[8:11], v[64:67]
	v_mfma_f32_16x16x32_f16 v[60:63], v[68:71], v[198:201], v[60:63]
	v_mfma_f32_16x16x32_f16 v[120:123], v[172:175], v[8:11], v[56:59]
	v_mfma_f32_16x16x32_f16 v[52:55], v[156:159], v[198:201], v[52:55]
	v_mfma_f32_16x16x32_f16 v[80:83], v[180:183], v[8:11], v[48:51]
	v_mfma_f32_16x16x32_f16 v[44:47], v[176:179], v[198:201], v[44:47]
	v_mfma_f32_16x16x32_f16 v[8:11], v[150:153], v[8:11], v[4:7]
	v_mfma_f32_16x16x32_f16 v[4:7], v[214:217], v[198:201], v[140:143]
	v_mfma_f32_16x16x32_f16 v[124:127], v[72:75], v[238:241], v[60:63]
	v_mfma_f32_16x16x32_f16 v[112:115], v[172:175], v[238:241], v[52:55]
	v_mfma_f32_16x16x32_f16 v[76:79], v[180:183], v[238:241], v[44:47]
	v_mfma_f32_16x16x32_f16 v[4:7], v[150:153], v[238:241], v[4:7]
	v_mfma_f32_16x16x32_f16 v[44:47], v[68:71], v[132:135], v[160:163]
	v_mfma_f32_16x16x32_f16 v[48:51], v[68:71], v[206:209], v[164:167]
	v_mfma_f32_16x16x32_f16 v[52:55], v[156:159], v[206:209], v[218:221]
	v_mfma_f32_16x16x32_f16 v[56:59], v[176:179], v[206:209], v[186:189]
	v_mfma_f32_16x16x32_f16 v[44:47], v[72:75], v[168:171], v[44:47]
	v_mfma_f32_16x16x32_f16 v[60:63], v[72:75], v[210:213], v[48:51]
	v_mfma_f32_16x16x32_f16 v[48:51], v[156:159], v[132:135], v[202:205]
	v_mfma_f32_16x16x32_f16 v[64:67], v[172:175], v[210:213], v[52:55]
	v_mfma_f32_16x16x32_f16 v[52:55], v[176:179], v[132:135], v[230:233]
	v_mfma_f32_16x16x32_f16 v[68:71], v[180:183], v[210:213], v[56:59]
	v_mfma_f32_16x16x32_f16 v[56:59], v[214:217], v[132:135], v[190:193]
	v_mfma_f32_16x16x32_f16 v[72:75], v[214:217], v[206:209], v[194:197]
	v_mfma_f32_16x16x32_f16 v[48:51], v[172:175], v[168:171], v[48:51]
	v_mfma_f32_16x16x32_f16 v[52:55], v[180:183], v[168:171], v[52:55]
	v_mfma_f32_16x16x32_f16 v[56:59], v[150:153], v[168:171], v[56:59]
	v_mfma_f32_16x16x32_f16 v[72:75], v[150:153], v[210:213], v[72:75]
	s_movk_i32 s4, 0x100
	v_cmp_gt_u32_e32 vcc, s4, v3
	s_barrier
	s_and_saveexec_b64 s[4:5], vcc
	s_cbranch_execz .LBB0_195
	s_barrier

; #define LDA8(dst, b, h) _Pragma("unroll") for (int m = 0; m < 4; ++m) _Pragma("unroll") for (int k = 0; k < 2; ++k) \
;     dst[m][k] = *(const bf16x8*)((const char*)SA8(b, h) + lds_byte8(wr * 64 + m * 16 + fr, k * 32 + fq * 8))
; #define LDB8(dst, b, h) _Pragma("unroll") for (int n = 0; n < 2; ++n) _Pragma("unroll") for (int k = 0; k < 2; ++k) \
;     dst[n][k] = *(const bf16x8*)((const char*)SB8(b, h) + lds_byte8(wc * 32 + n * 16 + fr, k * 32 + fq * 8))
; #define WAIT_L8(n) asm volatile("s_waitcnt lgkmcnt(" #n ")" ::: "memory")
; #define BAR8 __builtin_amdgcn_s_barrier()
; #define SCHED8 __builtin_amdgcn_sched_barrier(0)
;     ...
;     LDB8(B0, 0, 0); SCHED8; LDA8(At, 0, 0); STAGE8(SA8(1, 1), A, lda, brow + 128, tt + 1);
;     WAIT_L8(8); BAR8; WAIT_L8(0); MMA8(0, 0, At, B0); BAR8; SCHED8;
;     LDB8(B1, 0, 1); STAGE8(SB8(0, 0), Bt, K, bcol, tt + 2);
;     BAR8; WAIT_L8(0); MMA8(0, 1, At, B1); BAR8;
;     LDA8(At, 0, 1); STAGE8(SA8(0, 0), A, lda, brow, tt + 2);
;     BAR8; WAIT_L8(0); MMA8(1, 0, At, B0); BAR8; SCHED8;
;     STAGE8(SB8(0, 1), Bt, K, bcol + 128, tt + 2);
.LBB0_242:
	ds_read_b128 v[174:177], v171
	ds_read_b128 v[178:181], v171 offset:1024
	ds_read_b128 v[182:185], v171 offset:2048
	ds_read_b128 v[186:189], v171 offset:3072
	v_add_u32_e32 v172, 0xc000, v150
	v_lshl_add_u64 v[222:223], v[140:141], 0, s[14:15]
	v_readfirstlane_b32 s20, v172
	v_lshl_add_u64 v[226:227], v[222:223], 0, s[34:35]
	s_mov_b32 m0, s20
	v_add_u32_e32 v173, 0xe000, v150
	ds_read_b128 v[190:193], v156
	ds_read_b128 v[194:197], v156 offset:1024
	ds_read_b128 v[198:201], v154
	ds_read_b128 v[202:205], v154 offset:1024
	ds_read_b128 v[206:209], v153
	ds_read_b128 v[210:213], v153 offset:1024
	ds_read_b128 v[214:217], v152
	ds_read_b128 v[218:221], v152 offset:1024
	global_load_lds_dwordx4 v[226:227], off
	v_lshl_add_u64 v[226:227], v[138:139], 0, s[14:15]
	v_readfirstlane_b32 s20, v173
	v_lshl_add_u64 v[228:229], v[226:227], 0, s[34:35]
	s_mov_b32 m0, s20
	s_nop 0
	global_load_lds_dwordx4 v[228:229], off
	s_waitcnt lgkmcnt(8)
	s_barrier
	s_waitcnt lgkmcnt(0)
	s_waitcnt lgkmcnt(0)
	v_mfma_f32_16x16x32_f16 v[128:131], v[190:193], v[174:177], v[128:131]
	v_mfma_f32_16x16x32_f16 v[124:127], v[190:193], v[182:185], v[124:127]
	v_mfma_f32_16x16x32_f16 v[120:123], v[198:201], v[174:177], v[120:123]
	v_mfma_f32_16x16x32_f16 v[116:119], v[198:201], v[182:185], v[116:119]
	v_mfma_f32_16x16x32_f16 v[112:115], v[206:209], v[174:177], v[112:115]
	v_mfma_f32_16x16x32_f16 v[108:111], v[206:209], v[182:185], v[108:111]
	v_mfma_f32_16x16x32_f16 v[104:107], v[214:217], v[174:177], v[104:107]
	v_mfma_f32_16x16x32_f16 v[100:103], v[214:217], v[182:185], v[100:103]
	v_mfma_f32_16x16x32_f16 v[128:131], v[194:197], v[178:181], v[128:131]
	v_mfma_f32_16x16x32_f16 v[124:127], v[194:197], v[186:189], v[124:127]
	v_mfma_f32_16x16x32_f16 v[120:123], v[202:205], v[178:181], v[120:123]
	v_mfma_f32_16x16x32_f16 v[116:119], v[202:205], v[186:189], v[116:119]
	v_mfma_f32_16x16x32_f16 v[112:115], v[210:213], v[178:181], v[112:115]
	v_mfma_f32_16x16x32_f16 v[108:111], v[210:213], v[186:189], v[108:111]
	v_mfma_f32_16x16x32_f16 v[104:107], v[218:221], v[178:181], v[104:107]
	v_mfma_f32_16x16x32_f16 v[100:103], v[218:221], v[186:189], v[100:103]
	s_barrier
	v_lshl_add_u64 v[228:229], v[142:143], 0, s[14:15]
	v_readfirstlane_b32 s20, v151
	v_lshl_add_u64 v[236:237], v[228:229], 0, s[30:31]
	s_mov_b32 m0, s20
	ds_read_b128 v[230:233], v168
	ds_read_b128 v[238:241], v168 offset:1024
	ds_read_b128 v[242:245], v168 offset:2048
	ds_read_b128 v[246:249], v168 offset:3072
	global_load_lds_dwordx4 v[236:237], off
	v_lshl_add_u64 v[236:237], v[144:145], 0, s[14:15]
	v_readfirstlane_b32 s20, v158
	v_lshl_add_u64 v[250:251], v[236:237], 0, s[30:31]
	s_mov_b32 m0, s20
	s_nop 0
	global_load_lds_dwordx4 v[250:251], off
	s_barrier
	s_waitcnt lgkmcnt(0)
	s_waitcnt lgkmcnt(0)
	v_mfma_f32_16x16x32_f16 v[96:99], v[190:193], v[230:233], v[96:99]
	v_mfma_f32_16x16x32_f16 v[92:95], v[190:193], v[242:245], v[92:95]
	v_mfma_f32_16x16x32_f16 v[88:91], v[198:201], v[230:233], v[88:91]
	v_mfma_f32_16x16x32_f16 v[84:87], v[198:201], v[242:245], v[84:87]
	v_mfma_f32_16x16x32_f16 v[80:83], v[206:209], v[230:233], v[80:83]
	v_mfma_f32_16x16x32_f16 v[76:79], v[206:209], v[242:245], v[76:79]
	v_mfma_f32_16x16x32_f16 v[72:75], v[214:217], v[230:233], v[72:75]
	v_mfma_f32_16x16x32_f16 v[68:71], v[214:217], v[242:245], v[68:71]
	v_mfma_f32_16x16x32_f16 v[96:99], v[194:197], v[238:241], v[96:99]
	v_mfma_f32_16x16x32_f16 v[92:95], v[194:197], v[246:249], v[92:95]
	v_mfma_f32_16x16x32_f16 v[88:91], v[202:205], v[238:241], v[88:91]
	v_mfma_f32_16x16x32_f16 v[84:87], v[202:205], v[246:249], v[84:87]
	v_mfma_f32_16x16x32_f16 v[80:83], v[210:213], v[238:241], v[80:83]
	v_mfma_f32_16x16x32_f16 v[76:79], v[210:213], v[246:249], v[76:79]
	v_mfma_f32_16x16x32_f16 v[72:75], v[218:221], v[238:241], v[72:75]
	v_mfma_f32_16x16x32_f16 v[68:71], v[218:221], v[246:249], v[68:71]
	v_readfirstlane_b32 s20, v150
	v_lshl_add_u64 v[250:251], v[222:223], 0, s[10:11]
	s_mov_b32 m0, s20
	v_readfirstlane_b32 s20, v155
	s_barrier
	ds_read_b128 v[190:193], v156 offset:16384
	ds_read_b128 v[194:197], v156 offset:17408
	ds_read_b128 v[198:201], v154 offset:16384
	ds_read_b128 v[202:205], v154 offset:17408
	ds_read_b128 v[206:209], v153 offset:16384
	ds_read_b128 v[210:213], v153 offset:17408
	ds_read_b128 v[214:217], v152 offset:16384
	ds_read_b128 v[218:221], v152 offset:17408
	global_load_lds_dwordx4 v[250:251], off
	v_lshl_add_u64 v[250:251], v[226:227], 0, s[10:11]
	s_mov_b32 m0, s20
	s_nop 0
	global_load_lds_dwordx4 v[250:251], off
	s_barrier
	s_waitcnt lgkmcnt(0)
	s_waitcnt lgkmcnt(0)
	v_mfma_f32_16x16x32_f16 v[64:67], v[190:193], v[174:177], v[64:67]
	v_mfma_f32_16x16x32_f16 v[60:63], v[190:193], v[182:185], v[60:63]
	v_mfma_f32_16x16x32_f16 v[56:59], v[198:201], v[174:177], v[56:59]
	v_mfma_f32_16x16x32_f16 v[52:55], v[198:201], v[182:185], v[52:55]
	v_mfma_f32_16x16x32_f16 v[48:51], v[206:209], v[174:177], v[48:51]
	v_mfma_f32_16x16x32_f16 v[44:47], v[206:209], v[182:185], v[44:47]
	v_mfma_f32_16x16x32_f16 v[40:43], v[214:217], v[174:177], v[40:43]
	v_mfma_f32_16x16x32_f16 v[36:39], v[214:217], v[182:185], v[36:39]
	v_mfma_f32_16x16x32_f16 v[64:67], v[194:197], v[178:181], v[64:67]
	v_mfma_f32_16x16x32_f16 v[60:63], v[194:197], v[186:189], v[60:63]
	v_mfma_f32_16x16x32_f16 v[56:59], v[202:205], v[178:181], v[56:59]
	v_mfma_f32_16x16x32_f16 v[52:55], v[202:205], v[186:189], v[52:55]
	v_mfma_f32_16x16x32_f16 v[48:51], v[210:213], v[178:181], v[48:51]
	v_mfma_f32_16x16x32_f16 v[44:47], v[210:213], v[186:189], v[44:47]
	v_mfma_f32_16x16x32_f16 v[40:43], v[218:221], v[178:181], v[40:43]
	v_mfma_f32_16x16x32_f16 v[36:39], v[218:221], v[186:189], v[36:39]
	s_barrier
; #define LDA8(dst, b, h) _Pragma("unroll") for (int m = 0; m < 4; ++m) _Pragma("unroll") for (int k = 0; k < 2; ++k) \
;     dst[m][k] = *(const bf16x8*)((const char*)SA8(b, h) + lds_byte8(wr * 64 + m * 16 + fr, k * 32 + fq * 8))
; #define LDB8(dst, b, h) _Pragma("unroll") for (int n = 0; n < 2; ++n) _Pragma("unroll") for (int k = 0; k < 2; ++k) \
;     dst[n][k] = *(const bf16x8*)((const char*)SB8(b, h) + lds_byte8(wc * 32 + n * 16 + fr, k * 32 + fq * 8))
; #define WAIT_V8(n) asm volatile("s_waitcnt vmcnt(" #n ")" ::: "memory")
; #define WAIT_L8(n) asm volatile("s_waitcnt lgkmcnt(" #n ")" ::: "memory")
; #define BAR8 __builtin_amdgcn_s_barrier()
; #define SCHED8 __builtin_amdgcn_sched_barrier(0)
;     ...
;     STAGE8(SB8(0, 1), Bt, K, bcol + 128, tt + 2);
;     WAIT_V8(6); BAR8; MMA8(1, 1, At, B1); BAR8;
;     LDB8(B0, 1, 0); SCHED8; LDA8(At, 1, 0); STAGE8(SA8(0, 1), A, lda, brow + 128, tt + 2);
;     WAIT_L8(8); BAR8; WAIT_L8(0); MMA8(0, 0, At, B0); BAR8; SCHED8;
;     LDB8(B1, 1, 1); STAGE8(SB8(1, 0), Bt, K, bcol, tt + 3);
;     BAR8; WAIT_L8(0); MMA8(0, 1, At, B1); BAR8;
;     LDA8(At, 1, 1); STAGE8(SA8(1, 0), A, lda, brow, tt + 3);
	v_readfirstlane_b32 s20, v160
	v_lshl_add_u64 v[174:175], v[228:229], 0, s[56:57]
	s_mov_b32 m0, s20
	v_readfirstlane_b32 s20, v161
	global_load_lds_dwordx4 v[174:175], off
	v_lshl_add_u64 v[174:175], v[236:237], 0, s[56:57]
	s_mov_b32 m0, s20
	s_nop 0
	global_load_lds_dwordx4 v[174:175], off
	s_waitcnt vmcnt(6)
	s_barrier
	v_mfma_f32_16x16x32_f16 v[32:35], v[190:193], v[230:233], v[32:35]
	v_mfma_f32_16x16x32_f16 v[28:31], v[190:193], v[242:245], v[28:31]
	v_mfma_f32_16x16x32_f16 v[24:27], v[198:201], v[230:233], v[24:27]
	v_mfma_f32_16x16x32_f16 v[20:23], v[198:201], v[242:245], v[20:23]
	v_mfma_f32_16x16x32_f16 v[16:19], v[206:209], v[230:233], v[16:19]
	v_mfma_f32_16x16x32_f16 v[12:15], v[206:209], v[242:245], v[12:15]
	v_mfma_f32_16x16x32_f16 v[8:11], v[214:217], v[230:233], v[8:11]
	v_mfma_f32_16x16x32_f16 v[4:7], v[214:217], v[242:245], v[4:7]
	v_mfma_f32_16x16x32_f16 v[32:35], v[194:197], v[238:241], v[32:35]
	v_mfma_f32_16x16x32_f16 v[28:31], v[194:197], v[246:249], v[28:31]
	v_mfma_f32_16x16x32_f16 v[24:27], v[202:205], v[238:241], v[24:27]
	v_mfma_f32_16x16x32_f16 v[20:23], v[202:205], v[246:249], v[20:23]
	v_mfma_f32_16x16x32_f16 v[16:19], v[210:213], v[238:241], v[16:19]
	v_mfma_f32_16x16x32_f16 v[12:15], v[210:213], v[246:249], v[12:15]
	v_mfma_f32_16x16x32_f16 v[8:11], v[218:221], v[238:241], v[8:11]
	v_mfma_f32_16x16x32_f16 v[4:7], v[218:221], v[246:249], v[4:7]
	s_barrier
	ds_read_b128 v[174:177], v159
	ds_read_b128 v[178:181], v159 offset:1024
	ds_read_b128 v[182:185], v159 offset:2048
	ds_read_b128 v[186:189], v159 offset:3072
	v_readfirstlane_b32 s20, v162
	v_lshl_add_u64 v[230:231], v[222:223], 0, s[18:19]
	s_mov_b32 m0, s20
	v_readfirstlane_b32 s20, v163
	ds_read_b128 v[190:193], v156 offset:32768
	ds_read_b128 v[194:197], v156 offset:33792
	ds_read_b128 v[198:201], v154 offset:32768
	ds_read_b128 v[202:205], v154 offset:33792
	ds_read_b128 v[206:209], v153 offset:32768
	ds_read_b128 v[210:213], v153 offset:33792
	ds_read_b128 v[214:217], v152 offset:32768
	ds_read_b128 v[218:221], v152 offset:33792
	global_load_lds_dwordx4 v[230:231], off
	v_lshl_add_u64 v[230:231], v[226:227], 0, s[18:19]
	s_mov_b32 m0, s20
	s_nop 0
	global_load_lds_dwordx4 v[230:231], off
	s_waitcnt lgkmcnt(8)
	s_barrier
	s_waitcnt lgkmcnt(0)
	s_waitcnt lgkmcnt(0)
	v_mfma_f32_16x16x32_f16 v[128:131], v[190:193], v[174:177], v[128:131]
	v_mfma_f32_16x16x32_f16 v[124:127], v[190:193], v[182:185], v[124:127]
	v_mfma_f32_16x16x32_f16 v[120:123], v[198:201], v[174:177], v[120:123]
	v_mfma_f32_16x16x32_f16 v[116:119], v[198:201], v[182:185], v[116:119]
	v_mfma_f32_16x16x32_f16 v[112:115], v[206:209], v[174:177], v[112:115]
	v_mfma_f32_16x16x32_f16 v[108:111], v[206:209], v[182:185], v[108:111]
	v_mfma_f32_16x16x32_f16 v[104:107], v[214:217], v[174:177], v[104:107]
	v_mfma_f32_16x16x32_f16 v[100:103], v[214:217], v[182:185], v[100:103]
	v_mfma_f32_16x16x32_f16 v[128:131], v[194:197], v[178:181], v[128:131]
	v_mfma_f32_16x16x32_f16 v[124:127], v[194:197], v[186:189], v[124:127]
	v_mfma_f32_16x16x32_f16 v[120:123], v[202:205], v[178:181], v[120:123]
	v_mfma_f32_16x16x32_f16 v[116:119], v[202:205], v[186:189], v[116:119]
	v_mfma_f32_16x16x32_f16 v[112:115], v[210:213], v[178:181], v[112:115]
	v_mfma_f32_16x16x32_f16 v[108:111], v[210:213], v[186:189], v[108:111]
	v_mfma_f32_16x16x32_f16 v[104:107], v[218:221], v[178:181], v[104:107]
	v_mfma_f32_16x16x32_f16 v[100:103], v[218:221], v[186:189], v[100:103]
	s_barrier
	v_readfirstlane_b32 s20, v164
	v_lshl_add_u64 v[250:251], v[228:229], 0, s[58:59]
	s_mov_b32 m0, s20
	v_readfirstlane_b32 s20, v165
	ds_read_b128 v[230:233], v157
	ds_read_b128 v[238:241], v157 offset:1024
	ds_read_b128 v[242:245], v157 offset:2048
	ds_read_b128 v[246:249], v157 offset:3072
	global_load_lds_dwordx4 v[250:251], off
	v_lshl_add_u64 v[250:251], v[236:237], 0, s[58:59]
	s_mov_b32 m0, s20
	s_nop 0
	global_load_lds_dwordx4 v[250:251], off
	s_barrier
	s_waitcnt lgkmcnt(0)
	s_waitcnt lgkmcnt(0)
	v_mfma_f32_16x16x32_f16 v[96:99], v[190:193], v[230:233], v[96:99]
	v_mfma_f32_16x16x32_f16 v[92:95], v[190:193], v[242:245], v[92:95]
	v_mfma_f32_16x16x32_f16 v[88:91], v[198:201], v[230:233], v[88:91]
	v_mfma_f32_16x16x32_f16 v[84:87], v[198:201], v[242:245], v[84:87]
	v_mfma_f32_16x16x32_f16 v[80:83], v[206:209], v[230:233], v[80:83]
	v_mfma_f32_16x16x32_f16 v[76:79], v[206:209], v[242:245], v[76:79]
	v_mfma_f32_16x16x32_f16 v[72:75], v[214:217], v[230:233], v[72:75]
	v_mfma_f32_16x16x32_f16 v[68:71], v[214:217], v[242:245], v[68:71]
	v_mfma_f32_16x16x32_f16 v[96:99], v[194:197], v[238:241], v[96:99]
	v_mfma_f32_16x16x32_f16 v[92:95], v[194:197], v[246:249], v[92:95]
	v_mfma_f32_16x16x32_f16 v[88:91], v[202:205], v[238:241], v[88:91]
	v_mfma_f32_16x16x32_f16 v[84:87], v[202:205], v[246:249], v[84:87]
	v_mfma_f32_16x16x32_f16 v[80:83], v[210:213], v[238:241], v[80:83]
	v_mfma_f32_16x16x32_f16 v[76:79], v[210:213], v[246:249], v[76:79]
	v_mfma_f32_16x16x32_f16 v[72:75], v[218:221], v[238:241], v[72:75]
	v_mfma_f32_16x16x32_f16 v[68:71], v[218:221], v[246:249], v[68:71]
	v_readfirstlane_b32 s20, v166
	v_lshl_add_u64 v[222:223], v[222:223], 0, s[22:23]
	s_mov_b32 m0, s20
	v_readfirstlane_b32 s20, v167
	s_barrier
	ds_read_b128 v[190:193], v156 offset:49152
	ds_read_b128 v[194:197], v156 offset:50176
	ds_read_b128 v[198:201], v154 offset:49152
	ds_read_b128 v[202:205], v154 offset:50176
	ds_read_b128 v[206:209], v153 offset:49152
	ds_read_b128 v[210:213], v153 offset:50176
	ds_read_b128 v[214:217], v152 offset:49152
	ds_read_b128 v[218:221], v152 offset:50176
	global_load_lds_dwordx4 v[222:223], off
	v_lshl_add_u64 v[222:223], v[226:227], 0, s[22:23]
	s_mov_b32 m0, s20
	s_nop 0
	global_load_lds_dwordx4 v[222:223], off
	s_barrier
; #define LDA8(dst, b, h) _Pragma("unroll") for (int m = 0; m < 4; ++m) _Pragma("unroll") for (int k = 0; k < 2; ++k) \
;     dst[m][k] = *(const bf16x8*)((const char*)SA8(b, h) + lds_byte8(wr * 64 + m * 16 + fr, k * 32 + fq * 8))
; #define LDB8(dst, b, h) _Pragma("unroll") for (int n = 0; n < 2; ++n) _Pragma("unroll") for (int k = 0; k < 2; ++k) \
;     dst[n][k] = *(const bf16x8*)((const char*)SB8(b, h) + lds_byte8(wc * 32 + n * 16 + fr, k * 32 + fq * 8))
; #define WAIT_V8(n) asm volatile("s_waitcnt vmcnt(" #n ")" ::: "memory")
; #define WAIT_L8(n) asm volatile("s_waitcnt lgkmcnt(" #n ")" ::: "memory")
; #define BAR8 __builtin_amdgcn_s_barrier()
; #define SCHED8 __builtin_amdgcn_sched_barrier(0)
;     ...
;     BAR8; WAIT_L8(0); MMA8(1, 0, At, B0); BAR8; SCHED8;
;     STAGE8(SB8(1, 1), Bt, K, bcol + 128, tt + 3);
;     WAIT_V8(6); BAR8; MMA8(1, 1, At, B1); BAR8;
;   }
;   { LDB8(B0, 0, 0); LDA8(At, 0, 0); STAGE8(SA8(1, 1), A, lda, brow + 128, nt - 1);
;     BAR8; WAIT_L8(0); MMA8(0, 0, At, B0); BAR8;
;     LDB8(B1, 0, 1); BAR8; WAIT_L8(0); MMA8(0, 1, At, B1); BAR8;
	s_waitcnt lgkmcnt(0)
	s_waitcnt lgkmcnt(0)
	v_mfma_f32_16x16x32_f16 v[64:67], v[190:193], v[174:177], v[64:67]
	v_mfma_f32_16x16x32_f16 v[60:63], v[190:193], v[182:185], v[60:63]
	v_mfma_f32_16x16x32_f16 v[56:59], v[198:201], v[174:177], v[56:59]
	v_mfma_f32_16x16x32_f16 v[52:55], v[198:201], v[182:185], v[52:55]
	v_mfma_f32_16x16x32_f16 v[48:51], v[206:209], v[174:177], v[48:51]
	v_mfma_f32_16x16x32_f16 v[44:47], v[206:209], v[182:185], v[44:47]
	v_mfma_f32_16x16x32_f16 v[40:43], v[214:217], v[174:177], v[40:43]
	v_mfma_f32_16x16x32_f16 v[36:39], v[214:217], v[182:185], v[36:39]
	v_mfma_f32_16x16x32_f16 v[64:67], v[194:197], v[178:181], v[64:67]
	v_mfma_f32_16x16x32_f16 v[60:63], v[194:197], v[186:189], v[60:63]
	v_mfma_f32_16x16x32_f16 v[56:59], v[202:205], v[178:181], v[56:59]
	v_mfma_f32_16x16x32_f16 v[52:55], v[202:205], v[186:189], v[52:55]
	v_mfma_f32_16x16x32_f16 v[48:51], v[210:213], v[178:181], v[48:51]
	v_mfma_f32_16x16x32_f16 v[44:47], v[210:213], v[186:189], v[44:47]
	v_mfma_f32_16x16x32_f16 v[40:43], v[218:221], v[178:181], v[40:43]
	v_mfma_f32_16x16x32_f16 v[36:39], v[218:221], v[186:189], v[36:39]
	s_barrier
	v_readfirstlane_b32 s20, v169
	v_lshl_add_u64 v[174:175], v[228:229], 0, s[60:61]
	s_mov_b32 m0, s20
	v_readfirstlane_b32 s20, v170
	global_load_lds_dwordx4 v[174:175], off
	v_lshl_add_u64 v[174:175], v[236:237], 0, s[60:61]
	s_mov_b32 m0, s20
	s_nop 0
	global_load_lds_dwordx4 v[174:175], off
	s_waitcnt vmcnt(6)
	s_barrier
	v_mfma_f32_16x16x32_f16 v[32:35], v[190:193], v[230:233], v[32:35]
	v_mfma_f32_16x16x32_f16 v[28:31], v[190:193], v[242:245], v[28:31]
	v_mfma_f32_16x16x32_f16 v[24:27], v[198:201], v[230:233], v[24:27]
	v_mfma_f32_16x16x32_f16 v[20:23], v[198:201], v[242:245], v[20:23]
	v_mfma_f32_16x16x32_f16 v[16:19], v[206:209], v[230:233], v[16:19]
	v_mfma_f32_16x16x32_f16 v[12:15], v[206:209], v[242:245], v[12:15]
	v_mfma_f32_16x16x32_f16 v[8:11], v[214:217], v[230:233], v[8:11]
	v_mfma_f32_16x16x32_f16 v[4:7], v[214:217], v[242:245], v[4:7]
	v_mfma_f32_16x16x32_f16 v[32:35], v[194:197], v[238:241], v[32:35]
	v_mfma_f32_16x16x32_f16 v[28:31], v[194:197], v[246:249], v[28:31]
	v_mfma_f32_16x16x32_f16 v[24:27], v[202:205], v[238:241], v[24:27]
	v_mfma_f32_16x16x32_f16 v[20:23], v[202:205], v[246:249], v[20:23]
	v_mfma_f32_16x16x32_f16 v[16:19], v[210:213], v[238:241], v[16:19]
	v_mfma_f32_16x16x32_f16 v[12:15], v[210:213], v[246:249], v[12:15]
	v_mfma_f32_16x16x32_f16 v[8:11], v[218:221], v[238:241], v[8:11]
	v_mfma_f32_16x16x32_f16 v[4:7], v[218:221], v[246:249], v[4:7]
	s_add_i32 s1, s1, 2
	s_add_u32 s14, s14, 0x100
	s_addc_u32 s15, s15, 0
	s_cmp_lt_u32 s1, 12
	s_barrier
	s_cbranch_scc1 .LBB0_242
	s_add_u32 s12, s12, 0x40780
	s_addc_u32 s13, s13, 0
	v_lshl_add_u64 v[132:133], s[12:13], 0, v[132:133]
	v_readfirstlane_b32 s1, v172
	v_lshl_add_u64 v[0:1], v[0:1], 1, v[132:133]
	s_mov_b32 m0, s1
	ds_read_b128 v[138:141], v171
	ds_read_b128 v[142:145], v171 offset:1024
	ds_read_b128 v[160:163], v171 offset:2048
	ds_read_b128 v[164:167], v171 offset:3072
	ds_read_b128 v[174:177], v156
	ds_read_b128 v[178:181], v156 offset:1024
	ds_read_b128 v[182:185], v154
	ds_read_b128 v[186:189], v154 offset:1024
	ds_read_b128 v[190:193], v153
	ds_read_b128 v[194:197], v153 offset:1024
	ds_read_b128 v[198:201], v152
	ds_read_b128 v[202:205], v152 offset:1024
	global_load_lds_dwordx4 v[0:1], off
	v_lshl_add_u64 v[0:1], s[12:13], 0, v[136:137]
	v_readfirstlane_b32 s1, v173
	v_lshl_add_u64 v[0:1], v[134:135], 1, v[0:1]
	s_mov_b32 m0, s1
	s_nop 0
	global_load_lds_dwordx4 v[0:1], off
	s_barrier
	s_waitcnt lgkmcnt(0)
	s_waitcnt lgkmcnt(0)
	v_mfma_f32_16x16x32_f16 v[128:131], v[174:177], v[138:141], v[128:131]
	v_mfma_f32_16x16x32_f16 v[124:127], v[174:177], v[160:163], v[124:127]
	v_mfma_f32_16x16x32_f16 v[120:123], v[182:185], v[138:141], v[120:123]
	v_mfma_f32_16x16x32_f16 v[112:115], v[190:193], v[138:141], v[112:115]
	v_mfma_f32_16x16x32_f16 v[128:131], v[178:181], v[142:145], v[128:131]
	v_mfma_f32_16x16x32_f16 v[124:127], v[178:181], v[164:167], v[124:127]
	v_mfma_f32_16x16x32_f16 v[120:123], v[186:189], v[142:145], v[120:123]
	v_mfma_f32_16x16x32_f16 v[116:119], v[182:185], v[160:163], v[116:119]
	v_mfma_f32_16x16x32_f16 v[112:115], v[194:197], v[142:145], v[112:115]
	v_mfma_f32_16x16x32_f16 v[108:111], v[190:193], v[160:163], v[108:111]
	v_mfma_f32_16x16x32_f16 v[104:107], v[198:201], v[138:141], v[104:107]
	v_mfma_f32_16x16x32_f16 v[100:103], v[198:201], v[160:163], v[100:103]
	v_mfma_f32_16x16x32_f16 v[132:135], v[186:189], v[164:167], v[116:119]
	v_mfma_f32_16x16x32_f16 v[170:173], v[194:197], v[164:167], v[108:111]
	v_mfma_f32_16x16x32_f16 v[206:209], v[202:205], v[142:145], v[104:107]
	v_mfma_f32_16x16x32_f16 v[210:213], v[202:205], v[164:167], v[100:103]
	s_barrier
	s_nop 1
	ds_read_b128 v[100:103], v168
	ds_read_b128 v[104:107], v168 offset:1024
	ds_read_b128 v[108:111], v168 offset:2048
	ds_read_b128 v[116:119], v168 offset:3072
	s_barrier
	s_waitcnt lgkmcnt(0)
	s_waitcnt lgkmcnt(0)
	v_mfma_f32_16x16x32_f16 v[80:83], v[190:193], v[100:103], v[80:83]
	v_mfma_f32_16x16x32_f16 v[76:79], v[190:193], v[108:111], v[76:79]
	v_mfma_f32_16x16x32_f16 v[72:75], v[198:201], v[100:103], v[72:75]
	v_mfma_f32_16x16x32_f16 v[68:71], v[198:201], v[108:111], v[68:71]
	v_mfma_f32_16x16x32_f16 v[96:99], v[174:177], v[100:103], v[96:99]
	v_mfma_f32_16x16x32_f16 v[92:95], v[174:177], v[108:111], v[92:95]
	v_mfma_f32_16x16x32_f16 v[88:91], v[182:185], v[100:103], v[88:91]
	v_mfma_f32_16x16x32_f16 v[84:87], v[182:185], v[108:111], v[84:87]
	v_mfma_f32_16x16x32_f16 v[80:83], v[194:197], v[104:107], v[80:83]
	v_mfma_f32_16x16x32_f16 v[76:79], v[194:197], v[116:119], v[76:79]
	v_mfma_f32_16x16x32_f16 v[72:75], v[202:205], v[104:107], v[72:75]
	v_mfma_f32_16x16x32_f16 v[68:71], v[202:205], v[116:119], v[68:71]
	v_mfma_f32_16x16x32_f16 v[214:217], v[178:181], v[104:107], v[96:99]
	v_mfma_f32_16x16x32_f16 v[174:177], v[178:181], v[116:119], v[92:95]
	v_mfma_f32_16x16x32_f16 v[178:181], v[186:189], v[104:107], v[88:91]
	v_mfma_f32_16x16x32_f16 v[182:185], v[186:189], v[116:119], v[84:87]
	s_barrier
; #define LDA8(dst, b, h) _Pragma("unroll") for (int m = 0; m < 4; ++m) _Pragma("unroll") for (int k = 0; k < 2; ++k) \
;     dst[m][k] = *(const bf16x8*)((const char*)SA8(b, h) + lds_byte8(wr * 64 + m * 16 + fr, k * 32 + fq * 8))
; #define LDB8(dst, b, h) _Pragma("unroll") for (int n = 0; n < 2; ++n) _Pragma("unroll") for (int k = 0; k < 2; ++k) \
;     dst[n][k] = *(const bf16x8*)((const char*)SB8(b, h) + lds_byte8(wc * 32 + n * 16 + fr, k * 32 + fq * 8))
; #define WAIT_V8(n) asm volatile("s_waitcnt vmcnt(" #n ")" ::: "memory")
; #define WAIT_L8(n) asm volatile("s_waitcnt lgkmcnt(" #n ")" ::: "memory")
; #define BAR8 __builtin_amdgcn_s_barrier()
;     ...
;     LDA8(At, 0, 1); WAIT_V8(4); BAR8; WAIT_L8(0); MMA8(1, 0, At, B0); MMA8(1, 1, At, B1); BAR8; }
;   { LDB8(B0, 1, 0); LDA8(At, 1, 0); WAIT_V8(2); BAR8; WAIT_L8(0); MMA8(0, 0, At, B0); BAR8;
	s_nop 0
	ds_read_b128 v[84:87], v156 offset:16384
	ds_read_b128 v[88:91], v156 offset:17408
	ds_read_b128 v[92:95], v154 offset:16384
	ds_read_b128 v[96:99], v154 offset:17408
	ds_read_b128 v[186:189], v153 offset:16384
	ds_read_b128 v[190:193], v153 offset:17408
	ds_read_b128 v[194:197], v152 offset:16384
	ds_read_b128 v[198:201], v152 offset:17408
	s_waitcnt vmcnt(4)
	s_barrier
	s_waitcnt lgkmcnt(0)
	s_waitcnt lgkmcnt(0)
	v_mfma_f32_16x16x32_f16 v[64:67], v[84:87], v[138:141], v[64:67]
	v_mfma_f32_16x16x32_f16 v[60:63], v[84:87], v[160:163], v[60:63]
	v_mfma_f32_16x16x32_f16 v[56:59], v[92:95], v[138:141], v[56:59]
	v_mfma_f32_16x16x32_f16 v[52:55], v[92:95], v[160:163], v[52:55]
	v_mfma_f32_16x16x32_f16 v[48:51], v[186:189], v[138:141], v[48:51]
	v_mfma_f32_16x16x32_f16 v[44:47], v[186:189], v[160:163], v[44:47]
	v_mfma_f32_16x16x32_f16 v[40:43], v[194:197], v[138:141], v[40:43]
	v_mfma_f32_16x16x32_f16 v[36:39], v[194:197], v[160:163], v[36:39]
	v_mfma_f32_16x16x32_f16 v[64:67], v[88:91], v[142:145], v[64:67]
	v_mfma_f32_16x16x32_f16 v[60:63], v[88:91], v[164:167], v[60:63]
	v_mfma_f32_16x16x32_f16 v[56:59], v[96:99], v[142:145], v[56:59]
	v_mfma_f32_16x16x32_f16 v[52:55], v[96:99], v[164:167], v[52:55]
	v_mfma_f32_16x16x32_f16 v[48:51], v[190:193], v[142:145], v[48:51]
	v_mfma_f32_16x16x32_f16 v[44:47], v[190:193], v[164:167], v[44:47]
	v_mfma_f32_16x16x32_f16 v[40:43], v[198:201], v[142:145], v[40:43]
	v_mfma_f32_16x16x32_f16 v[36:39], v[198:201], v[164:167], v[36:39]
	v_mfma_f32_16x16x32_f16 v[32:35], v[84:87], v[100:103], v[32:35]
	v_mfma_f32_16x16x32_f16 v[28:31], v[84:87], v[108:111], v[28:31]
	v_mfma_f32_16x16x32_f16 v[24:27], v[92:95], v[100:103], v[24:27]
	v_mfma_f32_16x16x32_f16 v[20:23], v[92:95], v[108:111], v[20:23]
	v_mfma_f32_16x16x32_f16 v[16:19], v[186:189], v[100:103], v[16:19]
	v_mfma_f32_16x16x32_f16 v[12:15], v[186:189], v[108:111], v[12:15]
	v_mfma_f32_16x16x32_f16 v[8:11], v[194:197], v[100:103], v[8:11]
	v_mfma_f32_16x16x32_f16 v[4:7], v[194:197], v[108:111], v[4:7]
	v_mfma_f32_16x16x32_f16 v[136:139], v[88:91], v[104:107], v[32:35]
	v_mfma_f32_16x16x32_f16 v[140:143], v[88:91], v[116:119], v[28:31]
	v_mfma_f32_16x16x32_f16 v[160:163], v[96:99], v[104:107], v[24:27]
	v_mfma_f32_16x16x32_f16 v[164:167], v[96:99], v[116:119], v[20:23]
	v_mfma_f32_16x16x32_f16 v[202:205], v[190:193], v[104:107], v[16:19]
	v_mfma_f32_16x16x32_f16 v[186:189], v[190:193], v[116:119], v[12:15]
	v_mfma_f32_16x16x32_f16 v[190:193], v[198:201], v[104:107], v[8:11]
	v_mfma_f32_16x16x32_f16 v[194:197], v[198:201], v[116:119], v[4:7]
	s_barrier
	ds_read_b128 v[198:201], v159
	ds_read_b128 v[218:221], v159 offset:1024
	ds_read_b128 v[230:233], v159 offset:2048
	ds_read_b128 v[238:241], v159 offset:3072
	ds_read_b128 v[8:11], v156 offset:32768
	ds_read_b128 v[12:15], v156 offset:33792
	ds_read_b128 v[16:19], v154 offset:32768
	ds_read_b128 v[24:27], v154 offset:33792
	ds_read_b128 v[28:31], v153 offset:32768
	ds_read_b128 v[32:35], v153 offset:33792
	ds_read_b128 v[242:245], v152 offset:32768
	ds_read_b128 v[246:249], v152 offset:33792
	s_waitcnt vmcnt(2)
	s_barrier
	s_waitcnt lgkmcnt(0)
	s_waitcnt lgkmcnt(0)
	v_mfma_f32_16x16x32_f16 v[4:7], v[8:11], v[198:201], v[128:131]
	v_mfma_f32_16x16x32_f16 v[104:107], v[12:15], v[218:221], v[4:7]
	v_mfma_f32_16x16x32_f16 v[4:7], v[8:11], v[230:233], v[124:127]
	v_mfma_f32_16x16x32_f16 v[116:119], v[12:15], v[238:241], v[4:7]
	v_mfma_f32_16x16x32_f16 v[4:7], v[16:19], v[198:201], v[120:123]
	v_mfma_f32_16x16x32_f16 v[100:103], v[24:27], v[218:221], v[4:7]
	v_mfma_f32_16x16x32_f16 v[4:7], v[16:19], v[230:233], v[132:135]
	v_mfma_f32_16x16x32_f16 v[108:111], v[24:27], v[238:241], v[4:7]
	v_mfma_f32_16x16x32_f16 v[4:7], v[28:31], v[198:201], v[112:115]
	v_mfma_f32_16x16x32_f16 v[92:95], v[32:35], v[218:221], v[4:7]
	v_mfma_f32_16x16x32_f16 v[4:7], v[28:31], v[230:233], v[170:173]
	v_mfma_f32_16x16x32_f16 v[96:99], v[32:35], v[238:241], v[4:7]
	v_mfma_f32_16x16x32_f16 v[4:7], v[242:245], v[198:201], v[206:209]
	v_mfma_f32_16x16x32_f16 v[84:87], v[246:249], v[218:221], v[4:7]
	v_mfma_f32_16x16x32_f16 v[4:7], v[242:245], v[230:233], v[210:213]
	v_mfma_f32_16x16x32_f16 v[88:91], v[246:249], v[238:241], v[4:7]
	s_barrier
; #define LDA8(dst, b, h) _Pragma("unroll") for (int m = 0; m < 4; ++m) _Pragma("unroll") for (int k = 0; k < 2; ++k) \
;     dst[m][k] = *(const bf16x8*)((const char*)SA8(b, h) + lds_byte8(wr * 64 + m * 16 + fr, k * 32 + fq * 8))
; #define LDB8(dst, b, h) _Pragma("unroll") for (int n = 0; n < 2; ++n) _Pragma("unroll") for (int k = 0; k < 2; ++k) \
;     dst[n][k] = *(const bf16x8*)((const char*)SB8(b, h) + lds_byte8(wc * 32 + n * 16 + fr, k * 32 + fq * 8))
; #define WAIT_V8(n) asm volatile("s_waitcnt vmcnt(" #n ")" ::: "memory")
; #define WAIT_L8(n) asm volatile("s_waitcnt lgkmcnt(" #n ")" ::: "memory")
; #define BAR8 __builtin_amdgcn_s_barrier()
;     ...
;     LDB8(B1, 1, 1); WAIT_V8(0); BAR8; WAIT_L8(0); MMA8(0, 1, At, B1); BAR8;
;     LDA8(At, 1, 1); BAR8; WAIT_L8(0); MMA8(1, 0, At, B0); MMA8(1, 1, At, B1); BAR8; }
;   if (wr == 0) BAR8;
;   __syncthreads();
	ds_read_b128 v[132:135], v157
	ds_read_b128 v[168:171], v157 offset:1024
	ds_read_b128 v[206:209], v157 offset:2048
	ds_read_b128 v[210:213], v157 offset:3072
	s_waitcnt vmcnt(0)
	s_barrier
	s_waitcnt lgkmcnt(0)
	s_waitcnt lgkmcnt(0)
	v_mfma_f32_16x16x32_f16 v[4:7], v[8:11], v[132:135], v[214:217]
	v_mfma_f32_16x16x32_f16 v[8:11], v[8:11], v[206:209], v[174:177]
	v_mfma_f32_16x16x32_f16 v[4:7], v[12:15], v[168:171], v[4:7]
	v_mfma_f32_16x16x32_f16 v[20:23], v[12:15], v[210:213], v[8:11]
	v_mfma_f32_16x16x32_f16 v[8:11], v[16:19], v[132:135], v[178:181]
	v_mfma_f32_16x16x32_f16 v[12:15], v[16:19], v[206:209], v[182:185]
	v_mfma_f32_16x16x32_f16 v[8:11], v[24:27], v[168:171], v[8:11]
	v_mfma_f32_16x16x32_f16 v[24:27], v[24:27], v[210:213], v[12:15]
	v_mfma_f32_16x16x32_f16 v[12:15], v[28:31], v[132:135], v[80:83]
	v_mfma_f32_16x16x32_f16 v[16:19], v[28:31], v[206:209], v[76:79]
	v_mfma_f32_16x16x32_f16 v[12:15], v[32:35], v[168:171], v[12:15]
	v_mfma_f32_16x16x32_f16 v[28:31], v[32:35], v[210:213], v[16:19]
	v_mfma_f32_16x16x32_f16 v[16:19], v[242:245], v[132:135], v[72:75]
	v_mfma_f32_16x16x32_f16 v[32:35], v[242:245], v[206:209], v[68:71]
	v_mfma_f32_16x16x32_f16 v[16:19], v[246:249], v[168:171], v[16:19]
	v_mfma_f32_16x16x32_f16 v[32:35], v[246:249], v[210:213], v[32:35]
	s_barrier
	ds_read_b128 v[172:175], v156 offset:49152
	ds_read_b128 v[156:159], v156 offset:50176
	ds_read_b128 v[176:179], v154 offset:49152
	ds_read_b128 v[180:183], v154 offset:50176
	ds_read_b128 v[214:217], v153 offset:49152
	ds_read_b128 v[242:245], v153 offset:50176
	ds_read_b128 v[246:249], v152 offset:49152
	ds_read_b128 v[150:153], v152 offset:50176
	s_barrier
	s_waitcnt lgkmcnt(0)
	s_waitcnt lgkmcnt(0)
	v_mfma_f32_16x16x32_f16 v[64:67], v[172:175], v[198:201], v[64:67]
	v_mfma_f32_16x16x32_f16 v[60:63], v[172:175], v[230:233], v[60:63]
	v_mfma_f32_16x16x32_f16 v[56:59], v[176:179], v[198:201], v[56:59]
	v_mfma_f32_16x16x32_f16 v[52:55], v[176:179], v[230:233], v[52:55]
	v_mfma_f32_16x16x32_f16 v[48:51], v[214:217], v[198:201], v[48:51]
	v_mfma_f32_16x16x32_f16 v[44:47], v[214:217], v[230:233], v[44:47]
	v_mfma_f32_16x16x32_f16 v[40:43], v[246:249], v[198:201], v[40:43]
	v_mfma_f32_16x16x32_f16 v[36:39], v[246:249], v[230:233], v[36:39]
	v_mfma_f32_16x16x32_f16 v[128:131], v[156:159], v[218:221], v[64:67]
	v_mfma_f32_16x16x32_f16 v[124:127], v[156:159], v[238:241], v[60:63]
	v_mfma_f32_16x16x32_f16 v[120:123], v[180:183], v[218:221], v[56:59]
	v_mfma_f32_16x16x32_f16 v[112:115], v[180:183], v[238:241], v[52:55]
	v_mfma_f32_16x16x32_f16 v[80:83], v[242:245], v[218:221], v[48:51]
	v_mfma_f32_16x16x32_f16 v[76:79], v[242:245], v[238:241], v[44:47]
	v_mfma_f32_16x16x32_f16 v[72:75], v[150:153], v[218:221], v[40:43]
	v_mfma_f32_16x16x32_f16 v[68:71], v[150:153], v[238:241], v[36:39]
	v_mfma_f32_16x16x32_f16 v[40:43], v[172:175], v[206:209], v[140:143]
	v_mfma_f32_16x16x32_f16 v[44:47], v[176:179], v[206:209], v[164:167]
	v_mfma_f32_16x16x32_f16 v[48:51], v[214:217], v[206:209], v[186:189]
	v_mfma_f32_16x16x32_f16 v[36:39], v[172:175], v[132:135], v[136:139]
	v_mfma_f32_16x16x32_f16 v[52:55], v[156:159], v[210:213], v[40:43]
	v_mfma_f32_16x16x32_f16 v[40:43], v[176:179], v[132:135], v[160:163]
	v_mfma_f32_16x16x32_f16 v[56:59], v[180:183], v[210:213], v[44:47]
	v_mfma_f32_16x16x32_f16 v[44:47], v[214:217], v[132:135], v[202:205]
	v_mfma_f32_16x16x32_f16 v[60:63], v[242:245], v[210:213], v[48:51]
	v_mfma_f32_16x16x32_f16 v[48:51], v[246:249], v[132:135], v[190:193]
	v_mfma_f32_16x16x32_f16 v[64:67], v[246:249], v[206:209], v[194:197]
	v_mfma_f32_16x16x32_f16 v[36:39], v[156:159], v[168:171], v[36:39]
	v_mfma_f32_16x16x32_f16 v[40:43], v[180:183], v[168:171], v[40:43]
	v_mfma_f32_16x16x32_f16 v[44:47], v[242:245], v[168:171], v[44:47]
	v_mfma_f32_16x16x32_f16 v[48:51], v[150:153], v[168:171], v[48:51]
	v_mfma_f32_16x16x32_f16 v[64:67], v[150:153], v[210:213], v[64:67]
	s_movk_i32 s1, 0x100
	v_cmp_gt_u32_e32 vcc, s1, v3
	s_barrier
	s_and_saveexec_b64 s[12:13], vcc
	s_cbranch_execz .LBB0_245
	s_barrier

; #define LDA8(dst, b, h) _Pragma("unroll") for (int m = 0; m < 4; ++m) _Pragma("unroll") for (int k = 0; k < 2; ++k) \
;     dst[m][k] = *(const bf16x8*)((const char*)SA8(b, h) + lds_byte8(wr * 64 + m * 16 + fr, k * 32 + fq * 8))
; #define LDB8(dst, b, h) _Pragma("unroll") for (int n = 0; n < 2; ++n) _Pragma("unroll") for (int k = 0; k < 2; ++k) \
;     dst[n][k] = *(const bf16x8*)((const char*)SB8(b, h) + lds_byte8(wc * 32 + n * 16 + fr, k * 32 + fq * 8))
; #define WAIT_V8(n) asm volatile("s_waitcnt vmcnt(" #n ")" ::: "memory")
; #define WAIT_L8(n) asm volatile("s_waitcnt lgkmcnt(" #n ")" ::: "memory")
; #define BAR8 __builtin_amdgcn_s_barrier()
; #define SCHED8 __builtin_amdgcn_sched_barrier(0)
;     ...
;   const int brow = m0, bcol = n0;
;   const int wid = t >> 6, lane = t & 63, wr = wid >> 2, wc = wid & 3, fr = lane & 15, fq = lane >> 4;
;   f32x4 acc[2][2][4][2];
;   {
;     float zinit = 0.f;
;     asm volatile("" : "+v"(zinit));
; #pragma unroll
;     for (int a = 0; a < 2; ++a)
; #pragma unroll
;       for (int b = 0; b < 2; ++b)
; #pragma unroll
;         for (int m = 0; m < 4; ++m)
; #pragma unroll
;           for (int n = 0; n < 2; ++n)
; #pragma unroll
;             for (int j = 0; j < 4; ++j) acc[a][b][m][n][j] = zinit;
;   }
;   bf16x8 At[4][2], B0[2][2], B1[2][2];
;   const int nt = K / 64;
;   if (!pre) {
;     STAGE8(SB8(0, 0), Bt, K, bcol, 0); STAGE8(SA8(0, 0), A, lda, brow, 0);
;     STAGE8(SB8(0, 1), Bt, K, bcol + 128, 0); STAGE8(SA8(0, 1), A, lda, brow + 128, 0);
;   }
;   if (wr == 1) BAR8;
;   WAIT_V8(4); BAR8;
;   STAGE8(SB8(1, 0), Bt, K, bcol, 1); STAGE8(SA8(1, 0), A, lda, brow, 1); STAGE8(SB8(1, 1), Bt, K, bcol + 128, 1);
;   WAIT_V8(6); BAR8;
;   for (int tt = 0; tt < nt - 2; tt += 2) {
;     LDB8(B0, 0, 0); SCHED8; LDA8(At, 0, 0); STAGE8(SA8(1, 1), A, lda, brow + 128, tt + 1);
;     WAIT_L8(8); BAR8; WAIT_L8(0); MMA8(0, 0, At, B0); BAR8; SCHED8;
;     LDB8(B1, 0, 1); STAGE8(SB8(0, 0), Bt, K, bcol, tt + 2);
;     BAR8; WAIT_L8(0); MMA8(0, 1, At, B1); BAR8;
.LBB0_554:
	s_or_b64 exec, exec, s[14:15]
	v_add_u32_e32 v5, 0x18000, v26
	s_mov_b64 s[14:15], 0x80
	v_readfirstlane_b32 s43, v5
	v_add_u32_e32 v5, 0x1a000, v26
	v_lshl_add_u64 v[6:7], v[14:15], 0, s[14:15]
	s_mov_b32 m0, s43
	v_readfirstlane_b32 s42, v5
	v_add_u32_e32 v5, 0x8000, v26
	s_waitcnt vmcnt(4)
	s_barrier
	global_load_lds_dwordx4 v[6:7], off
	v_lshl_add_u64 v[6:7], v[24:25], 0, s[14:15]
	s_mov_b32 m0, s42
	v_readfirstlane_b32 s40, v5
	v_add_u32_e32 v5, 0xa000, v26
	global_load_lds_dwordx4 v[6:7], off
	v_lshl_add_u64 v[6:7], v[20:21], 0, s[14:15]
	s_mov_b32 m0, s40
	v_readfirstlane_b32 s39, v5
	v_add_u32_e32 v5, 0x1c000, v26
	global_load_lds_dwordx4 v[6:7], off
	v_lshl_add_u64 v[6:7], v[22:23], 0, s[14:15]
	s_mov_b32 m0, s39
	v_readfirstlane_b32 s29, v5
	v_add_u32_e32 v5, 0x1e000, v26
	global_load_lds_dwordx4 v[6:7], off
	v_lshl_add_u64 v[6:7], v[16:17], 0, s[14:15]
	s_mov_b32 m0, s29
	v_readfirstlane_b32 s27, v5
	global_load_lds_dwordx4 v[6:7], off
	v_lshl_add_u64 v[6:7], v[18:19], 0, s[14:15]
	s_mov_b32 m0, s27
	v_bfe_u32 v135, v3, 4, 2
	global_load_lds_dwordx4 v[6:7], off
	v_bfe_u32 v133, v3, 6, 2
	v_and_b32_e32 v134, 15, v3
	v_lshlrev_b32_e32 v58, 4, v135
	v_lshlrev_b32_e32 v35, 2, v3
	v_lshlrev_b32_e32 v34, 12, v133
	v_lshl_or_b32 v50, v134, 6, v58
	v_and_b32_e32 v59, 32, v35
	v_bitop3_b32 v212, v50, v34, v59 bitop3:0xde
	v_or_b32_e32 v220, 0x10000, v212
	v_or_b32_e32 v222, 0x10800, v212
	s_waitcnt vmcnt(6)
	s_barrier
	v_or_b32_e32 v221, 0x10400, v212
	ds_read_b128 v[34:37], v220
	ds_read_b128 v[38:41], v221
	v_or_b32_e32 v223, 0x10c00, v212
	ds_read_b128 v[42:45], v222
	ds_read_b128 v[46:49], v223
	s_add_u32 s44, s12, 0x80080
	s_addc_u32 s45, s13, 0
	v_mov_b32_e32 v5, v4
	v_mov_b32_e32 v6, v4
	v_mov_b32_e32 v7, v4
	s_add_u32 s14, s12, 0x80100
	s_addc_u32 s15, s13, 0
	v_lshlrev_b32_e32 v61, 6, v3
	s_movk_i32 s37, 0x3c0
	v_add_u32_e32 v84, 0xc000, v26
	v_lshlrev_b32_e32 v60, 13, v132
	v_and_or_b32 v58, v61, s37, v58
	v_lshl_add_u64 v[82:83], s[44:45], 0, v[10:11]
	v_readfirstlane_b32 s41, v84
	v_bitop3_b32 v226, v50, v60, v59 bitop3:0xde
	v_bitop3_b32 v227, v60, v58, v59 bitop3:0xf6
	v_lshl_add_u64 v[82:83], v[82:83], 0, v[0:1]
	s_mov_b32 m0, s41
	v_add_u32_e32 v84, 0xe000, v26
	ds_read_b128 v[50:53], v226
	ds_read_b128 v[54:57], v226 offset:1024
	ds_read_b128 v[58:61], v227 offset:2048
	ds_read_b128 v[62:65], v227 offset:3072
	ds_read_b128 v[66:69], v227 offset:4096
	ds_read_b128 v[70:73], v227 offset:5120
	ds_read_b128 v[74:77], v227 offset:6144
	ds_read_b128 v[78:81], v227 offset:7168
	global_load_lds_dwordx4 v[82:83], off
	v_lshl_add_u64 v[82:83], s[44:45], 0, v[12:13]
	v_readfirstlane_b32 s37, v84
	v_lshl_add_u64 v[82:83], v[82:83], 0, v[8:9]
	s_mov_b32 m0, s37
	s_nop 0
	global_load_lds_dwordx4 v[82:83], off
	s_waitcnt lgkmcnt(8)
	s_barrier
	s_waitcnt lgkmcnt(0)
	s_waitcnt lgkmcnt(0)
	v_mfma_f32_16x16x32_bf16 v[82:85], v[50:53], v[34:37], v[4:7]
	v_mfma_f32_16x16x32_bf16 v[86:89], v[50:53], v[42:45], v[4:7]
	v_mfma_f32_16x16x32_bf16 v[90:93], v[58:61], v[34:37], v[4:7]
	v_mfma_f32_16x16x32_bf16 v[94:97], v[58:61], v[42:45], v[4:7]
	v_mfma_f32_16x16x32_bf16 v[98:101], v[66:69], v[34:37], v[4:7]
	v_mfma_f32_16x16x32_bf16 v[102:105], v[66:69], v[42:45], v[4:7]
	v_mfma_f32_16x16x32_bf16 v[106:109], v[74:77], v[34:37], v[4:7]
	v_mfma_f32_16x16x32_bf16 v[110:113], v[74:77], v[42:45], v[4:7]
	v_mfma_f32_16x16x32_bf16 v[82:85], v[54:57], v[38:41], v[82:85]
	v_mfma_f32_16x16x32_bf16 v[86:89], v[54:57], v[46:49], v[86:89]
	v_mfma_f32_16x16x32_bf16 v[90:93], v[62:65], v[38:41], v[90:93]
	v_mfma_f32_16x16x32_bf16 v[94:97], v[62:65], v[46:49], v[94:97]
	v_mfma_f32_16x16x32_bf16 v[98:101], v[70:73], v[38:41], v[98:101]
	v_mfma_f32_16x16x32_bf16 v[102:105], v[70:73], v[46:49], v[102:105]
	v_mfma_f32_16x16x32_bf16 v[106:109], v[78:81], v[38:41], v[106:109]
	v_mfma_f32_16x16x32_bf16 v[110:113], v[78:81], v[46:49], v[110:113]
	s_barrier
	v_readfirstlane_b32 s44, v30
	v_or_b32_e32 v228, 0x14000, v212
	v_or_b32_e32 v230, 0x14800, v212
	v_lshl_add_u64 v[130:131], v[14:15], 0, s[10:11]
	s_mov_b32 m0, s44
	v_readfirstlane_b32 s44, v33
	v_or_b32_e32 v229, 0x14400, v212
	ds_read_b128 v[114:117], v228
	ds_read_b128 v[118:121], v229
	v_or_b32_e32 v231, 0x14c00, v212
	ds_read_b128 v[122:125], v230
	ds_read_b128 v[126:129], v231
	global_load_lds_dwordx4 v[130:131], off
	v_lshl_add_u64 v[130:131], v[24:25], 0, s[10:11]
	s_mov_b32 m0, s44
	s_nop 0
	global_load_lds_dwordx4 v[130:131], off
	s_barrier
	s_waitcnt lgkmcnt(0)
	s_waitcnt lgkmcnt(0)
	v_mfma_f32_16x16x32_bf16 v[136:139], v[50:53], v[114:117], v[4:7]
	v_mfma_f32_16x16x32_bf16 v[50:53], v[50:53], v[122:125], v[4:7]
	v_mfma_f32_16x16x32_bf16 v[136:139], v[54:57], v[118:121], v[136:139]
	v_mfma_f32_16x16x32_bf16 v[50:53], v[54:57], v[126:129], v[50:53]
	v_mfma_f32_16x16x32_bf16 v[54:57], v[58:61], v[114:117], v[4:7]
	v_mfma_f32_16x16x32_bf16 v[58:61], v[58:61], v[122:125], v[4:7]
	v_mfma_f32_16x16x32_bf16 v[54:57], v[62:65], v[118:121], v[54:57]
	v_mfma_f32_16x16x32_bf16 v[58:61], v[62:65], v[126:129], v[58:61]
	v_mfma_f32_16x16x32_bf16 v[62:65], v[66:69], v[114:117], v[4:7]
	v_mfma_f32_16x16x32_bf16 v[66:69], v[66:69], v[122:125], v[4:7]
	v_mfma_f32_16x16x32_bf16 v[62:65], v[70:73], v[118:121], v[62:65]
	v_mfma_f32_16x16x32_bf16 v[66:69], v[70:73], v[126:129], v[66:69]
	v_mfma_f32_16x16x32_bf16 v[70:73], v[74:77], v[114:117], v[4:7]
	v_mfma_f32_16x16x32_bf16 v[74:77], v[74:77], v[122:125], v[4:7]
	v_mfma_f32_16x16x32_bf16 v[70:73], v[78:81], v[118:121], v[70:73]
	v_mfma_f32_16x16x32_bf16 v[74:77], v[78:81], v[126:129], v[74:77]
	v_readfirstlane_b32 s44, v26
	v_lshl_add_u64 v[130:131], v[20:21], 0, s[10:11]
	s_mov_b32 m0, s44
	v_readfirstlane_b32 s44, v27
	s_barrier
; #define LDA8(dst, b, h) _Pragma("unroll") for (int m = 0; m < 4; ++m) _Pragma("unroll") for (int k = 0; k < 2; ++k) \
;     dst[m][k] = *(const bf16x8*)((const char*)SA8(b, h) + lds_byte8(wr * 64 + m * 16 + fr, k * 32 + fq * 8))
; #define LDB8(dst, b, h) _Pragma("unroll") for (int n = 0; n < 2; ++n) _Pragma("unroll") for (int k = 0; k < 2; ++k) \
;     dst[n][k] = *(const bf16x8*)((const char*)SB8(b, h) + lds_byte8(wc * 32 + n * 16 + fr, k * 32 + fq * 8))
; #define WAIT_V8(n) asm volatile("s_waitcnt vmcnt(" #n ")" ::: "memory")
; #define WAIT_L8(n) asm volatile("s_waitcnt lgkmcnt(" #n ")" ::: "memory")
; #define BAR8 __builtin_amdgcn_s_barrier()
; #define SCHED8 __builtin_amdgcn_sched_barrier(0)
;     ...
;     LDA8(At, 0, 1); STAGE8(SA8(0, 0), A, lda, brow, tt + 2);
;     BAR8; WAIT_L8(0); MMA8(1, 0, At, B0); BAR8; SCHED8;
;     STAGE8(SB8(0, 1), Bt, K, bcol + 128, tt + 2);
;     WAIT_V8(6); BAR8; MMA8(1, 1, At, B1); BAR8;
;     LDB8(B0, 1, 0); SCHED8; LDA8(At, 1, 0); STAGE8(SA8(0, 1), A, lda, brow + 128, tt + 2);
;     WAIT_L8(8); BAR8; WAIT_L8(0); MMA8(0, 0, At, B0); BAR8; SCHED8;
;     LDB8(B1, 1, 1); STAGE8(SB8(1, 0), Bt, K, bcol, tt + 3);
	ds_read_b128 v[78:81], v226 offset:16384
	ds_read_b128 v[140:143], v226 offset:17408
	s_waitcnt vmcnt(0)
	ds_read_b128 v[144:147], v227 offset:18432
	ds_read_b128 v[148:151], v227 offset:19456
	ds_read_b128 v[152:155], v227 offset:20480
	ds_read_b128 v[156:159], v227 offset:21504
	ds_read_b128 v[160:163], v227 offset:22528
	ds_read_b128 v[164:167], v227 offset:23552
	global_load_lds_dwordx4 v[130:131], off
	v_lshl_add_u64 v[130:131], v[22:23], 0, s[10:11]
	s_mov_b32 m0, s44
	s_nop 0
	global_load_lds_dwordx4 v[130:131], off
	s_barrier
	s_waitcnt lgkmcnt(0)
	s_waitcnt lgkmcnt(0)
	v_mfma_f32_16x16x32_bf16 v[168:171], v[78:81], v[34:37], v[4:7]
	v_mfma_f32_16x16x32_bf16 v[176:179], v[144:147], v[34:37], v[4:7]
	v_mfma_f32_16x16x32_bf16 v[184:187], v[152:155], v[34:37], v[4:7]
	v_mfma_f32_16x16x32_bf16 v[34:37], v[160:163], v[34:37], v[4:7]
	v_mfma_f32_16x16x32_bf16 v[168:171], v[140:143], v[38:41], v[168:171]
	v_mfma_f32_16x16x32_bf16 v[176:179], v[148:151], v[38:41], v[176:179]
	v_mfma_f32_16x16x32_bf16 v[184:187], v[156:159], v[38:41], v[184:187]
	v_mfma_f32_16x16x32_bf16 v[34:37], v[164:167], v[38:41], v[34:37]
	v_mfma_f32_16x16x32_bf16 v[38:41], v[160:163], v[42:45], v[4:7]
	v_mfma_f32_16x16x32_bf16 v[172:175], v[78:81], v[42:45], v[4:7]
	v_mfma_f32_16x16x32_bf16 v[180:183], v[144:147], v[42:45], v[4:7]
	v_mfma_f32_16x16x32_bf16 v[188:191], v[152:155], v[42:45], v[4:7]
	v_mfma_f32_16x16x32_bf16 v[38:41], v[164:167], v[46:49], v[38:41]
	v_mfma_f32_16x16x32_bf16 v[172:175], v[140:143], v[46:49], v[172:175]
	v_mfma_f32_16x16x32_bf16 v[180:183], v[148:151], v[46:49], v[180:183]
	v_mfma_f32_16x16x32_bf16 v[188:191], v[156:159], v[46:49], v[188:191]
	s_barrier
	v_readfirstlane_b32 s44, v31
	v_lshl_add_u64 v[26:27], v[16:17], 0, s[10:11]
	s_mov_b32 m0, s44
	v_readfirstlane_b32 s44, v32
	global_load_lds_dwordx4 v[26:27], off
	v_lshl_add_u64 v[26:27], v[18:19], 0, s[10:11]
	s_mov_b32 m0, s44
	s_nop 0
	global_load_lds_dwordx4 v[26:27], off
	s_waitcnt vmcnt(6)
	s_barrier
	v_mfma_f32_16x16x32_bf16 v[30:33], v[78:81], v[114:117], v[4:7]
	v_mfma_f32_16x16x32_bf16 v[42:45], v[78:81], v[122:125], v[4:7]
	v_mfma_f32_16x16x32_bf16 v[30:33], v[140:143], v[118:121], v[30:33]
	v_mfma_f32_16x16x32_bf16 v[42:45], v[140:143], v[126:129], v[42:45]
	v_mfma_f32_16x16x32_bf16 v[46:49], v[144:147], v[114:117], v[4:7]
	v_mfma_f32_16x16x32_bf16 v[78:81], v[144:147], v[122:125], v[4:7]
	v_mfma_f32_16x16x32_bf16 v[140:143], v[152:155], v[114:117], v[4:7]
	v_mfma_f32_16x16x32_bf16 v[144:147], v[152:155], v[122:125], v[4:7]
	v_mfma_f32_16x16x32_bf16 v[114:117], v[160:163], v[114:117], v[4:7]
	v_mfma_f32_16x16x32_bf16 v[4:7], v[160:163], v[122:125], v[4:7]
	v_mfma_f32_16x16x32_bf16 v[46:49], v[148:151], v[118:121], v[46:49]
	v_mfma_f32_16x16x32_bf16 v[78:81], v[148:151], v[126:129], v[78:81]
	v_mfma_f32_16x16x32_bf16 v[114:117], v[164:167], v[118:121], v[114:117]
	v_mfma_f32_16x16x32_bf16 v[4:7], v[164:167], v[126:129], v[4:7]
	v_mfma_f32_16x16x32_bf16 v[140:143], v[156:159], v[118:121], v[140:143]
	v_mfma_f32_16x16x32_bf16 v[144:147], v[156:159], v[126:129], v[144:147]
	v_or_b32_e32 v130, 0x18000, v212
	v_or_b32_e32 v232, 0x18800, v212
	s_barrier
	v_or_b32_e32 v131, 0x18400, v212
	ds_read_b128 v[118:121], v130
	ds_read_b128 v[122:125], v131
	v_or_b32_e32 v233, 0x18c00, v212
	ds_read_b128 v[126:129], v232
	ds_read_b128 v[148:151], v233
	v_lshl_add_u64 v[26:27], s[14:15], 0, v[10:11]
	v_readfirstlane_b32 s44, v28
	v_lshl_add_u64 v[26:27], v[26:27], 0, v[0:1]
	s_mov_b32 m0, s44
	ds_read_b128 v[152:155], v226 offset:32768
	ds_read_b128 v[156:159], v226 offset:33792
	ds_read_b128 v[160:163], v227 offset:34816
	ds_read_b128 v[164:167], v227 offset:35840
	ds_read_b128 v[192:195], v227 offset:36864
	ds_read_b128 v[196:199], v227 offset:37888
	ds_read_b128 v[200:203], v227 offset:38912
	ds_read_b128 v[204:207], v227 offset:39936
	global_load_lds_dwordx4 v[26:27], off
	v_lshl_add_u64 v[26:27], s[14:15], 0, v[12:13]
	v_readfirstlane_b32 s14, v29
	v_lshl_add_u64 v[26:27], v[26:27], 0, v[8:9]
	s_mov_b32 m0, s14
	s_nop 0
	global_load_lds_dwordx4 v[26:27], off
	s_waitcnt lgkmcnt(8)
	s_barrier
	s_waitcnt lgkmcnt(0)
	s_waitcnt lgkmcnt(0)
	v_mfma_f32_16x16x32_bf16 v[26:29], v[152:155], v[118:121], v[82:85]
	v_mfma_f32_16x16x32_bf16 v[82:85], v[152:155], v[126:129], v[86:89]
	v_mfma_f32_16x16x32_bf16 v[86:89], v[160:163], v[118:121], v[90:93]
	v_mfma_f32_16x16x32_bf16 v[90:93], v[160:163], v[126:129], v[94:97]
	v_mfma_f32_16x16x32_bf16 v[94:97], v[192:195], v[118:121], v[98:101]
	v_mfma_f32_16x16x32_bf16 v[98:101], v[192:195], v[126:129], v[102:105]
	v_mfma_f32_16x16x32_bf16 v[102:105], v[200:203], v[118:121], v[106:109]
	v_mfma_f32_16x16x32_bf16 v[106:109], v[200:203], v[126:129], v[110:113]
	v_mfma_f32_16x16x32_bf16 v[26:29], v[156:159], v[122:125], v[26:29]
	v_mfma_f32_16x16x32_bf16 v[82:85], v[156:159], v[148:151], v[82:85]
	v_mfma_f32_16x16x32_bf16 v[86:89], v[164:167], v[122:125], v[86:89]
	v_mfma_f32_16x16x32_bf16 v[90:93], v[164:167], v[148:151], v[90:93]
	v_mfma_f32_16x16x32_bf16 v[94:97], v[196:199], v[122:125], v[94:97]
	v_mfma_f32_16x16x32_bf16 v[98:101], v[196:199], v[148:151], v[98:101]
	v_mfma_f32_16x16x32_bf16 v[102:105], v[204:207], v[122:125], v[102:105]
	v_mfma_f32_16x16x32_bf16 v[106:109], v[204:207], v[148:151], v[106:109]
	s_barrier
	s_mov_b32 m0, s43
	v_or_b32_e32 v236, 0x1c000, v212
	v_or_b32_e32 v238, 0x1c800, v212
	v_lshl_add_u64 v[14:15], v[14:15], 0, s[22:23]
	v_or_b32_e32 v237, 0x1c400, v212
	ds_read_b128 v[110:113], v236
	ds_read_b128 v[208:211], v237
	v_or_b32_e32 v239, 0x1cc00, v212
	ds_read_b128 v[212:215], v238
	ds_read_b128 v[216:219], v239
	global_load_lds_dwordx4 v[14:15], off
	v_lshl_add_u64 v[14:15], v[24:25], 0, s[22:23]
	s_mov_b32 m0, s42
	s_nop 0
	global_load_lds_dwordx4 v[14:15], off
	s_barrier
; #define LDA8(dst, b, h) _Pragma("unroll") for (int m = 0; m < 4; ++m) _Pragma("unroll") for (int k = 0; k < 2; ++k) \
;     dst[m][k] = *(const bf16x8*)((const char*)SA8(b, h) + lds_byte8(wr * 64 + m * 16 + fr, k * 32 + fq * 8))
; #define LDB8(dst, b, h) _Pragma("unroll") for (int n = 0; n < 2; ++n) _Pragma("unroll") for (int k = 0; k < 2; ++k) \
;     dst[n][k] = *(const bf16x8*)((const char*)SB8(b, h) + lds_byte8(wc * 32 + n * 16 + fr, k * 32 + fq * 8))
; #define WAIT_V8(n) asm volatile("s_waitcnt vmcnt(" #n ")" ::: "memory")
; #define WAIT_L8(n) asm volatile("s_waitcnt lgkmcnt(" #n ")" ::: "memory")
; #define BAR8 __builtin_amdgcn_s_barrier()
; #define SCHED8 __builtin_amdgcn_sched_barrier(0)
;     ...
;     BAR8; WAIT_L8(0); MMA8(0, 1, At, B1); BAR8;
;     LDA8(At, 1, 1); STAGE8(SA8(1, 0), A, lda, brow, tt + 3);
;     BAR8; WAIT_L8(0); MMA8(1, 0, At, B0); BAR8; SCHED8;
;     STAGE8(SB8(1, 1), Bt, K, bcol + 128, tt + 3);
;     WAIT_V8(6); BAR8; MMA8(1, 1, At, B1); BAR8;
;   }
;   { LDB8(B0, 0, 0); LDA8(At, 0, 0); STAGE8(SA8(1, 1), A, lda, brow + 128, nt - 1);
	s_waitcnt lgkmcnt(0)
	s_waitcnt lgkmcnt(0)
	v_mfma_f32_16x16x32_bf16 v[50:53], v[152:155], v[212:215], v[50:53]
	v_mfma_f32_16x16x32_bf16 v[54:57], v[160:163], v[110:113], v[54:57]
	v_mfma_f32_16x16x32_bf16 v[58:61], v[160:163], v[212:215], v[58:61]
	v_mfma_f32_16x16x32_bf16 v[62:65], v[192:195], v[110:113], v[62:65]
	v_mfma_f32_16x16x32_bf16 v[66:69], v[192:195], v[212:215], v[66:69]
	v_mfma_f32_16x16x32_bf16 v[70:73], v[200:203], v[110:113], v[70:73]
	v_mfma_f32_16x16x32_bf16 v[74:77], v[200:203], v[212:215], v[74:77]
	v_mfma_f32_16x16x32_bf16 v[136:139], v[152:155], v[110:113], v[136:139]
	v_mfma_f32_16x16x32_bf16 v[50:53], v[156:159], v[216:219], v[50:53]
	v_mfma_f32_16x16x32_bf16 v[54:57], v[164:167], v[208:211], v[54:57]
	v_mfma_f32_16x16x32_bf16 v[58:61], v[164:167], v[216:219], v[58:61]
	v_mfma_f32_16x16x32_bf16 v[62:65], v[196:199], v[208:211], v[62:65]
	v_mfma_f32_16x16x32_bf16 v[66:69], v[196:199], v[216:219], v[66:69]
	v_mfma_f32_16x16x32_bf16 v[70:73], v[204:207], v[208:211], v[70:73]
	v_mfma_f32_16x16x32_bf16 v[74:77], v[204:207], v[216:219], v[74:77]
	v_mfma_f32_16x16x32_bf16 v[136:139], v[156:159], v[208:211], v[136:139]
	s_mov_b32 m0, s40
	v_lshl_add_u64 v[14:15], v[20:21], 0, s[22:23]
	s_barrier
	ds_read_b128 v[152:155], v226 offset:49152
	ds_read_b128 v[156:159], v226 offset:50176
	ds_read_b128 v[160:163], v227 offset:51200
	ds_read_b128 v[164:167], v227 offset:52224
	ds_read_b128 v[192:195], v227 offset:53248
	ds_read_b128 v[196:199], v227 offset:54272
	ds_read_b128 v[200:203], v227 offset:55296
	ds_read_b128 v[204:207], v227 offset:56320
	global_load_lds_dwordx4 v[14:15], off
	v_lshl_add_u64 v[14:15], v[22:23], 0, s[22:23]
	s_mov_b32 m0, s39
	s_nop 0
	global_load_lds_dwordx4 v[14:15], off
	s_barrier
	s_waitcnt lgkmcnt(0)
	s_waitcnt lgkmcnt(0)
	v_mfma_f32_16x16x32_bf16 v[20:23], v[152:155], v[118:121], v[168:171]
	v_mfma_f32_16x16x32_bf16 v[34:37], v[200:203], v[118:121], v[34:37]
	v_mfma_f32_16x16x32_bf16 v[38:41], v[200:203], v[126:129], v[38:41]
	v_mfma_f32_16x16x32_bf16 v[20:23], v[156:159], v[122:125], v[20:23]
	v_mfma_f32_16x16x32_bf16 v[168:171], v[152:155], v[126:129], v[172:175]
	v_mfma_f32_16x16x32_bf16 v[172:175], v[160:163], v[118:121], v[176:179]
	v_mfma_f32_16x16x32_bf16 v[176:179], v[160:163], v[126:129], v[180:183]
	v_mfma_f32_16x16x32_bf16 v[180:183], v[192:195], v[118:121], v[184:187]
	v_mfma_f32_16x16x32_bf16 v[184:187], v[192:195], v[126:129], v[188:191]
	v_mfma_f32_16x16x32_bf16 v[34:37], v[204:207], v[122:125], v[34:37]
	v_mfma_f32_16x16x32_bf16 v[38:41], v[204:207], v[148:151], v[38:41]
	v_mfma_f32_16x16x32_bf16 v[168:171], v[156:159], v[148:151], v[168:171]
	v_mfma_f32_16x16x32_bf16 v[172:175], v[164:167], v[122:125], v[172:175]
	v_mfma_f32_16x16x32_bf16 v[176:179], v[164:167], v[148:151], v[176:179]
	v_mfma_f32_16x16x32_bf16 v[180:183], v[196:199], v[122:125], v[180:183]
	v_mfma_f32_16x16x32_bf16 v[184:187], v[196:199], v[148:151], v[184:187]
	s_barrier
	s_mov_b32 m0, s29
	v_lshl_add_u64 v[14:15], v[16:17], 0, s[22:23]
	global_load_lds_dwordx4 v[14:15], off
	v_lshl_add_u64 v[14:15], v[18:19], 0, s[22:23]
	s_mov_b32 m0, s27
	s_nop 0
	global_load_lds_dwordx4 v[14:15], off
	s_waitcnt vmcnt(6)
	s_barrier
	v_mfma_f32_16x16x32_bf16 v[14:17], v[152:155], v[110:113], v[30:33]
	v_mfma_f32_16x16x32_bf16 v[30:33], v[152:155], v[212:215], v[42:45]
	v_mfma_f32_16x16x32_bf16 v[42:45], v[160:163], v[110:113], v[46:49]
	v_mfma_f32_16x16x32_bf16 v[46:49], v[160:163], v[212:215], v[78:81]
	v_mfma_f32_16x16x32_bf16 v[78:81], v[192:195], v[110:113], v[140:143]
	v_mfma_f32_16x16x32_bf16 v[118:121], v[192:195], v[212:215], v[144:147]
	v_mfma_f32_16x16x32_bf16 v[110:113], v[200:203], v[110:113], v[114:117]
	v_mfma_f32_16x16x32_bf16 v[4:7], v[200:203], v[212:215], v[4:7]
	v_mfma_f32_16x16x32_bf16 v[14:17], v[156:159], v[208:211], v[14:17]
	v_mfma_f32_16x16x32_bf16 v[30:33], v[156:159], v[216:219], v[30:33]
	v_mfma_f32_16x16x32_bf16 v[42:45], v[164:167], v[208:211], v[42:45]
	v_mfma_f32_16x16x32_bf16 v[46:49], v[164:167], v[216:219], v[46:49]
	v_mfma_f32_16x16x32_bf16 v[78:81], v[196:199], v[208:211], v[78:81]
	v_mfma_f32_16x16x32_bf16 v[118:121], v[196:199], v[216:219], v[118:121]
	v_mfma_f32_16x16x32_bf16 v[110:113], v[204:207], v[208:211], v[110:113]
	v_mfma_f32_16x16x32_bf16 v[4:7], v[204:207], v[216:219], v[4:7]
	s_add_u32 s12, s12, 0x80180
	s_addc_u32 s13, s13, 0
	v_lshl_add_u64 v[10:11], s[12:13], 0, v[10:11]
	s_mov_b32 m0, s41
	v_lshl_add_u64 v[0:1], v[10:11], 0, v[0:1]
	s_barrier
	ds_read_b128 v[114:117], v220
	ds_read_b128 v[122:125], v221
	ds_read_b128 v[126:129], v222
	ds_read_b128 v[140:143], v223
	ds_read_b128 v[144:147], v226
	ds_read_b128 v[148:151], v226 offset:1024
	ds_read_b128 v[152:155], v227 offset:2048
	ds_read_b128 v[156:159], v227 offset:3072
	ds_read_b128 v[160:163], v227 offset:4096
	ds_read_b128 v[164:167], v227 offset:5120
	ds_read_b128 v[188:191], v227 offset:6144
	ds_read_b128 v[192:195], v227 offset:7168
	global_load_lds_dwordx4 v[0:1], off
	v_lshl_add_u64 v[0:1], s[12:13], 0, v[12:13]
	v_lshl_add_u64 v[0:1], v[0:1], 0, v[8:9]
	s_mov_b32 m0, s37
	s_nop 0
	global_load_lds_dwordx4 v[0:1], off
	s_barrier
; #define LDA8(dst, b, h) _Pragma("unroll") for (int m = 0; m < 4; ++m) _Pragma("unroll") for (int k = 0; k < 2; ++k) \
;     dst[m][k] = *(const bf16x8*)((const char*)SA8(b, h) + lds_byte8(wr * 64 + m * 16 + fr, k * 32 + fq * 8))
; #define LDB8(dst, b, h) _Pragma("unroll") for (int n = 0; n < 2; ++n) _Pragma("unroll") for (int k = 0; k < 2; ++k) \
;     dst[n][k] = *(const bf16x8*)((const char*)SB8(b, h) + lds_byte8(wc * 32 + n * 16 + fr, k * 32 + fq * 8))
; #define WAIT_V8(n) asm volatile("s_waitcnt vmcnt(" #n ")" ::: "memory")
; #define WAIT_L8(n) asm volatile("s_waitcnt lgkmcnt(" #n ")" ::: "memory")
; #define BAR8 __builtin_amdgcn_s_barrier()
;     ...
;     BAR8; WAIT_L8(0); MMA8(0, 0, At, B0); BAR8;
;     LDB8(B1, 0, 1); BAR8; WAIT_L8(0); MMA8(0, 1, At, B1); BAR8;
;     LDA8(At, 0, 1); WAIT_V8(4); BAR8; WAIT_L8(0); MMA8(1, 0, At, B0); MMA8(1, 1, At, B1); BAR8; }
;   { LDB8(B0, 1, 0); LDA8(At, 1, 0); WAIT_V8(2); BAR8; WAIT_L8(0); MMA8(0, 0, At, B0); BAR8;
	s_waitcnt lgkmcnt(0)
	s_waitcnt lgkmcnt(0)
	v_mfma_f32_16x16x32_bf16 v[8:11], v[144:147], v[114:117], v[26:29]
	v_mfma_f32_16x16x32_bf16 v[24:27], v[144:147], v[126:129], v[82:85]
	v_mfma_f32_16x16x32_bf16 v[82:85], v[152:155], v[114:117], v[86:89]
	v_mfma_f32_16x16x32_bf16 v[86:89], v[152:155], v[126:129], v[90:93]
	v_mfma_f32_16x16x32_bf16 v[90:93], v[160:163], v[114:117], v[94:97]
	v_mfma_f32_16x16x32_bf16 v[94:97], v[160:163], v[126:129], v[98:101]
	v_mfma_f32_16x16x32_bf16 v[100:103], v[188:191], v[114:117], v[102:105]
	v_mfma_f32_16x16x32_bf16 v[8:11], v[148:151], v[122:125], v[8:11]
	v_mfma_f32_16x16x32_bf16 v[24:27], v[148:151], v[140:143], v[24:27]
	v_mfma_f32_16x16x32_bf16 v[82:85], v[156:159], v[122:125], v[82:85]
	v_mfma_f32_16x16x32_bf16 v[86:89], v[156:159], v[140:143], v[86:89]
	v_mfma_f32_16x16x32_bf16 v[90:93], v[164:167], v[122:125], v[90:93]
	v_mfma_f32_16x16x32_bf16 v[96:99], v[164:167], v[140:143], v[94:97]
	v_mfma_f32_16x16x32_bf16 v[196:199], v[192:195], v[122:125], v[100:103]
	v_mfma_f32_16x16x32_bf16 v[100:103], v[188:191], v[126:129], v[106:109]
	v_mfma_f32_16x16x32_bf16 v[200:203], v[192:195], v[140:143], v[100:103]
	s_barrier
	s_nop 4
	ds_read_b128 v[100:103], v228
	ds_read_b128 v[104:107], v229
	ds_read_b128 v[204:207], v230
	ds_read_b128 v[208:211], v231
	s_barrier
	s_waitcnt lgkmcnt(0)
	s_waitcnt lgkmcnt(0)
	v_mfma_f32_16x16x32_bf16 v[50:53], v[144:147], v[204:207], v[50:53]
	v_mfma_f32_16x16x32_bf16 v[54:57], v[152:155], v[100:103], v[54:57]
	v_mfma_f32_16x16x32_bf16 v[58:61], v[152:155], v[204:207], v[58:61]
	v_mfma_f32_16x16x32_bf16 v[62:65], v[160:163], v[100:103], v[62:65]
	v_mfma_f32_16x16x32_bf16 v[66:69], v[160:163], v[204:207], v[66:69]
	v_mfma_f32_16x16x32_bf16 v[70:73], v[188:191], v[100:103], v[70:73]
	v_mfma_f32_16x16x32_bf16 v[74:77], v[188:191], v[204:207], v[74:77]
	v_mfma_f32_16x16x32_bf16 v[136:139], v[144:147], v[100:103], v[136:139]
	v_mfma_f32_16x16x32_bf16 v[50:53], v[148:151], v[208:211], v[50:53]
	v_mfma_f32_16x16x32_bf16 v[54:57], v[156:159], v[104:107], v[54:57]
	v_mfma_f32_16x16x32_bf16 v[58:61], v[156:159], v[208:211], v[58:61]
	v_mfma_f32_16x16x32_bf16 v[62:65], v[164:167], v[104:107], v[62:65]
	v_mfma_f32_16x16x32_bf16 v[66:69], v[164:167], v[208:211], v[66:69]
	v_mfma_f32_16x16x32_bf16 v[70:73], v[192:195], v[104:107], v[70:73]
	v_mfma_f32_16x16x32_bf16 v[74:77], v[192:195], v[208:211], v[74:77]
	v_mfma_f32_16x16x32_bf16 v[136:139], v[148:151], v[104:107], v[136:139]
	s_barrier
	ds_read_b128 v[144:147], v226 offset:16384
	ds_read_b128 v[148:151], v226 offset:17408
	ds_read_b128 v[152:155], v227 offset:18432
	ds_read_b128 v[156:159], v227 offset:19456
	ds_read_b128 v[160:163], v227 offset:20480
	ds_read_b128 v[164:167], v227 offset:21504
	ds_read_b128 v[188:191], v227 offset:22528
	ds_read_b128 v[192:195], v227 offset:23552
	s_waitcnt vmcnt(4)
	s_barrier
	s_waitcnt lgkmcnt(0)
	s_waitcnt lgkmcnt(0)
	v_mfma_f32_16x16x32_bf16 v[18:21], v[144:147], v[114:117], v[20:23]
	v_mfma_f32_16x16x32_bf16 v[212:215], v[148:151], v[122:125], v[18:21]
	v_mfma_f32_16x16x32_bf16 v[18:21], v[144:147], v[126:129], v[168:171]
	v_mfma_f32_16x16x32_bf16 v[168:171], v[148:151], v[140:143], v[18:21]
	v_mfma_f32_16x16x32_bf16 v[18:21], v[152:155], v[114:117], v[172:175]
	v_mfma_f32_16x16x32_bf16 v[172:175], v[156:159], v[122:125], v[18:21]
	v_mfma_f32_16x16x32_bf16 v[18:21], v[152:155], v[126:129], v[176:179]
	v_mfma_f32_16x16x32_bf16 v[176:179], v[156:159], v[140:143], v[18:21]
	v_mfma_f32_16x16x32_bf16 v[18:21], v[160:163], v[114:117], v[180:183]
	v_mfma_f32_16x16x32_bf16 v[180:183], v[164:167], v[122:125], v[18:21]
	v_mfma_f32_16x16x32_bf16 v[18:21], v[160:163], v[126:129], v[184:187]
	v_mfma_f32_16x16x32_bf16 v[184:187], v[164:167], v[140:143], v[18:21]
	v_mfma_f32_16x16x32_bf16 v[18:21], v[188:191], v[114:117], v[34:37]
	v_mfma_f32_16x16x32_bf16 v[216:219], v[192:195], v[122:125], v[18:21]
	v_mfma_f32_16x16x32_bf16 v[18:21], v[188:191], v[126:129], v[38:41]
	v_mfma_f32_16x16x32_bf16 v[36:39], v[192:195], v[140:143], v[18:21]
	v_mfma_f32_16x16x32_bf16 v[12:15], v[144:147], v[100:103], v[14:17]
	v_mfma_f32_16x16x32_bf16 v[140:143], v[148:151], v[104:107], v[12:15]
	v_mfma_f32_16x16x32_bf16 v[12:15], v[144:147], v[204:207], v[30:33]
	v_mfma_f32_16x16x32_bf16 v[144:147], v[148:151], v[208:211], v[12:15]
	v_mfma_f32_16x16x32_bf16 v[12:15], v[152:155], v[100:103], v[42:45]
	v_mfma_f32_16x16x32_bf16 v[40:43], v[156:159], v[104:107], v[12:15]
	v_mfma_f32_16x16x32_bf16 v[12:15], v[152:155], v[204:207], v[46:49]
	v_mfma_f32_16x16x32_bf16 v[44:47], v[156:159], v[208:211], v[12:15]
	v_mfma_f32_16x16x32_bf16 v[12:15], v[160:163], v[100:103], v[78:81]
	v_mfma_f32_16x16x32_bf16 v[148:151], v[164:167], v[104:107], v[12:15]
	v_mfma_f32_16x16x32_bf16 v[12:15], v[160:163], v[204:207], v[118:121]
	v_mfma_f32_16x16x32_bf16 v[152:155], v[164:167], v[208:211], v[12:15]
	v_mfma_f32_16x16x32_bf16 v[12:15], v[188:191], v[100:103], v[110:113]
	v_mfma_f32_16x16x32_bf16 v[4:7], v[188:191], v[204:207], v[4:7]
	v_mfma_f32_16x16x32_bf16 v[156:159], v[192:195], v[104:107], v[12:15]
	v_mfma_f32_16x16x32_bf16 v[160:163], v[192:195], v[208:211], v[4:7]
	s_barrier
; DI int tid_opaque() { int t = threadIdx.x; asm volatile("" : "+v"(t)); return t; }
; #define LDA8(dst, b, h) _Pragma("unroll") for (int m = 0; m < 4; ++m) _Pragma("unroll") for (int k = 0; k < 2; ++k) \
;     dst[m][k] = *(const bf16x8*)((const char*)SA8(b, h) + lds_byte8(wr * 64 + m * 16 + fr, k * 32 + fq * 8))
; #define LDB8(dst, b, h) _Pragma("unroll") for (int n = 0; n < 2; ++n) _Pragma("unroll") for (int k = 0; k < 2; ++k) \
;     dst[n][k] = *(const bf16x8*)((const char*)SB8(b, h) + lds_byte8(wc * 32 + n * 16 + fr, k * 32 + fq * 8))
; #define WAIT_V8(n) asm volatile("s_waitcnt vmcnt(" #n ")" ::: "memory")
; #define WAIT_L8(n) asm volatile("s_waitcnt lgkmcnt(" #n ")" ::: "memory")
; #define BAR8 __builtin_amdgcn_s_barrier()
;     ...
;   { LDB8(B0, 1, 0); LDA8(At, 1, 0); WAIT_V8(2); BAR8; WAIT_L8(0); MMA8(0, 0, At, B0); BAR8;
;     LDB8(B1, 1, 1); WAIT_V8(0); BAR8; WAIT_L8(0); MMA8(0, 1, At, B1); BAR8;
;     LDA8(At, 1, 1); BAR8; WAIT_L8(0); MMA8(1, 0, At, B0); MMA8(1, 1, At, B1); BAR8; }
;   if (wr == 0) BAR8;
;   __syncthreads();
;   if (EPI == EPI_GU && nm0 >= 0) {
;     const int t = tid_opaque();
;     STAGE8(SB8(0, 0), Bt, K, nn0, 0); STAGE8(SA8(0, 0), A, lda, nm0, 0);
;     STAGE8(SB8(0, 1), Bt, K, nn0 + 128, 0); STAGE8(SA8(0, 1), A, lda, nm0 + 128, 0);
;   }
;     ...
;   if (t < 256) {
	ds_read_b128 v[164:167], v130
	ds_read_b128 v[188:191], v131
	ds_read_b128 v[192:195], v232
	ds_read_b128 v[204:207], v233
	ds_read_b128 v[12:15], v226 offset:32768
	ds_read_b128 v[16:19], v226 offset:33792
	ds_read_b128 v[28:31], v227 offset:34816
	ds_read_b128 v[32:35], v227 offset:35840
	ds_read_b128 v[78:81], v227 offset:36864
	ds_read_b128 v[112:115], v227 offset:37888
	ds_read_b128 v[120:123], v227 offset:38912
	ds_read_b128 v[124:127], v227 offset:39936
	s_waitcnt vmcnt(2)
	s_barrier
	s_waitcnt lgkmcnt(0)
	s_waitcnt lgkmcnt(0)
	v_mfma_f32_16x16x32_bf16 v[4:7], v[12:15], v[164:167], v[8:11]
	v_mfma_f32_16x16x32_bf16 v[104:107], v[16:19], v[188:191], v[4:7]
	v_mfma_f32_16x16x32_bf16 v[4:7], v[12:15], v[192:195], v[24:27]
	v_mfma_f32_16x16x32_bf16 v[116:119], v[16:19], v[204:207], v[4:7]
	v_mfma_f32_16x16x32_bf16 v[4:7], v[28:31], v[164:167], v[82:85]
	v_mfma_f32_16x16x32_bf16 v[100:103], v[32:35], v[188:191], v[4:7]
	v_mfma_f32_16x16x32_bf16 v[4:7], v[28:31], v[192:195], v[86:89]
	v_mfma_f32_16x16x32_bf16 v[108:111], v[32:35], v[204:207], v[4:7]
	v_mfma_f32_16x16x32_bf16 v[4:7], v[78:81], v[164:167], v[90:93]
	v_mfma_f32_16x16x32_bf16 v[92:95], v[112:115], v[188:191], v[4:7]
	v_mfma_f32_16x16x32_bf16 v[4:7], v[78:81], v[192:195], v[96:99]
	v_mfma_f32_16x16x32_bf16 v[96:99], v[112:115], v[204:207], v[4:7]
	v_mfma_f32_16x16x32_bf16 v[4:7], v[120:123], v[164:167], v[196:199]
	v_mfma_f32_16x16x32_bf16 v[84:87], v[124:127], v[188:191], v[4:7]
	v_mfma_f32_16x16x32_bf16 v[4:7], v[120:123], v[192:195], v[200:203]
	v_mfma_f32_16x16x32_bf16 v[88:91], v[124:127], v[204:207], v[4:7]
	s_barrier
	ds_read_b128 v[196:199], v236
	ds_read_b128 v[200:203], v237
	ds_read_b128 v[208:211], v238
	ds_read_b128 v[220:223], v239
	s_waitcnt vmcnt(0)
	s_barrier
	s_waitcnt lgkmcnt(0)
	s_waitcnt lgkmcnt(0)
	v_mfma_f32_16x16x32_bf16 v[4:7], v[12:15], v[196:199], v[136:139]
	v_mfma_f32_16x16x32_bf16 v[8:11], v[12:15], v[208:211], v[50:53]
	v_mfma_f32_16x16x32_bf16 v[4:7], v[16:19], v[200:203], v[4:7]
	v_mfma_f32_16x16x32_bf16 v[20:23], v[16:19], v[220:223], v[8:11]
	v_mfma_f32_16x16x32_bf16 v[8:11], v[28:31], v[196:199], v[54:57]
	v_mfma_f32_16x16x32_bf16 v[12:15], v[28:31], v[208:211], v[58:61]
	v_mfma_f32_16x16x32_bf16 v[16:19], v[78:81], v[208:211], v[66:69]
	v_mfma_f32_16x16x32_bf16 v[8:11], v[32:35], v[200:203], v[8:11]
	v_mfma_f32_16x16x32_bf16 v[24:27], v[32:35], v[220:223], v[12:15]
	v_mfma_f32_16x16x32_bf16 v[12:15], v[78:81], v[196:199], v[62:65]
	v_mfma_f32_16x16x32_bf16 v[28:31], v[112:115], v[220:223], v[16:19]
	v_mfma_f32_16x16x32_bf16 v[16:19], v[120:123], v[196:199], v[70:73]
	v_mfma_f32_16x16x32_bf16 v[32:35], v[120:123], v[208:211], v[74:77]
	v_mfma_f32_16x16x32_bf16 v[12:15], v[112:115], v[200:203], v[12:15]
	v_mfma_f32_16x16x32_bf16 v[16:19], v[124:127], v[200:203], v[16:19]
	v_mfma_f32_16x16x32_bf16 v[32:35], v[124:127], v[220:223], v[32:35]
	s_barrier
	ds_read_b128 v[48:51], v226 offset:49152
	ds_read_b128 v[52:55], v226 offset:50176
	ds_read_b128 v[56:59], v227 offset:51200
	ds_read_b128 v[60:63], v227 offset:52224
	ds_read_b128 v[64:67], v227 offset:53248
	ds_read_b128 v[136:139], v227 offset:54272
	ds_read_b128 v[230:233], v227 offset:55296
	ds_read_b128 v[238:241], v227 offset:56320
	s_barrier
	s_waitcnt lgkmcnt(0)
	s_waitcnt lgkmcnt(0)
	v_mfma_f32_16x16x32_bf16 v[68:71], v[48:51], v[164:167], v[212:215]
	v_mfma_f32_16x16x32_bf16 v[128:131], v[52:55], v[188:191], v[68:71]
	v_mfma_f32_16x16x32_bf16 v[68:71], v[48:51], v[192:195], v[168:171]
	v_mfma_f32_16x16x32_bf16 v[124:127], v[52:55], v[204:207], v[68:71]
	v_mfma_f32_16x16x32_bf16 v[68:71], v[56:59], v[164:167], v[172:175]
	v_mfma_f32_16x16x32_bf16 v[120:123], v[60:63], v[188:191], v[68:71]
	v_mfma_f32_16x16x32_bf16 v[68:71], v[56:59], v[192:195], v[176:179]
	v_mfma_f32_16x16x32_bf16 v[112:115], v[60:63], v[204:207], v[68:71]
	v_mfma_f32_16x16x32_bf16 v[68:71], v[64:67], v[164:167], v[180:183]
	v_mfma_f32_16x16x32_bf16 v[80:83], v[136:139], v[188:191], v[68:71]
	v_mfma_f32_16x16x32_bf16 v[68:71], v[64:67], v[192:195], v[184:187]
	v_mfma_f32_16x16x32_bf16 v[76:79], v[136:139], v[204:207], v[68:71]
	v_mfma_f32_16x16x32_bf16 v[68:71], v[230:233], v[164:167], v[216:219]
	v_mfma_f32_16x16x32_bf16 v[36:39], v[230:233], v[192:195], v[36:39]
	v_mfma_f32_16x16x32_bf16 v[72:75], v[238:241], v[188:191], v[68:71]
	v_mfma_f32_16x16x32_bf16 v[68:71], v[238:241], v[204:207], v[36:39]
	v_mfma_f32_16x16x32_bf16 v[36:39], v[48:51], v[196:199], v[140:143]
	v_mfma_f32_16x16x32_bf16 v[48:51], v[48:51], v[208:211], v[144:147]
	v_mfma_f32_16x16x32_bf16 v[36:39], v[52:55], v[200:203], v[36:39]
	v_mfma_f32_16x16x32_bf16 v[52:55], v[52:55], v[220:223], v[48:51]
	v_mfma_f32_16x16x32_bf16 v[40:43], v[56:59], v[196:199], v[40:43]
	v_mfma_f32_16x16x32_bf16 v[44:47], v[56:59], v[208:211], v[44:47]
	v_mfma_f32_16x16x32_bf16 v[48:51], v[64:67], v[208:211], v[152:155]
	v_mfma_f32_16x16x32_bf16 v[40:43], v[60:63], v[200:203], v[40:43]
	v_mfma_f32_16x16x32_bf16 v[56:59], v[60:63], v[220:223], v[44:47]
	v_mfma_f32_16x16x32_bf16 v[44:47], v[64:67], v[196:199], v[148:151]
	v_mfma_f32_16x16x32_bf16 v[60:63], v[136:139], v[220:223], v[48:51]
	v_mfma_f32_16x16x32_bf16 v[48:51], v[230:233], v[196:199], v[156:159]
	v_mfma_f32_16x16x32_bf16 v[64:67], v[230:233], v[208:211], v[160:163]
	v_mfma_f32_16x16x32_bf16 v[44:47], v[136:139], v[200:203], v[44:47]
	v_mfma_f32_16x16x32_bf16 v[48:51], v[238:241], v[200:203], v[48:51]
	v_mfma_f32_16x16x32_bf16 v[64:67], v[238:241], v[220:223], v[64:67]
	s_movk_i32 s12, 0x100
	v_cmp_gt_u32_e32 vcc, s12, v3
	s_barrier
	s_and_saveexec_b64 s[12:13], vcc
	s_cbranch_execz .LBB0_556
	s_barrier

; #define LDA8(dst, b, h) _Pragma("unroll") for (int m = 0; m < 4; ++m) _Pragma("unroll") for (int k = 0; k < 2; ++k) \
;     dst[m][k] = *(const bf16x8*)((const char*)SA8(b, h) + lds_byte8(wr * 64 + m * 16 + fr, k * 32 + fq * 8))
; #define LDB8(dst, b, h) _Pragma("unroll") for (int n = 0; n < 2; ++n) _Pragma("unroll") for (int k = 0; k < 2; ++k) \
;     dst[n][k] = *(const bf16x8*)((const char*)SB8(b, h) + lds_byte8(wc * 32 + n * 16 + fr, k * 32 + fq * 8))
; #define WAIT_L8(n) asm volatile("s_waitcnt lgkmcnt(" #n ")" ::: "memory")
; #define BAR8 __builtin_amdgcn_s_barrier()
; #define SCHED8 __builtin_amdgcn_sched_barrier(0)
;     ...
;   for (int tt = 0; tt < nt - 2; tt += 2) {
;     LDB8(B0, 0, 0); SCHED8; LDA8(At, 0, 0); STAGE8(SA8(1, 1), A, lda, brow + 128, tt + 1);
;     WAIT_L8(8); BAR8; WAIT_L8(0); MMA8(0, 0, At, B0); BAR8; SCHED8;
;     LDB8(B1, 0, 1); STAGE8(SB8(0, 0), Bt, K, bcol, tt + 2);
;     BAR8; WAIT_L8(0); MMA8(0, 1, At, B1); BAR8;
;     LDA8(At, 0, 1); STAGE8(SA8(0, 0), A, lda, brow, tt + 2);
;     BAR8; WAIT_L8(0); MMA8(1, 0, At, B0); BAR8; SCHED8;
.LBB0_908:
	ds_read_b128 v[174:177], v171
	ds_read_b128 v[178:181], v171 offset:1024
	ds_read_b128 v[182:185], v171 offset:2048
	ds_read_b128 v[186:189], v171 offset:3072
	v_add_u32_e32 v172, 0xc000, v150
	v_lshl_add_u64 v[222:223], v[142:143], 0, s[12:13]
	v_readfirstlane_b32 s31, v172
	v_lshl_add_u64 v[226:227], v[222:223], 0, s[36:37]
	s_mov_b32 m0, s31
	v_add_u32_e32 v173, 0xe000, v150
	ds_read_b128 v[190:193], v156
	ds_read_b128 v[194:197], v156 offset:1024
	ds_read_b128 v[198:201], v155
	ds_read_b128 v[202:205], v155 offset:1024
	ds_read_b128 v[206:209], v154
	ds_read_b128 v[210:213], v154 offset:1024
	ds_read_b128 v[214:217], v153
	ds_read_b128 v[218:221], v153 offset:1024
	global_load_lds_dwordx4 v[226:227], off
	v_lshl_add_u64 v[226:227], v[144:145], 0, s[12:13]
	v_readfirstlane_b32 s31, v173
	v_lshl_add_u64 v[228:229], v[226:227], 0, s[36:37]
	s_mov_b32 m0, s31
	s_nop 0
	global_load_lds_dwordx4 v[228:229], off
	s_waitcnt lgkmcnt(8)
	s_barrier
	s_waitcnt lgkmcnt(0)
	s_waitcnt lgkmcnt(0)
	v_mfma_f32_16x16x32_bf16 v[128:131], v[190:193], v[174:177], v[128:131]
	v_mfma_f32_16x16x32_bf16 v[124:127], v[190:193], v[182:185], v[124:127]
	v_mfma_f32_16x16x32_bf16 v[120:123], v[198:201], v[174:177], v[120:123]
	v_mfma_f32_16x16x32_bf16 v[116:119], v[198:201], v[182:185], v[116:119]
	v_mfma_f32_16x16x32_bf16 v[112:115], v[206:209], v[174:177], v[112:115]
	v_mfma_f32_16x16x32_bf16 v[108:111], v[206:209], v[182:185], v[108:111]
	v_mfma_f32_16x16x32_bf16 v[104:107], v[214:217], v[174:177], v[104:107]
	v_mfma_f32_16x16x32_bf16 v[100:103], v[214:217], v[182:185], v[100:103]
	v_mfma_f32_16x16x32_bf16 v[128:131], v[194:197], v[178:181], v[128:131]
	v_mfma_f32_16x16x32_bf16 v[124:127], v[194:197], v[186:189], v[124:127]
	v_mfma_f32_16x16x32_bf16 v[120:123], v[202:205], v[178:181], v[120:123]
	v_mfma_f32_16x16x32_bf16 v[116:119], v[202:205], v[186:189], v[116:119]
	v_mfma_f32_16x16x32_bf16 v[112:115], v[210:213], v[178:181], v[112:115]
	v_mfma_f32_16x16x32_bf16 v[108:111], v[210:213], v[186:189], v[108:111]
	v_mfma_f32_16x16x32_bf16 v[104:107], v[218:221], v[178:181], v[104:107]
	v_mfma_f32_16x16x32_bf16 v[100:103], v[218:221], v[186:189], v[100:103]
	s_barrier
	v_lshl_add_u64 v[228:229], v[138:139], 0, s[12:13]
	v_readfirstlane_b32 s31, v151
	v_lshl_add_u64 v[236:237], v[228:229], 0, s[38:39]
	s_mov_b32 m0, s31
	ds_read_b128 v[230:233], v167
	ds_read_b128 v[238:241], v167 offset:1024
	ds_read_b128 v[242:245], v167 offset:2048
	ds_read_b128 v[246:249], v167 offset:3072
	global_load_lds_dwordx4 v[236:237], off
	v_lshl_add_u64 v[236:237], v[140:141], 0, s[12:13]
	v_readfirstlane_b32 s31, v157
	v_lshl_add_u64 v[250:251], v[236:237], 0, s[38:39]
	s_mov_b32 m0, s31
	s_nop 0
	global_load_lds_dwordx4 v[250:251], off
	s_barrier
	s_waitcnt lgkmcnt(0)
	s_waitcnt lgkmcnt(0)
	v_mfma_f32_16x16x32_bf16 v[96:99], v[190:193], v[230:233], v[96:99]
	v_mfma_f32_16x16x32_bf16 v[92:95], v[190:193], v[242:245], v[92:95]
	v_mfma_f32_16x16x32_bf16 v[88:91], v[198:201], v[230:233], v[88:91]
	v_mfma_f32_16x16x32_bf16 v[84:87], v[198:201], v[242:245], v[84:87]
	v_mfma_f32_16x16x32_bf16 v[80:83], v[206:209], v[230:233], v[80:83]
	v_mfma_f32_16x16x32_bf16 v[76:79], v[206:209], v[242:245], v[76:79]
	v_mfma_f32_16x16x32_bf16 v[72:75], v[214:217], v[230:233], v[72:75]
	v_mfma_f32_16x16x32_bf16 v[68:71], v[214:217], v[242:245], v[68:71]
	v_mfma_f32_16x16x32_bf16 v[96:99], v[194:197], v[238:241], v[96:99]
	v_mfma_f32_16x16x32_bf16 v[92:95], v[194:197], v[246:249], v[92:95]
	v_mfma_f32_16x16x32_bf16 v[88:91], v[202:205], v[238:241], v[88:91]
	v_mfma_f32_16x16x32_bf16 v[84:87], v[202:205], v[246:249], v[84:87]
	v_mfma_f32_16x16x32_bf16 v[80:83], v[210:213], v[238:241], v[80:83]
	v_mfma_f32_16x16x32_bf16 v[76:79], v[210:213], v[246:249], v[76:79]
	v_mfma_f32_16x16x32_bf16 v[72:75], v[218:221], v[238:241], v[72:75]
	v_mfma_f32_16x16x32_bf16 v[68:71], v[218:221], v[246:249], v[68:71]
	v_readfirstlane_b32 s31, v150
	v_lshl_add_u64 v[250:251], v[222:223], 0, s[40:41]
	s_mov_b32 m0, s31
	v_readfirstlane_b32 s31, v152
	s_barrier
	ds_read_b128 v[190:193], v156 offset:16384
	ds_read_b128 v[194:197], v156 offset:17408
	ds_read_b128 v[198:201], v155 offset:16384
	ds_read_b128 v[202:205], v155 offset:17408
	ds_read_b128 v[206:209], v154 offset:16384
	ds_read_b128 v[210:213], v154 offset:17408
	ds_read_b128 v[214:217], v153 offset:16384
	ds_read_b128 v[218:221], v153 offset:17408
	global_load_lds_dwordx4 v[250:251], off
	v_lshl_add_u64 v[250:251], v[226:227], 0, s[40:41]
	s_mov_b32 m0, s31
	s_nop 0
	global_load_lds_dwordx4 v[250:251], off
	s_barrier
	s_waitcnt lgkmcnt(0)
	s_waitcnt lgkmcnt(0)
	v_mfma_f32_16x16x32_bf16 v[64:67], v[190:193], v[174:177], v[64:67]
	v_mfma_f32_16x16x32_bf16 v[60:63], v[190:193], v[182:185], v[60:63]
	v_mfma_f32_16x16x32_bf16 v[56:59], v[198:201], v[174:177], v[56:59]
	v_mfma_f32_16x16x32_bf16 v[52:55], v[198:201], v[182:185], v[52:55]
	v_mfma_f32_16x16x32_bf16 v[48:51], v[206:209], v[174:177], v[48:51]
	v_mfma_f32_16x16x32_bf16 v[44:47], v[206:209], v[182:185], v[44:47]
	v_mfma_f32_16x16x32_bf16 v[40:43], v[214:217], v[174:177], v[40:43]
	v_mfma_f32_16x16x32_bf16 v[36:39], v[214:217], v[182:185], v[36:39]
	v_mfma_f32_16x16x32_bf16 v[64:67], v[194:197], v[178:181], v[64:67]
	v_mfma_f32_16x16x32_bf16 v[60:63], v[194:197], v[186:189], v[60:63]
	v_mfma_f32_16x16x32_bf16 v[56:59], v[202:205], v[178:181], v[56:59]
	v_mfma_f32_16x16x32_bf16 v[52:55], v[202:205], v[186:189], v[52:55]
	v_mfma_f32_16x16x32_bf16 v[48:51], v[210:213], v[178:181], v[48:51]
	v_mfma_f32_16x16x32_bf16 v[44:47], v[210:213], v[186:189], v[44:47]
	v_mfma_f32_16x16x32_bf16 v[40:43], v[218:221], v[178:181], v[40:43]
	v_mfma_f32_16x16x32_bf16 v[36:39], v[218:221], v[186:189], v[36:39]
	s_barrier
; #define LDA8(dst, b, h) _Pragma("unroll") for (int m = 0; m < 4; ++m) _Pragma("unroll") for (int k = 0; k < 2; ++k) \
;     dst[m][k] = *(const bf16x8*)((const char*)SA8(b, h) + lds_byte8(wr * 64 + m * 16 + fr, k * 32 + fq * 8))
; #define LDB8(dst, b, h) _Pragma("unroll") for (int n = 0; n < 2; ++n) _Pragma("unroll") for (int k = 0; k < 2; ++k) \
;     dst[n][k] = *(const bf16x8*)((const char*)SB8(b, h) + lds_byte8(wc * 32 + n * 16 + fr, k * 32 + fq * 8))
; #define WAIT_V8(n) asm volatile("s_waitcnt vmcnt(" #n ")" ::: "memory")
; #define WAIT_L8(n) asm volatile("s_waitcnt lgkmcnt(" #n ")" ::: "memory")
; #define BAR8 __builtin_amdgcn_s_barrier()
; #define SCHED8 __builtin_amdgcn_sched_barrier(0)
;     ...
;     STAGE8(SB8(0, 1), Bt, K, bcol + 128, tt + 2);
;     WAIT_V8(6); BAR8; MMA8(1, 1, At, B1); BAR8;
;     LDB8(B0, 1, 0); SCHED8; LDA8(At, 1, 0); STAGE8(SA8(0, 1), A, lda, brow + 128, tt + 2);
;     WAIT_L8(8); BAR8; WAIT_L8(0); MMA8(0, 0, At, B0); BAR8; SCHED8;
;     LDB8(B1, 1, 1); STAGE8(SB8(1, 0), Bt, K, bcol, tt + 3);
;     BAR8; WAIT_L8(0); MMA8(0, 1, At, B1); BAR8;
;     LDA8(At, 1, 1); STAGE8(SA8(1, 0), A, lda, brow, tt + 3);
	v_readfirstlane_b32 s31, v159
	v_lshl_add_u64 v[174:175], v[228:229], 0, s[42:43]
	s_mov_b32 m0, s31
	v_readfirstlane_b32 s31, v161
	global_load_lds_dwordx4 v[174:175], off
	v_lshl_add_u64 v[174:175], v[236:237], 0, s[42:43]
	s_mov_b32 m0, s31
	s_nop 0
	global_load_lds_dwordx4 v[174:175], off
	s_waitcnt vmcnt(6)
	s_barrier
	v_mfma_f32_16x16x32_bf16 v[32:35], v[190:193], v[230:233], v[32:35]
	v_mfma_f32_16x16x32_bf16 v[28:31], v[190:193], v[242:245], v[28:31]
	v_mfma_f32_16x16x32_bf16 v[24:27], v[198:201], v[230:233], v[24:27]
	v_mfma_f32_16x16x32_bf16 v[20:23], v[198:201], v[242:245], v[20:23]
	v_mfma_f32_16x16x32_bf16 v[16:19], v[206:209], v[230:233], v[16:19]
	v_mfma_f32_16x16x32_bf16 v[12:15], v[206:209], v[242:245], v[12:15]
	v_mfma_f32_16x16x32_bf16 v[8:11], v[214:217], v[230:233], v[8:11]
	v_mfma_f32_16x16x32_bf16 v[4:7], v[214:217], v[242:245], v[4:7]
	v_mfma_f32_16x16x32_bf16 v[32:35], v[194:197], v[238:241], v[32:35]
	v_mfma_f32_16x16x32_bf16 v[28:31], v[194:197], v[246:249], v[28:31]
	v_mfma_f32_16x16x32_bf16 v[24:27], v[202:205], v[238:241], v[24:27]
	v_mfma_f32_16x16x32_bf16 v[20:23], v[202:205], v[246:249], v[20:23]
	v_mfma_f32_16x16x32_bf16 v[16:19], v[210:213], v[238:241], v[16:19]
	v_mfma_f32_16x16x32_bf16 v[12:15], v[210:213], v[246:249], v[12:15]
	v_mfma_f32_16x16x32_bf16 v[8:11], v[218:221], v[238:241], v[8:11]
	v_mfma_f32_16x16x32_bf16 v[4:7], v[218:221], v[246:249], v[4:7]
	s_barrier
	ds_read_b128 v[174:177], v160
	ds_read_b128 v[178:181], v160 offset:1024
	ds_read_b128 v[182:185], v160 offset:2048
	ds_read_b128 v[186:189], v160 offset:3072
	v_readfirstlane_b32 s31, v162
	v_lshl_add_u64 v[230:231], v[222:223], 0, s[44:45]
	s_mov_b32 m0, s31
	v_readfirstlane_b32 s31, v163
	ds_read_b128 v[190:193], v156 offset:32768
	ds_read_b128 v[194:197], v156 offset:33792
	ds_read_b128 v[198:201], v155 offset:32768
	ds_read_b128 v[202:205], v155 offset:33792
	ds_read_b128 v[206:209], v154 offset:32768
	ds_read_b128 v[210:213], v154 offset:33792
	ds_read_b128 v[214:217], v153 offset:32768
	ds_read_b128 v[218:221], v153 offset:33792
	global_load_lds_dwordx4 v[230:231], off
	v_lshl_add_u64 v[230:231], v[226:227], 0, s[44:45]
	s_mov_b32 m0, s31
	s_nop 0
	global_load_lds_dwordx4 v[230:231], off
	s_waitcnt lgkmcnt(8)
	s_barrier
	s_waitcnt lgkmcnt(0)
	s_waitcnt lgkmcnt(0)
	v_mfma_f32_16x16x32_bf16 v[128:131], v[190:193], v[174:177], v[128:131]
	v_mfma_f32_16x16x32_bf16 v[124:127], v[190:193], v[182:185], v[124:127]
	v_mfma_f32_16x16x32_bf16 v[120:123], v[198:201], v[174:177], v[120:123]
	v_mfma_f32_16x16x32_bf16 v[116:119], v[198:201], v[182:185], v[116:119]
	v_mfma_f32_16x16x32_bf16 v[112:115], v[206:209], v[174:177], v[112:115]
	v_mfma_f32_16x16x32_bf16 v[108:111], v[206:209], v[182:185], v[108:111]
	v_mfma_f32_16x16x32_bf16 v[104:107], v[214:217], v[174:177], v[104:107]
	v_mfma_f32_16x16x32_bf16 v[100:103], v[214:217], v[182:185], v[100:103]
	v_mfma_f32_16x16x32_bf16 v[128:131], v[194:197], v[178:181], v[128:131]
	v_mfma_f32_16x16x32_bf16 v[124:127], v[194:197], v[186:189], v[124:127]
	v_mfma_f32_16x16x32_bf16 v[120:123], v[202:205], v[178:181], v[120:123]
	v_mfma_f32_16x16x32_bf16 v[116:119], v[202:205], v[186:189], v[116:119]
	v_mfma_f32_16x16x32_bf16 v[112:115], v[210:213], v[178:181], v[112:115]
	v_mfma_f32_16x16x32_bf16 v[108:111], v[210:213], v[186:189], v[108:111]
	v_mfma_f32_16x16x32_bf16 v[104:107], v[218:221], v[178:181], v[104:107]
	v_mfma_f32_16x16x32_bf16 v[100:103], v[218:221], v[186:189], v[100:103]
	s_barrier
	v_readfirstlane_b32 s31, v164
	v_lshl_add_u64 v[250:251], v[228:229], 0, s[46:47]
	s_mov_b32 m0, s31
	v_readfirstlane_b32 s31, v165
	ds_read_b128 v[230:233], v158
	ds_read_b128 v[238:241], v158 offset:1024
	ds_read_b128 v[242:245], v158 offset:2048
	ds_read_b128 v[246:249], v158 offset:3072
	global_load_lds_dwordx4 v[250:251], off
	v_lshl_add_u64 v[250:251], v[236:237], 0, s[46:47]
	s_mov_b32 m0, s31
	s_nop 0
	global_load_lds_dwordx4 v[250:251], off
	s_barrier
	s_waitcnt lgkmcnt(0)
	s_waitcnt lgkmcnt(0)
	v_mfma_f32_16x16x32_bf16 v[96:99], v[190:193], v[230:233], v[96:99]
	v_mfma_f32_16x16x32_bf16 v[92:95], v[190:193], v[242:245], v[92:95]
	v_mfma_f32_16x16x32_bf16 v[88:91], v[198:201], v[230:233], v[88:91]
	v_mfma_f32_16x16x32_bf16 v[84:87], v[198:201], v[242:245], v[84:87]
	v_mfma_f32_16x16x32_bf16 v[80:83], v[206:209], v[230:233], v[80:83]
	v_mfma_f32_16x16x32_bf16 v[76:79], v[206:209], v[242:245], v[76:79]
	v_mfma_f32_16x16x32_bf16 v[72:75], v[214:217], v[230:233], v[72:75]
	v_mfma_f32_16x16x32_bf16 v[68:71], v[214:217], v[242:245], v[68:71]
	v_mfma_f32_16x16x32_bf16 v[96:99], v[194:197], v[238:241], v[96:99]
	v_mfma_f32_16x16x32_bf16 v[92:95], v[194:197], v[246:249], v[92:95]
	v_mfma_f32_16x16x32_bf16 v[88:91], v[202:205], v[238:241], v[88:91]
	v_mfma_f32_16x16x32_bf16 v[84:87], v[202:205], v[246:249], v[84:87]
	v_mfma_f32_16x16x32_bf16 v[80:83], v[210:213], v[238:241], v[80:83]
	v_mfma_f32_16x16x32_bf16 v[76:79], v[210:213], v[246:249], v[76:79]
	v_mfma_f32_16x16x32_bf16 v[72:75], v[218:221], v[238:241], v[72:75]
	v_mfma_f32_16x16x32_bf16 v[68:71], v[218:221], v[246:249], v[68:71]
	v_readfirstlane_b32 s31, v166
	v_lshl_add_u64 v[222:223], v[222:223], 0, s[48:49]
	s_mov_b32 m0, s31
	v_readfirstlane_b32 s31, v168
	s_barrier
	ds_read_b128 v[190:193], v156 offset:49152
	ds_read_b128 v[194:197], v156 offset:50176
	ds_read_b128 v[198:201], v155 offset:49152
	ds_read_b128 v[202:205], v155 offset:50176
	ds_read_b128 v[206:209], v154 offset:49152
	ds_read_b128 v[210:213], v154 offset:50176
	ds_read_b128 v[214:217], v153 offset:49152
	ds_read_b128 v[218:221], v153 offset:50176
	global_load_lds_dwordx4 v[222:223], off
	v_lshl_add_u64 v[222:223], v[226:227], 0, s[48:49]
	s_mov_b32 m0, s31
	s_nop 0
	global_load_lds_dwordx4 v[222:223], off
	s_barrier
; #define LDA8(dst, b, h) _Pragma("unroll") for (int m = 0; m < 4; ++m) _Pragma("unroll") for (int k = 0; k < 2; ++k) \
;     dst[m][k] = *(const bf16x8*)((const char*)SA8(b, h) + lds_byte8(wr * 64 + m * 16 + fr, k * 32 + fq * 8))
; #define LDB8(dst, b, h) _Pragma("unroll") for (int n = 0; n < 2; ++n) _Pragma("unroll") for (int k = 0; k < 2; ++k) \
;     dst[n][k] = *(const bf16x8*)((const char*)SB8(b, h) + lds_byte8(wc * 32 + n * 16 + fr, k * 32 + fq * 8))
; #define WAIT_V8(n) asm volatile("s_waitcnt vmcnt(" #n ")" ::: "memory")
; #define WAIT_L8(n) asm volatile("s_waitcnt lgkmcnt(" #n ")" ::: "memory")
; #define BAR8 __builtin_amdgcn_s_barrier()
; #define SCHED8 __builtin_amdgcn_sched_barrier(0)
;     ...
;     BAR8; WAIT_L8(0); MMA8(1, 0, At, B0); BAR8; SCHED8;
;     STAGE8(SB8(1, 1), Bt, K, bcol + 128, tt + 3);
;     WAIT_V8(6); BAR8; MMA8(1, 1, At, B1); BAR8;
;   }
;   { LDB8(B0, 0, 0); LDA8(At, 0, 0); STAGE8(SA8(1, 1), A, lda, brow + 128, nt - 1);
;     BAR8; WAIT_L8(0); MMA8(0, 0, At, B0); BAR8;
;     LDB8(B1, 0, 1); BAR8; WAIT_L8(0); MMA8(0, 1, At, B1); BAR8;
	s_waitcnt lgkmcnt(0)
	s_waitcnt lgkmcnt(0)
	v_mfma_f32_16x16x32_bf16 v[64:67], v[190:193], v[174:177], v[64:67]
	v_mfma_f32_16x16x32_bf16 v[60:63], v[190:193], v[182:185], v[60:63]
	v_mfma_f32_16x16x32_bf16 v[56:59], v[198:201], v[174:177], v[56:59]
	v_mfma_f32_16x16x32_bf16 v[52:55], v[198:201], v[182:185], v[52:55]
	v_mfma_f32_16x16x32_bf16 v[48:51], v[206:209], v[174:177], v[48:51]
	v_mfma_f32_16x16x32_bf16 v[44:47], v[206:209], v[182:185], v[44:47]
	v_mfma_f32_16x16x32_bf16 v[40:43], v[214:217], v[174:177], v[40:43]
	v_mfma_f32_16x16x32_bf16 v[36:39], v[214:217], v[182:185], v[36:39]
	v_mfma_f32_16x16x32_bf16 v[64:67], v[194:197], v[178:181], v[64:67]
	v_mfma_f32_16x16x32_bf16 v[60:63], v[194:197], v[186:189], v[60:63]
	v_mfma_f32_16x16x32_bf16 v[56:59], v[202:205], v[178:181], v[56:59]
	v_mfma_f32_16x16x32_bf16 v[52:55], v[202:205], v[186:189], v[52:55]
	v_mfma_f32_16x16x32_bf16 v[48:51], v[210:213], v[178:181], v[48:51]
	v_mfma_f32_16x16x32_bf16 v[44:47], v[210:213], v[186:189], v[44:47]
	v_mfma_f32_16x16x32_bf16 v[40:43], v[218:221], v[178:181], v[40:43]
	v_mfma_f32_16x16x32_bf16 v[36:39], v[218:221], v[186:189], v[36:39]
	s_barrier
	v_readfirstlane_b32 s31, v169
	v_lshl_add_u64 v[174:175], v[228:229], 0, s[50:51]
	s_mov_b32 m0, s31
	v_readfirstlane_b32 s31, v170
	global_load_lds_dwordx4 v[174:175], off
	v_lshl_add_u64 v[174:175], v[236:237], 0, s[50:51]
	s_mov_b32 m0, s31
	s_nop 0
	global_load_lds_dwordx4 v[174:175], off
	s_waitcnt vmcnt(6)
	s_barrier
	v_mfma_f32_16x16x32_bf16 v[32:35], v[190:193], v[230:233], v[32:35]
	v_mfma_f32_16x16x32_bf16 v[28:31], v[190:193], v[242:245], v[28:31]
	v_mfma_f32_16x16x32_bf16 v[24:27], v[198:201], v[230:233], v[24:27]
	v_mfma_f32_16x16x32_bf16 v[20:23], v[198:201], v[242:245], v[20:23]
	v_mfma_f32_16x16x32_bf16 v[16:19], v[206:209], v[230:233], v[16:19]
	v_mfma_f32_16x16x32_bf16 v[12:15], v[206:209], v[242:245], v[12:15]
	v_mfma_f32_16x16x32_bf16 v[8:11], v[214:217], v[230:233], v[8:11]
	v_mfma_f32_16x16x32_bf16 v[4:7], v[214:217], v[242:245], v[4:7]
	v_mfma_f32_16x16x32_bf16 v[32:35], v[194:197], v[238:241], v[32:35]
	v_mfma_f32_16x16x32_bf16 v[28:31], v[194:197], v[246:249], v[28:31]
	v_mfma_f32_16x16x32_bf16 v[24:27], v[202:205], v[238:241], v[24:27]
	v_mfma_f32_16x16x32_bf16 v[20:23], v[202:205], v[246:249], v[20:23]
	v_mfma_f32_16x16x32_bf16 v[16:19], v[210:213], v[238:241], v[16:19]
	v_mfma_f32_16x16x32_bf16 v[12:15], v[210:213], v[246:249], v[12:15]
	v_mfma_f32_16x16x32_bf16 v[8:11], v[218:221], v[238:241], v[8:11]
	v_mfma_f32_16x16x32_bf16 v[4:7], v[218:221], v[246:249], v[4:7]
	s_add_i32 s29, s29, 2
	s_add_u32 s12, s12, 0x100
	s_addc_u32 s13, s13, 0
	s_cmp_lt_u32 s29, 12
	s_barrier
	s_cbranch_scc1 .LBB0_908
	s_add_u32 s2, s2, s27
	s_addc_u32 s3, s3, 0
	s_add_u32 s2, s2, 0x6000780
	s_addc_u32 s3, s3, 0
	v_lshl_add_u64 v[136:137], v[136:137], 1, s[2:3]
	v_readfirstlane_b32 s12, v172
	v_lshl_add_u64 v[0:1], v[0:1], 1, v[136:137]
	s_mov_b32 m0, s12
	ds_read_b128 v[138:141], v171
	ds_read_b128 v[142:145], v171 offset:1024
	ds_read_b128 v[162:165], v171 offset:2048
	ds_read_b128 v[168:171], v171 offset:3072
	ds_read_b128 v[174:177], v156
	ds_read_b128 v[178:181], v156 offset:1024
	ds_read_b128 v[182:185], v155
	ds_read_b128 v[186:189], v155 offset:1024
	ds_read_b128 v[190:193], v154
	ds_read_b128 v[194:197], v154 offset:1024
	ds_read_b128 v[198:201], v153
	ds_read_b128 v[202:205], v153 offset:1024
	global_load_lds_dwordx4 v[0:1], off
	v_lshl_add_u64 v[0:1], v[134:135], 1, s[2:3]
	v_readfirstlane_b32 s2, v173
	v_lshl_add_u64 v[0:1], v[132:133], 1, v[0:1]
	s_mov_b32 m0, s2
	s_nop 0
	global_load_lds_dwordx4 v[0:1], off
	s_barrier
	s_waitcnt lgkmcnt(0)
	s_waitcnt lgkmcnt(0)
	v_mfma_f32_16x16x32_bf16 v[128:131], v[174:177], v[138:141], v[128:131]
	v_mfma_f32_16x16x32_bf16 v[124:127], v[174:177], v[162:165], v[124:127]
	v_mfma_f32_16x16x32_bf16 v[120:123], v[182:185], v[138:141], v[120:123]
	v_mfma_f32_16x16x32_bf16 v[112:115], v[190:193], v[138:141], v[112:115]
	v_mfma_f32_16x16x32_bf16 v[128:131], v[178:181], v[142:145], v[128:131]
	v_mfma_f32_16x16x32_bf16 v[124:127], v[178:181], v[168:171], v[124:127]
	v_mfma_f32_16x16x32_bf16 v[120:123], v[186:189], v[142:145], v[120:123]
	v_mfma_f32_16x16x32_bf16 v[116:119], v[182:185], v[162:165], v[116:119]
	v_mfma_f32_16x16x32_bf16 v[112:115], v[194:197], v[142:145], v[112:115]
	v_mfma_f32_16x16x32_bf16 v[108:111], v[190:193], v[162:165], v[108:111]
	v_mfma_f32_16x16x32_bf16 v[104:107], v[198:201], v[138:141], v[104:107]
	v_mfma_f32_16x16x32_bf16 v[100:103], v[198:201], v[162:165], v[100:103]
	v_mfma_f32_16x16x32_bf16 v[132:135], v[186:189], v[168:171], v[116:119]
	v_mfma_f32_16x16x32_bf16 v[206:209], v[194:197], v[168:171], v[108:111]
	v_mfma_f32_16x16x32_bf16 v[210:213], v[202:205], v[142:145], v[104:107]
	v_mfma_f32_16x16x32_bf16 v[214:217], v[202:205], v[168:171], v[100:103]
	s_barrier
	s_nop 1
	ds_read_b128 v[100:103], v167
	ds_read_b128 v[104:107], v167 offset:1024
	ds_read_b128 v[108:111], v167 offset:2048
	ds_read_b128 v[116:119], v167 offset:3072
	s_barrier
	s_waitcnt lgkmcnt(0)
	s_waitcnt lgkmcnt(0)
	v_mfma_f32_16x16x32_bf16 v[80:83], v[190:193], v[100:103], v[80:83]
	v_mfma_f32_16x16x32_bf16 v[76:79], v[190:193], v[108:111], v[76:79]
	v_mfma_f32_16x16x32_bf16 v[72:75], v[198:201], v[100:103], v[72:75]
	v_mfma_f32_16x16x32_bf16 v[68:71], v[198:201], v[108:111], v[68:71]
	v_mfma_f32_16x16x32_bf16 v[96:99], v[174:177], v[100:103], v[96:99]
	v_mfma_f32_16x16x32_bf16 v[92:95], v[174:177], v[108:111], v[92:95]
	v_mfma_f32_16x16x32_bf16 v[88:91], v[182:185], v[100:103], v[88:91]
	v_mfma_f32_16x16x32_bf16 v[84:87], v[182:185], v[108:111], v[84:87]
	v_mfma_f32_16x16x32_bf16 v[80:83], v[194:197], v[104:107], v[80:83]
	v_mfma_f32_16x16x32_bf16 v[76:79], v[194:197], v[116:119], v[76:79]
	v_mfma_f32_16x16x32_bf16 v[72:75], v[202:205], v[104:107], v[72:75]
	v_mfma_f32_16x16x32_bf16 v[68:71], v[202:205], v[116:119], v[68:71]
	v_mfma_f32_16x16x32_bf16 v[218:221], v[178:181], v[104:107], v[96:99]
	v_mfma_f32_16x16x32_bf16 v[172:175], v[178:181], v[116:119], v[92:95]
	v_mfma_f32_16x16x32_bf16 v[176:179], v[186:189], v[104:107], v[88:91]
	v_mfma_f32_16x16x32_bf16 v[180:183], v[186:189], v[116:119], v[84:87]
	s_barrier
; #define LDA8(dst, b, h) _Pragma("unroll") for (int m = 0; m < 4; ++m) _Pragma("unroll") for (int k = 0; k < 2; ++k) \
;     dst[m][k] = *(const bf16x8*)((const char*)SA8(b, h) + lds_byte8(wr * 64 + m * 16 + fr, k * 32 + fq * 8))
; #define LDB8(dst, b, h) _Pragma("unroll") for (int n = 0; n < 2; ++n) _Pragma("unroll") for (int k = 0; k < 2; ++k) \
;     dst[n][k] = *(const bf16x8*)((const char*)SB8(b, h) + lds_byte8(wc * 32 + n * 16 + fr, k * 32 + fq * 8))
; #define WAIT_V8(n) asm volatile("s_waitcnt vmcnt(" #n ")" ::: "memory")
; #define WAIT_L8(n) asm volatile("s_waitcnt lgkmcnt(" #n ")" ::: "memory")
; #define BAR8 __builtin_amdgcn_s_barrier()
;     ...
;     LDA8(At, 0, 1); WAIT_V8(4); BAR8; WAIT_L8(0); MMA8(1, 0, At, B0); MMA8(1, 1, At, B1); BAR8; }
;   { LDB8(B0, 1, 0); LDA8(At, 1, 0); WAIT_V8(2); BAR8; WAIT_L8(0); MMA8(0, 0, At, B0); BAR8;
	s_nop 0
	ds_read_b128 v[84:87], v156 offset:16384
	ds_read_b128 v[88:91], v156 offset:17408
	ds_read_b128 v[92:95], v155 offset:16384
	ds_read_b128 v[96:99], v155 offset:17408
	ds_read_b128 v[184:187], v154 offset:16384
	ds_read_b128 v[188:191], v154 offset:17408
	ds_read_b128 v[192:195], v153 offset:16384
	ds_read_b128 v[196:199], v153 offset:17408
	s_waitcnt vmcnt(4)
	s_barrier
	s_waitcnt lgkmcnt(0)
	s_waitcnt lgkmcnt(0)
	v_mfma_f32_16x16x32_bf16 v[64:67], v[84:87], v[138:141], v[64:67]
	v_mfma_f32_16x16x32_bf16 v[60:63], v[84:87], v[162:165], v[60:63]
	v_mfma_f32_16x16x32_bf16 v[56:59], v[92:95], v[138:141], v[56:59]
	v_mfma_f32_16x16x32_bf16 v[52:55], v[92:95], v[162:165], v[52:55]
	v_mfma_f32_16x16x32_bf16 v[48:51], v[184:187], v[138:141], v[48:51]
	v_mfma_f32_16x16x32_bf16 v[44:47], v[184:187], v[162:165], v[44:47]
	v_mfma_f32_16x16x32_bf16 v[40:43], v[192:195], v[138:141], v[40:43]
	v_mfma_f32_16x16x32_bf16 v[36:39], v[192:195], v[162:165], v[36:39]
	v_mfma_f32_16x16x32_bf16 v[64:67], v[88:91], v[142:145], v[64:67]
	v_mfma_f32_16x16x32_bf16 v[60:63], v[88:91], v[168:171], v[60:63]
	v_mfma_f32_16x16x32_bf16 v[56:59], v[96:99], v[142:145], v[56:59]
	v_mfma_f32_16x16x32_bf16 v[52:55], v[96:99], v[168:171], v[52:55]
	v_mfma_f32_16x16x32_bf16 v[48:51], v[188:191], v[142:145], v[48:51]
	v_mfma_f32_16x16x32_bf16 v[44:47], v[188:191], v[168:171], v[44:47]
	v_mfma_f32_16x16x32_bf16 v[40:43], v[196:199], v[142:145], v[40:43]
	v_mfma_f32_16x16x32_bf16 v[36:39], v[196:199], v[168:171], v[36:39]
	v_mfma_f32_16x16x32_bf16 v[32:35], v[84:87], v[100:103], v[32:35]
	v_mfma_f32_16x16x32_bf16 v[28:31], v[84:87], v[108:111], v[28:31]
	v_mfma_f32_16x16x32_bf16 v[24:27], v[92:95], v[100:103], v[24:27]
	v_mfma_f32_16x16x32_bf16 v[20:23], v[92:95], v[108:111], v[20:23]
	v_mfma_f32_16x16x32_bf16 v[16:19], v[184:187], v[100:103], v[16:19]
	v_mfma_f32_16x16x32_bf16 v[12:15], v[184:187], v[108:111], v[12:15]
	v_mfma_f32_16x16x32_bf16 v[8:11], v[192:195], v[100:103], v[8:11]
	v_mfma_f32_16x16x32_bf16 v[4:7], v[192:195], v[108:111], v[4:7]
	v_mfma_f32_16x16x32_bf16 v[136:139], v[88:91], v[104:107], v[32:35]
	v_mfma_f32_16x16x32_bf16 v[140:143], v[88:91], v[116:119], v[28:31]
	v_mfma_f32_16x16x32_bf16 v[162:165], v[96:99], v[104:107], v[24:27]
	v_mfma_f32_16x16x32_bf16 v[166:169], v[96:99], v[116:119], v[20:23]
	v_mfma_f32_16x16x32_bf16 v[200:203], v[188:191], v[104:107], v[16:19]
	v_mfma_f32_16x16x32_bf16 v[184:187], v[188:191], v[116:119], v[12:15]
	v_mfma_f32_16x16x32_bf16 v[188:191], v[196:199], v[104:107], v[8:11]
	v_mfma_f32_16x16x32_bf16 v[192:195], v[196:199], v[116:119], v[4:7]
	s_barrier
	ds_read_b128 v[196:199], v160
	ds_read_b128 v[230:233], v160 offset:1024
	ds_read_b128 v[238:241], v160 offset:2048
	ds_read_b128 v[242:245], v160 offset:3072
	ds_read_b128 v[8:11], v156 offset:32768
	ds_read_b128 v[12:15], v156 offset:33792
	ds_read_b128 v[16:19], v155 offset:32768
	ds_read_b128 v[24:27], v155 offset:33792
	ds_read_b128 v[28:31], v154 offset:32768
	ds_read_b128 v[32:35], v154 offset:33792
	ds_read_b128 v[246:249], v153 offset:32768
	ds_read_b128 v[226:229], v153 offset:33792
	s_waitcnt vmcnt(2)
	s_barrier
	s_waitcnt lgkmcnt(0)
	s_waitcnt lgkmcnt(0)
	v_mfma_f32_16x16x32_bf16 v[4:7], v[8:11], v[196:199], v[128:131]
	v_mfma_f32_16x16x32_bf16 v[104:107], v[12:15], v[230:233], v[4:7]
	v_mfma_f32_16x16x32_bf16 v[4:7], v[8:11], v[238:241], v[124:127]
	v_mfma_f32_16x16x32_bf16 v[116:119], v[12:15], v[242:245], v[4:7]
	v_mfma_f32_16x16x32_bf16 v[4:7], v[16:19], v[196:199], v[120:123]
	v_mfma_f32_16x16x32_bf16 v[100:103], v[24:27], v[230:233], v[4:7]
	v_mfma_f32_16x16x32_bf16 v[4:7], v[16:19], v[238:241], v[132:135]
	v_mfma_f32_16x16x32_bf16 v[108:111], v[24:27], v[242:245], v[4:7]
	v_mfma_f32_16x16x32_bf16 v[4:7], v[28:31], v[196:199], v[112:115]
	v_mfma_f32_16x16x32_bf16 v[92:95], v[32:35], v[230:233], v[4:7]
	v_mfma_f32_16x16x32_bf16 v[4:7], v[28:31], v[238:241], v[206:209]
	v_mfma_f32_16x16x32_bf16 v[96:99], v[32:35], v[242:245], v[4:7]
	v_mfma_f32_16x16x32_bf16 v[4:7], v[246:249], v[196:199], v[210:213]
	v_mfma_f32_16x16x32_bf16 v[84:87], v[226:229], v[230:233], v[4:7]
	v_mfma_f32_16x16x32_bf16 v[4:7], v[246:249], v[238:241], v[214:217]
	v_mfma_f32_16x16x32_bf16 v[88:91], v[226:229], v[242:245], v[4:7]
	s_barrier
; DI int tid_opaque() { int t = threadIdx.x; asm volatile("" : "+v"(t)); return t; }
; #define LDA8(dst, b, h) _Pragma("unroll") for (int m = 0; m < 4; ++m) _Pragma("unroll") for (int k = 0; k < 2; ++k) \
;     dst[m][k] = *(const bf16x8*)((const char*)SA8(b, h) + lds_byte8(wr * 64 + m * 16 + fr, k * 32 + fq * 8))
; #define LDB8(dst, b, h) _Pragma("unroll") for (int n = 0; n < 2; ++n) _Pragma("unroll") for (int k = 0; k < 2; ++k) \
;     dst[n][k] = *(const bf16x8*)((const char*)SB8(b, h) + lds_byte8(wc * 32 + n * 16 + fr, k * 32 + fq * 8))
; #define WAIT_V8(n) asm volatile("s_waitcnt vmcnt(" #n ")" ::: "memory")
; #define WAIT_L8(n) asm volatile("s_waitcnt lgkmcnt(" #n ")" ::: "memory")
; #define BAR8 __builtin_amdgcn_s_barrier()
;     ...
;     LDB8(B1, 1, 1); WAIT_V8(0); BAR8; WAIT_L8(0); MMA8(0, 1, At, B1); BAR8;
;     LDA8(At, 1, 1); BAR8; WAIT_L8(0); MMA8(1, 0, At, B0); MMA8(1, 1, At, B1); BAR8; }
;   if (wr == 0) BAR8;
;   __syncthreads();
;   if (EPI == EPI_GU && nm0 >= 0) {
;     const int t = tid_opaque();
;     STAGE8(SB8(0, 0), Bt, K, nn0, 0); STAGE8(SA8(0, 0), A, lda, nm0, 0);
;     STAGE8(SB8(0, 1), Bt, K, nn0 + 128, 0); STAGE8(SA8(0, 1), A, lda, nm0 + 128, 0);
;   }
;     ...
;   if (t < 256) {
	ds_read_b128 v[132:135], v158
	ds_read_b128 v[204:207], v158 offset:1024
	ds_read_b128 v[208:211], v158 offset:2048
	ds_read_b128 v[158:161], v158 offset:3072
	s_waitcnt vmcnt(0)
	s_barrier
	s_waitcnt lgkmcnt(0)
	s_waitcnt lgkmcnt(0)
	v_mfma_f32_16x16x32_bf16 v[4:7], v[8:11], v[132:135], v[218:221]
	v_mfma_f32_16x16x32_bf16 v[8:11], v[8:11], v[208:211], v[172:175]
	v_mfma_f32_16x16x32_bf16 v[4:7], v[12:15], v[204:207], v[4:7]
	v_mfma_f32_16x16x32_bf16 v[20:23], v[12:15], v[158:161], v[8:11]
	v_mfma_f32_16x16x32_bf16 v[8:11], v[16:19], v[132:135], v[176:179]
	v_mfma_f32_16x16x32_bf16 v[12:15], v[16:19], v[208:211], v[180:183]
	v_mfma_f32_16x16x32_bf16 v[8:11], v[24:27], v[204:207], v[8:11]
	v_mfma_f32_16x16x32_bf16 v[24:27], v[24:27], v[158:161], v[12:15]
	v_mfma_f32_16x16x32_bf16 v[12:15], v[28:31], v[132:135], v[80:83]
	v_mfma_f32_16x16x32_bf16 v[16:19], v[28:31], v[208:211], v[76:79]
	v_mfma_f32_16x16x32_bf16 v[12:15], v[32:35], v[204:207], v[12:15]
	v_mfma_f32_16x16x32_bf16 v[28:31], v[32:35], v[158:161], v[16:19]
	v_mfma_f32_16x16x32_bf16 v[16:19], v[246:249], v[132:135], v[72:75]
	v_mfma_f32_16x16x32_bf16 v[32:35], v[246:249], v[208:211], v[68:71]
	v_mfma_f32_16x16x32_bf16 v[16:19], v[226:229], v[204:207], v[16:19]
	v_mfma_f32_16x16x32_bf16 v[32:35], v[226:229], v[158:161], v[32:35]
	s_barrier
	ds_read_b128 v[170:173], v156 offset:49152
	ds_read_b128 v[174:177], v156 offset:50176
	ds_read_b128 v[178:181], v155 offset:49152
	ds_read_b128 v[212:215], v155 offset:50176
	ds_read_b128 v[216:219], v154 offset:49152
	ds_read_b128 v[154:157], v154 offset:50176
	ds_read_b128 v[220:223], v153 offset:49152
	ds_read_b128 v[150:153], v153 offset:50176
	s_barrier
	s_waitcnt lgkmcnt(0)
	s_waitcnt lgkmcnt(0)
	v_mfma_f32_16x16x32_bf16 v[64:67], v[170:173], v[196:199], v[64:67]
	v_mfma_f32_16x16x32_bf16 v[60:63], v[170:173], v[238:241], v[60:63]
	v_mfma_f32_16x16x32_bf16 v[56:59], v[178:181], v[196:199], v[56:59]
	v_mfma_f32_16x16x32_bf16 v[52:55], v[178:181], v[238:241], v[52:55]
	v_mfma_f32_16x16x32_bf16 v[48:51], v[216:219], v[196:199], v[48:51]
	v_mfma_f32_16x16x32_bf16 v[44:47], v[216:219], v[238:241], v[44:47]
	v_mfma_f32_16x16x32_bf16 v[40:43], v[220:223], v[196:199], v[40:43]
	v_mfma_f32_16x16x32_bf16 v[36:39], v[220:223], v[238:241], v[36:39]
	v_mfma_f32_16x16x32_bf16 v[128:131], v[174:177], v[230:233], v[64:67]
	v_mfma_f32_16x16x32_bf16 v[124:127], v[174:177], v[242:245], v[60:63]
	v_mfma_f32_16x16x32_bf16 v[120:123], v[212:215], v[230:233], v[56:59]
	v_mfma_f32_16x16x32_bf16 v[112:115], v[212:215], v[242:245], v[52:55]
	v_mfma_f32_16x16x32_bf16 v[80:83], v[154:157], v[230:233], v[48:51]
	v_mfma_f32_16x16x32_bf16 v[76:79], v[154:157], v[242:245], v[44:47]
	v_mfma_f32_16x16x32_bf16 v[72:75], v[150:153], v[230:233], v[40:43]
	v_mfma_f32_16x16x32_bf16 v[68:71], v[150:153], v[242:245], v[36:39]
	v_mfma_f32_16x16x32_bf16 v[40:43], v[170:173], v[208:211], v[140:143]
	v_mfma_f32_16x16x32_bf16 v[44:47], v[178:181], v[208:211], v[166:169]
	v_mfma_f32_16x16x32_bf16 v[48:51], v[216:219], v[208:211], v[184:187]
	v_mfma_f32_16x16x32_bf16 v[36:39], v[170:173], v[132:135], v[136:139]
	v_mfma_f32_16x16x32_bf16 v[52:55], v[174:177], v[158:161], v[40:43]
	v_mfma_f32_16x16x32_bf16 v[40:43], v[178:181], v[132:135], v[162:165]
	v_mfma_f32_16x16x32_bf16 v[56:59], v[212:215], v[158:161], v[44:47]
	v_mfma_f32_16x16x32_bf16 v[44:47], v[216:219], v[132:135], v[200:203]
	v_mfma_f32_16x16x32_bf16 v[60:63], v[154:157], v[158:161], v[48:51]
	v_mfma_f32_16x16x32_bf16 v[48:51], v[220:223], v[132:135], v[188:191]
	v_mfma_f32_16x16x32_bf16 v[64:67], v[220:223], v[208:211], v[192:195]
	v_mfma_f32_16x16x32_bf16 v[36:39], v[174:177], v[204:207], v[36:39]
	v_mfma_f32_16x16x32_bf16 v[40:43], v[212:215], v[204:207], v[40:43]
	v_mfma_f32_16x16x32_bf16 v[44:47], v[154:157], v[204:207], v[44:47]
	v_mfma_f32_16x16x32_bf16 v[48:51], v[150:153], v[204:207], v[48:51]
	v_mfma_f32_16x16x32_bf16 v[64:67], v[150:153], v[158:161], v[64:67]
	s_movk_i32 s2, 0x100
	v_cmp_gt_u32_e32 vcc, s2, v3
	s_barrier
	s_and_saveexec_b64 s[2:3], vcc
	s_cbranch_execz .LBB0_911
	s_barrier

; #define LDA8(dst, b, h) _Pragma("unroll") for (int m = 0; m < 4; ++m) _Pragma("unroll") for (int k = 0; k < 2; ++k) \
;     dst[m][k] = *(const bf16x8*)((const char*)SA8(b, h) + lds_byte8(wr * 64 + m * 16 + fr, k * 32 + fq * 8))
; #define LDB8(dst, b, h) _Pragma("unroll") for (int n = 0; n < 2; ++n) _Pragma("unroll") for (int k = 0; k < 2; ++k) \
;     dst[n][k] = *(const bf16x8*)((const char*)SB8(b, h) + lds_byte8(wc * 32 + n * 16 + fr, k * 32 + fq * 8))
; #define WAIT_L8(n) asm volatile("s_waitcnt lgkmcnt(" #n ")" ::: "memory")
; #define BAR8 __builtin_amdgcn_s_barrier()
; #define SCHED8 __builtin_amdgcn_sched_barrier(0)
;     ...
;   for (int tt = 0; tt < nt - 2; tt += 2) {
;     LDB8(B0, 0, 0); SCHED8; LDA8(At, 0, 0); STAGE8(SA8(1, 1), A, lda, brow + 128, tt + 1);
;     WAIT_L8(8); BAR8; WAIT_L8(0); MMA8(0, 0, At, B0); BAR8; SCHED8;
;     LDB8(B1, 0, 1); STAGE8(SB8(0, 0), Bt, K, bcol, tt + 2);
;     BAR8; WAIT_L8(0); MMA8(0, 1, At, B1); BAR8;
;     LDA8(At, 0, 1); STAGE8(SA8(0, 0), A, lda, brow, tt + 2);
;     BAR8; WAIT_L8(0); MMA8(1, 0, At, B0); BAR8; SCHED8;
.LBB0_1005:
	ds_read_b128 v[174:177], v171
	ds_read_b128 v[178:181], v171 offset:1024
	ds_read_b128 v[182:185], v171 offset:2048
	ds_read_b128 v[186:189], v171 offset:3072
	v_add_u32_e32 v172, 0xc000, v150
	v_lshl_add_u64 v[222:223], v[140:141], 0, s[12:13]
	v_readfirstlane_b32 s14, v172
	v_add_u32_e32 v173, 0xe000, v150
	v_lshl_add_u64 v[226:227], v[222:223], 0, s[20:21]
	s_mov_b32 m0, s14
	v_lshl_add_u64 v[236:237], v[138:139], 0, s[12:13]
	v_readfirstlane_b32 s14, v173
	ds_read_b128 v[190:193], v156
	ds_read_b128 v[194:197], v156 offset:1024
	ds_read_b128 v[198:201], v155
	ds_read_b128 v[202:205], v155 offset:1024
	ds_read_b128 v[206:209], v154
	ds_read_b128 v[210:213], v154 offset:1024
	ds_read_b128 v[214:217], v153
	ds_read_b128 v[218:221], v153 offset:1024
	global_load_lds_dwordx4 v[226:227], off
	v_lshl_add_u64 v[226:227], v[236:237], 0, s[20:21]
	s_mov_b32 m0, s14
	s_nop 0
	global_load_lds_dwordx4 v[226:227], off
	s_waitcnt lgkmcnt(8)
	s_barrier
	s_waitcnt lgkmcnt(0)
	s_waitcnt lgkmcnt(0)
	v_mfma_f32_16x16x32_bf16 v[128:131], v[190:193], v[174:177], v[128:131]
	v_mfma_f32_16x16x32_bf16 v[124:127], v[190:193], v[182:185], v[124:127]
	v_mfma_f32_16x16x32_bf16 v[120:123], v[198:201], v[174:177], v[120:123]
	v_mfma_f32_16x16x32_bf16 v[116:119], v[198:201], v[182:185], v[116:119]
	v_mfma_f32_16x16x32_bf16 v[112:115], v[206:209], v[174:177], v[112:115]
	v_mfma_f32_16x16x32_bf16 v[108:111], v[206:209], v[182:185], v[108:111]
	v_mfma_f32_16x16x32_bf16 v[104:107], v[214:217], v[174:177], v[104:107]
	v_mfma_f32_16x16x32_bf16 v[100:103], v[214:217], v[182:185], v[100:103]
	v_mfma_f32_16x16x32_bf16 v[128:131], v[194:197], v[178:181], v[128:131]
	v_mfma_f32_16x16x32_bf16 v[124:127], v[194:197], v[186:189], v[124:127]
	v_mfma_f32_16x16x32_bf16 v[120:123], v[202:205], v[178:181], v[120:123]
	v_mfma_f32_16x16x32_bf16 v[116:119], v[202:205], v[186:189], v[116:119]
	v_mfma_f32_16x16x32_bf16 v[112:115], v[210:213], v[178:181], v[112:115]
	v_mfma_f32_16x16x32_bf16 v[108:111], v[210:213], v[186:189], v[108:111]
	v_mfma_f32_16x16x32_bf16 v[104:107], v[218:221], v[178:181], v[104:107]
	v_mfma_f32_16x16x32_bf16 v[100:103], v[218:221], v[186:189], v[100:103]
	s_barrier
	v_lshl_add_u64 v[246:247], v[142:143], 0, s[12:13]
	v_readfirstlane_b32 s14, v151
	v_lshl_add_u64 v[248:249], v[246:247], 0, s[40:41]
	s_mov_b32 m0, s14
	ds_read_b128 v[226:229], v168
	ds_read_b128 v[230:233], v168 offset:1024
	ds_read_b128 v[238:241], v168 offset:2048
	ds_read_b128 v[242:245], v168 offset:3072
	global_load_lds_dwordx4 v[248:249], off
	v_lshl_add_u64 v[248:249], v[144:145], 0, s[12:13]
	v_readfirstlane_b32 s14, v157
	v_lshl_add_u64 v[250:251], v[248:249], 0, s[40:41]
	s_mov_b32 m0, s14
	s_nop 0
	global_load_lds_dwordx4 v[250:251], off
	s_barrier
	s_waitcnt lgkmcnt(0)
	s_waitcnt lgkmcnt(0)
	v_mfma_f32_16x16x32_bf16 v[96:99], v[190:193], v[226:229], v[96:99]
	v_mfma_f32_16x16x32_bf16 v[92:95], v[190:193], v[238:241], v[92:95]
	v_mfma_f32_16x16x32_bf16 v[88:91], v[198:201], v[226:229], v[88:91]
	v_mfma_f32_16x16x32_bf16 v[84:87], v[198:201], v[238:241], v[84:87]
	v_mfma_f32_16x16x32_bf16 v[80:83], v[206:209], v[226:229], v[80:83]
	v_mfma_f32_16x16x32_bf16 v[76:79], v[206:209], v[238:241], v[76:79]
	v_mfma_f32_16x16x32_bf16 v[72:75], v[214:217], v[226:229], v[72:75]
	v_mfma_f32_16x16x32_bf16 v[68:71], v[214:217], v[238:241], v[68:71]
	v_mfma_f32_16x16x32_bf16 v[96:99], v[194:197], v[230:233], v[96:99]
	v_mfma_f32_16x16x32_bf16 v[92:95], v[194:197], v[242:245], v[92:95]
	v_mfma_f32_16x16x32_bf16 v[88:91], v[202:205], v[230:233], v[88:91]
	v_mfma_f32_16x16x32_bf16 v[84:87], v[202:205], v[242:245], v[84:87]
	v_mfma_f32_16x16x32_bf16 v[80:83], v[210:213], v[230:233], v[80:83]
	v_mfma_f32_16x16x32_bf16 v[76:79], v[210:213], v[242:245], v[76:79]
	v_mfma_f32_16x16x32_bf16 v[72:75], v[218:221], v[230:233], v[72:75]
	v_mfma_f32_16x16x32_bf16 v[68:71], v[218:221], v[242:245], v[68:71]
	v_readfirstlane_b32 s14, v150
	v_lshl_add_u64 v[250:251], v[222:223], 0, s[42:43]
	s_mov_b32 m0, s14
	v_readfirstlane_b32 s14, v152
	s_barrier
	ds_read_b128 v[190:193], v156 offset:16384
	ds_read_b128 v[194:197], v156 offset:17408
	ds_read_b128 v[198:201], v155 offset:16384
	ds_read_b128 v[202:205], v155 offset:17408
	ds_read_b128 v[206:209], v154 offset:16384
	ds_read_b128 v[210:213], v154 offset:17408
	ds_read_b128 v[214:217], v153 offset:16384
	ds_read_b128 v[218:221], v153 offset:17408
	global_load_lds_dwordx4 v[250:251], off
	v_lshl_add_u64 v[250:251], v[236:237], 0, s[42:43]
	s_mov_b32 m0, s14
	s_nop 0
	global_load_lds_dwordx4 v[250:251], off
	s_barrier
	s_waitcnt lgkmcnt(0)
	s_waitcnt lgkmcnt(0)
	v_mfma_f32_16x16x32_bf16 v[64:67], v[190:193], v[174:177], v[64:67]
	v_mfma_f32_16x16x32_bf16 v[60:63], v[190:193], v[182:185], v[60:63]
	v_mfma_f32_16x16x32_bf16 v[56:59], v[198:201], v[174:177], v[56:59]
	v_mfma_f32_16x16x32_bf16 v[52:55], v[198:201], v[182:185], v[52:55]
	v_mfma_f32_16x16x32_bf16 v[48:51], v[206:209], v[174:177], v[48:51]
	v_mfma_f32_16x16x32_bf16 v[44:47], v[206:209], v[182:185], v[44:47]
	v_mfma_f32_16x16x32_bf16 v[40:43], v[214:217], v[174:177], v[40:43]
	v_mfma_f32_16x16x32_bf16 v[36:39], v[214:217], v[182:185], v[36:39]
	v_mfma_f32_16x16x32_bf16 v[64:67], v[194:197], v[178:181], v[64:67]
	v_mfma_f32_16x16x32_bf16 v[60:63], v[194:197], v[186:189], v[60:63]
	v_mfma_f32_16x16x32_bf16 v[56:59], v[202:205], v[178:181], v[56:59]
	v_mfma_f32_16x16x32_bf16 v[52:55], v[202:205], v[186:189], v[52:55]
	v_mfma_f32_16x16x32_bf16 v[48:51], v[210:213], v[178:181], v[48:51]
	v_mfma_f32_16x16x32_bf16 v[44:47], v[210:213], v[186:189], v[44:47]
	v_mfma_f32_16x16x32_bf16 v[40:43], v[218:221], v[178:181], v[40:43]
	v_mfma_f32_16x16x32_bf16 v[36:39], v[218:221], v[186:189], v[36:39]
	s_barrier
; #define LDA8(dst, b, h) _Pragma("unroll") for (int m = 0; m < 4; ++m) _Pragma("unroll") for (int k = 0; k < 2; ++k) \
;     dst[m][k] = *(const bf16x8*)((const char*)SA8(b, h) + lds_byte8(wr * 64 + m * 16 + fr, k * 32 + fq * 8))
; #define LDB8(dst, b, h) _Pragma("unroll") for (int n = 0; n < 2; ++n) _Pragma("unroll") for (int k = 0; k < 2; ++k) \
;     dst[n][k] = *(const bf16x8*)((const char*)SB8(b, h) + lds_byte8(wc * 32 + n * 16 + fr, k * 32 + fq * 8))
; #define WAIT_V8(n) asm volatile("s_waitcnt vmcnt(" #n ")" ::: "memory")
; #define WAIT_L8(n) asm volatile("s_waitcnt lgkmcnt(" #n ")" ::: "memory")
; #define BAR8 __builtin_amdgcn_s_barrier()
; #define SCHED8 __builtin_amdgcn_sched_barrier(0)
;     ...
;     STAGE8(SB8(0, 1), Bt, K, bcol + 128, tt + 2);
;     WAIT_V8(6); BAR8; MMA8(1, 1, At, B1); BAR8;
;     LDB8(B0, 1, 0); SCHED8; LDA8(At, 1, 0); STAGE8(SA8(0, 1), A, lda, brow + 128, tt + 2);
;     WAIT_L8(8); BAR8; WAIT_L8(0); MMA8(0, 0, At, B0); BAR8; SCHED8;
;     LDB8(B1, 1, 1); STAGE8(SB8(1, 0), Bt, K, bcol, tt + 3);
;     BAR8; WAIT_L8(0); MMA8(0, 1, At, B1); BAR8;
;     LDA8(At, 1, 1); STAGE8(SA8(1, 0), A, lda, brow, tt + 3);
	v_readfirstlane_b32 s14, v159
	v_lshl_add_u64 v[174:175], v[246:247], 0, s[44:45]
	s_mov_b32 m0, s14
	v_readfirstlane_b32 s14, v160
	global_load_lds_dwordx4 v[174:175], off
	v_lshl_add_u64 v[174:175], v[248:249], 0, s[44:45]
	s_mov_b32 m0, s14
	s_nop 0
	global_load_lds_dwordx4 v[174:175], off
	s_waitcnt vmcnt(6)
	s_barrier
	v_mfma_f32_16x16x32_bf16 v[32:35], v[190:193], v[226:229], v[32:35]
	v_mfma_f32_16x16x32_bf16 v[28:31], v[190:193], v[238:241], v[28:31]
	v_mfma_f32_16x16x32_bf16 v[24:27], v[198:201], v[226:229], v[24:27]
	v_mfma_f32_16x16x32_bf16 v[20:23], v[198:201], v[238:241], v[20:23]
	v_mfma_f32_16x16x32_bf16 v[16:19], v[206:209], v[226:229], v[16:19]
	v_mfma_f32_16x16x32_bf16 v[12:15], v[206:209], v[238:241], v[12:15]
	v_mfma_f32_16x16x32_bf16 v[8:11], v[214:217], v[226:229], v[8:11]
	v_mfma_f32_16x16x32_bf16 v[4:7], v[214:217], v[238:241], v[4:7]
	v_mfma_f32_16x16x32_bf16 v[32:35], v[194:197], v[230:233], v[32:35]
	v_mfma_f32_16x16x32_bf16 v[28:31], v[194:197], v[242:245], v[28:31]
	v_mfma_f32_16x16x32_bf16 v[24:27], v[202:205], v[230:233], v[24:27]
	v_mfma_f32_16x16x32_bf16 v[20:23], v[202:205], v[242:245], v[20:23]
	v_mfma_f32_16x16x32_bf16 v[16:19], v[210:213], v[230:233], v[16:19]
	v_mfma_f32_16x16x32_bf16 v[12:15], v[210:213], v[242:245], v[12:15]
	v_mfma_f32_16x16x32_bf16 v[8:11], v[218:221], v[230:233], v[8:11]
	v_mfma_f32_16x16x32_bf16 v[4:7], v[218:221], v[242:245], v[4:7]
	s_barrier
	ds_read_b128 v[174:177], v161
	ds_read_b128 v[178:181], v161 offset:1024
	ds_read_b128 v[182:185], v161 offset:2048
	ds_read_b128 v[186:189], v161 offset:3072
	v_readfirstlane_b32 s14, v162
	v_lshl_add_u64 v[226:227], v[222:223], 0, s[46:47]
	s_mov_b32 m0, s14
	v_readfirstlane_b32 s14, v163
	ds_read_b128 v[190:193], v156 offset:32768
	ds_read_b128 v[194:197], v156 offset:33792
	ds_read_b128 v[198:201], v155 offset:32768
	ds_read_b128 v[202:205], v155 offset:33792
	ds_read_b128 v[206:209], v154 offset:32768
	ds_read_b128 v[210:213], v154 offset:33792
	ds_read_b128 v[214:217], v153 offset:32768
	ds_read_b128 v[218:221], v153 offset:33792
	global_load_lds_dwordx4 v[226:227], off
	v_lshl_add_u64 v[226:227], v[236:237], 0, s[46:47]
	s_mov_b32 m0, s14
	s_nop 0
	global_load_lds_dwordx4 v[226:227], off
	s_waitcnt lgkmcnt(8)
	s_barrier
	s_waitcnt lgkmcnt(0)
	s_waitcnt lgkmcnt(0)
	v_mfma_f32_16x16x32_bf16 v[128:131], v[190:193], v[174:177], v[128:131]
	v_mfma_f32_16x16x32_bf16 v[124:127], v[190:193], v[182:185], v[124:127]
	v_mfma_f32_16x16x32_bf16 v[120:123], v[198:201], v[174:177], v[120:123]
	v_mfma_f32_16x16x32_bf16 v[116:119], v[198:201], v[182:185], v[116:119]
	v_mfma_f32_16x16x32_bf16 v[112:115], v[206:209], v[174:177], v[112:115]
	v_mfma_f32_16x16x32_bf16 v[108:111], v[206:209], v[182:185], v[108:111]
	v_mfma_f32_16x16x32_bf16 v[104:107], v[214:217], v[174:177], v[104:107]
	v_mfma_f32_16x16x32_bf16 v[100:103], v[214:217], v[182:185], v[100:103]
	v_mfma_f32_16x16x32_bf16 v[128:131], v[194:197], v[178:181], v[128:131]
	v_mfma_f32_16x16x32_bf16 v[124:127], v[194:197], v[186:189], v[124:127]
	v_mfma_f32_16x16x32_bf16 v[120:123], v[202:205], v[178:181], v[120:123]
	v_mfma_f32_16x16x32_bf16 v[116:119], v[202:205], v[186:189], v[116:119]
	v_mfma_f32_16x16x32_bf16 v[112:115], v[210:213], v[178:181], v[112:115]
	v_mfma_f32_16x16x32_bf16 v[108:111], v[210:213], v[186:189], v[108:111]
	v_mfma_f32_16x16x32_bf16 v[104:107], v[218:221], v[178:181], v[104:107]
	v_mfma_f32_16x16x32_bf16 v[100:103], v[218:221], v[186:189], v[100:103]
	s_barrier
	v_readfirstlane_b32 s14, v164
	v_lshl_add_u64 v[250:251], v[246:247], 0, s[48:49]
	s_mov_b32 m0, s14
	v_readfirstlane_b32 s14, v165
	ds_read_b128 v[226:229], v158
	ds_read_b128 v[230:233], v158 offset:1024
	ds_read_b128 v[238:241], v158 offset:2048
	ds_read_b128 v[242:245], v158 offset:3072
	global_load_lds_dwordx4 v[250:251], off
	v_lshl_add_u64 v[250:251], v[248:249], 0, s[48:49]
	s_mov_b32 m0, s14
	s_nop 0
	global_load_lds_dwordx4 v[250:251], off
	s_barrier
	s_waitcnt lgkmcnt(0)
	s_waitcnt lgkmcnt(0)
	v_mfma_f32_16x16x32_bf16 v[96:99], v[190:193], v[226:229], v[96:99]
	v_mfma_f32_16x16x32_bf16 v[92:95], v[190:193], v[238:241], v[92:95]
	v_mfma_f32_16x16x32_bf16 v[88:91], v[198:201], v[226:229], v[88:91]
	v_mfma_f32_16x16x32_bf16 v[84:87], v[198:201], v[238:241], v[84:87]
	v_mfma_f32_16x16x32_bf16 v[80:83], v[206:209], v[226:229], v[80:83]
	v_mfma_f32_16x16x32_bf16 v[76:79], v[206:209], v[238:241], v[76:79]
	v_mfma_f32_16x16x32_bf16 v[72:75], v[214:217], v[226:229], v[72:75]
	v_mfma_f32_16x16x32_bf16 v[68:71], v[214:217], v[238:241], v[68:71]
	v_mfma_f32_16x16x32_bf16 v[96:99], v[194:197], v[230:233], v[96:99]
	v_mfma_f32_16x16x32_bf16 v[92:95], v[194:197], v[242:245], v[92:95]
	v_mfma_f32_16x16x32_bf16 v[88:91], v[202:205], v[230:233], v[88:91]
	v_mfma_f32_16x16x32_bf16 v[84:87], v[202:205], v[242:245], v[84:87]
	v_mfma_f32_16x16x32_bf16 v[80:83], v[210:213], v[230:233], v[80:83]
	v_mfma_f32_16x16x32_bf16 v[76:79], v[210:213], v[242:245], v[76:79]
	v_mfma_f32_16x16x32_bf16 v[72:75], v[218:221], v[230:233], v[72:75]
	v_mfma_f32_16x16x32_bf16 v[68:71], v[218:221], v[242:245], v[68:71]
	v_readfirstlane_b32 s14, v166
	v_lshl_add_u64 v[222:223], v[222:223], 0, s[50:51]
	s_mov_b32 m0, s14
	v_readfirstlane_b32 s14, v167
	s_barrier
	ds_read_b128 v[190:193], v156 offset:49152
	ds_read_b128 v[194:197], v156 offset:50176
	ds_read_b128 v[198:201], v155 offset:49152
	ds_read_b128 v[202:205], v155 offset:50176
	ds_read_b128 v[206:209], v154 offset:49152
	ds_read_b128 v[210:213], v154 offset:50176
	ds_read_b128 v[214:217], v153 offset:49152
	ds_read_b128 v[218:221], v153 offset:50176
	global_load_lds_dwordx4 v[222:223], off
	v_lshl_add_u64 v[222:223], v[236:237], 0, s[50:51]
	s_mov_b32 m0, s14
	s_nop 0
	global_load_lds_dwordx4 v[222:223], off
	s_barrier
; #define LDA8(dst, b, h) _Pragma("unroll") for (int m = 0; m < 4; ++m) _Pragma("unroll") for (int k = 0; k < 2; ++k) \
;     dst[m][k] = *(const bf16x8*)((const char*)SA8(b, h) + lds_byte8(wr * 64 + m * 16 + fr, k * 32 + fq * 8))
; #define LDB8(dst, b, h) _Pragma("unroll") for (int n = 0; n < 2; ++n) _Pragma("unroll") for (int k = 0; k < 2; ++k) \
;     dst[n][k] = *(const bf16x8*)((const char*)SB8(b, h) + lds_byte8(wc * 32 + n * 16 + fr, k * 32 + fq * 8))
; #define WAIT_V8(n) asm volatile("s_waitcnt vmcnt(" #n ")" ::: "memory")
; #define WAIT_L8(n) asm volatile("s_waitcnt lgkmcnt(" #n ")" ::: "memory")
; #define BAR8 __builtin_amdgcn_s_barrier()
; #define SCHED8 __builtin_amdgcn_sched_barrier(0)
;     ...
;     BAR8; WAIT_L8(0); MMA8(1, 0, At, B0); BAR8; SCHED8;
;     STAGE8(SB8(1, 1), Bt, K, bcol + 128, tt + 3);
;     WAIT_V8(6); BAR8; MMA8(1, 1, At, B1); BAR8;
;   }
;   { LDB8(B0, 0, 0); LDA8(At, 0, 0); STAGE8(SA8(1, 1), A, lda, brow + 128, nt - 1);
;     BAR8; WAIT_L8(0); MMA8(0, 0, At, B0); BAR8;
;     LDB8(B1, 0, 1); BAR8; WAIT_L8(0); MMA8(0, 1, At, B1); BAR8;
	s_waitcnt lgkmcnt(0)
	s_waitcnt lgkmcnt(0)
	v_mfma_f32_16x16x32_bf16 v[64:67], v[190:193], v[174:177], v[64:67]
	v_mfma_f32_16x16x32_bf16 v[60:63], v[190:193], v[182:185], v[60:63]
	v_mfma_f32_16x16x32_bf16 v[56:59], v[198:201], v[174:177], v[56:59]
	v_mfma_f32_16x16x32_bf16 v[52:55], v[198:201], v[182:185], v[52:55]
	v_mfma_f32_16x16x32_bf16 v[48:51], v[206:209], v[174:177], v[48:51]
	v_mfma_f32_16x16x32_bf16 v[44:47], v[206:209], v[182:185], v[44:47]
	v_mfma_f32_16x16x32_bf16 v[40:43], v[214:217], v[174:177], v[40:43]
	v_mfma_f32_16x16x32_bf16 v[36:39], v[214:217], v[182:185], v[36:39]
	v_mfma_f32_16x16x32_bf16 v[64:67], v[194:197], v[178:181], v[64:67]
	v_mfma_f32_16x16x32_bf16 v[60:63], v[194:197], v[186:189], v[60:63]
	v_mfma_f32_16x16x32_bf16 v[56:59], v[202:205], v[178:181], v[56:59]
	v_mfma_f32_16x16x32_bf16 v[52:55], v[202:205], v[186:189], v[52:55]
	v_mfma_f32_16x16x32_bf16 v[48:51], v[210:213], v[178:181], v[48:51]
	v_mfma_f32_16x16x32_bf16 v[44:47], v[210:213], v[186:189], v[44:47]
	v_mfma_f32_16x16x32_bf16 v[40:43], v[218:221], v[178:181], v[40:43]
	v_mfma_f32_16x16x32_bf16 v[36:39], v[218:221], v[186:189], v[36:39]
	s_barrier
	v_readfirstlane_b32 s14, v169
	v_lshl_add_u64 v[174:175], v[246:247], 0, s[52:53]
	s_mov_b32 m0, s14
	v_readfirstlane_b32 s14, v170
	global_load_lds_dwordx4 v[174:175], off
	v_lshl_add_u64 v[174:175], v[248:249], 0, s[52:53]
	s_mov_b32 m0, s14
	s_nop 0
	global_load_lds_dwordx4 v[174:175], off
	s_waitcnt vmcnt(6)
	s_barrier
	v_mfma_f32_16x16x32_bf16 v[32:35], v[190:193], v[226:229], v[32:35]
	v_mfma_f32_16x16x32_bf16 v[28:31], v[190:193], v[238:241], v[28:31]
	v_mfma_f32_16x16x32_bf16 v[24:27], v[198:201], v[226:229], v[24:27]
	v_mfma_f32_16x16x32_bf16 v[20:23], v[198:201], v[238:241], v[20:23]
	v_mfma_f32_16x16x32_bf16 v[16:19], v[206:209], v[226:229], v[16:19]
	v_mfma_f32_16x16x32_bf16 v[12:15], v[206:209], v[238:241], v[12:15]
	v_mfma_f32_16x16x32_bf16 v[8:11], v[214:217], v[226:229], v[8:11]
	v_mfma_f32_16x16x32_bf16 v[4:7], v[214:217], v[238:241], v[4:7]
	v_mfma_f32_16x16x32_bf16 v[32:35], v[194:197], v[230:233], v[32:35]
	v_mfma_f32_16x16x32_bf16 v[28:31], v[194:197], v[242:245], v[28:31]
	v_mfma_f32_16x16x32_bf16 v[24:27], v[202:205], v[230:233], v[24:27]
	v_mfma_f32_16x16x32_bf16 v[20:23], v[202:205], v[242:245], v[20:23]
	v_mfma_f32_16x16x32_bf16 v[16:19], v[210:213], v[230:233], v[16:19]
	v_mfma_f32_16x16x32_bf16 v[12:15], v[210:213], v[242:245], v[12:15]
	v_mfma_f32_16x16x32_bf16 v[8:11], v[218:221], v[230:233], v[8:11]
	v_mfma_f32_16x16x32_bf16 v[4:7], v[218:221], v[242:245], v[4:7]
	s_add_i32 s1, s1, 2
	s_add_u32 s12, s12, 0x100
	s_addc_u32 s13, s13, 0
	s_cmp_lt_u32 s1, 12
	s_barrier
	s_cbranch_scc1 .LBB0_1005
	s_add_u32 s8, s8, 0x40780
	s_addc_u32 s9, s9, 0
	v_lshl_add_u64 v[132:133], s[8:9], 0, v[132:133]
	v_readfirstlane_b32 s1, v172
	v_lshl_add_u64 v[0:1], v[0:1], 1, v[132:133]
	s_mov_b32 m0, s1
	ds_read_b128 v[138:141], v171
	ds_read_b128 v[142:145], v171 offset:1024
	ds_read_b128 v[162:165], v171 offset:2048
	ds_read_b128 v[174:177], v171 offset:3072
	ds_read_b128 v[178:181], v156
	ds_read_b128 v[182:185], v156 offset:1024
	ds_read_b128 v[186:189], v155
	ds_read_b128 v[190:193], v155 offset:1024
	ds_read_b128 v[194:197], v154
	ds_read_b128 v[198:201], v154 offset:1024
	ds_read_b128 v[202:205], v153
	ds_read_b128 v[206:209], v153 offset:1024
	global_load_lds_dwordx4 v[0:1], off
	v_lshl_add_u64 v[0:1], s[8:9], 0, v[136:137]
	v_readfirstlane_b32 s1, v173
	v_lshl_add_u64 v[0:1], v[134:135], 1, v[0:1]
	s_mov_b32 m0, s1
	s_nop 0
	global_load_lds_dwordx4 v[0:1], off
	s_barrier
	s_waitcnt lgkmcnt(0)
	s_waitcnt lgkmcnt(0)
	v_mfma_f32_16x16x32_bf16 v[128:131], v[178:181], v[138:141], v[128:131]
	v_mfma_f32_16x16x32_bf16 v[124:127], v[178:181], v[162:165], v[124:127]
	v_mfma_f32_16x16x32_bf16 v[120:123], v[186:189], v[138:141], v[120:123]
	v_mfma_f32_16x16x32_bf16 v[112:115], v[194:197], v[138:141], v[112:115]
	v_mfma_f32_16x16x32_bf16 v[128:131], v[182:185], v[142:145], v[128:131]
	v_mfma_f32_16x16x32_bf16 v[124:127], v[182:185], v[174:177], v[124:127]
	v_mfma_f32_16x16x32_bf16 v[120:123], v[190:193], v[142:145], v[120:123]
	v_mfma_f32_16x16x32_bf16 v[116:119], v[186:189], v[162:165], v[116:119]
	v_mfma_f32_16x16x32_bf16 v[112:115], v[198:201], v[142:145], v[112:115]
	v_mfma_f32_16x16x32_bf16 v[108:111], v[194:197], v[162:165], v[108:111]
	v_mfma_f32_16x16x32_bf16 v[104:107], v[202:205], v[138:141], v[104:107]
	v_mfma_f32_16x16x32_bf16 v[100:103], v[202:205], v[162:165], v[100:103]
	v_mfma_f32_16x16x32_bf16 v[132:135], v[190:193], v[174:177], v[116:119]
	v_mfma_f32_16x16x32_bf16 v[170:173], v[198:201], v[174:177], v[108:111]
	v_mfma_f32_16x16x32_bf16 v[210:213], v[206:209], v[142:145], v[104:107]
	v_mfma_f32_16x16x32_bf16 v[214:217], v[206:209], v[174:177], v[100:103]
	s_barrier
	s_nop 1
	ds_read_b128 v[100:103], v168
	ds_read_b128 v[104:107], v168 offset:1024
	ds_read_b128 v[108:111], v168 offset:2048
	ds_read_b128 v[116:119], v168 offset:3072
	s_barrier
	s_waitcnt lgkmcnt(0)
	s_waitcnt lgkmcnt(0)
	v_mfma_f32_16x16x32_bf16 v[80:83], v[194:197], v[100:103], v[80:83]
	v_mfma_f32_16x16x32_bf16 v[76:79], v[194:197], v[108:111], v[76:79]
	v_mfma_f32_16x16x32_bf16 v[72:75], v[202:205], v[100:103], v[72:75]
	v_mfma_f32_16x16x32_bf16 v[68:71], v[202:205], v[108:111], v[68:71]
	v_mfma_f32_16x16x32_bf16 v[96:99], v[178:181], v[100:103], v[96:99]
	v_mfma_f32_16x16x32_bf16 v[92:95], v[178:181], v[108:111], v[92:95]
	v_mfma_f32_16x16x32_bf16 v[88:91], v[186:189], v[100:103], v[88:91]
	v_mfma_f32_16x16x32_bf16 v[84:87], v[186:189], v[108:111], v[84:87]
	v_mfma_f32_16x16x32_bf16 v[80:83], v[198:201], v[104:107], v[80:83]
	v_mfma_f32_16x16x32_bf16 v[76:79], v[198:201], v[116:119], v[76:79]
	v_mfma_f32_16x16x32_bf16 v[72:75], v[206:209], v[104:107], v[72:75]
	v_mfma_f32_16x16x32_bf16 v[68:71], v[206:209], v[116:119], v[68:71]
	v_mfma_f32_16x16x32_bf16 v[166:169], v[182:185], v[104:107], v[96:99]
	v_mfma_f32_16x16x32_bf16 v[178:181], v[182:185], v[116:119], v[92:95]
	v_mfma_f32_16x16x32_bf16 v[182:185], v[190:193], v[104:107], v[88:91]
	v_mfma_f32_16x16x32_bf16 v[186:189], v[190:193], v[116:119], v[84:87]
	s_barrier
; #define LDA8(dst, b, h) _Pragma("unroll") for (int m = 0; m < 4; ++m) _Pragma("unroll") for (int k = 0; k < 2; ++k) \
;     dst[m][k] = *(const bf16x8*)((const char*)SA8(b, h) + lds_byte8(wr * 64 + m * 16 + fr, k * 32 + fq * 8))
; #define LDB8(dst, b, h) _Pragma("unroll") for (int n = 0; n < 2; ++n) _Pragma("unroll") for (int k = 0; k < 2; ++k) \
;     dst[n][k] = *(const bf16x8*)((const char*)SB8(b, h) + lds_byte8(wc * 32 + n * 16 + fr, k * 32 + fq * 8))
; #define WAIT_V8(n) asm volatile("s_waitcnt vmcnt(" #n ")" ::: "memory")
; #define WAIT_L8(n) asm volatile("s_waitcnt lgkmcnt(" #n ")" ::: "memory")
; #define BAR8 __builtin_amdgcn_s_barrier()
;     ...
;     LDA8(At, 0, 1); WAIT_V8(4); BAR8; WAIT_L8(0); MMA8(1, 0, At, B0); MMA8(1, 1, At, B1); BAR8; }
;   { LDB8(B0, 1, 0); LDA8(At, 1, 0); WAIT_V8(2); BAR8; WAIT_L8(0); MMA8(0, 0, At, B0); BAR8;
	s_nop 0
	ds_read_b128 v[84:87], v156 offset:16384
	ds_read_b128 v[88:91], v156 offset:17408
	ds_read_b128 v[92:95], v155 offset:16384
	ds_read_b128 v[96:99], v155 offset:17408
	ds_read_b128 v[190:193], v154 offset:16384
	ds_read_b128 v[194:197], v154 offset:17408
	ds_read_b128 v[198:201], v153 offset:16384
	ds_read_b128 v[202:205], v153 offset:17408
	s_waitcnt vmcnt(4)
	s_barrier
	s_waitcnt lgkmcnt(0)
	s_waitcnt lgkmcnt(0)
	v_mfma_f32_16x16x32_bf16 v[64:67], v[84:87], v[138:141], v[64:67]
	v_mfma_f32_16x16x32_bf16 v[60:63], v[84:87], v[162:165], v[60:63]
	v_mfma_f32_16x16x32_bf16 v[56:59], v[92:95], v[138:141], v[56:59]
	v_mfma_f32_16x16x32_bf16 v[52:55], v[92:95], v[162:165], v[52:55]
	v_mfma_f32_16x16x32_bf16 v[48:51], v[190:193], v[138:141], v[48:51]
	v_mfma_f32_16x16x32_bf16 v[44:47], v[190:193], v[162:165], v[44:47]
	v_mfma_f32_16x16x32_bf16 v[40:43], v[198:201], v[138:141], v[40:43]
	v_mfma_f32_16x16x32_bf16 v[36:39], v[198:201], v[162:165], v[36:39]
	v_mfma_f32_16x16x32_bf16 v[64:67], v[88:91], v[142:145], v[64:67]
	v_mfma_f32_16x16x32_bf16 v[60:63], v[88:91], v[174:177], v[60:63]
	v_mfma_f32_16x16x32_bf16 v[56:59], v[96:99], v[142:145], v[56:59]
	v_mfma_f32_16x16x32_bf16 v[52:55], v[96:99], v[174:177], v[52:55]
	v_mfma_f32_16x16x32_bf16 v[48:51], v[194:197], v[142:145], v[48:51]
	v_mfma_f32_16x16x32_bf16 v[44:47], v[194:197], v[174:177], v[44:47]
	v_mfma_f32_16x16x32_bf16 v[40:43], v[202:205], v[142:145], v[40:43]
	v_mfma_f32_16x16x32_bf16 v[36:39], v[202:205], v[174:177], v[36:39]
	v_mfma_f32_16x16x32_bf16 v[32:35], v[84:87], v[100:103], v[32:35]
	v_mfma_f32_16x16x32_bf16 v[28:31], v[84:87], v[108:111], v[28:31]
	v_mfma_f32_16x16x32_bf16 v[24:27], v[92:95], v[100:103], v[24:27]
	v_mfma_f32_16x16x32_bf16 v[20:23], v[92:95], v[108:111], v[20:23]
	v_mfma_f32_16x16x32_bf16 v[16:19], v[190:193], v[100:103], v[16:19]
	v_mfma_f32_16x16x32_bf16 v[12:15], v[190:193], v[108:111], v[12:15]
	v_mfma_f32_16x16x32_bf16 v[8:11], v[198:201], v[100:103], v[8:11]
	v_mfma_f32_16x16x32_bf16 v[4:7], v[198:201], v[108:111], v[4:7]
	v_mfma_f32_16x16x32_bf16 v[136:139], v[88:91], v[104:107], v[32:35]
	v_mfma_f32_16x16x32_bf16 v[140:143], v[88:91], v[116:119], v[28:31]
	v_mfma_f32_16x16x32_bf16 v[162:165], v[96:99], v[104:107], v[24:27]
	v_mfma_f32_16x16x32_bf16 v[174:177], v[96:99], v[116:119], v[20:23]
	v_mfma_f32_16x16x32_bf16 v[206:209], v[194:197], v[104:107], v[16:19]
	v_mfma_f32_16x16x32_bf16 v[190:193], v[194:197], v[116:119], v[12:15]
	v_mfma_f32_16x16x32_bf16 v[194:197], v[202:205], v[104:107], v[8:11]
	v_mfma_f32_16x16x32_bf16 v[198:201], v[202:205], v[116:119], v[4:7]
	s_barrier
	ds_read_b128 v[202:205], v161
	ds_read_b128 v[218:221], v161 offset:1024
	ds_read_b128 v[226:229], v161 offset:2048
	ds_read_b128 v[230:233], v161 offset:3072
	ds_read_b128 v[8:11], v156 offset:32768
	ds_read_b128 v[12:15], v156 offset:33792
	ds_read_b128 v[16:19], v155 offset:32768
	ds_read_b128 v[24:27], v155 offset:33792
	ds_read_b128 v[28:31], v154 offset:32768
	ds_read_b128 v[32:35], v154 offset:33792
	ds_read_b128 v[238:241], v153 offset:32768
	ds_read_b128 v[242:245], v153 offset:33792
	s_waitcnt vmcnt(2)
	s_barrier
	s_waitcnt lgkmcnt(0)
	s_waitcnt lgkmcnt(0)
	v_mfma_f32_16x16x32_bf16 v[4:7], v[8:11], v[202:205], v[128:131]
	v_mfma_f32_16x16x32_bf16 v[104:107], v[12:15], v[218:221], v[4:7]
	v_mfma_f32_16x16x32_bf16 v[4:7], v[8:11], v[226:229], v[124:127]
	v_mfma_f32_16x16x32_bf16 v[116:119], v[12:15], v[230:233], v[4:7]
	v_mfma_f32_16x16x32_bf16 v[4:7], v[16:19], v[202:205], v[120:123]
	v_mfma_f32_16x16x32_bf16 v[100:103], v[24:27], v[218:221], v[4:7]
	v_mfma_f32_16x16x32_bf16 v[4:7], v[16:19], v[226:229], v[132:135]
	v_mfma_f32_16x16x32_bf16 v[108:111], v[24:27], v[230:233], v[4:7]
	v_mfma_f32_16x16x32_bf16 v[4:7], v[28:31], v[202:205], v[112:115]
	v_mfma_f32_16x16x32_bf16 v[92:95], v[32:35], v[218:221], v[4:7]
	v_mfma_f32_16x16x32_bf16 v[4:7], v[28:31], v[226:229], v[170:173]
	v_mfma_f32_16x16x32_bf16 v[96:99], v[32:35], v[230:233], v[4:7]
	v_mfma_f32_16x16x32_bf16 v[4:7], v[238:241], v[202:205], v[210:213]
	v_mfma_f32_16x16x32_bf16 v[84:87], v[242:245], v[218:221], v[4:7]
	v_mfma_f32_16x16x32_bf16 v[4:7], v[238:241], v[226:229], v[214:217]
	v_mfma_f32_16x16x32_bf16 v[88:91], v[242:245], v[230:233], v[4:7]
	s_barrier
; DI int tid_opaque() { int t = threadIdx.x; asm volatile("" : "+v"(t)); return t; }
; #define LDA8(dst, b, h) _Pragma("unroll") for (int m = 0; m < 4; ++m) _Pragma("unroll") for (int k = 0; k < 2; ++k) \
;     dst[m][k] = *(const bf16x8*)((const char*)SA8(b, h) + lds_byte8(wr * 64 + m * 16 + fr, k * 32 + fq * 8))
; #define LDB8(dst, b, h) _Pragma("unroll") for (int n = 0; n < 2; ++n) _Pragma("unroll") for (int k = 0; k < 2; ++k) \
;     dst[n][k] = *(const bf16x8*)((const char*)SB8(b, h) + lds_byte8(wc * 32 + n * 16 + fr, k * 32 + fq * 8))
; #define WAIT_V8(n) asm volatile("s_waitcnt vmcnt(" #n ")" ::: "memory")
; #define WAIT_L8(n) asm volatile("s_waitcnt lgkmcnt(" #n ")" ::: "memory")
; #define BAR8 __builtin_amdgcn_s_barrier()
;     ...
;     LDB8(B1, 1, 1); WAIT_V8(0); BAR8; WAIT_L8(0); MMA8(0, 1, At, B1); BAR8;
;     LDA8(At, 1, 1); BAR8; WAIT_L8(0); MMA8(1, 0, At, B0); MMA8(1, 1, At, B1); BAR8; }
;   if (wr == 0) BAR8;
;   __syncthreads();
;   if (EPI == EPI_GU && nm0 >= 0) {
;     const int t = tid_opaque();
;     STAGE8(SB8(0, 0), Bt, K, nn0, 0); STAGE8(SA8(0, 0), A, lda, nm0, 0);
;     STAGE8(SB8(0, 1), Bt, K, nn0 + 128, 0); STAGE8(SA8(0, 1), A, lda, nm0 + 128, 0);
;   }
;     ...
;   if (t < 256) {
	ds_read_b128 v[132:135], v158
	ds_read_b128 v[170:173], v158 offset:1024
	ds_read_b128 v[210:213], v158 offset:2048
	ds_read_b128 v[158:161], v158 offset:3072
	s_waitcnt vmcnt(0)
	s_barrier
	s_waitcnt lgkmcnt(0)
	s_waitcnt lgkmcnt(0)
	v_mfma_f32_16x16x32_bf16 v[4:7], v[8:11], v[132:135], v[166:169]
	v_mfma_f32_16x16x32_bf16 v[8:11], v[8:11], v[210:213], v[178:181]
	v_mfma_f32_16x16x32_bf16 v[4:7], v[12:15], v[170:173], v[4:7]
	v_mfma_f32_16x16x32_bf16 v[20:23], v[12:15], v[158:161], v[8:11]
	v_mfma_f32_16x16x32_bf16 v[8:11], v[16:19], v[132:135], v[182:185]
	v_mfma_f32_16x16x32_bf16 v[12:15], v[16:19], v[210:213], v[186:189]
	v_mfma_f32_16x16x32_bf16 v[8:11], v[24:27], v[170:173], v[8:11]
	v_mfma_f32_16x16x32_bf16 v[24:27], v[24:27], v[158:161], v[12:15]
	v_mfma_f32_16x16x32_bf16 v[12:15], v[28:31], v[132:135], v[80:83]
	v_mfma_f32_16x16x32_bf16 v[16:19], v[28:31], v[210:213], v[76:79]
	v_mfma_f32_16x16x32_bf16 v[12:15], v[32:35], v[170:173], v[12:15]
	v_mfma_f32_16x16x32_bf16 v[28:31], v[32:35], v[158:161], v[16:19]
	v_mfma_f32_16x16x32_bf16 v[16:19], v[238:241], v[132:135], v[72:75]
	v_mfma_f32_16x16x32_bf16 v[32:35], v[238:241], v[210:213], v[68:71]
	v_mfma_f32_16x16x32_bf16 v[16:19], v[242:245], v[170:173], v[16:19]
	v_mfma_f32_16x16x32_bf16 v[32:35], v[242:245], v[158:161], v[32:35]
	s_barrier
	ds_read_b128 v[166:169], v156 offset:49152
	ds_read_b128 v[178:181], v156 offset:50176
	ds_read_b128 v[182:185], v155 offset:49152
	ds_read_b128 v[186:189], v155 offset:50176
	ds_read_b128 v[214:217], v154 offset:49152
	ds_read_b128 v[154:157], v154 offset:50176
	ds_read_b128 v[238:241], v153 offset:49152
	ds_read_b128 v[150:153], v153 offset:50176
	s_barrier
	s_waitcnt lgkmcnt(0)
	s_waitcnt lgkmcnt(0)
	v_mfma_f32_16x16x32_bf16 v[64:67], v[166:169], v[202:205], v[64:67]
	v_mfma_f32_16x16x32_bf16 v[60:63], v[166:169], v[226:229], v[60:63]
	v_mfma_f32_16x16x32_bf16 v[56:59], v[182:185], v[202:205], v[56:59]
	v_mfma_f32_16x16x32_bf16 v[52:55], v[182:185], v[226:229], v[52:55]
	v_mfma_f32_16x16x32_bf16 v[48:51], v[214:217], v[202:205], v[48:51]
	v_mfma_f32_16x16x32_bf16 v[44:47], v[214:217], v[226:229], v[44:47]
	v_mfma_f32_16x16x32_bf16 v[40:43], v[238:241], v[202:205], v[40:43]
	v_mfma_f32_16x16x32_bf16 v[36:39], v[238:241], v[226:229], v[36:39]
	v_mfma_f32_16x16x32_bf16 v[128:131], v[178:181], v[218:221], v[64:67]
	v_mfma_f32_16x16x32_bf16 v[124:127], v[178:181], v[230:233], v[60:63]
	v_mfma_f32_16x16x32_bf16 v[120:123], v[186:189], v[218:221], v[56:59]
	v_mfma_f32_16x16x32_bf16 v[112:115], v[186:189], v[230:233], v[52:55]
	v_mfma_f32_16x16x32_bf16 v[80:83], v[154:157], v[218:221], v[48:51]
	v_mfma_f32_16x16x32_bf16 v[76:79], v[154:157], v[230:233], v[44:47]
	v_mfma_f32_16x16x32_bf16 v[72:75], v[150:153], v[218:221], v[40:43]
	v_mfma_f32_16x16x32_bf16 v[68:71], v[150:153], v[230:233], v[36:39]
	v_mfma_f32_16x16x32_bf16 v[36:39], v[166:169], v[132:135], v[136:139]
	v_mfma_f32_16x16x32_bf16 v[64:67], v[178:181], v[170:173], v[36:39]
	v_mfma_f32_16x16x32_bf16 v[36:39], v[166:169], v[210:213], v[140:143]
	v_mfma_f32_16x16x32_bf16 v[60:63], v[178:181], v[158:161], v[36:39]
	v_mfma_f32_16x16x32_bf16 v[36:39], v[182:185], v[132:135], v[162:165]
	v_mfma_f32_16x16x32_bf16 v[56:59], v[186:189], v[170:173], v[36:39]
	v_mfma_f32_16x16x32_bf16 v[36:39], v[182:185], v[210:213], v[174:177]
	v_mfma_f32_16x16x32_bf16 v[52:55], v[186:189], v[158:161], v[36:39]
	v_mfma_f32_16x16x32_bf16 v[36:39], v[214:217], v[132:135], v[206:209]
	v_mfma_f32_16x16x32_bf16 v[48:51], v[154:157], v[170:173], v[36:39]
	v_mfma_f32_16x16x32_bf16 v[36:39], v[214:217], v[210:213], v[190:193]
	v_mfma_f32_16x16x32_bf16 v[44:47], v[154:157], v[158:161], v[36:39]
	v_mfma_f32_16x16x32_bf16 v[36:39], v[238:241], v[132:135], v[194:197]
	v_mfma_f32_16x16x32_bf16 v[40:43], v[150:153], v[170:173], v[36:39]
	v_mfma_f32_16x16x32_bf16 v[36:39], v[238:241], v[210:213], v[198:201]
	v_mfma_f32_16x16x32_bf16 v[36:39], v[150:153], v[158:161], v[36:39]
	s_movk_i32 s1, 0x100
	v_cmp_gt_u32_e32 vcc, s1, v3
	s_barrier
	s_and_saveexec_b64 s[8:9], vcc
	s_cbranch_execz .LBB0_1008
	s_barrier

; #define LDA8(dst, b, h) _Pragma("unroll") for (int m = 0; m < 4; ++m) _Pragma("unroll") for (int k = 0; k < 2; ++k) \
;     dst[m][k] = *(const bf16x8*)((const char*)SA8(b, h) + lds_byte8(wr * 64 + m * 16 + fr, k * 32 + fq * 8))
; #define LDB8(dst, b, h) _Pragma("unroll") for (int n = 0; n < 2; ++n) _Pragma("unroll") for (int k = 0; k < 2; ++k) \
;     dst[n][k] = *(const bf16x8*)((const char*)SB8(b, h) + lds_byte8(wc * 32 + n * 16 + fr, k * 32 + fq * 8))
; #define WAIT_L8(n) asm volatile("s_waitcnt lgkmcnt(" #n ")" ::: "memory")
; #define BAR8 __builtin_amdgcn_s_barrier()
; #define SCHED8 __builtin_amdgcn_sched_barrier(0)
;     ...
;   for (int tt = 0; tt < nt - 2; tt += 2) {
;     LDB8(B0, 0, 0); SCHED8; LDA8(At, 0, 0); STAGE8(SA8(1, 1), A, lda, brow + 128, tt + 1);
;     WAIT_L8(8); BAR8; WAIT_L8(0); MMA8(0, 0, At, B0); BAR8; SCHED8;
;     LDB8(B1, 0, 1); STAGE8(SB8(0, 0), Bt, K, bcol, tt + 2);
;     BAR8; WAIT_L8(0); MMA8(0, 1, At, B1); BAR8;
;     LDA8(At, 0, 1); STAGE8(SA8(0, 0), A, lda, brow, tt + 2);
;     BAR8; WAIT_L8(0); MMA8(1, 0, At, B0); BAR8; SCHED8;
.LBB0_1015:
	ds_read_b128 v[174:177], v171
	ds_read_b128 v[178:181], v171 offset:1024
	ds_read_b128 v[182:185], v171 offset:2048
	ds_read_b128 v[186:189], v171 offset:3072
	v_add_u32_e32 v172, 0xc000, v150
	v_lshl_add_u64 v[222:223], v[140:141], 0, s[12:13]
	v_readfirstlane_b32 s15, v172
	v_add_u32_e32 v173, 0xe000, v150
	v_lshl_add_u64 v[226:227], v[222:223], 0, s[34:35]
	s_mov_b32 m0, s15
	v_lshl_add_u64 v[236:237], v[138:139], 0, s[12:13]
	v_readfirstlane_b32 s15, v173
	ds_read_b128 v[190:193], v156
	ds_read_b128 v[194:197], v156 offset:1024
	ds_read_b128 v[198:201], v155
	ds_read_b128 v[202:205], v155 offset:1024
	ds_read_b128 v[206:209], v154
	ds_read_b128 v[210:213], v154 offset:1024
	ds_read_b128 v[214:217], v153
	ds_read_b128 v[218:221], v153 offset:1024
	global_load_lds_dwordx4 v[226:227], off
	v_lshl_add_u64 v[226:227], v[236:237], 0, s[34:35]
	s_mov_b32 m0, s15
	s_nop 0
	global_load_lds_dwordx4 v[226:227], off
	s_waitcnt lgkmcnt(8)
	s_barrier
	s_waitcnt lgkmcnt(0)
	s_waitcnt lgkmcnt(0)
	v_mfma_f32_16x16x32_f16 v[128:131], v[190:193], v[174:177], v[128:131]
	v_mfma_f32_16x16x32_f16 v[124:127], v[190:193], v[182:185], v[124:127]
	v_mfma_f32_16x16x32_f16 v[120:123], v[198:201], v[174:177], v[120:123]
	v_mfma_f32_16x16x32_f16 v[116:119], v[198:201], v[182:185], v[116:119]
	v_mfma_f32_16x16x32_f16 v[112:115], v[206:209], v[174:177], v[112:115]
	v_mfma_f32_16x16x32_f16 v[108:111], v[206:209], v[182:185], v[108:111]
	v_mfma_f32_16x16x32_f16 v[104:107], v[214:217], v[174:177], v[104:107]
	v_mfma_f32_16x16x32_f16 v[100:103], v[214:217], v[182:185], v[100:103]
	v_mfma_f32_16x16x32_f16 v[128:131], v[194:197], v[178:181], v[128:131]
	v_mfma_f32_16x16x32_f16 v[124:127], v[194:197], v[186:189], v[124:127]
	v_mfma_f32_16x16x32_f16 v[120:123], v[202:205], v[178:181], v[120:123]
	v_mfma_f32_16x16x32_f16 v[116:119], v[202:205], v[186:189], v[116:119]
	v_mfma_f32_16x16x32_f16 v[112:115], v[210:213], v[178:181], v[112:115]
	v_mfma_f32_16x16x32_f16 v[108:111], v[210:213], v[186:189], v[108:111]
	v_mfma_f32_16x16x32_f16 v[104:107], v[218:221], v[178:181], v[104:107]
	v_mfma_f32_16x16x32_f16 v[100:103], v[218:221], v[186:189], v[100:103]
	s_barrier
	v_lshl_add_u64 v[246:247], v[142:143], 0, s[12:13]
	v_readfirstlane_b32 s15, v151
	v_lshl_add_u64 v[248:249], v[246:247], 0, s[40:41]
	s_mov_b32 m0, s15
	ds_read_b128 v[226:229], v168
	ds_read_b128 v[230:233], v168 offset:1024
	ds_read_b128 v[238:241], v168 offset:2048
	ds_read_b128 v[242:245], v168 offset:3072
	global_load_lds_dwordx4 v[248:249], off
	v_lshl_add_u64 v[248:249], v[144:145], 0, s[12:13]
	v_readfirstlane_b32 s15, v157
	v_lshl_add_u64 v[250:251], v[248:249], 0, s[40:41]
	s_mov_b32 m0, s15
	s_nop 0
	global_load_lds_dwordx4 v[250:251], off
	s_barrier
	s_waitcnt lgkmcnt(0)
	s_waitcnt lgkmcnt(0)
	v_mfma_f32_16x16x32_f16 v[96:99], v[190:193], v[226:229], v[96:99]
	v_mfma_f32_16x16x32_f16 v[92:95], v[190:193], v[238:241], v[92:95]
	v_mfma_f32_16x16x32_f16 v[88:91], v[198:201], v[226:229], v[88:91]
	v_mfma_f32_16x16x32_f16 v[84:87], v[198:201], v[238:241], v[84:87]
	v_mfma_f32_16x16x32_f16 v[80:83], v[206:209], v[226:229], v[80:83]
	v_mfma_f32_16x16x32_f16 v[76:79], v[206:209], v[238:241], v[76:79]
	v_mfma_f32_16x16x32_f16 v[72:75], v[214:217], v[226:229], v[72:75]
	v_mfma_f32_16x16x32_f16 v[68:71], v[214:217], v[238:241], v[68:71]
	v_mfma_f32_16x16x32_f16 v[96:99], v[194:197], v[230:233], v[96:99]
	v_mfma_f32_16x16x32_f16 v[92:95], v[194:197], v[242:245], v[92:95]
	v_mfma_f32_16x16x32_f16 v[88:91], v[202:205], v[230:233], v[88:91]
	v_mfma_f32_16x16x32_f16 v[84:87], v[202:205], v[242:245], v[84:87]
	v_mfma_f32_16x16x32_f16 v[80:83], v[210:213], v[230:233], v[80:83]
	v_mfma_f32_16x16x32_f16 v[76:79], v[210:213], v[242:245], v[76:79]
	v_mfma_f32_16x16x32_f16 v[72:75], v[218:221], v[230:233], v[72:75]
	v_mfma_f32_16x16x32_f16 v[68:71], v[218:221], v[242:245], v[68:71]
	v_readfirstlane_b32 s15, v150
	v_lshl_add_u64 v[250:251], v[222:223], 0, s[10:11]
	s_mov_b32 m0, s15
	v_readfirstlane_b32 s15, v152
	s_barrier
	ds_read_b128 v[190:193], v156 offset:16384
	ds_read_b128 v[194:197], v156 offset:17408
	ds_read_b128 v[198:201], v155 offset:16384
	ds_read_b128 v[202:205], v155 offset:17408
	ds_read_b128 v[206:209], v154 offset:16384
	ds_read_b128 v[210:213], v154 offset:17408
	ds_read_b128 v[214:217], v153 offset:16384
	ds_read_b128 v[218:221], v153 offset:17408
	global_load_lds_dwordx4 v[250:251], off
	v_lshl_add_u64 v[250:251], v[236:237], 0, s[10:11]
	s_mov_b32 m0, s15
	s_nop 0
	global_load_lds_dwordx4 v[250:251], off
	s_barrier
	s_waitcnt lgkmcnt(0)
	s_waitcnt lgkmcnt(0)
	v_mfma_f32_16x16x32_f16 v[64:67], v[190:193], v[174:177], v[64:67]
	v_mfma_f32_16x16x32_f16 v[60:63], v[190:193], v[182:185], v[60:63]
	v_mfma_f32_16x16x32_f16 v[56:59], v[198:201], v[174:177], v[56:59]
	v_mfma_f32_16x16x32_f16 v[52:55], v[198:201], v[182:185], v[52:55]
	v_mfma_f32_16x16x32_f16 v[48:51], v[206:209], v[174:177], v[48:51]
	v_mfma_f32_16x16x32_f16 v[44:47], v[206:209], v[182:185], v[44:47]
	v_mfma_f32_16x16x32_f16 v[40:43], v[214:217], v[174:177], v[40:43]
	v_mfma_f32_16x16x32_f16 v[36:39], v[214:217], v[182:185], v[36:39]
	v_mfma_f32_16x16x32_f16 v[64:67], v[194:197], v[178:181], v[64:67]
	v_mfma_f32_16x16x32_f16 v[60:63], v[194:197], v[186:189], v[60:63]
	v_mfma_f32_16x16x32_f16 v[56:59], v[202:205], v[178:181], v[56:59]
	v_mfma_f32_16x16x32_f16 v[52:55], v[202:205], v[186:189], v[52:55]
	v_mfma_f32_16x16x32_f16 v[48:51], v[210:213], v[178:181], v[48:51]
	v_mfma_f32_16x16x32_f16 v[44:47], v[210:213], v[186:189], v[44:47]
	v_mfma_f32_16x16x32_f16 v[40:43], v[218:221], v[178:181], v[40:43]
	v_mfma_f32_16x16x32_f16 v[36:39], v[218:221], v[186:189], v[36:39]
	s_barrier
; #define LDA8(dst, b, h) _Pragma("unroll") for (int m = 0; m < 4; ++m) _Pragma("unroll") for (int k = 0; k < 2; ++k) \
;     dst[m][k] = *(const bf16x8*)((const char*)SA8(b, h) + lds_byte8(wr * 64 + m * 16 + fr, k * 32 + fq * 8))
; #define LDB8(dst, b, h) _Pragma("unroll") for (int n = 0; n < 2; ++n) _Pragma("unroll") for (int k = 0; k < 2; ++k) \
;     dst[n][k] = *(const bf16x8*)((const char*)SB8(b, h) + lds_byte8(wc * 32 + n * 16 + fr, k * 32 + fq * 8))
; #define WAIT_V8(n) asm volatile("s_waitcnt vmcnt(" #n ")" ::: "memory")
; #define WAIT_L8(n) asm volatile("s_waitcnt lgkmcnt(" #n ")" ::: "memory")
; #define BAR8 __builtin_amdgcn_s_barrier()
; #define SCHED8 __builtin_amdgcn_sched_barrier(0)
;     ...
;     STAGE8(SB8(0, 1), Bt, K, bcol + 128, tt + 2);
;     WAIT_V8(6); BAR8; MMA8(1, 1, At, B1); BAR8;
;     LDB8(B0, 1, 0); SCHED8; LDA8(At, 1, 0); STAGE8(SA8(0, 1), A, lda, brow + 128, tt + 2);
;     WAIT_L8(8); BAR8; WAIT_L8(0); MMA8(0, 0, At, B0); BAR8; SCHED8;
;     LDB8(B1, 1, 1); STAGE8(SB8(1, 0), Bt, K, bcol, tt + 3);
;     BAR8; WAIT_L8(0); MMA8(0, 1, At, B1); BAR8;
;     LDA8(At, 1, 1); STAGE8(SA8(1, 0), A, lda, brow, tt + 3);
	v_readfirstlane_b32 s15, v159
	v_lshl_add_u64 v[174:175], v[246:247], 0, s[42:43]
	s_mov_b32 m0, s15
	v_readfirstlane_b32 s15, v160
	global_load_lds_dwordx4 v[174:175], off
	v_lshl_add_u64 v[174:175], v[248:249], 0, s[42:43]
	s_mov_b32 m0, s15
	s_nop 0
	global_load_lds_dwordx4 v[174:175], off
	s_waitcnt vmcnt(6)
	s_barrier
	v_mfma_f32_16x16x32_f16 v[32:35], v[190:193], v[226:229], v[32:35]
	v_mfma_f32_16x16x32_f16 v[28:31], v[190:193], v[238:241], v[28:31]
	v_mfma_f32_16x16x32_f16 v[24:27], v[198:201], v[226:229], v[24:27]
	v_mfma_f32_16x16x32_f16 v[20:23], v[198:201], v[238:241], v[20:23]
	v_mfma_f32_16x16x32_f16 v[16:19], v[206:209], v[226:229], v[16:19]
	v_mfma_f32_16x16x32_f16 v[12:15], v[206:209], v[238:241], v[12:15]
	v_mfma_f32_16x16x32_f16 v[8:11], v[214:217], v[226:229], v[8:11]
	v_mfma_f32_16x16x32_f16 v[4:7], v[214:217], v[238:241], v[4:7]
	v_mfma_f32_16x16x32_f16 v[32:35], v[194:197], v[230:233], v[32:35]
	v_mfma_f32_16x16x32_f16 v[28:31], v[194:197], v[242:245], v[28:31]
	v_mfma_f32_16x16x32_f16 v[24:27], v[202:205], v[230:233], v[24:27]
	v_mfma_f32_16x16x32_f16 v[20:23], v[202:205], v[242:245], v[20:23]
	v_mfma_f32_16x16x32_f16 v[16:19], v[210:213], v[230:233], v[16:19]
	v_mfma_f32_16x16x32_f16 v[12:15], v[210:213], v[242:245], v[12:15]
	v_mfma_f32_16x16x32_f16 v[8:11], v[218:221], v[230:233], v[8:11]
	v_mfma_f32_16x16x32_f16 v[4:7], v[218:221], v[242:245], v[4:7]
	s_barrier
	ds_read_b128 v[174:177], v161
	ds_read_b128 v[178:181], v161 offset:1024
	ds_read_b128 v[182:185], v161 offset:2048
	ds_read_b128 v[186:189], v161 offset:3072
	v_readfirstlane_b32 s15, v162
	v_lshl_add_u64 v[226:227], v[222:223], 0, s[18:19]
	s_mov_b32 m0, s15
	v_readfirstlane_b32 s15, v163
	ds_read_b128 v[190:193], v156 offset:32768
	ds_read_b128 v[194:197], v156 offset:33792
	ds_read_b128 v[198:201], v155 offset:32768
	ds_read_b128 v[202:205], v155 offset:33792
	ds_read_b128 v[206:209], v154 offset:32768
	ds_read_b128 v[210:213], v154 offset:33792
	ds_read_b128 v[214:217], v153 offset:32768
	ds_read_b128 v[218:221], v153 offset:33792
	global_load_lds_dwordx4 v[226:227], off
	v_lshl_add_u64 v[226:227], v[236:237], 0, s[18:19]
	s_mov_b32 m0, s15
	s_nop 0
	global_load_lds_dwordx4 v[226:227], off
	s_waitcnt lgkmcnt(8)
	s_barrier
	s_waitcnt lgkmcnt(0)
	s_waitcnt lgkmcnt(0)
	v_mfma_f32_16x16x32_f16 v[128:131], v[190:193], v[174:177], v[128:131]
	v_mfma_f32_16x16x32_f16 v[124:127], v[190:193], v[182:185], v[124:127]
	v_mfma_f32_16x16x32_f16 v[120:123], v[198:201], v[174:177], v[120:123]
	v_mfma_f32_16x16x32_f16 v[116:119], v[198:201], v[182:185], v[116:119]
	v_mfma_f32_16x16x32_f16 v[112:115], v[206:209], v[174:177], v[112:115]
	v_mfma_f32_16x16x32_f16 v[108:111], v[206:209], v[182:185], v[108:111]
	v_mfma_f32_16x16x32_f16 v[104:107], v[214:217], v[174:177], v[104:107]
	v_mfma_f32_16x16x32_f16 v[100:103], v[214:217], v[182:185], v[100:103]
	v_mfma_f32_16x16x32_f16 v[128:131], v[194:197], v[178:181], v[128:131]
	v_mfma_f32_16x16x32_f16 v[124:127], v[194:197], v[186:189], v[124:127]
	v_mfma_f32_16x16x32_f16 v[120:123], v[202:205], v[178:181], v[120:123]
	v_mfma_f32_16x16x32_f16 v[116:119], v[202:205], v[186:189], v[116:119]
	v_mfma_f32_16x16x32_f16 v[112:115], v[210:213], v[178:181], v[112:115]
	v_mfma_f32_16x16x32_f16 v[108:111], v[210:213], v[186:189], v[108:111]
	v_mfma_f32_16x16x32_f16 v[104:107], v[218:221], v[178:181], v[104:107]
	v_mfma_f32_16x16x32_f16 v[100:103], v[218:221], v[186:189], v[100:103]
	s_barrier
	v_readfirstlane_b32 s15, v164
	v_lshl_add_u64 v[250:251], v[246:247], 0, s[44:45]
	s_mov_b32 m0, s15
	v_readfirstlane_b32 s15, v165
	ds_read_b128 v[226:229], v158
	ds_read_b128 v[230:233], v158 offset:1024
	ds_read_b128 v[238:241], v158 offset:2048
	ds_read_b128 v[242:245], v158 offset:3072
	global_load_lds_dwordx4 v[250:251], off
	v_lshl_add_u64 v[250:251], v[248:249], 0, s[44:45]
	s_mov_b32 m0, s15
	s_nop 0
	global_load_lds_dwordx4 v[250:251], off
	s_barrier
	s_waitcnt lgkmcnt(0)
	s_waitcnt lgkmcnt(0)
	v_mfma_f32_16x16x32_f16 v[96:99], v[190:193], v[226:229], v[96:99]
	v_mfma_f32_16x16x32_f16 v[92:95], v[190:193], v[238:241], v[92:95]
	v_mfma_f32_16x16x32_f16 v[88:91], v[198:201], v[226:229], v[88:91]
	v_mfma_f32_16x16x32_f16 v[84:87], v[198:201], v[238:241], v[84:87]
	v_mfma_f32_16x16x32_f16 v[80:83], v[206:209], v[226:229], v[80:83]
	v_mfma_f32_16x16x32_f16 v[76:79], v[206:209], v[238:241], v[76:79]
	v_mfma_f32_16x16x32_f16 v[72:75], v[214:217], v[226:229], v[72:75]
	v_mfma_f32_16x16x32_f16 v[68:71], v[214:217], v[238:241], v[68:71]
	v_mfma_f32_16x16x32_f16 v[96:99], v[194:197], v[230:233], v[96:99]
	v_mfma_f32_16x16x32_f16 v[92:95], v[194:197], v[242:245], v[92:95]
	v_mfma_f32_16x16x32_f16 v[88:91], v[202:205], v[230:233], v[88:91]
	v_mfma_f32_16x16x32_f16 v[84:87], v[202:205], v[242:245], v[84:87]
	v_mfma_f32_16x16x32_f16 v[80:83], v[210:213], v[230:233], v[80:83]
	v_mfma_f32_16x16x32_f16 v[76:79], v[210:213], v[242:245], v[76:79]
	v_mfma_f32_16x16x32_f16 v[72:75], v[218:221], v[230:233], v[72:75]
	v_mfma_f32_16x16x32_f16 v[68:71], v[218:221], v[242:245], v[68:71]
	v_readfirstlane_b32 s15, v166
	v_lshl_add_u64 v[222:223], v[222:223], 0, s[22:23]
	s_mov_b32 m0, s15
	v_readfirstlane_b32 s15, v167
	s_barrier
	ds_read_b128 v[190:193], v156 offset:49152
	ds_read_b128 v[194:197], v156 offset:50176
	ds_read_b128 v[198:201], v155 offset:49152
	ds_read_b128 v[202:205], v155 offset:50176
	ds_read_b128 v[206:209], v154 offset:49152
	ds_read_b128 v[210:213], v154 offset:50176
	ds_read_b128 v[214:217], v153 offset:49152
	ds_read_b128 v[218:221], v153 offset:50176
	global_load_lds_dwordx4 v[222:223], off
	v_lshl_add_u64 v[222:223], v[236:237], 0, s[22:23]
	s_mov_b32 m0, s15
	s_nop 0
	global_load_lds_dwordx4 v[222:223], off
	s_barrier
; #define LDA8(dst, b, h) _Pragma("unroll") for (int m = 0; m < 4; ++m) _Pragma("unroll") for (int k = 0; k < 2; ++k) \
;     dst[m][k] = *(const bf16x8*)((const char*)SA8(b, h) + lds_byte8(wr * 64 + m * 16 + fr, k * 32 + fq * 8))
; #define LDB8(dst, b, h) _Pragma("unroll") for (int n = 0; n < 2; ++n) _Pragma("unroll") for (int k = 0; k < 2; ++k) \
;     dst[n][k] = *(const bf16x8*)((const char*)SB8(b, h) + lds_byte8(wc * 32 + n * 16 + fr, k * 32 + fq * 8))
; #define WAIT_V8(n) asm volatile("s_waitcnt vmcnt(" #n ")" ::: "memory")
; #define WAIT_L8(n) asm volatile("s_waitcnt lgkmcnt(" #n ")" ::: "memory")
; #define BAR8 __builtin_amdgcn_s_barrier()
; #define SCHED8 __builtin_amdgcn_sched_barrier(0)
;     ...
;     BAR8; WAIT_L8(0); MMA8(1, 0, At, B0); BAR8; SCHED8;
;     STAGE8(SB8(1, 1), Bt, K, bcol + 128, tt + 3);
;     WAIT_V8(6); BAR8; MMA8(1, 1, At, B1); BAR8;
;   }
;   { LDB8(B0, 0, 0); LDA8(At, 0, 0); STAGE8(SA8(1, 1), A, lda, brow + 128, nt - 1);
;     BAR8; WAIT_L8(0); MMA8(0, 0, At, B0); BAR8;
;     LDB8(B1, 0, 1); BAR8; WAIT_L8(0); MMA8(0, 1, At, B1); BAR8;
	s_waitcnt lgkmcnt(0)
	s_waitcnt lgkmcnt(0)
	v_mfma_f32_16x16x32_f16 v[64:67], v[190:193], v[174:177], v[64:67]
	v_mfma_f32_16x16x32_f16 v[60:63], v[190:193], v[182:185], v[60:63]
	v_mfma_f32_16x16x32_f16 v[56:59], v[198:201], v[174:177], v[56:59]
	v_mfma_f32_16x16x32_f16 v[52:55], v[198:201], v[182:185], v[52:55]
	v_mfma_f32_16x16x32_f16 v[48:51], v[206:209], v[174:177], v[48:51]
	v_mfma_f32_16x16x32_f16 v[44:47], v[206:209], v[182:185], v[44:47]
	v_mfma_f32_16x16x32_f16 v[40:43], v[214:217], v[174:177], v[40:43]
	v_mfma_f32_16x16x32_f16 v[36:39], v[214:217], v[182:185], v[36:39]
	v_mfma_f32_16x16x32_f16 v[64:67], v[194:197], v[178:181], v[64:67]
	v_mfma_f32_16x16x32_f16 v[60:63], v[194:197], v[186:189], v[60:63]
	v_mfma_f32_16x16x32_f16 v[56:59], v[202:205], v[178:181], v[56:59]
	v_mfma_f32_16x16x32_f16 v[52:55], v[202:205], v[186:189], v[52:55]
	v_mfma_f32_16x16x32_f16 v[48:51], v[210:213], v[178:181], v[48:51]
	v_mfma_f32_16x16x32_f16 v[44:47], v[210:213], v[186:189], v[44:47]
	v_mfma_f32_16x16x32_f16 v[40:43], v[218:221], v[178:181], v[40:43]
	v_mfma_f32_16x16x32_f16 v[36:39], v[218:221], v[186:189], v[36:39]
	s_barrier
	v_readfirstlane_b32 s15, v169
	v_lshl_add_u64 v[174:175], v[246:247], 0, s[46:47]
	s_mov_b32 m0, s15
	v_readfirstlane_b32 s15, v170
	global_load_lds_dwordx4 v[174:175], off
	v_lshl_add_u64 v[174:175], v[248:249], 0, s[46:47]
	s_mov_b32 m0, s15
	s_nop 0
	global_load_lds_dwordx4 v[174:175], off
	s_waitcnt vmcnt(6)
	s_barrier
	v_mfma_f32_16x16x32_f16 v[32:35], v[190:193], v[226:229], v[32:35]
	v_mfma_f32_16x16x32_f16 v[28:31], v[190:193], v[238:241], v[28:31]
	v_mfma_f32_16x16x32_f16 v[24:27], v[198:201], v[226:229], v[24:27]
	v_mfma_f32_16x16x32_f16 v[20:23], v[198:201], v[238:241], v[20:23]
	v_mfma_f32_16x16x32_f16 v[16:19], v[206:209], v[226:229], v[16:19]
	v_mfma_f32_16x16x32_f16 v[12:15], v[206:209], v[238:241], v[12:15]
	v_mfma_f32_16x16x32_f16 v[8:11], v[214:217], v[226:229], v[8:11]
	v_mfma_f32_16x16x32_f16 v[4:7], v[214:217], v[238:241], v[4:7]
	v_mfma_f32_16x16x32_f16 v[32:35], v[194:197], v[230:233], v[32:35]
	v_mfma_f32_16x16x32_f16 v[28:31], v[194:197], v[242:245], v[28:31]
	v_mfma_f32_16x16x32_f16 v[24:27], v[202:205], v[230:233], v[24:27]
	v_mfma_f32_16x16x32_f16 v[20:23], v[202:205], v[242:245], v[20:23]
	v_mfma_f32_16x16x32_f16 v[16:19], v[210:213], v[230:233], v[16:19]
	v_mfma_f32_16x16x32_f16 v[12:15], v[210:213], v[242:245], v[12:15]
	v_mfma_f32_16x16x32_f16 v[8:11], v[218:221], v[230:233], v[8:11]
	v_mfma_f32_16x16x32_f16 v[4:7], v[218:221], v[242:245], v[4:7]
	s_add_i32 s14, s14, 2
	s_add_u32 s12, s12, 0x100
	s_addc_u32 s13, s13, 0
	s_cmp_lt_u32 s14, 12
	s_barrier
	s_cbranch_scc1 .LBB0_1015
	s_add_u32 s8, s8, 0x40780
	s_addc_u32 s9, s9, 0
	v_lshl_add_u64 v[132:133], s[8:9], 0, v[132:133]
	v_readfirstlane_b32 s12, v172
	v_lshl_add_u64 v[0:1], v[0:1], 1, v[132:133]
	s_mov_b32 m0, s12
	ds_read_b128 v[138:141], v171
	ds_read_b128 v[142:145], v171 offset:1024
	ds_read_b128 v[162:165], v171 offset:2048
	ds_read_b128 v[174:177], v171 offset:3072
	ds_read_b128 v[178:181], v156
	ds_read_b128 v[182:185], v156 offset:1024
	ds_read_b128 v[186:189], v155
	ds_read_b128 v[190:193], v155 offset:1024
	ds_read_b128 v[194:197], v154
	ds_read_b128 v[198:201], v154 offset:1024
	ds_read_b128 v[202:205], v153
	ds_read_b128 v[206:209], v153 offset:1024
	global_load_lds_dwordx4 v[0:1], off
	v_lshl_add_u64 v[0:1], s[8:9], 0, v[136:137]
	v_readfirstlane_b32 s8, v173
	v_lshl_add_u64 v[0:1], v[134:135], 1, v[0:1]
	s_mov_b32 m0, s8
	s_nop 0
	global_load_lds_dwordx4 v[0:1], off
	s_barrier
	s_waitcnt lgkmcnt(0)
	s_waitcnt lgkmcnt(0)
	v_mfma_f32_16x16x32_f16 v[128:131], v[178:181], v[138:141], v[128:131]
	v_mfma_f32_16x16x32_f16 v[124:127], v[178:181], v[162:165], v[124:127]
	v_mfma_f32_16x16x32_f16 v[120:123], v[186:189], v[138:141], v[120:123]
	v_mfma_f32_16x16x32_f16 v[112:115], v[194:197], v[138:141], v[112:115]
	v_mfma_f32_16x16x32_f16 v[128:131], v[182:185], v[142:145], v[128:131]
	v_mfma_f32_16x16x32_f16 v[124:127], v[182:185], v[174:177], v[124:127]
	v_mfma_f32_16x16x32_f16 v[120:123], v[190:193], v[142:145], v[120:123]
	v_mfma_f32_16x16x32_f16 v[116:119], v[186:189], v[162:165], v[116:119]
	v_mfma_f32_16x16x32_f16 v[112:115], v[198:201], v[142:145], v[112:115]
	v_mfma_f32_16x16x32_f16 v[108:111], v[194:197], v[162:165], v[108:111]
	v_mfma_f32_16x16x32_f16 v[104:107], v[202:205], v[138:141], v[104:107]
	v_mfma_f32_16x16x32_f16 v[100:103], v[202:205], v[162:165], v[100:103]
	v_mfma_f32_16x16x32_f16 v[132:135], v[190:193], v[174:177], v[116:119]
	v_mfma_f32_16x16x32_f16 v[170:173], v[198:201], v[174:177], v[108:111]
	v_mfma_f32_16x16x32_f16 v[210:213], v[206:209], v[142:145], v[104:107]
	v_mfma_f32_16x16x32_f16 v[214:217], v[206:209], v[174:177], v[100:103]
	s_barrier
	s_nop 1
	ds_read_b128 v[100:103], v168
	ds_read_b128 v[104:107], v168 offset:1024
	ds_read_b128 v[108:111], v168 offset:2048
	ds_read_b128 v[116:119], v168 offset:3072
	s_barrier
	s_waitcnt lgkmcnt(0)
	s_waitcnt lgkmcnt(0)
	v_mfma_f32_16x16x32_f16 v[80:83], v[194:197], v[100:103], v[80:83]
	v_mfma_f32_16x16x32_f16 v[76:79], v[194:197], v[108:111], v[76:79]
	v_mfma_f32_16x16x32_f16 v[72:75], v[202:205], v[100:103], v[72:75]
	v_mfma_f32_16x16x32_f16 v[68:71], v[202:205], v[108:111], v[68:71]
	v_mfma_f32_16x16x32_f16 v[96:99], v[178:181], v[100:103], v[96:99]
	v_mfma_f32_16x16x32_f16 v[92:95], v[178:181], v[108:111], v[92:95]
	v_mfma_f32_16x16x32_f16 v[88:91], v[186:189], v[100:103], v[88:91]
	v_mfma_f32_16x16x32_f16 v[84:87], v[186:189], v[108:111], v[84:87]
	v_mfma_f32_16x16x32_f16 v[80:83], v[198:201], v[104:107], v[80:83]
	v_mfma_f32_16x16x32_f16 v[76:79], v[198:201], v[116:119], v[76:79]
	v_mfma_f32_16x16x32_f16 v[72:75], v[206:209], v[104:107], v[72:75]
	v_mfma_f32_16x16x32_f16 v[68:71], v[206:209], v[116:119], v[68:71]
	v_mfma_f32_16x16x32_f16 v[166:169], v[182:185], v[104:107], v[96:99]
	v_mfma_f32_16x16x32_f16 v[178:181], v[182:185], v[116:119], v[92:95]
	v_mfma_f32_16x16x32_f16 v[182:185], v[190:193], v[104:107], v[88:91]
	v_mfma_f32_16x16x32_f16 v[186:189], v[190:193], v[116:119], v[84:87]
	s_barrier
; #define LDA8(dst, b, h) _Pragma("unroll") for (int m = 0; m < 4; ++m) _Pragma("unroll") for (int k = 0; k < 2; ++k) \
;     dst[m][k] = *(const bf16x8*)((const char*)SA8(b, h) + lds_byte8(wr * 64 + m * 16 + fr, k * 32 + fq * 8))
; #define LDB8(dst, b, h) _Pragma("unroll") for (int n = 0; n < 2; ++n) _Pragma("unroll") for (int k = 0; k < 2; ++k) \
;     dst[n][k] = *(const bf16x8*)((const char*)SB8(b, h) + lds_byte8(wc * 32 + n * 16 + fr, k * 32 + fq * 8))
; #define WAIT_V8(n) asm volatile("s_waitcnt vmcnt(" #n ")" ::: "memory")
; #define WAIT_L8(n) asm volatile("s_waitcnt lgkmcnt(" #n ")" ::: "memory")
; #define BAR8 __builtin_amdgcn_s_barrier()
;     ...
;     LDA8(At, 0, 1); WAIT_V8(4); BAR8; WAIT_L8(0); MMA8(1, 0, At, B0); MMA8(1, 1, At, B1); BAR8; }
;   { LDB8(B0, 1, 0); LDA8(At, 1, 0); WAIT_V8(2); BAR8; WAIT_L8(0); MMA8(0, 0, At, B0); BAR8;
	s_nop 0
	ds_read_b128 v[84:87], v156 offset:16384
	ds_read_b128 v[88:91], v156 offset:17408
	ds_read_b128 v[92:95], v155 offset:16384
	ds_read_b128 v[96:99], v155 offset:17408
	ds_read_b128 v[190:193], v154 offset:16384
	ds_read_b128 v[194:197], v154 offset:17408
	ds_read_b128 v[198:201], v153 offset:16384
	ds_read_b128 v[202:205], v153 offset:17408
	s_waitcnt vmcnt(4)
	s_barrier
	s_waitcnt lgkmcnt(0)
	s_waitcnt lgkmcnt(0)
	v_mfma_f32_16x16x32_f16 v[64:67], v[84:87], v[138:141], v[64:67]
	v_mfma_f32_16x16x32_f16 v[60:63], v[84:87], v[162:165], v[60:63]
	v_mfma_f32_16x16x32_f16 v[56:59], v[92:95], v[138:141], v[56:59]
	v_mfma_f32_16x16x32_f16 v[52:55], v[92:95], v[162:165], v[52:55]
	v_mfma_f32_16x16x32_f16 v[48:51], v[190:193], v[138:141], v[48:51]
	v_mfma_f32_16x16x32_f16 v[44:47], v[190:193], v[162:165], v[44:47]
	v_mfma_f32_16x16x32_f16 v[40:43], v[198:201], v[138:141], v[40:43]
	v_mfma_f32_16x16x32_f16 v[36:39], v[198:201], v[162:165], v[36:39]
	v_mfma_f32_16x16x32_f16 v[64:67], v[88:91], v[142:145], v[64:67]
	v_mfma_f32_16x16x32_f16 v[60:63], v[88:91], v[174:177], v[60:63]
	v_mfma_f32_16x16x32_f16 v[56:59], v[96:99], v[142:145], v[56:59]
	v_mfma_f32_16x16x32_f16 v[52:55], v[96:99], v[174:177], v[52:55]
	v_mfma_f32_16x16x32_f16 v[48:51], v[194:197], v[142:145], v[48:51]
	v_mfma_f32_16x16x32_f16 v[44:47], v[194:197], v[174:177], v[44:47]
	v_mfma_f32_16x16x32_f16 v[40:43], v[202:205], v[142:145], v[40:43]
	v_mfma_f32_16x16x32_f16 v[36:39], v[202:205], v[174:177], v[36:39]
	v_mfma_f32_16x16x32_f16 v[32:35], v[84:87], v[100:103], v[32:35]
	v_mfma_f32_16x16x32_f16 v[28:31], v[84:87], v[108:111], v[28:31]
	v_mfma_f32_16x16x32_f16 v[24:27], v[92:95], v[100:103], v[24:27]
	v_mfma_f32_16x16x32_f16 v[20:23], v[92:95], v[108:111], v[20:23]
	v_mfma_f32_16x16x32_f16 v[16:19], v[190:193], v[100:103], v[16:19]
	v_mfma_f32_16x16x32_f16 v[12:15], v[190:193], v[108:111], v[12:15]
	v_mfma_f32_16x16x32_f16 v[8:11], v[198:201], v[100:103], v[8:11]
	v_mfma_f32_16x16x32_f16 v[4:7], v[198:201], v[108:111], v[4:7]
	v_mfma_f32_16x16x32_f16 v[136:139], v[88:91], v[104:107], v[32:35]
	v_mfma_f32_16x16x32_f16 v[140:143], v[88:91], v[116:119], v[28:31]
	v_mfma_f32_16x16x32_f16 v[162:165], v[96:99], v[104:107], v[24:27]
	v_mfma_f32_16x16x32_f16 v[174:177], v[96:99], v[116:119], v[20:23]
	v_mfma_f32_16x16x32_f16 v[206:209], v[194:197], v[104:107], v[16:19]
	v_mfma_f32_16x16x32_f16 v[190:193], v[194:197], v[116:119], v[12:15]
	v_mfma_f32_16x16x32_f16 v[194:197], v[202:205], v[104:107], v[8:11]
	v_mfma_f32_16x16x32_f16 v[198:201], v[202:205], v[116:119], v[4:7]
	s_barrier
	ds_read_b128 v[202:205], v161
	ds_read_b128 v[218:221], v161 offset:1024
	ds_read_b128 v[226:229], v161 offset:2048
	ds_read_b128 v[230:233], v161 offset:3072
	ds_read_b128 v[8:11], v156 offset:32768
	ds_read_b128 v[12:15], v156 offset:33792
	ds_read_b128 v[16:19], v155 offset:32768
	ds_read_b128 v[24:27], v155 offset:33792
	ds_read_b128 v[28:31], v154 offset:32768
	ds_read_b128 v[32:35], v154 offset:33792
	ds_read_b128 v[238:241], v153 offset:32768
	ds_read_b128 v[242:245], v153 offset:33792
	s_waitcnt vmcnt(2)
	s_barrier
	s_waitcnt lgkmcnt(0)
	s_waitcnt lgkmcnt(0)
	v_mfma_f32_16x16x32_f16 v[4:7], v[8:11], v[202:205], v[128:131]
	v_mfma_f32_16x16x32_f16 v[104:107], v[12:15], v[218:221], v[4:7]
	v_mfma_f32_16x16x32_f16 v[4:7], v[8:11], v[226:229], v[124:127]
	v_mfma_f32_16x16x32_f16 v[116:119], v[12:15], v[230:233], v[4:7]
	v_mfma_f32_16x16x32_f16 v[4:7], v[16:19], v[202:205], v[120:123]
	v_mfma_f32_16x16x32_f16 v[100:103], v[24:27], v[218:221], v[4:7]
	v_mfma_f32_16x16x32_f16 v[4:7], v[16:19], v[226:229], v[132:135]
	v_mfma_f32_16x16x32_f16 v[108:111], v[24:27], v[230:233], v[4:7]
	v_mfma_f32_16x16x32_f16 v[4:7], v[28:31], v[202:205], v[112:115]
	v_mfma_f32_16x16x32_f16 v[92:95], v[32:35], v[218:221], v[4:7]
	v_mfma_f32_16x16x32_f16 v[4:7], v[28:31], v[226:229], v[170:173]
	v_mfma_f32_16x16x32_f16 v[96:99], v[32:35], v[230:233], v[4:7]
	v_mfma_f32_16x16x32_f16 v[4:7], v[238:241], v[202:205], v[210:213]
	v_mfma_f32_16x16x32_f16 v[84:87], v[242:245], v[218:221], v[4:7]
	v_mfma_f32_16x16x32_f16 v[4:7], v[238:241], v[226:229], v[214:217]
	v_mfma_f32_16x16x32_f16 v[88:91], v[242:245], v[230:233], v[4:7]
	s_barrier
; DI int tid_opaque() { int t = threadIdx.x; asm volatile("" : "+v"(t)); return t; }
; #define LDA8(dst, b, h) _Pragma("unroll") for (int m = 0; m < 4; ++m) _Pragma("unroll") for (int k = 0; k < 2; ++k) \
;     dst[m][k] = *(const bf16x8*)((const char*)SA8(b, h) + lds_byte8(wr * 64 + m * 16 + fr, k * 32 + fq * 8))
; #define LDB8(dst, b, h) _Pragma("unroll") for (int n = 0; n < 2; ++n) _Pragma("unroll") for (int k = 0; k < 2; ++k) \
;     dst[n][k] = *(const bf16x8*)((const char*)SB8(b, h) + lds_byte8(wc * 32 + n * 16 + fr, k * 32 + fq * 8))
; #define WAIT_V8(n) asm volatile("s_waitcnt vmcnt(" #n ")" ::: "memory")
; #define WAIT_L8(n) asm volatile("s_waitcnt lgkmcnt(" #n ")" ::: "memory")
; #define BAR8 __builtin_amdgcn_s_barrier()
;     ...
;     LDB8(B1, 1, 1); WAIT_V8(0); BAR8; WAIT_L8(0); MMA8(0, 1, At, B1); BAR8;
;     LDA8(At, 1, 1); BAR8; WAIT_L8(0); MMA8(1, 0, At, B0); MMA8(1, 1, At, B1); BAR8; }
;   if (wr == 0) BAR8;
;   __syncthreads();
;   if (EPI == EPI_GU && nm0 >= 0) {
;     const int t = tid_opaque();
;     STAGE8(SB8(0, 0), Bt, K, nn0, 0); STAGE8(SA8(0, 0), A, lda, nm0, 0);
;     STAGE8(SB8(0, 1), Bt, K, nn0 + 128, 0); STAGE8(SA8(0, 1), A, lda, nm0 + 128, 0);
;   }
;     ...
;   if (t < 256) {
	ds_read_b128 v[132:135], v158
	ds_read_b128 v[170:173], v158 offset:1024
	ds_read_b128 v[210:213], v158 offset:2048
	ds_read_b128 v[158:161], v158 offset:3072
	s_waitcnt vmcnt(0)
	s_barrier
	s_waitcnt lgkmcnt(0)
	s_waitcnt lgkmcnt(0)
	v_mfma_f32_16x16x32_f16 v[4:7], v[8:11], v[132:135], v[166:169]
	v_mfma_f32_16x16x32_f16 v[8:11], v[8:11], v[210:213], v[178:181]
	v_mfma_f32_16x16x32_f16 v[4:7], v[12:15], v[170:173], v[4:7]
	v_mfma_f32_16x16x32_f16 v[20:23], v[12:15], v[158:161], v[8:11]
	v_mfma_f32_16x16x32_f16 v[8:11], v[16:19], v[132:135], v[182:185]
	v_mfma_f32_16x16x32_f16 v[12:15], v[16:19], v[210:213], v[186:189]
	v_mfma_f32_16x16x32_f16 v[8:11], v[24:27], v[170:173], v[8:11]
	v_mfma_f32_16x16x32_f16 v[24:27], v[24:27], v[158:161], v[12:15]
	v_mfma_f32_16x16x32_f16 v[12:15], v[28:31], v[132:135], v[80:83]
	v_mfma_f32_16x16x32_f16 v[16:19], v[28:31], v[210:213], v[76:79]
	v_mfma_f32_16x16x32_f16 v[12:15], v[32:35], v[170:173], v[12:15]
	v_mfma_f32_16x16x32_f16 v[28:31], v[32:35], v[158:161], v[16:19]
	v_mfma_f32_16x16x32_f16 v[16:19], v[238:241], v[132:135], v[72:75]
	v_mfma_f32_16x16x32_f16 v[32:35], v[238:241], v[210:213], v[68:71]
	v_mfma_f32_16x16x32_f16 v[16:19], v[242:245], v[170:173], v[16:19]
	v_mfma_f32_16x16x32_f16 v[32:35], v[242:245], v[158:161], v[32:35]
	s_barrier
	ds_read_b128 v[166:169], v156 offset:49152
	ds_read_b128 v[178:181], v156 offset:50176
	ds_read_b128 v[182:185], v155 offset:49152
	ds_read_b128 v[186:189], v155 offset:50176
	ds_read_b128 v[214:217], v154 offset:49152
	ds_read_b128 v[154:157], v154 offset:50176
	ds_read_b128 v[238:241], v153 offset:49152
	ds_read_b128 v[150:153], v153 offset:50176
	s_barrier
	s_waitcnt lgkmcnt(0)
	s_waitcnt lgkmcnt(0)
	v_mfma_f32_16x16x32_f16 v[64:67], v[166:169], v[202:205], v[64:67]
	v_mfma_f32_16x16x32_f16 v[60:63], v[166:169], v[226:229], v[60:63]
	v_mfma_f32_16x16x32_f16 v[56:59], v[182:185], v[202:205], v[56:59]
	v_mfma_f32_16x16x32_f16 v[52:55], v[182:185], v[226:229], v[52:55]
	v_mfma_f32_16x16x32_f16 v[48:51], v[214:217], v[202:205], v[48:51]
	v_mfma_f32_16x16x32_f16 v[44:47], v[214:217], v[226:229], v[44:47]
	v_mfma_f32_16x16x32_f16 v[40:43], v[238:241], v[202:205], v[40:43]
	v_mfma_f32_16x16x32_f16 v[36:39], v[238:241], v[226:229], v[36:39]
	v_mfma_f32_16x16x32_f16 v[128:131], v[178:181], v[218:221], v[64:67]
	v_mfma_f32_16x16x32_f16 v[124:127], v[178:181], v[230:233], v[60:63]
	v_mfma_f32_16x16x32_f16 v[120:123], v[186:189], v[218:221], v[56:59]
	v_mfma_f32_16x16x32_f16 v[112:115], v[186:189], v[230:233], v[52:55]
	v_mfma_f32_16x16x32_f16 v[80:83], v[154:157], v[218:221], v[48:51]
	v_mfma_f32_16x16x32_f16 v[76:79], v[154:157], v[230:233], v[44:47]
	v_mfma_f32_16x16x32_f16 v[72:75], v[150:153], v[218:221], v[40:43]
	v_mfma_f32_16x16x32_f16 v[68:71], v[150:153], v[230:233], v[36:39]
	v_mfma_f32_16x16x32_f16 v[36:39], v[166:169], v[132:135], v[136:139]
	v_mfma_f32_16x16x32_f16 v[64:67], v[178:181], v[170:173], v[36:39]
	v_mfma_f32_16x16x32_f16 v[36:39], v[166:169], v[210:213], v[140:143]
	v_mfma_f32_16x16x32_f16 v[60:63], v[178:181], v[158:161], v[36:39]
	v_mfma_f32_16x16x32_f16 v[36:39], v[182:185], v[132:135], v[162:165]
	v_mfma_f32_16x16x32_f16 v[56:59], v[186:189], v[170:173], v[36:39]
	v_mfma_f32_16x16x32_f16 v[36:39], v[182:185], v[210:213], v[174:177]
	v_mfma_f32_16x16x32_f16 v[52:55], v[186:189], v[158:161], v[36:39]
	v_mfma_f32_16x16x32_f16 v[36:39], v[214:217], v[132:135], v[206:209]
	v_mfma_f32_16x16x32_f16 v[48:51], v[154:157], v[170:173], v[36:39]
	v_mfma_f32_16x16x32_f16 v[36:39], v[214:217], v[210:213], v[190:193]
	v_mfma_f32_16x16x32_f16 v[44:47], v[154:157], v[158:161], v[36:39]
	v_mfma_f32_16x16x32_f16 v[36:39], v[238:241], v[132:135], v[194:197]
	v_mfma_f32_16x16x32_f16 v[40:43], v[150:153], v[170:173], v[36:39]
	v_mfma_f32_16x16x32_f16 v[36:39], v[238:241], v[210:213], v[198:201]
	v_mfma_f32_16x16x32_f16 v[36:39], v[150:153], v[158:161], v[36:39]
	s_movk_i32 s8, 0x100
	v_cmp_gt_u32_e32 vcc, s8, v3
	s_barrier
	s_and_saveexec_b64 s[8:9], vcc
	s_cbranch_execz .LBB0_1018
	s_barrier

; #define LDA8(dst, b, h) _Pragma("unroll") for (int m = 0; m < 4; ++m) _Pragma("unroll") for (int k = 0; k < 2; ++k) \
;     dst[m][k] = *(const bf16x8*)((const char*)SA8(b, h) + lds_byte8(wr * 64 + m * 16 + fr, k * 32 + fq * 8))
; #define LDB8(dst, b, h) _Pragma("unroll") for (int n = 0; n < 2; ++n) _Pragma("unroll") for (int k = 0; k < 2; ++k) \
;     dst[n][k] = *(const bf16x8*)((const char*)SB8(b, h) + lds_byte8(wc * 32 + n * 16 + fr, k * 32 + fq * 8))
; #define WAIT_L8(n) asm volatile("s_waitcnt lgkmcnt(" #n ")" ::: "memory")
; #define BAR8 __builtin_amdgcn_s_barrier()
; #define SCHED8 __builtin_amdgcn_sched_barrier(0)
;     ...
;   for (int tt = 0; tt < nt - 2; tt += 2) {
;     LDB8(B0, 0, 0); SCHED8; LDA8(At, 0, 0); STAGE8(SA8(1, 1), A, lda, brow + 128, tt + 1);
;     WAIT_L8(8); BAR8; WAIT_L8(0); MMA8(0, 0, At, B0); BAR8; SCHED8;
;     LDB8(B1, 0, 1); STAGE8(SB8(0, 0), Bt, K, bcol, tt + 2);
;     BAR8; WAIT_L8(0); MMA8(0, 1, At, B1); BAR8;
;     LDA8(At, 0, 1); STAGE8(SA8(0, 0), A, lda, brow, tt + 2);
;     BAR8; WAIT_L8(0); MMA8(1, 0, At, B0); BAR8; SCHED8;
.LBB0_1152:
	ds_read_b128 v[174:177], v171
	ds_read_b128 v[178:181], v171 offset:1024
	ds_read_b128 v[182:185], v171 offset:2048
	ds_read_b128 v[186:189], v171 offset:3072
	v_add_u32_e32 v172, 0xc000, v150
	v_lshl_add_u64 v[222:223], v[142:143], 0, s[12:13]
	v_readfirstlane_b32 s31, v172
	v_add_u32_e32 v173, 0xe000, v150
	v_lshl_add_u64 v[226:227], v[222:223], 0, s[36:37]
	s_mov_b32 m0, s31
	v_lshl_add_u64 v[236:237], v[144:145], 0, s[12:13]
	v_readfirstlane_b32 s31, v173
	ds_read_b128 v[190:193], v156
	ds_read_b128 v[194:197], v156 offset:1024
	ds_read_b128 v[198:201], v155
	ds_read_b128 v[202:205], v155 offset:1024
	ds_read_b128 v[206:209], v154
	ds_read_b128 v[210:213], v154 offset:1024
	ds_read_b128 v[214:217], v153
	ds_read_b128 v[218:221], v153 offset:1024
	global_load_lds_dwordx4 v[226:227], off
	v_lshl_add_u64 v[226:227], v[236:237], 0, s[36:37]
	s_mov_b32 m0, s31
	s_nop 0
	global_load_lds_dwordx4 v[226:227], off
	s_waitcnt lgkmcnt(8)
	s_barrier
	s_waitcnt lgkmcnt(0)
	s_waitcnt lgkmcnt(0)
	v_mfma_f32_16x16x32_bf16 v[128:131], v[190:193], v[174:177], v[128:131]
	v_mfma_f32_16x16x32_bf16 v[124:127], v[190:193], v[182:185], v[124:127]
	v_mfma_f32_16x16x32_bf16 v[120:123], v[198:201], v[174:177], v[120:123]
	v_mfma_f32_16x16x32_bf16 v[116:119], v[198:201], v[182:185], v[116:119]
	v_mfma_f32_16x16x32_bf16 v[112:115], v[206:209], v[174:177], v[112:115]
	v_mfma_f32_16x16x32_bf16 v[108:111], v[206:209], v[182:185], v[108:111]
	v_mfma_f32_16x16x32_bf16 v[104:107], v[214:217], v[174:177], v[104:107]
	v_mfma_f32_16x16x32_bf16 v[100:103], v[214:217], v[182:185], v[100:103]
	v_mfma_f32_16x16x32_bf16 v[128:131], v[194:197], v[178:181], v[128:131]
	v_mfma_f32_16x16x32_bf16 v[124:127], v[194:197], v[186:189], v[124:127]
	v_mfma_f32_16x16x32_bf16 v[120:123], v[202:205], v[178:181], v[120:123]
	v_mfma_f32_16x16x32_bf16 v[116:119], v[202:205], v[186:189], v[116:119]
	v_mfma_f32_16x16x32_bf16 v[112:115], v[210:213], v[178:181], v[112:115]
	v_mfma_f32_16x16x32_bf16 v[108:111], v[210:213], v[186:189], v[108:111]
	v_mfma_f32_16x16x32_bf16 v[104:107], v[218:221], v[178:181], v[104:107]
	v_mfma_f32_16x16x32_bf16 v[100:103], v[218:221], v[186:189], v[100:103]
	s_barrier
	v_lshl_add_u64 v[246:247], v[138:139], 0, s[12:13]
	v_readfirstlane_b32 s31, v151
	v_lshl_add_u64 v[248:249], v[246:247], 0, s[38:39]
	s_mov_b32 m0, s31
	ds_read_b128 v[226:229], v167
	ds_read_b128 v[230:233], v167 offset:1024
	ds_read_b128 v[238:241], v167 offset:2048
	ds_read_b128 v[242:245], v167 offset:3072
	global_load_lds_dwordx4 v[248:249], off
	v_lshl_add_u64 v[248:249], v[140:141], 0, s[12:13]
	v_readfirstlane_b32 s31, v157
	v_lshl_add_u64 v[250:251], v[248:249], 0, s[38:39]
	s_mov_b32 m0, s31
	s_nop 0
	global_load_lds_dwordx4 v[250:251], off
	s_barrier
	s_waitcnt lgkmcnt(0)
	s_waitcnt lgkmcnt(0)
	v_mfma_f32_16x16x32_bf16 v[96:99], v[190:193], v[226:229], v[96:99]
	v_mfma_f32_16x16x32_bf16 v[92:95], v[190:193], v[238:241], v[92:95]
	v_mfma_f32_16x16x32_bf16 v[88:91], v[198:201], v[226:229], v[88:91]
	v_mfma_f32_16x16x32_bf16 v[84:87], v[198:201], v[238:241], v[84:87]
	v_mfma_f32_16x16x32_bf16 v[80:83], v[206:209], v[226:229], v[80:83]
	v_mfma_f32_16x16x32_bf16 v[76:79], v[206:209], v[238:241], v[76:79]
	v_mfma_f32_16x16x32_bf16 v[72:75], v[214:217], v[226:229], v[72:75]
	v_mfma_f32_16x16x32_bf16 v[68:71], v[214:217], v[238:241], v[68:71]
	v_mfma_f32_16x16x32_bf16 v[96:99], v[194:197], v[230:233], v[96:99]
	v_mfma_f32_16x16x32_bf16 v[92:95], v[194:197], v[242:245], v[92:95]
	v_mfma_f32_16x16x32_bf16 v[88:91], v[202:205], v[230:233], v[88:91]
	v_mfma_f32_16x16x32_bf16 v[84:87], v[202:205], v[242:245], v[84:87]
	v_mfma_f32_16x16x32_bf16 v[80:83], v[210:213], v[230:233], v[80:83]
	v_mfma_f32_16x16x32_bf16 v[76:79], v[210:213], v[242:245], v[76:79]
	v_mfma_f32_16x16x32_bf16 v[72:75], v[218:221], v[230:233], v[72:75]
	v_mfma_f32_16x16x32_bf16 v[68:71], v[218:221], v[242:245], v[68:71]
	v_readfirstlane_b32 s31, v150
	v_lshl_add_u64 v[250:251], v[222:223], 0, s[40:41]
	s_mov_b32 m0, s31
	v_readfirstlane_b32 s31, v152
	s_barrier
	ds_read_b128 v[190:193], v156 offset:16384
	ds_read_b128 v[194:197], v156 offset:17408
	ds_read_b128 v[198:201], v155 offset:16384
	ds_read_b128 v[202:205], v155 offset:17408
	ds_read_b128 v[206:209], v154 offset:16384
	ds_read_b128 v[210:213], v154 offset:17408
	ds_read_b128 v[214:217], v153 offset:16384
	ds_read_b128 v[218:221], v153 offset:17408
	global_load_lds_dwordx4 v[250:251], off
	v_lshl_add_u64 v[250:251], v[236:237], 0, s[40:41]
	s_mov_b32 m0, s31
	s_nop 0
	global_load_lds_dwordx4 v[250:251], off
	s_barrier
	s_waitcnt lgkmcnt(0)
	s_waitcnt lgkmcnt(0)
	v_mfma_f32_16x16x32_bf16 v[64:67], v[190:193], v[174:177], v[64:67]
	v_mfma_f32_16x16x32_bf16 v[60:63], v[190:193], v[182:185], v[60:63]
	v_mfma_f32_16x16x32_bf16 v[56:59], v[198:201], v[174:177], v[56:59]
	v_mfma_f32_16x16x32_bf16 v[52:55], v[198:201], v[182:185], v[52:55]
	v_mfma_f32_16x16x32_bf16 v[48:51], v[206:209], v[174:177], v[48:51]
	v_mfma_f32_16x16x32_bf16 v[44:47], v[206:209], v[182:185], v[44:47]
	v_mfma_f32_16x16x32_bf16 v[40:43], v[214:217], v[174:177], v[40:43]
	v_mfma_f32_16x16x32_bf16 v[36:39], v[214:217], v[182:185], v[36:39]
	v_mfma_f32_16x16x32_bf16 v[64:67], v[194:197], v[178:181], v[64:67]
	v_mfma_f32_16x16x32_bf16 v[60:63], v[194:197], v[186:189], v[60:63]
	v_mfma_f32_16x16x32_bf16 v[56:59], v[202:205], v[178:181], v[56:59]
	v_mfma_f32_16x16x32_bf16 v[52:55], v[202:205], v[186:189], v[52:55]
	v_mfma_f32_16x16x32_bf16 v[48:51], v[210:213], v[178:181], v[48:51]
	v_mfma_f32_16x16x32_bf16 v[44:47], v[210:213], v[186:189], v[44:47]
	v_mfma_f32_16x16x32_bf16 v[40:43], v[218:221], v[178:181], v[40:43]
	v_mfma_f32_16x16x32_bf16 v[36:39], v[218:221], v[186:189], v[36:39]
	s_barrier
; #define LDA8(dst, b, h) _Pragma("unroll") for (int m = 0; m < 4; ++m) _Pragma("unroll") for (int k = 0; k < 2; ++k) \
;     dst[m][k] = *(const bf16x8*)((const char*)SA8(b, h) + lds_byte8(wr * 64 + m * 16 + fr, k * 32 + fq * 8))
; #define LDB8(dst, b, h) _Pragma("unroll") for (int n = 0; n < 2; ++n) _Pragma("unroll") for (int k = 0; k < 2; ++k) \
;     dst[n][k] = *(const bf16x8*)((const char*)SB8(b, h) + lds_byte8(wc * 32 + n * 16 + fr, k * 32 + fq * 8))
; #define WAIT_V8(n) asm volatile("s_waitcnt vmcnt(" #n ")" ::: "memory")
; #define WAIT_L8(n) asm volatile("s_waitcnt lgkmcnt(" #n ")" ::: "memory")
; #define BAR8 __builtin_amdgcn_s_barrier()
; #define SCHED8 __builtin_amdgcn_sched_barrier(0)
;     ...
;     STAGE8(SB8(0, 1), Bt, K, bcol + 128, tt + 2);
;     WAIT_V8(6); BAR8; MMA8(1, 1, At, B1); BAR8;
;     LDB8(B0, 1, 0); SCHED8; LDA8(At, 1, 0); STAGE8(SA8(0, 1), A, lda, brow + 128, tt + 2);
;     WAIT_L8(8); BAR8; WAIT_L8(0); MMA8(0, 0, At, B0); BAR8; SCHED8;
;     LDB8(B1, 1, 1); STAGE8(SB8(1, 0), Bt, K, bcol, tt + 3);
;     BAR8; WAIT_L8(0); MMA8(0, 1, At, B1); BAR8;
;     LDA8(At, 1, 1); STAGE8(SA8(1, 0), A, lda, brow, tt + 3);
	v_readfirstlane_b32 s31, v159
	v_lshl_add_u64 v[174:175], v[246:247], 0, s[42:43]
	s_mov_b32 m0, s31
	v_readfirstlane_b32 s31, v161
	global_load_lds_dwordx4 v[174:175], off
	v_lshl_add_u64 v[174:175], v[248:249], 0, s[42:43]
	s_mov_b32 m0, s31
	s_nop 0
	global_load_lds_dwordx4 v[174:175], off
	s_waitcnt vmcnt(6)
	s_barrier
	v_mfma_f32_16x16x32_bf16 v[32:35], v[190:193], v[226:229], v[32:35]
	v_mfma_f32_16x16x32_bf16 v[28:31], v[190:193], v[238:241], v[28:31]
	v_mfma_f32_16x16x32_bf16 v[24:27], v[198:201], v[226:229], v[24:27]
	v_mfma_f32_16x16x32_bf16 v[20:23], v[198:201], v[238:241], v[20:23]
	v_mfma_f32_16x16x32_bf16 v[16:19], v[206:209], v[226:229], v[16:19]
	v_mfma_f32_16x16x32_bf16 v[12:15], v[206:209], v[238:241], v[12:15]
	v_mfma_f32_16x16x32_bf16 v[8:11], v[214:217], v[226:229], v[8:11]
	v_mfma_f32_16x16x32_bf16 v[4:7], v[214:217], v[238:241], v[4:7]
	v_mfma_f32_16x16x32_bf16 v[32:35], v[194:197], v[230:233], v[32:35]
	v_mfma_f32_16x16x32_bf16 v[28:31], v[194:197], v[242:245], v[28:31]
	v_mfma_f32_16x16x32_bf16 v[24:27], v[202:205], v[230:233], v[24:27]
	v_mfma_f32_16x16x32_bf16 v[20:23], v[202:205], v[242:245], v[20:23]
	v_mfma_f32_16x16x32_bf16 v[16:19], v[210:213], v[230:233], v[16:19]
	v_mfma_f32_16x16x32_bf16 v[12:15], v[210:213], v[242:245], v[12:15]
	v_mfma_f32_16x16x32_bf16 v[8:11], v[218:221], v[230:233], v[8:11]
	v_mfma_f32_16x16x32_bf16 v[4:7], v[218:221], v[242:245], v[4:7]
	s_barrier
	ds_read_b128 v[174:177], v160
	ds_read_b128 v[178:181], v160 offset:1024
	ds_read_b128 v[182:185], v160 offset:2048
	ds_read_b128 v[186:189], v160 offset:3072
	v_readfirstlane_b32 s31, v162
	v_lshl_add_u64 v[226:227], v[222:223], 0, s[44:45]
	s_mov_b32 m0, s31
	v_readfirstlane_b32 s31, v163
	ds_read_b128 v[190:193], v156 offset:32768
	ds_read_b128 v[194:197], v156 offset:33792
	ds_read_b128 v[198:201], v155 offset:32768
	ds_read_b128 v[202:205], v155 offset:33792
	ds_read_b128 v[206:209], v154 offset:32768
	ds_read_b128 v[210:213], v154 offset:33792
	ds_read_b128 v[214:217], v153 offset:32768
	ds_read_b128 v[218:221], v153 offset:33792
	global_load_lds_dwordx4 v[226:227], off
	v_lshl_add_u64 v[226:227], v[236:237], 0, s[44:45]
	s_mov_b32 m0, s31
	s_nop 0
	global_load_lds_dwordx4 v[226:227], off
	s_waitcnt lgkmcnt(8)
	s_barrier
	s_waitcnt lgkmcnt(0)
	s_waitcnt lgkmcnt(0)
	v_mfma_f32_16x16x32_bf16 v[128:131], v[190:193], v[174:177], v[128:131]
	v_mfma_f32_16x16x32_bf16 v[124:127], v[190:193], v[182:185], v[124:127]
	v_mfma_f32_16x16x32_bf16 v[120:123], v[198:201], v[174:177], v[120:123]
	v_mfma_f32_16x16x32_bf16 v[116:119], v[198:201], v[182:185], v[116:119]
	v_mfma_f32_16x16x32_bf16 v[112:115], v[206:209], v[174:177], v[112:115]
	v_mfma_f32_16x16x32_bf16 v[108:111], v[206:209], v[182:185], v[108:111]
	v_mfma_f32_16x16x32_bf16 v[104:107], v[214:217], v[174:177], v[104:107]
	v_mfma_f32_16x16x32_bf16 v[100:103], v[214:217], v[182:185], v[100:103]
	v_mfma_f32_16x16x32_bf16 v[128:131], v[194:197], v[178:181], v[128:131]
	v_mfma_f32_16x16x32_bf16 v[124:127], v[194:197], v[186:189], v[124:127]
	v_mfma_f32_16x16x32_bf16 v[120:123], v[202:205], v[178:181], v[120:123]
	v_mfma_f32_16x16x32_bf16 v[116:119], v[202:205], v[186:189], v[116:119]
	v_mfma_f32_16x16x32_bf16 v[112:115], v[210:213], v[178:181], v[112:115]
	v_mfma_f32_16x16x32_bf16 v[108:111], v[210:213], v[186:189], v[108:111]
	v_mfma_f32_16x16x32_bf16 v[104:107], v[218:221], v[178:181], v[104:107]
	v_mfma_f32_16x16x32_bf16 v[100:103], v[218:221], v[186:189], v[100:103]
	s_barrier
	v_readfirstlane_b32 s31, v164
	v_lshl_add_u64 v[250:251], v[246:247], 0, s[46:47]
	s_mov_b32 m0, s31
	v_readfirstlane_b32 s31, v165
	ds_read_b128 v[226:229], v158
	ds_read_b128 v[230:233], v158 offset:1024
	ds_read_b128 v[238:241], v158 offset:2048
	ds_read_b128 v[242:245], v158 offset:3072
	global_load_lds_dwordx4 v[250:251], off
	v_lshl_add_u64 v[250:251], v[248:249], 0, s[46:47]
	s_mov_b32 m0, s31
	s_nop 0
	global_load_lds_dwordx4 v[250:251], off
	s_barrier
	s_waitcnt lgkmcnt(0)
	s_waitcnt lgkmcnt(0)
	v_mfma_f32_16x16x32_bf16 v[96:99], v[190:193], v[226:229], v[96:99]
	v_mfma_f32_16x16x32_bf16 v[92:95], v[190:193], v[238:241], v[92:95]
	v_mfma_f32_16x16x32_bf16 v[88:91], v[198:201], v[226:229], v[88:91]
	v_mfma_f32_16x16x32_bf16 v[84:87], v[198:201], v[238:241], v[84:87]
	v_mfma_f32_16x16x32_bf16 v[80:83], v[206:209], v[226:229], v[80:83]
	v_mfma_f32_16x16x32_bf16 v[76:79], v[206:209], v[238:241], v[76:79]
	v_mfma_f32_16x16x32_bf16 v[72:75], v[214:217], v[226:229], v[72:75]
	v_mfma_f32_16x16x32_bf16 v[68:71], v[214:217], v[238:241], v[68:71]
	v_mfma_f32_16x16x32_bf16 v[96:99], v[194:197], v[230:233], v[96:99]
	v_mfma_f32_16x16x32_bf16 v[92:95], v[194:197], v[242:245], v[92:95]
	v_mfma_f32_16x16x32_bf16 v[88:91], v[202:205], v[230:233], v[88:91]
	v_mfma_f32_16x16x32_bf16 v[84:87], v[202:205], v[242:245], v[84:87]
	v_mfma_f32_16x16x32_bf16 v[80:83], v[210:213], v[230:233], v[80:83]
	v_mfma_f32_16x16x32_bf16 v[76:79], v[210:213], v[242:245], v[76:79]
	v_mfma_f32_16x16x32_bf16 v[72:75], v[218:221], v[230:233], v[72:75]
	v_mfma_f32_16x16x32_bf16 v[68:71], v[218:221], v[242:245], v[68:71]
	v_readfirstlane_b32 s31, v166
	v_lshl_add_u64 v[222:223], v[222:223], 0, s[48:49]
	s_mov_b32 m0, s31
	v_readfirstlane_b32 s31, v168
	s_barrier
	ds_read_b128 v[190:193], v156 offset:49152
	ds_read_b128 v[194:197], v156 offset:50176
	ds_read_b128 v[198:201], v155 offset:49152
	ds_read_b128 v[202:205], v155 offset:50176
	ds_read_b128 v[206:209], v154 offset:49152
	ds_read_b128 v[210:213], v154 offset:50176
	ds_read_b128 v[214:217], v153 offset:49152
	ds_read_b128 v[218:221], v153 offset:50176
	global_load_lds_dwordx4 v[222:223], off
	v_lshl_add_u64 v[222:223], v[236:237], 0, s[48:49]
	s_mov_b32 m0, s31
	s_nop 0
	global_load_lds_dwordx4 v[222:223], off
	s_barrier
; #define LDA8(dst, b, h) _Pragma("unroll") for (int m = 0; m < 4; ++m) _Pragma("unroll") for (int k = 0; k < 2; ++k) \
;     dst[m][k] = *(const bf16x8*)((const char*)SA8(b, h) + lds_byte8(wr * 64 + m * 16 + fr, k * 32 + fq * 8))
; #define LDB8(dst, b, h) _Pragma("unroll") for (int n = 0; n < 2; ++n) _Pragma("unroll") for (int k = 0; k < 2; ++k) \
;     dst[n][k] = *(const bf16x8*)((const char*)SB8(b, h) + lds_byte8(wc * 32 + n * 16 + fr, k * 32 + fq * 8))
; #define WAIT_V8(n) asm volatile("s_waitcnt vmcnt(" #n ")" ::: "memory")
; #define WAIT_L8(n) asm volatile("s_waitcnt lgkmcnt(" #n ")" ::: "memory")
; #define BAR8 __builtin_amdgcn_s_barrier()
; #define SCHED8 __builtin_amdgcn_sched_barrier(0)
;     ...
;     BAR8; WAIT_L8(0); MMA8(1, 0, At, B0); BAR8; SCHED8;
;     STAGE8(SB8(1, 1), Bt, K, bcol + 128, tt + 3);
;     WAIT_V8(6); BAR8; MMA8(1, 1, At, B1); BAR8;
;   }
;   { LDB8(B0, 0, 0); LDA8(At, 0, 0); STAGE8(SA8(1, 1), A, lda, brow + 128, nt - 1);
;     BAR8; WAIT_L8(0); MMA8(0, 0, At, B0); BAR8;
;     LDB8(B1, 0, 1); BAR8; WAIT_L8(0); MMA8(0, 1, At, B1); BAR8;
	s_waitcnt lgkmcnt(0)
	s_waitcnt lgkmcnt(0)
	v_mfma_f32_16x16x32_bf16 v[64:67], v[190:193], v[174:177], v[64:67]
	v_mfma_f32_16x16x32_bf16 v[60:63], v[190:193], v[182:185], v[60:63]
	v_mfma_f32_16x16x32_bf16 v[56:59], v[198:201], v[174:177], v[56:59]
	v_mfma_f32_16x16x32_bf16 v[52:55], v[198:201], v[182:185], v[52:55]
	v_mfma_f32_16x16x32_bf16 v[48:51], v[206:209], v[174:177], v[48:51]
	v_mfma_f32_16x16x32_bf16 v[44:47], v[206:209], v[182:185], v[44:47]
	v_mfma_f32_16x16x32_bf16 v[40:43], v[214:217], v[174:177], v[40:43]
	v_mfma_f32_16x16x32_bf16 v[36:39], v[214:217], v[182:185], v[36:39]
	v_mfma_f32_16x16x32_bf16 v[64:67], v[194:197], v[178:181], v[64:67]
	v_mfma_f32_16x16x32_bf16 v[60:63], v[194:197], v[186:189], v[60:63]
	v_mfma_f32_16x16x32_bf16 v[56:59], v[202:205], v[178:181], v[56:59]
	v_mfma_f32_16x16x32_bf16 v[52:55], v[202:205], v[186:189], v[52:55]
	v_mfma_f32_16x16x32_bf16 v[48:51], v[210:213], v[178:181], v[48:51]
	v_mfma_f32_16x16x32_bf16 v[44:47], v[210:213], v[186:189], v[44:47]
	v_mfma_f32_16x16x32_bf16 v[40:43], v[218:221], v[178:181], v[40:43]
	v_mfma_f32_16x16x32_bf16 v[36:39], v[218:221], v[186:189], v[36:39]
	s_barrier
	v_readfirstlane_b32 s31, v169
	v_lshl_add_u64 v[174:175], v[246:247], 0, s[50:51]
	s_mov_b32 m0, s31
	v_readfirstlane_b32 s31, v170
	global_load_lds_dwordx4 v[174:175], off
	v_lshl_add_u64 v[174:175], v[248:249], 0, s[50:51]
	s_mov_b32 m0, s31
	s_nop 0
	global_load_lds_dwordx4 v[174:175], off
	s_waitcnt vmcnt(6)
	s_barrier
	v_mfma_f32_16x16x32_bf16 v[32:35], v[190:193], v[226:229], v[32:35]
	v_mfma_f32_16x16x32_bf16 v[28:31], v[190:193], v[238:241], v[28:31]
	v_mfma_f32_16x16x32_bf16 v[24:27], v[198:201], v[226:229], v[24:27]
	v_mfma_f32_16x16x32_bf16 v[20:23], v[198:201], v[238:241], v[20:23]
	v_mfma_f32_16x16x32_bf16 v[16:19], v[206:209], v[226:229], v[16:19]
	v_mfma_f32_16x16x32_bf16 v[12:15], v[206:209], v[238:241], v[12:15]
	v_mfma_f32_16x16x32_bf16 v[8:11], v[214:217], v[226:229], v[8:11]
	v_mfma_f32_16x16x32_bf16 v[4:7], v[214:217], v[238:241], v[4:7]
	v_mfma_f32_16x16x32_bf16 v[32:35], v[194:197], v[230:233], v[32:35]
	v_mfma_f32_16x16x32_bf16 v[28:31], v[194:197], v[242:245], v[28:31]
	v_mfma_f32_16x16x32_bf16 v[24:27], v[202:205], v[230:233], v[24:27]
	v_mfma_f32_16x16x32_bf16 v[20:23], v[202:205], v[242:245], v[20:23]
	v_mfma_f32_16x16x32_bf16 v[16:19], v[210:213], v[230:233], v[16:19]
	v_mfma_f32_16x16x32_bf16 v[12:15], v[210:213], v[242:245], v[12:15]
	v_mfma_f32_16x16x32_bf16 v[8:11], v[218:221], v[230:233], v[8:11]
	v_mfma_f32_16x16x32_bf16 v[4:7], v[218:221], v[242:245], v[4:7]
	s_add_i32 s29, s29, 2
	s_add_u32 s12, s12, 0x100
	s_addc_u32 s13, s13, 0
	s_cmp_lt_u32 s29, 4
	s_barrier
	s_cbranch_scc1 .LBB0_1152
	s_add_u32 s2, s2, s27
	s_addc_u32 s3, s3, 0
	s_add_u32 s2, s2, 0x3000380
	s_addc_u32 s3, s3, 0
	v_lshl_add_u64 v[136:137], v[136:137], 1, s[2:3]
	v_readfirstlane_b32 s12, v172
	v_lshl_add_u64 v[0:1], v[0:1], 1, v[136:137]
	s_mov_b32 m0, s12
	ds_read_b128 v[138:141], v171
	ds_read_b128 v[142:145], v171 offset:1024
	ds_read_b128 v[162:165], v171 offset:2048
	ds_read_b128 v[168:171], v171 offset:3072
	ds_read_b128 v[174:177], v156
	ds_read_b128 v[178:181], v156 offset:1024
	ds_read_b128 v[182:185], v155
	ds_read_b128 v[186:189], v155 offset:1024
	ds_read_b128 v[190:193], v154
	ds_read_b128 v[194:197], v154 offset:1024
	ds_read_b128 v[198:201], v153
	ds_read_b128 v[202:205], v153 offset:1024
	global_load_lds_dwordx4 v[0:1], off
	v_lshl_add_u64 v[0:1], v[134:135], 1, s[2:3]
	v_readfirstlane_b32 s2, v173
	v_lshl_add_u64 v[0:1], v[132:133], 1, v[0:1]
	s_mov_b32 m0, s2
	s_nop 0
	global_load_lds_dwordx4 v[0:1], off
	s_barrier
	s_waitcnt lgkmcnt(0)
	s_waitcnt lgkmcnt(0)
	v_mfma_f32_16x16x32_bf16 v[128:131], v[174:177], v[138:141], v[128:131]
	v_mfma_f32_16x16x32_bf16 v[124:127], v[174:177], v[162:165], v[124:127]
	v_mfma_f32_16x16x32_bf16 v[120:123], v[182:185], v[138:141], v[120:123]
	v_mfma_f32_16x16x32_bf16 v[112:115], v[190:193], v[138:141], v[112:115]
	v_mfma_f32_16x16x32_bf16 v[128:131], v[178:181], v[142:145], v[128:131]
	v_mfma_f32_16x16x32_bf16 v[124:127], v[178:181], v[168:171], v[124:127]
	v_mfma_f32_16x16x32_bf16 v[120:123], v[186:189], v[142:145], v[120:123]
	v_mfma_f32_16x16x32_bf16 v[116:119], v[182:185], v[162:165], v[116:119]
	v_mfma_f32_16x16x32_bf16 v[112:115], v[194:197], v[142:145], v[112:115]
	v_mfma_f32_16x16x32_bf16 v[108:111], v[190:193], v[162:165], v[108:111]
	v_mfma_f32_16x16x32_bf16 v[104:107], v[198:201], v[138:141], v[104:107]
	v_mfma_f32_16x16x32_bf16 v[100:103], v[198:201], v[162:165], v[100:103]
	v_mfma_f32_16x16x32_bf16 v[132:135], v[186:189], v[168:171], v[116:119]
	v_mfma_f32_16x16x32_bf16 v[206:209], v[194:197], v[168:171], v[108:111]
	v_mfma_f32_16x16x32_bf16 v[210:213], v[202:205], v[142:145], v[104:107]
	v_mfma_f32_16x16x32_bf16 v[214:217], v[202:205], v[168:171], v[100:103]
	s_barrier
	s_nop 1
	ds_read_b128 v[100:103], v167
	ds_read_b128 v[104:107], v167 offset:1024
	ds_read_b128 v[108:111], v167 offset:2048
	ds_read_b128 v[116:119], v167 offset:3072
	s_barrier
	s_waitcnt lgkmcnt(0)
	s_waitcnt lgkmcnt(0)
	v_mfma_f32_16x16x32_bf16 v[80:83], v[190:193], v[100:103], v[80:83]
	v_mfma_f32_16x16x32_bf16 v[76:79], v[190:193], v[108:111], v[76:79]
	v_mfma_f32_16x16x32_bf16 v[72:75], v[198:201], v[100:103], v[72:75]
	v_mfma_f32_16x16x32_bf16 v[68:71], v[198:201], v[108:111], v[68:71]
	v_mfma_f32_16x16x32_bf16 v[96:99], v[174:177], v[100:103], v[96:99]
	v_mfma_f32_16x16x32_bf16 v[92:95], v[174:177], v[108:111], v[92:95]
	v_mfma_f32_16x16x32_bf16 v[88:91], v[182:185], v[100:103], v[88:91]
	v_mfma_f32_16x16x32_bf16 v[84:87], v[182:185], v[108:111], v[84:87]
	v_mfma_f32_16x16x32_bf16 v[80:83], v[194:197], v[104:107], v[80:83]
	v_mfma_f32_16x16x32_bf16 v[76:79], v[194:197], v[116:119], v[76:79]
	v_mfma_f32_16x16x32_bf16 v[72:75], v[202:205], v[104:107], v[72:75]
	v_mfma_f32_16x16x32_bf16 v[68:71], v[202:205], v[116:119], v[68:71]
	v_mfma_f32_16x16x32_bf16 v[218:221], v[178:181], v[104:107], v[96:99]
	v_mfma_f32_16x16x32_bf16 v[172:175], v[178:181], v[116:119], v[92:95]
	v_mfma_f32_16x16x32_bf16 v[176:179], v[186:189], v[104:107], v[88:91]
	v_mfma_f32_16x16x32_bf16 v[180:183], v[186:189], v[116:119], v[84:87]
	s_barrier
; #define LDA8(dst, b, h) _Pragma("unroll") for (int m = 0; m < 4; ++m) _Pragma("unroll") for (int k = 0; k < 2; ++k) \
;     dst[m][k] = *(const bf16x8*)((const char*)SA8(b, h) + lds_byte8(wr * 64 + m * 16 + fr, k * 32 + fq * 8))
; #define LDB8(dst, b, h) _Pragma("unroll") for (int n = 0; n < 2; ++n) _Pragma("unroll") for (int k = 0; k < 2; ++k) \
;     dst[n][k] = *(const bf16x8*)((const char*)SB8(b, h) + lds_byte8(wc * 32 + n * 16 + fr, k * 32 + fq * 8))
; #define WAIT_V8(n) asm volatile("s_waitcnt vmcnt(" #n ")" ::: "memory")
; #define WAIT_L8(n) asm volatile("s_waitcnt lgkmcnt(" #n ")" ::: "memory")
; #define BAR8 __builtin_amdgcn_s_barrier()
;     ...
;     LDA8(At, 0, 1); WAIT_V8(4); BAR8; WAIT_L8(0); MMA8(1, 0, At, B0); MMA8(1, 1, At, B1); BAR8; }
;   { LDB8(B0, 1, 0); LDA8(At, 1, 0); WAIT_V8(2); BAR8; WAIT_L8(0); MMA8(0, 0, At, B0); BAR8;
	s_nop 0
	ds_read_b128 v[84:87], v156 offset:16384
	ds_read_b128 v[88:91], v156 offset:17408
	ds_read_b128 v[92:95], v155 offset:16384
	ds_read_b128 v[96:99], v155 offset:17408
	ds_read_b128 v[184:187], v154 offset:16384
	ds_read_b128 v[188:191], v154 offset:17408
	ds_read_b128 v[192:195], v153 offset:16384
	ds_read_b128 v[196:199], v153 offset:17408
	s_waitcnt vmcnt(4)
	s_barrier
	s_waitcnt lgkmcnt(0)
	s_waitcnt lgkmcnt(0)
	v_mfma_f32_16x16x32_bf16 v[64:67], v[84:87], v[138:141], v[64:67]
	v_mfma_f32_16x16x32_bf16 v[60:63], v[84:87], v[162:165], v[60:63]
	v_mfma_f32_16x16x32_bf16 v[56:59], v[92:95], v[138:141], v[56:59]
	v_mfma_f32_16x16x32_bf16 v[52:55], v[92:95], v[162:165], v[52:55]
	v_mfma_f32_16x16x32_bf16 v[48:51], v[184:187], v[138:141], v[48:51]
	v_mfma_f32_16x16x32_bf16 v[44:47], v[184:187], v[162:165], v[44:47]
	v_mfma_f32_16x16x32_bf16 v[40:43], v[192:195], v[138:141], v[40:43]
	v_mfma_f32_16x16x32_bf16 v[36:39], v[192:195], v[162:165], v[36:39]
	v_mfma_f32_16x16x32_bf16 v[64:67], v[88:91], v[142:145], v[64:67]
	v_mfma_f32_16x16x32_bf16 v[60:63], v[88:91], v[168:171], v[60:63]
	v_mfma_f32_16x16x32_bf16 v[56:59], v[96:99], v[142:145], v[56:59]
	v_mfma_f32_16x16x32_bf16 v[52:55], v[96:99], v[168:171], v[52:55]
	v_mfma_f32_16x16x32_bf16 v[48:51], v[188:191], v[142:145], v[48:51]
	v_mfma_f32_16x16x32_bf16 v[44:47], v[188:191], v[168:171], v[44:47]
	v_mfma_f32_16x16x32_bf16 v[40:43], v[196:199], v[142:145], v[40:43]
	v_mfma_f32_16x16x32_bf16 v[36:39], v[196:199], v[168:171], v[36:39]
	v_mfma_f32_16x16x32_bf16 v[32:35], v[84:87], v[100:103], v[32:35]
	v_mfma_f32_16x16x32_bf16 v[28:31], v[84:87], v[108:111], v[28:31]
	v_mfma_f32_16x16x32_bf16 v[24:27], v[92:95], v[100:103], v[24:27]
	v_mfma_f32_16x16x32_bf16 v[20:23], v[92:95], v[108:111], v[20:23]
	v_mfma_f32_16x16x32_bf16 v[16:19], v[184:187], v[100:103], v[16:19]
	v_mfma_f32_16x16x32_bf16 v[12:15], v[184:187], v[108:111], v[12:15]
	v_mfma_f32_16x16x32_bf16 v[8:11], v[192:195], v[100:103], v[8:11]
	v_mfma_f32_16x16x32_bf16 v[4:7], v[192:195], v[108:111], v[4:7]
	v_mfma_f32_16x16x32_bf16 v[136:139], v[88:91], v[104:107], v[32:35]
	v_mfma_f32_16x16x32_bf16 v[140:143], v[88:91], v[116:119], v[28:31]
	v_mfma_f32_16x16x32_bf16 v[162:165], v[96:99], v[104:107], v[24:27]
	v_mfma_f32_16x16x32_bf16 v[166:169], v[96:99], v[116:119], v[20:23]
	v_mfma_f32_16x16x32_bf16 v[200:203], v[188:191], v[104:107], v[16:19]
	v_mfma_f32_16x16x32_bf16 v[184:187], v[188:191], v[116:119], v[12:15]
	v_mfma_f32_16x16x32_bf16 v[188:191], v[196:199], v[104:107], v[8:11]
	v_mfma_f32_16x16x32_bf16 v[192:195], v[196:199], v[116:119], v[4:7]
	s_barrier
	ds_read_b128 v[196:199], v160
	ds_read_b128 v[226:229], v160 offset:1024
	ds_read_b128 v[230:233], v160 offset:2048
	ds_read_b128 v[238:241], v160 offset:3072
	ds_read_b128 v[8:11], v156 offset:32768
	ds_read_b128 v[12:15], v156 offset:33792
	ds_read_b128 v[16:19], v155 offset:32768
	ds_read_b128 v[24:27], v155 offset:33792
	ds_read_b128 v[28:31], v154 offset:32768
	ds_read_b128 v[32:35], v154 offset:33792
	ds_read_b128 v[242:245], v153 offset:32768
	ds_read_b128 v[246:249], v153 offset:33792
	s_waitcnt vmcnt(2)
	s_barrier
	s_waitcnt lgkmcnt(0)
	s_waitcnt lgkmcnt(0)
	v_mfma_f32_16x16x32_bf16 v[4:7], v[8:11], v[196:199], v[128:131]
	v_mfma_f32_16x16x32_bf16 v[104:107], v[12:15], v[226:229], v[4:7]
	v_mfma_f32_16x16x32_bf16 v[4:7], v[8:11], v[230:233], v[124:127]
	v_mfma_f32_16x16x32_bf16 v[116:119], v[12:15], v[238:241], v[4:7]
	v_mfma_f32_16x16x32_bf16 v[4:7], v[16:19], v[196:199], v[120:123]
	v_mfma_f32_16x16x32_bf16 v[100:103], v[24:27], v[226:229], v[4:7]
	v_mfma_f32_16x16x32_bf16 v[4:7], v[16:19], v[230:233], v[132:135]
	v_mfma_f32_16x16x32_bf16 v[108:111], v[24:27], v[238:241], v[4:7]
	v_mfma_f32_16x16x32_bf16 v[4:7], v[28:31], v[196:199], v[112:115]
	v_mfma_f32_16x16x32_bf16 v[92:95], v[32:35], v[226:229], v[4:7]
	v_mfma_f32_16x16x32_bf16 v[4:7], v[28:31], v[230:233], v[206:209]
	v_mfma_f32_16x16x32_bf16 v[96:99], v[32:35], v[238:241], v[4:7]
	v_mfma_f32_16x16x32_bf16 v[4:7], v[242:245], v[196:199], v[210:213]
	v_mfma_f32_16x16x32_bf16 v[84:87], v[246:249], v[226:229], v[4:7]
	v_mfma_f32_16x16x32_bf16 v[4:7], v[242:245], v[230:233], v[214:217]
	v_mfma_f32_16x16x32_bf16 v[88:91], v[246:249], v[238:241], v[4:7]
	s_barrier
; DI int tid_opaque() { int t = threadIdx.x; asm volatile("" : "+v"(t)); return t; }
; #define LDA8(dst, b, h) _Pragma("unroll") for (int m = 0; m < 4; ++m) _Pragma("unroll") for (int k = 0; k < 2; ++k) \
;     dst[m][k] = *(const bf16x8*)((const char*)SA8(b, h) + lds_byte8(wr * 64 + m * 16 + fr, k * 32 + fq * 8))
; #define LDB8(dst, b, h) _Pragma("unroll") for (int n = 0; n < 2; ++n) _Pragma("unroll") for (int k = 0; k < 2; ++k) \
;     dst[n][k] = *(const bf16x8*)((const char*)SB8(b, h) + lds_byte8(wc * 32 + n * 16 + fr, k * 32 + fq * 8))
; #define WAIT_V8(n) asm volatile("s_waitcnt vmcnt(" #n ")" ::: "memory")
; #define WAIT_L8(n) asm volatile("s_waitcnt lgkmcnt(" #n ")" ::: "memory")
; #define BAR8 __builtin_amdgcn_s_barrier()
;     ...
;     LDB8(B1, 1, 1); WAIT_V8(0); BAR8; WAIT_L8(0); MMA8(0, 1, At, B1); BAR8;
;     LDA8(At, 1, 1); BAR8; WAIT_L8(0); MMA8(1, 0, At, B0); MMA8(1, 1, At, B1); BAR8; }
;   if (wr == 0) BAR8;
;   __syncthreads();
;   if (EPI == EPI_GU && nm0 >= 0) {
;     const int t = tid_opaque();
;     STAGE8(SB8(0, 0), Bt, K, nn0, 0); STAGE8(SA8(0, 0), A, lda, nm0, 0);
;     STAGE8(SB8(0, 1), Bt, K, nn0 + 128, 0); STAGE8(SA8(0, 1), A, lda, nm0 + 128, 0);
;   }
;     ...
;   if (t < 256) {
	ds_read_b128 v[132:135], v158
	ds_read_b128 v[204:207], v158 offset:1024
	ds_read_b128 v[208:211], v158 offset:2048
	ds_read_b128 v[158:161], v158 offset:3072
	s_waitcnt vmcnt(0)
	s_barrier
	s_waitcnt lgkmcnt(0)
	s_waitcnt lgkmcnt(0)
	v_mfma_f32_16x16x32_bf16 v[4:7], v[8:11], v[132:135], v[218:221]
	v_mfma_f32_16x16x32_bf16 v[8:11], v[8:11], v[208:211], v[172:175]
	v_mfma_f32_16x16x32_bf16 v[4:7], v[12:15], v[204:207], v[4:7]
	v_mfma_f32_16x16x32_bf16 v[20:23], v[12:15], v[158:161], v[8:11]
	v_mfma_f32_16x16x32_bf16 v[8:11], v[16:19], v[132:135], v[176:179]
	v_mfma_f32_16x16x32_bf16 v[12:15], v[16:19], v[208:211], v[180:183]
	v_mfma_f32_16x16x32_bf16 v[8:11], v[24:27], v[204:207], v[8:11]
	v_mfma_f32_16x16x32_bf16 v[24:27], v[24:27], v[158:161], v[12:15]
	v_mfma_f32_16x16x32_bf16 v[12:15], v[28:31], v[132:135], v[80:83]
	v_mfma_f32_16x16x32_bf16 v[16:19], v[28:31], v[208:211], v[76:79]
	v_mfma_f32_16x16x32_bf16 v[12:15], v[32:35], v[204:207], v[12:15]
	v_mfma_f32_16x16x32_bf16 v[28:31], v[32:35], v[158:161], v[16:19]
	v_mfma_f32_16x16x32_bf16 v[16:19], v[242:245], v[132:135], v[72:75]
	v_mfma_f32_16x16x32_bf16 v[32:35], v[242:245], v[208:211], v[68:71]
	v_mfma_f32_16x16x32_bf16 v[16:19], v[246:249], v[204:207], v[16:19]
	v_mfma_f32_16x16x32_bf16 v[32:35], v[246:249], v[158:161], v[32:35]
	s_barrier
	ds_read_b128 v[170:173], v156 offset:49152
	ds_read_b128 v[174:177], v156 offset:50176
	ds_read_b128 v[178:181], v155 offset:49152
	ds_read_b128 v[212:215], v155 offset:50176
	ds_read_b128 v[216:219], v154 offset:49152
	ds_read_b128 v[154:157], v154 offset:50176
	ds_read_b128 v[220:223], v153 offset:49152
	ds_read_b128 v[150:153], v153 offset:50176
	s_barrier
	s_waitcnt lgkmcnt(0)
	s_waitcnt lgkmcnt(0)
	v_mfma_f32_16x16x32_bf16 v[64:67], v[170:173], v[196:199], v[64:67]
	v_mfma_f32_16x16x32_bf16 v[60:63], v[170:173], v[230:233], v[60:63]
	v_mfma_f32_16x16x32_bf16 v[56:59], v[178:181], v[196:199], v[56:59]
	v_mfma_f32_16x16x32_bf16 v[52:55], v[178:181], v[230:233], v[52:55]
	v_mfma_f32_16x16x32_bf16 v[48:51], v[216:219], v[196:199], v[48:51]
	v_mfma_f32_16x16x32_bf16 v[44:47], v[216:219], v[230:233], v[44:47]
	v_mfma_f32_16x16x32_bf16 v[40:43], v[220:223], v[196:199], v[40:43]
	v_mfma_f32_16x16x32_bf16 v[36:39], v[220:223], v[230:233], v[36:39]
	v_mfma_f32_16x16x32_bf16 v[128:131], v[174:177], v[226:229], v[64:67]
	v_mfma_f32_16x16x32_bf16 v[124:127], v[174:177], v[238:241], v[60:63]
	v_mfma_f32_16x16x32_bf16 v[120:123], v[212:215], v[226:229], v[56:59]
	v_mfma_f32_16x16x32_bf16 v[112:115], v[212:215], v[238:241], v[52:55]
	v_mfma_f32_16x16x32_bf16 v[80:83], v[154:157], v[226:229], v[48:51]
	v_mfma_f32_16x16x32_bf16 v[76:79], v[154:157], v[238:241], v[44:47]
	v_mfma_f32_16x16x32_bf16 v[72:75], v[150:153], v[226:229], v[40:43]
	v_mfma_f32_16x16x32_bf16 v[68:71], v[150:153], v[238:241], v[36:39]
	v_mfma_f32_16x16x32_bf16 v[40:43], v[170:173], v[208:211], v[140:143]
	v_mfma_f32_16x16x32_bf16 v[44:47], v[178:181], v[208:211], v[166:169]
	v_mfma_f32_16x16x32_bf16 v[48:51], v[216:219], v[208:211], v[184:187]
	v_mfma_f32_16x16x32_bf16 v[36:39], v[170:173], v[132:135], v[136:139]
	v_mfma_f32_16x16x32_bf16 v[52:55], v[174:177], v[158:161], v[40:43]
	v_mfma_f32_16x16x32_bf16 v[40:43], v[178:181], v[132:135], v[162:165]
	v_mfma_f32_16x16x32_bf16 v[56:59], v[212:215], v[158:161], v[44:47]
	v_mfma_f32_16x16x32_bf16 v[44:47], v[216:219], v[132:135], v[200:203]
	v_mfma_f32_16x16x32_bf16 v[60:63], v[154:157], v[158:161], v[48:51]
	v_mfma_f32_16x16x32_bf16 v[48:51], v[220:223], v[132:135], v[188:191]
	v_mfma_f32_16x16x32_bf16 v[64:67], v[220:223], v[208:211], v[192:195]
	v_mfma_f32_16x16x32_bf16 v[36:39], v[174:177], v[204:207], v[36:39]
	v_mfma_f32_16x16x32_bf16 v[40:43], v[212:215], v[204:207], v[40:43]
	v_mfma_f32_16x16x32_bf16 v[44:47], v[154:157], v[204:207], v[44:47]
	v_mfma_f32_16x16x32_bf16 v[48:51], v[150:153], v[204:207], v[48:51]
	v_mfma_f32_16x16x32_bf16 v[64:67], v[150:153], v[158:161], v[64:67]
	s_movk_i32 s2, 0x100
	v_cmp_gt_u32_e32 vcc, s2, v3
	s_barrier
	s_and_saveexec_b64 s[2:3], vcc
	s_cbranch_execz .LBB0_1155
	s_barrier

; #define LDA8(dst, b, h) _Pragma("unroll") for (int m = 0; m < 4; ++m) _Pragma("unroll") for (int k = 0; k < 2; ++k) \
;     dst[m][k] = *(const bf16x8*)((const char*)SA8(b, h) + lds_byte8(wr * 64 + m * 16 + fr, k * 32 + fq * 8))
; #define LDB8(dst, b, h) _Pragma("unroll") for (int n = 0; n < 2; ++n) _Pragma("unroll") for (int k = 0; k < 2; ++k) \
;     dst[n][k] = *(const bf16x8*)((const char*)SB8(b, h) + lds_byte8(wc * 32 + n * 16 + fr, k * 32 + fq * 8))
; #define WAIT_L8(n) asm volatile("s_waitcnt lgkmcnt(" #n ")" ::: "memory")
; #define BAR8 __builtin_amdgcn_s_barrier()
; #define SCHED8 __builtin_amdgcn_sched_barrier(0)
;     ...
;   for (int tt = 0; tt < nt - 2; tt += 2) {
;     LDB8(B0, 0, 0); SCHED8; LDA8(At, 0, 0); STAGE8(SA8(1, 1), A, lda, brow + 128, tt + 1);
;     WAIT_L8(8); BAR8; WAIT_L8(0); MMA8(0, 0, At, B0); BAR8; SCHED8;
;     LDB8(B1, 0, 1); STAGE8(SB8(0, 0), Bt, K, bcol, tt + 2);
;     BAR8; WAIT_L8(0); MMA8(0, 1, At, B1); BAR8;
;     LDA8(At, 0, 1); STAGE8(SA8(0, 0), A, lda, brow, tt + 2);
;     BAR8; WAIT_L8(0); MMA8(1, 0, At, B0); BAR8; SCHED8;
.LBB0_1259:
	ds_read_b128 v[174:177], v171
	ds_read_b128 v[178:181], v171 offset:1024
	ds_read_b128 v[182:185], v171 offset:2048
	ds_read_b128 v[186:189], v171 offset:3072
	v_add_u32_e32 v172, 0xc000, v150
	v_lshl_add_u64 v[222:223], v[138:139], 0, s[12:13]
	v_readfirstlane_b32 s14, v172
	v_add_u32_e32 v173, 0xe000, v150
	v_lshl_add_u64 v[226:227], v[222:223], 0, s[34:35]
	s_mov_b32 m0, s14
	v_lshl_add_u64 v[236:237], v[140:141], 0, s[12:13]
	v_readfirstlane_b32 s14, v173
	ds_read_b128 v[190:193], v161
	ds_read_b128 v[194:197], v161 offset:1024
	ds_read_b128 v[198:201], v160
	ds_read_b128 v[202:205], v160 offset:1024
	ds_read_b128 v[206:209], v159
	ds_read_b128 v[210:213], v159 offset:1024
	ds_read_b128 v[214:217], v158
	ds_read_b128 v[218:221], v158 offset:1024
	global_load_lds_dwordx4 v[226:227], off
	v_lshl_add_u64 v[226:227], v[236:237], 0, s[34:35]
	s_mov_b32 m0, s14
	s_nop 0
	global_load_lds_dwordx4 v[226:227], off
	s_waitcnt lgkmcnt(8)
	s_barrier
	s_waitcnt lgkmcnt(0)
	s_waitcnt lgkmcnt(0)
	v_mfma_f32_16x16x32_f16 v[128:131], v[190:193], v[174:177], v[128:131]
	v_mfma_f32_16x16x32_f16 v[124:127], v[190:193], v[182:185], v[124:127]
	v_mfma_f32_16x16x32_f16 v[120:123], v[198:201], v[174:177], v[120:123]
	v_mfma_f32_16x16x32_f16 v[116:119], v[198:201], v[182:185], v[116:119]
	v_mfma_f32_16x16x32_f16 v[112:115], v[206:209], v[174:177], v[112:115]
	v_mfma_f32_16x16x32_f16 v[108:111], v[206:209], v[182:185], v[108:111]
	v_mfma_f32_16x16x32_f16 v[104:107], v[214:217], v[174:177], v[104:107]
	v_mfma_f32_16x16x32_f16 v[100:103], v[214:217], v[182:185], v[100:103]
	v_mfma_f32_16x16x32_f16 v[128:131], v[194:197], v[178:181], v[128:131]
	v_mfma_f32_16x16x32_f16 v[124:127], v[194:197], v[186:189], v[124:127]
	v_mfma_f32_16x16x32_f16 v[120:123], v[202:205], v[178:181], v[120:123]
	v_mfma_f32_16x16x32_f16 v[116:119], v[202:205], v[186:189], v[116:119]
	v_mfma_f32_16x16x32_f16 v[112:115], v[210:213], v[178:181], v[112:115]
	v_mfma_f32_16x16x32_f16 v[108:111], v[210:213], v[186:189], v[108:111]
	v_mfma_f32_16x16x32_f16 v[104:107], v[218:221], v[178:181], v[104:107]
	v_mfma_f32_16x16x32_f16 v[100:103], v[218:221], v[186:189], v[100:103]
	s_barrier
	v_lshl_add_u64 v[246:247], v[142:143], 0, s[12:13]
	v_readfirstlane_b32 s14, v151
	v_lshl_add_u64 v[248:249], v[246:247], 0, s[36:37]
	s_mov_b32 m0, s14
	ds_read_b128 v[226:229], v169
	ds_read_b128 v[230:233], v169 offset:1024
	ds_read_b128 v[238:241], v169 offset:2048
	ds_read_b128 v[242:245], v169 offset:3072
	global_load_lds_dwordx4 v[248:249], off
	v_lshl_add_u64 v[248:249], v[144:145], 0, s[12:13]
	v_readfirstlane_b32 s14, v153
	v_lshl_add_u64 v[250:251], v[248:249], 0, s[36:37]
	s_mov_b32 m0, s14
	s_nop 0
	global_load_lds_dwordx4 v[250:251], off
	s_barrier
	s_waitcnt lgkmcnt(0)
	s_waitcnt lgkmcnt(0)
	v_mfma_f32_16x16x32_f16 v[96:99], v[190:193], v[226:229], v[96:99]
	v_mfma_f32_16x16x32_f16 v[92:95], v[190:193], v[238:241], v[92:95]
	v_mfma_f32_16x16x32_f16 v[88:91], v[198:201], v[226:229], v[88:91]
	v_mfma_f32_16x16x32_f16 v[84:87], v[198:201], v[238:241], v[84:87]
	v_mfma_f32_16x16x32_f16 v[80:83], v[206:209], v[226:229], v[80:83]
	v_mfma_f32_16x16x32_f16 v[76:79], v[206:209], v[238:241], v[76:79]
	v_mfma_f32_16x16x32_f16 v[72:75], v[214:217], v[226:229], v[72:75]
	v_mfma_f32_16x16x32_f16 v[68:71], v[214:217], v[238:241], v[68:71]
	v_mfma_f32_16x16x32_f16 v[96:99], v[194:197], v[230:233], v[96:99]
	v_mfma_f32_16x16x32_f16 v[92:95], v[194:197], v[242:245], v[92:95]
	v_mfma_f32_16x16x32_f16 v[88:91], v[202:205], v[230:233], v[88:91]
	v_mfma_f32_16x16x32_f16 v[84:87], v[202:205], v[242:245], v[84:87]
	v_mfma_f32_16x16x32_f16 v[80:83], v[210:213], v[230:233], v[80:83]
	v_mfma_f32_16x16x32_f16 v[76:79], v[210:213], v[242:245], v[76:79]
	v_mfma_f32_16x16x32_f16 v[72:75], v[218:221], v[230:233], v[72:75]
	v_mfma_f32_16x16x32_f16 v[68:71], v[218:221], v[242:245], v[68:71]
	v_readfirstlane_b32 s14, v150
	v_lshl_add_u64 v[250:251], v[222:223], 0, s[10:11]
	s_mov_b32 m0, s14
	v_readfirstlane_b32 s14, v152
	s_barrier
	ds_read_b128 v[190:193], v161 offset:16384
	ds_read_b128 v[194:197], v161 offset:17408
	ds_read_b128 v[198:201], v160 offset:16384
	ds_read_b128 v[202:205], v160 offset:17408
	ds_read_b128 v[206:209], v159 offset:16384
	ds_read_b128 v[210:213], v159 offset:17408
	ds_read_b128 v[214:217], v158 offset:16384
	ds_read_b128 v[218:221], v158 offset:17408
	global_load_lds_dwordx4 v[250:251], off
	v_lshl_add_u64 v[250:251], v[236:237], 0, s[10:11]
	s_mov_b32 m0, s14
	s_nop 0
	global_load_lds_dwordx4 v[250:251], off
	s_barrier
	s_waitcnt lgkmcnt(0)
	s_waitcnt lgkmcnt(0)
	v_mfma_f32_16x16x32_f16 v[64:67], v[190:193], v[174:177], v[64:67]
	v_mfma_f32_16x16x32_f16 v[60:63], v[190:193], v[182:185], v[60:63]
	v_mfma_f32_16x16x32_f16 v[56:59], v[198:201], v[174:177], v[56:59]
	v_mfma_f32_16x16x32_f16 v[52:55], v[198:201], v[182:185], v[52:55]
	v_mfma_f32_16x16x32_f16 v[48:51], v[206:209], v[174:177], v[48:51]
	v_mfma_f32_16x16x32_f16 v[44:47], v[206:209], v[182:185], v[44:47]
	v_mfma_f32_16x16x32_f16 v[40:43], v[214:217], v[174:177], v[40:43]
	v_mfma_f32_16x16x32_f16 v[36:39], v[214:217], v[182:185], v[36:39]
	v_mfma_f32_16x16x32_f16 v[64:67], v[194:197], v[178:181], v[64:67]
	v_mfma_f32_16x16x32_f16 v[60:63], v[194:197], v[186:189], v[60:63]
	v_mfma_f32_16x16x32_f16 v[56:59], v[202:205], v[178:181], v[56:59]
	v_mfma_f32_16x16x32_f16 v[52:55], v[202:205], v[186:189], v[52:55]
	v_mfma_f32_16x16x32_f16 v[48:51], v[210:213], v[178:181], v[48:51]
	v_mfma_f32_16x16x32_f16 v[44:47], v[210:213], v[186:189], v[44:47]
	v_mfma_f32_16x16x32_f16 v[40:43], v[218:221], v[178:181], v[40:43]
	v_mfma_f32_16x16x32_f16 v[36:39], v[218:221], v[186:189], v[36:39]
	s_barrier
; #define LDA8(dst, b, h) _Pragma("unroll") for (int m = 0; m < 4; ++m) _Pragma("unroll") for (int k = 0; k < 2; ++k) \
;     dst[m][k] = *(const bf16x8*)((const char*)SA8(b, h) + lds_byte8(wr * 64 + m * 16 + fr, k * 32 + fq * 8))
; #define LDB8(dst, b, h) _Pragma("unroll") for (int n = 0; n < 2; ++n) _Pragma("unroll") for (int k = 0; k < 2; ++k) \
;     dst[n][k] = *(const bf16x8*)((const char*)SB8(b, h) + lds_byte8(wc * 32 + n * 16 + fr, k * 32 + fq * 8))
; #define WAIT_V8(n) asm volatile("s_waitcnt vmcnt(" #n ")" ::: "memory")
; #define WAIT_L8(n) asm volatile("s_waitcnt lgkmcnt(" #n ")" ::: "memory")
; #define BAR8 __builtin_amdgcn_s_barrier()
; #define SCHED8 __builtin_amdgcn_sched_barrier(0)
;     ...
;     STAGE8(SB8(0, 1), Bt, K, bcol + 128, tt + 2);
;     WAIT_V8(6); BAR8; MMA8(1, 1, At, B1); BAR8;
;     LDB8(B0, 1, 0); SCHED8; LDA8(At, 1, 0); STAGE8(SA8(0, 1), A, lda, brow + 128, tt + 2);
;     WAIT_L8(8); BAR8; WAIT_L8(0); MMA8(0, 0, At, B0); BAR8; SCHED8;
;     LDB8(B1, 1, 1); STAGE8(SB8(1, 0), Bt, K, bcol, tt + 3);
;     BAR8; WAIT_L8(0); MMA8(0, 1, At, B1); BAR8;
;     LDA8(At, 1, 1); STAGE8(SA8(1, 0), A, lda, brow, tt + 3);
	v_readfirstlane_b32 s14, v154
	v_lshl_add_u64 v[174:175], v[246:247], 0, s[40:41]
	s_mov_b32 m0, s14
	v_readfirstlane_b32 s14, v155
	global_load_lds_dwordx4 v[174:175], off
	v_lshl_add_u64 v[174:175], v[248:249], 0, s[40:41]
	s_mov_b32 m0, s14
	s_nop 0
	global_load_lds_dwordx4 v[174:175], off
	s_waitcnt vmcnt(6)
	s_barrier
	v_mfma_f32_16x16x32_f16 v[32:35], v[190:193], v[226:229], v[32:35]
	v_mfma_f32_16x16x32_f16 v[28:31], v[190:193], v[238:241], v[28:31]
	v_mfma_f32_16x16x32_f16 v[24:27], v[198:201], v[226:229], v[24:27]
	v_mfma_f32_16x16x32_f16 v[20:23], v[198:201], v[238:241], v[20:23]
	v_mfma_f32_16x16x32_f16 v[16:19], v[206:209], v[226:229], v[16:19]
	v_mfma_f32_16x16x32_f16 v[12:15], v[206:209], v[238:241], v[12:15]
	v_mfma_f32_16x16x32_f16 v[8:11], v[214:217], v[226:229], v[8:11]
	v_mfma_f32_16x16x32_f16 v[4:7], v[214:217], v[238:241], v[4:7]
	v_mfma_f32_16x16x32_f16 v[32:35], v[194:197], v[230:233], v[32:35]
	v_mfma_f32_16x16x32_f16 v[28:31], v[194:197], v[242:245], v[28:31]
	v_mfma_f32_16x16x32_f16 v[24:27], v[202:205], v[230:233], v[24:27]
	v_mfma_f32_16x16x32_f16 v[20:23], v[202:205], v[242:245], v[20:23]
	v_mfma_f32_16x16x32_f16 v[16:19], v[210:213], v[230:233], v[16:19]
	v_mfma_f32_16x16x32_f16 v[12:15], v[210:213], v[242:245], v[12:15]
	v_mfma_f32_16x16x32_f16 v[8:11], v[218:221], v[230:233], v[8:11]
	v_mfma_f32_16x16x32_f16 v[4:7], v[218:221], v[242:245], v[4:7]
	s_barrier
	ds_read_b128 v[174:177], v163
	ds_read_b128 v[178:181], v163 offset:1024
	ds_read_b128 v[182:185], v163 offset:2048
	ds_read_b128 v[186:189], v163 offset:3072
	v_readfirstlane_b32 s14, v156
	v_lshl_add_u64 v[226:227], v[222:223], 0, s[18:19]
	s_mov_b32 m0, s14
	v_readfirstlane_b32 s14, v157
	ds_read_b128 v[190:193], v161 offset:32768
	ds_read_b128 v[194:197], v161 offset:33792
	ds_read_b128 v[198:201], v160 offset:32768
	ds_read_b128 v[202:205], v160 offset:33792
	ds_read_b128 v[206:209], v159 offset:32768
	ds_read_b128 v[210:213], v159 offset:33792
	ds_read_b128 v[214:217], v158 offset:32768
	ds_read_b128 v[218:221], v158 offset:33792
	global_load_lds_dwordx4 v[226:227], off
	v_lshl_add_u64 v[226:227], v[236:237], 0, s[18:19]
	s_mov_b32 m0, s14
	s_nop 0
	global_load_lds_dwordx4 v[226:227], off
	s_waitcnt lgkmcnt(8)
	s_barrier
	s_waitcnt lgkmcnt(0)
	s_waitcnt lgkmcnt(0)
	v_mfma_f32_16x16x32_f16 v[128:131], v[190:193], v[174:177], v[128:131]
	v_mfma_f32_16x16x32_f16 v[124:127], v[190:193], v[182:185], v[124:127]
	v_mfma_f32_16x16x32_f16 v[120:123], v[198:201], v[174:177], v[120:123]
	v_mfma_f32_16x16x32_f16 v[116:119], v[198:201], v[182:185], v[116:119]
	v_mfma_f32_16x16x32_f16 v[112:115], v[206:209], v[174:177], v[112:115]
	v_mfma_f32_16x16x32_f16 v[108:111], v[206:209], v[182:185], v[108:111]
	v_mfma_f32_16x16x32_f16 v[104:107], v[214:217], v[174:177], v[104:107]
	v_mfma_f32_16x16x32_f16 v[100:103], v[214:217], v[182:185], v[100:103]
	v_mfma_f32_16x16x32_f16 v[128:131], v[194:197], v[178:181], v[128:131]
	v_mfma_f32_16x16x32_f16 v[124:127], v[194:197], v[186:189], v[124:127]
	v_mfma_f32_16x16x32_f16 v[120:123], v[202:205], v[178:181], v[120:123]
	v_mfma_f32_16x16x32_f16 v[116:119], v[202:205], v[186:189], v[116:119]
	v_mfma_f32_16x16x32_f16 v[112:115], v[210:213], v[178:181], v[112:115]
	v_mfma_f32_16x16x32_f16 v[108:111], v[210:213], v[186:189], v[108:111]
	v_mfma_f32_16x16x32_f16 v[104:107], v[218:221], v[178:181], v[104:107]
	v_mfma_f32_16x16x32_f16 v[100:103], v[218:221], v[186:189], v[100:103]
	s_barrier
	v_readfirstlane_b32 s14, v164
	v_lshl_add_u64 v[250:251], v[246:247], 0, s[42:43]
	s_mov_b32 m0, s14
	v_readfirstlane_b32 s14, v165
	ds_read_b128 v[226:229], v162
	ds_read_b128 v[230:233], v162 offset:1024
	ds_read_b128 v[238:241], v162 offset:2048
	ds_read_b128 v[242:245], v162 offset:3072
	global_load_lds_dwordx4 v[250:251], off
	v_lshl_add_u64 v[250:251], v[248:249], 0, s[42:43]
	s_mov_b32 m0, s14
	s_nop 0
	global_load_lds_dwordx4 v[250:251], off
	s_barrier
	s_waitcnt lgkmcnt(0)
	s_waitcnt lgkmcnt(0)
	v_mfma_f32_16x16x32_f16 v[96:99], v[190:193], v[226:229], v[96:99]
	v_mfma_f32_16x16x32_f16 v[92:95], v[190:193], v[238:241], v[92:95]
	v_mfma_f32_16x16x32_f16 v[88:91], v[198:201], v[226:229], v[88:91]
	v_mfma_f32_16x16x32_f16 v[84:87], v[198:201], v[238:241], v[84:87]
	v_mfma_f32_16x16x32_f16 v[80:83], v[206:209], v[226:229], v[80:83]
	v_mfma_f32_16x16x32_f16 v[76:79], v[206:209], v[238:241], v[76:79]
	v_mfma_f32_16x16x32_f16 v[72:75], v[214:217], v[226:229], v[72:75]
	v_mfma_f32_16x16x32_f16 v[68:71], v[214:217], v[238:241], v[68:71]
	v_mfma_f32_16x16x32_f16 v[96:99], v[194:197], v[230:233], v[96:99]
	v_mfma_f32_16x16x32_f16 v[92:95], v[194:197], v[242:245], v[92:95]
	v_mfma_f32_16x16x32_f16 v[88:91], v[202:205], v[230:233], v[88:91]
	v_mfma_f32_16x16x32_f16 v[84:87], v[202:205], v[242:245], v[84:87]
	v_mfma_f32_16x16x32_f16 v[80:83], v[210:213], v[230:233], v[80:83]
	v_mfma_f32_16x16x32_f16 v[76:79], v[210:213], v[242:245], v[76:79]
	v_mfma_f32_16x16x32_f16 v[72:75], v[218:221], v[230:233], v[72:75]
	v_mfma_f32_16x16x32_f16 v[68:71], v[218:221], v[242:245], v[68:71]
	v_readfirstlane_b32 s14, v166
	v_lshl_add_u64 v[222:223], v[222:223], 0, s[22:23]
	s_mov_b32 m0, s14
	v_readfirstlane_b32 s14, v167
	s_barrier
	ds_read_b128 v[190:193], v161 offset:49152
	ds_read_b128 v[194:197], v161 offset:50176
	ds_read_b128 v[198:201], v160 offset:49152
	ds_read_b128 v[202:205], v160 offset:50176
	ds_read_b128 v[206:209], v159 offset:49152
	ds_read_b128 v[210:213], v159 offset:50176
	ds_read_b128 v[214:217], v158 offset:49152
	ds_read_b128 v[218:221], v158 offset:50176
	global_load_lds_dwordx4 v[222:223], off
	v_lshl_add_u64 v[222:223], v[236:237], 0, s[22:23]
	s_mov_b32 m0, s14
	s_nop 0
	global_load_lds_dwordx4 v[222:223], off
	s_barrier
; #define LDA8(dst, b, h) _Pragma("unroll") for (int m = 0; m < 4; ++m) _Pragma("unroll") for (int k = 0; k < 2; ++k) \
;     dst[m][k] = *(const bf16x8*)((const char*)SA8(b, h) + lds_byte8(wr * 64 + m * 16 + fr, k * 32 + fq * 8))
; #define LDB8(dst, b, h) _Pragma("unroll") for (int n = 0; n < 2; ++n) _Pragma("unroll") for (int k = 0; k < 2; ++k) \
;     dst[n][k] = *(const bf16x8*)((const char*)SB8(b, h) + lds_byte8(wc * 32 + n * 16 + fr, k * 32 + fq * 8))
; #define WAIT_V8(n) asm volatile("s_waitcnt vmcnt(" #n ")" ::: "memory")
; #define WAIT_L8(n) asm volatile("s_waitcnt lgkmcnt(" #n ")" ::: "memory")
; #define BAR8 __builtin_amdgcn_s_barrier()
; #define SCHED8 __builtin_amdgcn_sched_barrier(0)
;     ...
;     LDA8(At, 1, 1); STAGE8(SA8(1, 0), A, lda, brow, tt + 3);
;     BAR8; WAIT_L8(0); MMA8(1, 0, At, B0); BAR8; SCHED8;
;     STAGE8(SB8(1, 1), Bt, K, bcol + 128, tt + 3);
;     WAIT_V8(6); BAR8; MMA8(1, 1, At, B1); BAR8;
;   }
;   { LDB8(B0, 0, 0); LDA8(At, 0, 0); STAGE8(SA8(1, 1), A, lda, brow + 128, nt - 1);
;     BAR8; WAIT_L8(0); MMA8(0, 0, At, B0); BAR8;
;     LDB8(B1, 0, 1); BAR8; WAIT_L8(0); MMA8(0, 1, At, B1); BAR8;
	s_waitcnt lgkmcnt(0)
	s_waitcnt lgkmcnt(0)
	v_mfma_f32_16x16x32_f16 v[64:67], v[190:193], v[174:177], v[64:67]
	v_mfma_f32_16x16x32_f16 v[60:63], v[190:193], v[182:185], v[60:63]
	v_mfma_f32_16x16x32_f16 v[56:59], v[198:201], v[174:177], v[56:59]
	v_mfma_f32_16x16x32_f16 v[52:55], v[198:201], v[182:185], v[52:55]
	v_mfma_f32_16x16x32_f16 v[48:51], v[206:209], v[174:177], v[48:51]
	v_mfma_f32_16x16x32_f16 v[44:47], v[206:209], v[182:185], v[44:47]
	v_mfma_f32_16x16x32_f16 v[40:43], v[214:217], v[174:177], v[40:43]
	v_mfma_f32_16x16x32_f16 v[36:39], v[214:217], v[182:185], v[36:39]
	v_mfma_f32_16x16x32_f16 v[64:67], v[194:197], v[178:181], v[64:67]
	v_mfma_f32_16x16x32_f16 v[60:63], v[194:197], v[186:189], v[60:63]
	v_mfma_f32_16x16x32_f16 v[56:59], v[202:205], v[178:181], v[56:59]
	v_mfma_f32_16x16x32_f16 v[52:55], v[202:205], v[186:189], v[52:55]
	v_mfma_f32_16x16x32_f16 v[48:51], v[210:213], v[178:181], v[48:51]
	v_mfma_f32_16x16x32_f16 v[44:47], v[210:213], v[186:189], v[44:47]
	v_mfma_f32_16x16x32_f16 v[40:43], v[218:221], v[178:181], v[40:43]
	v_mfma_f32_16x16x32_f16 v[36:39], v[218:221], v[186:189], v[36:39]
	s_barrier
	v_readfirstlane_b32 s14, v168
	v_lshl_add_u64 v[174:175], v[246:247], 0, s[44:45]
	s_mov_b32 m0, s14
	v_readfirstlane_b32 s14, v170
	global_load_lds_dwordx4 v[174:175], off
	v_lshl_add_u64 v[174:175], v[248:249], 0, s[44:45]
	s_mov_b32 m0, s14
	s_nop 0
	global_load_lds_dwordx4 v[174:175], off
	s_waitcnt vmcnt(6)
	s_barrier
	v_mfma_f32_16x16x32_f16 v[32:35], v[190:193], v[226:229], v[32:35]
	v_mfma_f32_16x16x32_f16 v[28:31], v[190:193], v[238:241], v[28:31]
	v_mfma_f32_16x16x32_f16 v[24:27], v[198:201], v[226:229], v[24:27]
	v_mfma_f32_16x16x32_f16 v[20:23], v[198:201], v[238:241], v[20:23]
	v_mfma_f32_16x16x32_f16 v[16:19], v[206:209], v[226:229], v[16:19]
	v_mfma_f32_16x16x32_f16 v[12:15], v[206:209], v[238:241], v[12:15]
	v_mfma_f32_16x16x32_f16 v[8:11], v[214:217], v[226:229], v[8:11]
	v_mfma_f32_16x16x32_f16 v[4:7], v[214:217], v[238:241], v[4:7]
	v_mfma_f32_16x16x32_f16 v[32:35], v[194:197], v[230:233], v[32:35]
	v_mfma_f32_16x16x32_f16 v[28:31], v[194:197], v[242:245], v[28:31]
	v_mfma_f32_16x16x32_f16 v[24:27], v[202:205], v[230:233], v[24:27]
	v_mfma_f32_16x16x32_f16 v[20:23], v[202:205], v[242:245], v[20:23]
	v_mfma_f32_16x16x32_f16 v[16:19], v[210:213], v[230:233], v[16:19]
	v_mfma_f32_16x16x32_f16 v[12:15], v[210:213], v[242:245], v[12:15]
	v_mfma_f32_16x16x32_f16 v[8:11], v[218:221], v[230:233], v[8:11]
	v_mfma_f32_16x16x32_f16 v[4:7], v[218:221], v[242:245], v[4:7]
	s_add_i32 s1, s1, 2
	s_add_u32 s12, s12, 0x100
	s_addc_u32 s13, s13, 0
	s_cmp_lt_u32 s1, 12
	s_barrier
	s_cbranch_scc1 .LBB0_1259
	s_add_u32 s8, s8, 0x40780
	s_addc_u32 s9, s9, 0
	v_lshl_add_u64 v[132:133], s[8:9], 0, v[132:133]
	v_readfirstlane_b32 s1, v172
	v_lshl_add_u64 v[0:1], v[0:1], 1, v[132:133]
	s_mov_b32 m0, s1
	ds_read_b128 v[138:141], v171
	ds_read_b128 v[142:145], v171 offset:1024
	ds_read_b128 v[150:153], v171 offset:2048
	ds_read_b128 v[154:157], v171 offset:3072
	ds_read_b128 v[164:167], v161
	ds_read_b128 v[174:177], v161 offset:1024
	ds_read_b128 v[178:181], v160
	ds_read_b128 v[182:185], v160 offset:1024
	ds_read_b128 v[186:189], v159
	ds_read_b128 v[190:193], v159 offset:1024
	ds_read_b128 v[194:197], v158
	ds_read_b128 v[198:201], v158 offset:1024
	global_load_lds_dwordx4 v[0:1], off
	v_lshl_add_u64 v[0:1], s[8:9], 0, v[136:137]
	v_readfirstlane_b32 s1, v173
	v_lshl_add_u64 v[0:1], v[134:135], 1, v[0:1]
	s_mov_b32 m0, s1
	s_nop 0
	global_load_lds_dwordx4 v[0:1], off
	s_barrier
	s_waitcnt lgkmcnt(0)
	s_waitcnt lgkmcnt(0)
	v_mfma_f32_16x16x32_f16 v[128:131], v[164:167], v[138:141], v[128:131]
	v_mfma_f32_16x16x32_f16 v[124:127], v[164:167], v[150:153], v[124:127]
	v_mfma_f32_16x16x32_f16 v[120:123], v[178:181], v[138:141], v[120:123]
	v_mfma_f32_16x16x32_f16 v[116:119], v[178:181], v[150:153], v[116:119]
	v_mfma_f32_16x16x32_f16 v[104:107], v[194:197], v[138:141], v[104:107]
	v_mfma_f32_16x16x32_f16 v[100:103], v[194:197], v[150:153], v[100:103]
	v_mfma_f32_16x16x32_f16 v[128:131], v[174:177], v[142:145], v[128:131]
	v_mfma_f32_16x16x32_f16 v[124:127], v[174:177], v[154:157], v[124:127]
	v_mfma_f32_16x16x32_f16 v[120:123], v[182:185], v[142:145], v[120:123]
	v_mfma_f32_16x16x32_f16 v[116:119], v[182:185], v[154:157], v[116:119]
	v_mfma_f32_16x16x32_f16 v[112:115], v[186:189], v[138:141], v[112:115]
	v_mfma_f32_16x16x32_f16 v[108:111], v[186:189], v[150:153], v[108:111]
	v_mfma_f32_16x16x32_f16 v[104:107], v[198:201], v[142:145], v[104:107]
	v_mfma_f32_16x16x32_f16 v[100:103], v[198:201], v[154:157], v[100:103]
	v_mfma_f32_16x16x32_f16 v[132:135], v[190:193], v[142:145], v[112:115]
	v_mfma_f32_16x16x32_f16 v[170:173], v[190:193], v[154:157], v[108:111]
	s_barrier
	s_nop 1
	ds_read_b128 v[108:111], v169
	ds_read_b128 v[112:115], v169 offset:1024
	ds_read_b128 v[202:205], v169 offset:2048
	ds_read_b128 v[206:209], v169 offset:3072
	s_barrier
	s_waitcnt lgkmcnt(0)
	s_waitcnt lgkmcnt(0)
	v_mfma_f32_16x16x32_f16 v[88:91], v[178:181], v[108:111], v[88:91]
	v_mfma_f32_16x16x32_f16 v[84:87], v[178:181], v[202:205], v[84:87]
	v_mfma_f32_16x16x32_f16 v[72:75], v[194:197], v[108:111], v[72:75]
	v_mfma_f32_16x16x32_f16 v[68:71], v[194:197], v[202:205], v[68:71]
	v_mfma_f32_16x16x32_f16 v[96:99], v[164:167], v[108:111], v[96:99]
	v_mfma_f32_16x16x32_f16 v[92:95], v[164:167], v[202:205], v[92:95]
	v_mfma_f32_16x16x32_f16 v[88:91], v[182:185], v[112:115], v[88:91]
	v_mfma_f32_16x16x32_f16 v[84:87], v[182:185], v[206:209], v[84:87]
	v_mfma_f32_16x16x32_f16 v[80:83], v[186:189], v[108:111], v[80:83]
	v_mfma_f32_16x16x32_f16 v[76:79], v[186:189], v[202:205], v[76:79]
	v_mfma_f32_16x16x32_f16 v[72:75], v[198:201], v[112:115], v[72:75]
	v_mfma_f32_16x16x32_f16 v[68:71], v[198:201], v[206:209], v[68:71]
	v_mfma_f32_16x16x32_f16 v[210:213], v[174:177], v[112:115], v[96:99]
	v_mfma_f32_16x16x32_f16 v[164:167], v[174:177], v[206:209], v[92:95]
	v_mfma_f32_16x16x32_f16 v[174:177], v[190:193], v[112:115], v[80:83]
	v_mfma_f32_16x16x32_f16 v[178:181], v[190:193], v[206:209], v[76:79]
	s_barrier
; #define LDA8(dst, b, h) _Pragma("unroll") for (int m = 0; m < 4; ++m) _Pragma("unroll") for (int k = 0; k < 2; ++k) \
;     dst[m][k] = *(const bf16x8*)((const char*)SA8(b, h) + lds_byte8(wr * 64 + m * 16 + fr, k * 32 + fq * 8))
; #define LDB8(dst, b, h) _Pragma("unroll") for (int n = 0; n < 2; ++n) _Pragma("unroll") for (int k = 0; k < 2; ++k) \
;     dst[n][k] = *(const bf16x8*)((const char*)SB8(b, h) + lds_byte8(wc * 32 + n * 16 + fr, k * 32 + fq * 8))
; #define WAIT_V8(n) asm volatile("s_waitcnt vmcnt(" #n ")" ::: "memory")
; #define WAIT_L8(n) asm volatile("s_waitcnt lgkmcnt(" #n ")" ::: "memory")
; #define BAR8 __builtin_amdgcn_s_barrier()
;     ...
;     LDA8(At, 0, 1); WAIT_V8(4); BAR8; WAIT_L8(0); MMA8(1, 0, At, B0); MMA8(1, 1, At, B1); BAR8; }
;   { LDB8(B0, 1, 0); LDA8(At, 1, 0); WAIT_V8(2); BAR8; WAIT_L8(0); MMA8(0, 0, At, B0); BAR8;
	s_nop 0
	ds_read_b128 v[76:79], v161 offset:16384
	ds_read_b128 v[80:83], v161 offset:17408
	ds_read_b128 v[92:95], v160 offset:16384
	ds_read_b128 v[96:99], v160 offset:17408
	ds_read_b128 v[182:185], v159 offset:16384
	ds_read_b128 v[186:189], v159 offset:17408
	ds_read_b128 v[190:193], v158 offset:16384
	ds_read_b128 v[194:197], v158 offset:17408
	s_waitcnt vmcnt(4)
	s_barrier
	s_waitcnt lgkmcnt(0)
	s_waitcnt lgkmcnt(0)
	v_mfma_f32_16x16x32_f16 v[64:67], v[76:79], v[138:141], v[64:67]
	v_mfma_f32_16x16x32_f16 v[60:63], v[76:79], v[150:153], v[60:63]
	v_mfma_f32_16x16x32_f16 v[56:59], v[92:95], v[138:141], v[56:59]
	v_mfma_f32_16x16x32_f16 v[52:55], v[92:95], v[150:153], v[52:55]
	v_mfma_f32_16x16x32_f16 v[40:43], v[190:193], v[138:141], v[40:43]
	v_mfma_f32_16x16x32_f16 v[36:39], v[190:193], v[150:153], v[36:39]
	v_mfma_f32_16x16x32_f16 v[64:67], v[80:83], v[142:145], v[64:67]
	v_mfma_f32_16x16x32_f16 v[60:63], v[80:83], v[154:157], v[60:63]
	v_mfma_f32_16x16x32_f16 v[56:59], v[96:99], v[142:145], v[56:59]
	v_mfma_f32_16x16x32_f16 v[52:55], v[96:99], v[154:157], v[52:55]
	v_mfma_f32_16x16x32_f16 v[48:51], v[182:185], v[138:141], v[48:51]
	v_mfma_f32_16x16x32_f16 v[44:47], v[182:185], v[150:153], v[44:47]
	v_mfma_f32_16x16x32_f16 v[40:43], v[194:197], v[142:145], v[40:43]
	v_mfma_f32_16x16x32_f16 v[36:39], v[194:197], v[154:157], v[36:39]
	v_mfma_f32_16x16x32_f16 v[198:201], v[186:189], v[142:145], v[48:51]
	v_mfma_f32_16x16x32_f16 v[214:217], v[186:189], v[154:157], v[44:47]
	v_mfma_f32_16x16x32_f16 v[24:27], v[92:95], v[108:111], v[24:27]
	v_mfma_f32_16x16x32_f16 v[20:23], v[92:95], v[202:205], v[20:23]
	v_mfma_f32_16x16x32_f16 v[8:11], v[190:193], v[108:111], v[8:11]
	v_mfma_f32_16x16x32_f16 v[4:7], v[190:193], v[202:205], v[4:7]
	v_mfma_f32_16x16x32_f16 v[32:35], v[76:79], v[108:111], v[32:35]
	v_mfma_f32_16x16x32_f16 v[28:31], v[76:79], v[202:205], v[28:31]
	v_mfma_f32_16x16x32_f16 v[24:27], v[96:99], v[112:115], v[24:27]
	v_mfma_f32_16x16x32_f16 v[20:23], v[96:99], v[206:209], v[20:23]
	v_mfma_f32_16x16x32_f16 v[16:19], v[182:185], v[108:111], v[16:19]
	v_mfma_f32_16x16x32_f16 v[12:15], v[182:185], v[202:205], v[12:15]
	v_mfma_f32_16x16x32_f16 v[8:11], v[194:197], v[112:115], v[8:11]
	v_mfma_f32_16x16x32_f16 v[4:7], v[194:197], v[206:209], v[4:7]
	v_mfma_f32_16x16x32_f16 v[136:139], v[80:83], v[112:115], v[32:35]
	v_mfma_f32_16x16x32_f16 v[140:143], v[80:83], v[206:209], v[28:31]
	v_mfma_f32_16x16x32_f16 v[150:153], v[186:189], v[112:115], v[16:19]
	v_mfma_f32_16x16x32_f16 v[154:157], v[186:189], v[206:209], v[12:15]
	s_barrier
	s_nop 0
	ds_read_b128 v[12:15], v163
	ds_read_b128 v[16:19], v163 offset:1024
	ds_read_b128 v[182:185], v163 offset:2048
	ds_read_b128 v[186:189], v163 offset:3072
	ds_read_b128 v[28:31], v161 offset:32768
	ds_read_b128 v[32:35], v161 offset:33792
	ds_read_b128 v[44:47], v160 offset:32768
	ds_read_b128 v[48:51], v160 offset:33792
	ds_read_b128 v[190:193], v159 offset:32768
	ds_read_b128 v[194:197], v159 offset:33792
	ds_read_b128 v[202:205], v158 offset:32768
	ds_read_b128 v[206:209], v158 offset:33792
	s_waitcnt vmcnt(2)
	s_barrier
	s_waitcnt lgkmcnt(0)
	s_waitcnt lgkmcnt(0)
	v_mfma_f32_16x16x32_f16 v[76:79], v[28:31], v[12:15], v[128:131]
	v_mfma_f32_16x16x32_f16 v[128:131], v[32:35], v[16:19], v[76:79]
	v_mfma_f32_16x16x32_f16 v[76:79], v[28:31], v[182:185], v[124:127]
	v_mfma_f32_16x16x32_f16 v[124:127], v[32:35], v[186:189], v[76:79]
	v_mfma_f32_16x16x32_f16 v[76:79], v[44:47], v[12:15], v[120:123]
	v_mfma_f32_16x16x32_f16 v[112:115], v[48:51], v[16:19], v[76:79]
	v_mfma_f32_16x16x32_f16 v[76:79], v[44:47], v[182:185], v[116:119]
	v_mfma_f32_16x16x32_f16 v[108:111], v[48:51], v[186:189], v[76:79]
	v_mfma_f32_16x16x32_f16 v[76:79], v[190:193], v[12:15], v[132:135]
	v_mfma_f32_16x16x32_f16 v[96:99], v[194:197], v[16:19], v[76:79]
	v_mfma_f32_16x16x32_f16 v[76:79], v[190:193], v[182:185], v[170:173]
	v_mfma_f32_16x16x32_f16 v[92:95], v[194:197], v[186:189], v[76:79]
	v_mfma_f32_16x16x32_f16 v[76:79], v[202:205], v[12:15], v[104:107]
	v_mfma_f32_16x16x32_f16 v[80:83], v[206:209], v[16:19], v[76:79]
	v_mfma_f32_16x16x32_f16 v[76:79], v[202:205], v[182:185], v[100:103]
	v_mfma_f32_16x16x32_f16 v[76:79], v[206:209], v[186:189], v[76:79]
	s_barrier
; DI int tid_opaque() { int t = threadIdx.x; asm volatile("" : "+v"(t)); return t; }
; #define LDA8(dst, b, h) _Pragma("unroll") for (int m = 0; m < 4; ++m) _Pragma("unroll") for (int k = 0; k < 2; ++k) \
;     dst[m][k] = *(const bf16x8*)((const char*)SA8(b, h) + lds_byte8(wr * 64 + m * 16 + fr, k * 32 + fq * 8))
; #define LDB8(dst, b, h) _Pragma("unroll") for (int n = 0; n < 2; ++n) _Pragma("unroll") for (int k = 0; k < 2; ++k) \
;     dst[n][k] = *(const bf16x8*)((const char*)SB8(b, h) + lds_byte8(wc * 32 + n * 16 + fr, k * 32 + fq * 8))
; #define WAIT_V8(n) asm volatile("s_waitcnt vmcnt(" #n ")" ::: "memory")
; #define WAIT_L8(n) asm volatile("s_waitcnt lgkmcnt(" #n ")" ::: "memory")
; #define BAR8 __builtin_amdgcn_s_barrier()
;     ...
;     LDB8(B1, 1, 1); WAIT_V8(0); BAR8; WAIT_L8(0); MMA8(0, 1, At, B1); BAR8;
;     LDA8(At, 1, 1); BAR8; WAIT_L8(0); MMA8(1, 0, At, B0); MMA8(1, 1, At, B1); BAR8; }
;   if (wr == 0) BAR8;
;   __syncthreads();
;   if (EPI == EPI_GU && nm0 >= 0) {
;     const int t = tid_opaque();
;     STAGE8(SB8(0, 0), Bt, K, nn0, 0); STAGE8(SA8(0, 0), A, lda, nm0, 0);
;     STAGE8(SB8(0, 1), Bt, K, nn0 + 128, 0); STAGE8(SA8(0, 1), A, lda, nm0 + 128, 0);
;   }
;     ...
;   if (t < 256) {
	ds_read_b128 v[132:135], v162
	ds_read_b128 v[168:171], v162 offset:1024
	ds_read_b128 v[218:221], v162 offset:2048
	ds_read_b128 v[226:229], v162 offset:3072
	s_waitcnt vmcnt(0)
	s_barrier
	s_waitcnt lgkmcnt(0)
	s_waitcnt lgkmcnt(0)
	v_mfma_f32_16x16x32_f16 v[100:103], v[28:31], v[132:135], v[210:213]
	v_mfma_f32_16x16x32_f16 v[28:31], v[28:31], v[218:221], v[164:167]
	v_mfma_f32_16x16x32_f16 v[116:119], v[32:35], v[226:229], v[28:31]
	v_mfma_f32_16x16x32_f16 v[28:31], v[44:47], v[132:135], v[88:91]
	v_mfma_f32_16x16x32_f16 v[104:107], v[48:51], v[168:171], v[28:31]
	v_mfma_f32_16x16x32_f16 v[28:31], v[44:47], v[218:221], v[84:87]
	v_mfma_f32_16x16x32_f16 v[120:123], v[32:35], v[168:171], v[100:103]
	v_mfma_f32_16x16x32_f16 v[100:103], v[48:51], v[226:229], v[28:31]
	v_mfma_f32_16x16x32_f16 v[28:31], v[190:193], v[132:135], v[174:177]
	v_mfma_f32_16x16x32_f16 v[88:91], v[194:197], v[168:171], v[28:31]
	v_mfma_f32_16x16x32_f16 v[28:31], v[190:193], v[218:221], v[178:181]
	v_mfma_f32_16x16x32_f16 v[84:87], v[194:197], v[226:229], v[28:31]
	v_mfma_f32_16x16x32_f16 v[28:31], v[202:205], v[132:135], v[72:75]
	v_mfma_f32_16x16x32_f16 v[72:75], v[206:209], v[168:171], v[28:31]
	v_mfma_f32_16x16x32_f16 v[28:31], v[202:205], v[218:221], v[68:71]
	v_mfma_f32_16x16x32_f16 v[68:71], v[206:209], v[226:229], v[28:31]
	s_barrier
	ds_read_b128 v[162:165], v161 offset:49152
	ds_read_b128 v[172:175], v161 offset:50176
	ds_read_b128 v[176:179], v160 offset:49152
	ds_read_b128 v[190:193], v160 offset:50176
	ds_read_b128 v[194:197], v159 offset:49152
	ds_read_b128 v[202:205], v159 offset:50176
	ds_read_b128 v[206:209], v158 offset:49152
	ds_read_b128 v[158:161], v158 offset:50176
	s_barrier
	s_waitcnt lgkmcnt(0)
	s_waitcnt lgkmcnt(0)
	v_mfma_f32_16x16x32_f16 v[28:31], v[162:165], v[12:15], v[64:67]
	v_mfma_f32_16x16x32_f16 v[64:67], v[172:175], v[16:19], v[28:31]
	v_mfma_f32_16x16x32_f16 v[28:31], v[162:165], v[182:185], v[60:63]
	v_mfma_f32_16x16x32_f16 v[60:63], v[172:175], v[186:189], v[28:31]
	v_mfma_f32_16x16x32_f16 v[28:31], v[176:179], v[12:15], v[56:59]
	v_mfma_f32_16x16x32_f16 v[48:51], v[190:193], v[16:19], v[28:31]
	v_mfma_f32_16x16x32_f16 v[28:31], v[176:179], v[182:185], v[52:55]
	v_mfma_f32_16x16x32_f16 v[44:47], v[190:193], v[186:189], v[28:31]
	v_mfma_f32_16x16x32_f16 v[28:31], v[194:197], v[12:15], v[198:201]
	v_mfma_f32_16x16x32_f16 v[12:15], v[206:209], v[12:15], v[40:43]
	v_mfma_f32_16x16x32_f16 v[32:35], v[202:205], v[16:19], v[28:31]
	v_mfma_f32_16x16x32_f16 v[28:31], v[194:197], v[182:185], v[214:217]
	v_mfma_f32_16x16x32_f16 v[16:19], v[158:161], v[16:19], v[12:15]
	v_mfma_f32_16x16x32_f16 v[12:15], v[206:209], v[182:185], v[36:39]
	v_mfma_f32_16x16x32_f16 v[28:31], v[202:205], v[186:189], v[28:31]
	v_mfma_f32_16x16x32_f16 v[12:15], v[158:161], v[186:189], v[12:15]
	v_mfma_f32_16x16x32_f16 v[36:39], v[162:165], v[132:135], v[136:139]
	v_mfma_f32_16x16x32_f16 v[56:59], v[172:175], v[168:171], v[36:39]
	v_mfma_f32_16x16x32_f16 v[36:39], v[162:165], v[218:221], v[140:143]
	v_mfma_f32_16x16x32_f16 v[20:23], v[176:179], v[218:221], v[20:23]
	v_mfma_f32_16x16x32_f16 v[52:55], v[172:175], v[226:229], v[36:39]
	v_mfma_f32_16x16x32_f16 v[24:27], v[176:179], v[132:135], v[24:27]
	v_mfma_f32_16x16x32_f16 v[36:39], v[190:193], v[226:229], v[20:23]
	v_mfma_f32_16x16x32_f16 v[20:23], v[194:197], v[132:135], v[150:153]
	v_mfma_f32_16x16x32_f16 v[40:43], v[190:193], v[168:171], v[24:27]
	v_mfma_f32_16x16x32_f16 v[24:27], v[202:205], v[168:171], v[20:23]
	v_mfma_f32_16x16x32_f16 v[20:23], v[194:197], v[218:221], v[154:157]
	v_mfma_f32_16x16x32_f16 v[8:11], v[206:209], v[132:135], v[8:11]
	v_mfma_f32_16x16x32_f16 v[4:7], v[206:209], v[218:221], v[4:7]
	v_mfma_f32_16x16x32_f16 v[20:23], v[202:205], v[226:229], v[20:23]
	v_mfma_f32_16x16x32_f16 v[8:11], v[158:161], v[168:171], v[8:11]
	v_mfma_f32_16x16x32_f16 v[4:7], v[158:161], v[226:229], v[4:7]
	s_movk_i32 s1, 0x100
	v_cmp_gt_u32_e32 vcc, s1, v3
	s_barrier
	s_and_saveexec_b64 s[8:9], vcc
	s_cbranch_execz .LBB0_1262
	s_barrier

; #define LDA8(dst, b, h) _Pragma("unroll") for (int m = 0; m < 4; ++m) _Pragma("unroll") for (int k = 0; k < 2; ++k) \
;     dst[m][k] = *(const bf16x8*)((const char*)SA8(b, h) + lds_byte8(wr * 64 + m * 16 + fr, k * 32 + fq * 8))
; #define LDB8(dst, b, h) _Pragma("unroll") for (int n = 0; n < 2; ++n) _Pragma("unroll") for (int k = 0; k < 2; ++k) \
;     dst[n][k] = *(const bf16x8*)((const char*)SB8(b, h) + lds_byte8(wc * 32 + n * 16 + fr, k * 32 + fq * 8))
; #define WAIT_L8(n) asm volatile("s_waitcnt lgkmcnt(" #n ")" ::: "memory")
; #define BAR8 __builtin_amdgcn_s_barrier()
; #define SCHED8 __builtin_amdgcn_sched_barrier(0)
;     ...
;     LDB8(B0, 0, 0); SCHED8; LDA8(At, 0, 0); STAGE8(SA8(1, 1), A, lda, brow + 128, tt + 1);
;     WAIT_L8(8); BAR8; WAIT_L8(0); MMA8(0, 0, At, B0); BAR8; SCHED8;
;     LDB8(B1, 0, 1); STAGE8(SB8(0, 0), Bt, K, bcol, tt + 2);
;     BAR8; WAIT_L8(0); MMA8(0, 1, At, B1); BAR8;
;     LDA8(At, 0, 1); STAGE8(SA8(0, 0), A, lda, brow, tt + 2);
;     BAR8; WAIT_L8(0); MMA8(1, 0, At, B0); BAR8; SCHED8;
.LBB0_1325:
	ds_read_b128 v[174:177], v171
	ds_read_b128 v[178:181], v171 offset:1024
	ds_read_b128 v[182:185], v171 offset:2048
	ds_read_b128 v[186:189], v171 offset:3072
	v_add_u32_e32 v172, 0xc000, v150
	v_lshl_add_u64 v[222:223], v[142:143], 0, s[12:13]
	v_readfirstlane_b32 s31, v172
	v_add_u32_e32 v173, 0xe000, v150
	v_lshl_add_u64 v[226:227], v[222:223], 0, s[36:37]
	s_mov_b32 m0, s31
	v_lshl_add_u64 v[236:237], v[144:145], 0, s[12:13]
	v_readfirstlane_b32 s31, v173
	ds_read_b128 v[190:193], v156
	ds_read_b128 v[194:197], v156 offset:1024
	ds_read_b128 v[198:201], v155
	ds_read_b128 v[202:205], v155 offset:1024
	ds_read_b128 v[206:209], v154
	ds_read_b128 v[210:213], v154 offset:1024
	ds_read_b128 v[214:217], v153
	ds_read_b128 v[218:221], v153 offset:1024
	global_load_lds_dwordx4 v[226:227], off
	v_lshl_add_u64 v[226:227], v[236:237], 0, s[36:37]
	s_mov_b32 m0, s31
	s_nop 0
	global_load_lds_dwordx4 v[226:227], off
	s_waitcnt lgkmcnt(8)
	s_barrier
	s_waitcnt lgkmcnt(0)
	s_waitcnt lgkmcnt(0)
	v_mfma_f32_16x16x32_bf16 v[128:131], v[190:193], v[174:177], v[128:131]
	v_mfma_f32_16x16x32_bf16 v[124:127], v[190:193], v[182:185], v[124:127]
	v_mfma_f32_16x16x32_bf16 v[120:123], v[198:201], v[174:177], v[120:123]
	v_mfma_f32_16x16x32_bf16 v[116:119], v[198:201], v[182:185], v[116:119]
	v_mfma_f32_16x16x32_bf16 v[112:115], v[206:209], v[174:177], v[112:115]
	v_mfma_f32_16x16x32_bf16 v[108:111], v[206:209], v[182:185], v[108:111]
	v_mfma_f32_16x16x32_bf16 v[104:107], v[214:217], v[174:177], v[104:107]
	v_mfma_f32_16x16x32_bf16 v[100:103], v[214:217], v[182:185], v[100:103]
	v_mfma_f32_16x16x32_bf16 v[128:131], v[194:197], v[178:181], v[128:131]
	v_mfma_f32_16x16x32_bf16 v[124:127], v[194:197], v[186:189], v[124:127]
	v_mfma_f32_16x16x32_bf16 v[120:123], v[202:205], v[178:181], v[120:123]
	v_mfma_f32_16x16x32_bf16 v[116:119], v[202:205], v[186:189], v[116:119]
	v_mfma_f32_16x16x32_bf16 v[112:115], v[210:213], v[178:181], v[112:115]
	v_mfma_f32_16x16x32_bf16 v[108:111], v[210:213], v[186:189], v[108:111]
	v_mfma_f32_16x16x32_bf16 v[104:107], v[218:221], v[178:181], v[104:107]
	v_mfma_f32_16x16x32_bf16 v[100:103], v[218:221], v[186:189], v[100:103]
	s_barrier
	v_lshl_add_u64 v[246:247], v[138:139], 0, s[12:13]
	v_readfirstlane_b32 s31, v151
	v_lshl_add_u64 v[248:249], v[246:247], 0, s[38:39]
	s_mov_b32 m0, s31
	ds_read_b128 v[226:229], v169
	ds_read_b128 v[230:233], v169 offset:1024
	ds_read_b128 v[238:241], v169 offset:2048
	ds_read_b128 v[242:245], v169 offset:3072
	global_load_lds_dwordx4 v[248:249], off
	v_lshl_add_u64 v[248:249], v[140:141], 0, s[12:13]
	v_readfirstlane_b32 s31, v157
	v_lshl_add_u64 v[250:251], v[248:249], 0, s[38:39]
	s_mov_b32 m0, s31
	s_nop 0
	global_load_lds_dwordx4 v[250:251], off
	s_barrier
	s_waitcnt lgkmcnt(0)
	s_waitcnt lgkmcnt(0)
	v_mfma_f32_16x16x32_bf16 v[96:99], v[190:193], v[226:229], v[96:99]
	v_mfma_f32_16x16x32_bf16 v[92:95], v[190:193], v[238:241], v[92:95]
	v_mfma_f32_16x16x32_bf16 v[88:91], v[198:201], v[226:229], v[88:91]
	v_mfma_f32_16x16x32_bf16 v[84:87], v[198:201], v[238:241], v[84:87]
	v_mfma_f32_16x16x32_bf16 v[80:83], v[206:209], v[226:229], v[80:83]
	v_mfma_f32_16x16x32_bf16 v[76:79], v[206:209], v[238:241], v[76:79]
	v_mfma_f32_16x16x32_bf16 v[72:75], v[214:217], v[226:229], v[72:75]
	v_mfma_f32_16x16x32_bf16 v[68:71], v[214:217], v[238:241], v[68:71]
	v_mfma_f32_16x16x32_bf16 v[96:99], v[194:197], v[230:233], v[96:99]
	v_mfma_f32_16x16x32_bf16 v[92:95], v[194:197], v[242:245], v[92:95]
	v_mfma_f32_16x16x32_bf16 v[88:91], v[202:205], v[230:233], v[88:91]
	v_mfma_f32_16x16x32_bf16 v[84:87], v[202:205], v[242:245], v[84:87]
	v_mfma_f32_16x16x32_bf16 v[80:83], v[210:213], v[230:233], v[80:83]
	v_mfma_f32_16x16x32_bf16 v[76:79], v[210:213], v[242:245], v[76:79]
	v_mfma_f32_16x16x32_bf16 v[72:75], v[218:221], v[230:233], v[72:75]
	v_mfma_f32_16x16x32_bf16 v[68:71], v[218:221], v[242:245], v[68:71]
	v_readfirstlane_b32 s31, v150
	v_lshl_add_u64 v[250:251], v[222:223], 0, s[40:41]
	s_mov_b32 m0, s31
	v_readfirstlane_b32 s31, v152
	s_barrier
	ds_read_b128 v[190:193], v156 offset:16384
	ds_read_b128 v[194:197], v156 offset:17408
	ds_read_b128 v[198:201], v155 offset:16384
	ds_read_b128 v[202:205], v155 offset:17408
	ds_read_b128 v[206:209], v154 offset:16384
	ds_read_b128 v[210:213], v154 offset:17408
	ds_read_b128 v[214:217], v153 offset:16384
	ds_read_b128 v[218:221], v153 offset:17408
	global_load_lds_dwordx4 v[250:251], off
	v_lshl_add_u64 v[250:251], v[236:237], 0, s[40:41]
	s_mov_b32 m0, s31
	s_nop 0
	global_load_lds_dwordx4 v[250:251], off
	s_barrier
	s_waitcnt lgkmcnt(0)
	s_waitcnt lgkmcnt(0)
	v_mfma_f32_16x16x32_bf16 v[64:67], v[190:193], v[174:177], v[64:67]
	v_mfma_f32_16x16x32_bf16 v[60:63], v[190:193], v[182:185], v[60:63]
	v_mfma_f32_16x16x32_bf16 v[56:59], v[198:201], v[174:177], v[56:59]
	v_mfma_f32_16x16x32_bf16 v[52:55], v[198:201], v[182:185], v[52:55]
	v_mfma_f32_16x16x32_bf16 v[48:51], v[206:209], v[174:177], v[48:51]
	v_mfma_f32_16x16x32_bf16 v[44:47], v[206:209], v[182:185], v[44:47]
	v_mfma_f32_16x16x32_bf16 v[40:43], v[214:217], v[174:177], v[40:43]
	v_mfma_f32_16x16x32_bf16 v[36:39], v[214:217], v[182:185], v[36:39]
	v_mfma_f32_16x16x32_bf16 v[64:67], v[194:197], v[178:181], v[64:67]
	v_mfma_f32_16x16x32_bf16 v[60:63], v[194:197], v[186:189], v[60:63]
	v_mfma_f32_16x16x32_bf16 v[56:59], v[202:205], v[178:181], v[56:59]
	v_mfma_f32_16x16x32_bf16 v[52:55], v[202:205], v[186:189], v[52:55]
	v_mfma_f32_16x16x32_bf16 v[48:51], v[210:213], v[178:181], v[48:51]
	v_mfma_f32_16x16x32_bf16 v[44:47], v[210:213], v[186:189], v[44:47]
	v_mfma_f32_16x16x32_bf16 v[40:43], v[218:221], v[178:181], v[40:43]
	v_mfma_f32_16x16x32_bf16 v[36:39], v[218:221], v[186:189], v[36:39]
	s_barrier
; #define LDA8(dst, b, h) _Pragma("unroll") for (int m = 0; m < 4; ++m) _Pragma("unroll") for (int k = 0; k < 2; ++k) \
;     dst[m][k] = *(const bf16x8*)((const char*)SA8(b, h) + lds_byte8(wr * 64 + m * 16 + fr, k * 32 + fq * 8))
; #define LDB8(dst, b, h) _Pragma("unroll") for (int n = 0; n < 2; ++n) _Pragma("unroll") for (int k = 0; k < 2; ++k) \
;     dst[n][k] = *(const bf16x8*)((const char*)SB8(b, h) + lds_byte8(wc * 32 + n * 16 + fr, k * 32 + fq * 8))
; #define WAIT_V8(n) asm volatile("s_waitcnt vmcnt(" #n ")" ::: "memory")
; #define WAIT_L8(n) asm volatile("s_waitcnt lgkmcnt(" #n ")" ::: "memory")
; #define BAR8 __builtin_amdgcn_s_barrier()
; #define SCHED8 __builtin_amdgcn_sched_barrier(0)
;     ...
;     STAGE8(SB8(0, 1), Bt, K, bcol + 128, tt + 2);
;     WAIT_V8(6); BAR8; MMA8(1, 1, At, B1); BAR8;
;     LDB8(B0, 1, 0); SCHED8; LDA8(At, 1, 0); STAGE8(SA8(0, 1), A, lda, brow + 128, tt + 2);
;     WAIT_L8(8); BAR8; WAIT_L8(0); MMA8(0, 0, At, B0); BAR8; SCHED8;
;     LDB8(B1, 1, 1); STAGE8(SB8(1, 0), Bt, K, bcol, tt + 3);
;     BAR8; WAIT_L8(0); MMA8(0, 1, At, B1); BAR8;
;     LDA8(At, 1, 1); STAGE8(SA8(1, 0), A, lda, brow, tt + 3);
	v_readfirstlane_b32 s31, v160
	v_lshl_add_u64 v[174:175], v[246:247], 0, s[42:43]
	s_mov_b32 m0, s31
	v_readfirstlane_b32 s31, v161
	global_load_lds_dwordx4 v[174:175], off
	v_lshl_add_u64 v[174:175], v[248:249], 0, s[42:43]
	s_mov_b32 m0, s31
	s_nop 0
	global_load_lds_dwordx4 v[174:175], off
	s_waitcnt vmcnt(6)
	s_barrier
	v_mfma_f32_16x16x32_bf16 v[32:35], v[190:193], v[226:229], v[32:35]
	v_mfma_f32_16x16x32_bf16 v[28:31], v[190:193], v[238:241], v[28:31]
	v_mfma_f32_16x16x32_bf16 v[24:27], v[198:201], v[226:229], v[24:27]
	v_mfma_f32_16x16x32_bf16 v[20:23], v[198:201], v[238:241], v[20:23]
	v_mfma_f32_16x16x32_bf16 v[16:19], v[206:209], v[226:229], v[16:19]
	v_mfma_f32_16x16x32_bf16 v[12:15], v[206:209], v[238:241], v[12:15]
	v_mfma_f32_16x16x32_bf16 v[8:11], v[214:217], v[226:229], v[8:11]
	v_mfma_f32_16x16x32_bf16 v[4:7], v[214:217], v[238:241], v[4:7]
	v_mfma_f32_16x16x32_bf16 v[32:35], v[194:197], v[230:233], v[32:35]
	v_mfma_f32_16x16x32_bf16 v[28:31], v[194:197], v[242:245], v[28:31]
	v_mfma_f32_16x16x32_bf16 v[24:27], v[202:205], v[230:233], v[24:27]
	v_mfma_f32_16x16x32_bf16 v[20:23], v[202:205], v[242:245], v[20:23]
	v_mfma_f32_16x16x32_bf16 v[16:19], v[210:213], v[230:233], v[16:19]
	v_mfma_f32_16x16x32_bf16 v[12:15], v[210:213], v[242:245], v[12:15]
	v_mfma_f32_16x16x32_bf16 v[8:11], v[218:221], v[230:233], v[8:11]
	v_mfma_f32_16x16x32_bf16 v[4:7], v[218:221], v[242:245], v[4:7]
	s_barrier
	ds_read_b128 v[174:177], v159
	ds_read_b128 v[178:181], v159 offset:1024
	ds_read_b128 v[182:185], v159 offset:2048
	ds_read_b128 v[186:189], v159 offset:3072
	v_readfirstlane_b32 s31, v162
	v_lshl_add_u64 v[226:227], v[222:223], 0, s[44:45]
	s_mov_b32 m0, s31
	v_readfirstlane_b32 s31, v163
	ds_read_b128 v[190:193], v156 offset:32768
	ds_read_b128 v[194:197], v156 offset:33792
	ds_read_b128 v[198:201], v155 offset:32768
	ds_read_b128 v[202:205], v155 offset:33792
	ds_read_b128 v[206:209], v154 offset:32768
	ds_read_b128 v[210:213], v154 offset:33792
	ds_read_b128 v[214:217], v153 offset:32768
	ds_read_b128 v[218:221], v153 offset:33792
	global_load_lds_dwordx4 v[226:227], off
	v_lshl_add_u64 v[226:227], v[236:237], 0, s[44:45]
	s_mov_b32 m0, s31
	s_nop 0
	global_load_lds_dwordx4 v[226:227], off
	s_waitcnt lgkmcnt(8)
	s_barrier
	s_waitcnt lgkmcnt(0)
	s_waitcnt lgkmcnt(0)
	v_mfma_f32_16x16x32_bf16 v[128:131], v[190:193], v[174:177], v[128:131]
	v_mfma_f32_16x16x32_bf16 v[124:127], v[190:193], v[182:185], v[124:127]
	v_mfma_f32_16x16x32_bf16 v[120:123], v[198:201], v[174:177], v[120:123]
	v_mfma_f32_16x16x32_bf16 v[116:119], v[198:201], v[182:185], v[116:119]
	v_mfma_f32_16x16x32_bf16 v[112:115], v[206:209], v[174:177], v[112:115]
	v_mfma_f32_16x16x32_bf16 v[108:111], v[206:209], v[182:185], v[108:111]
	v_mfma_f32_16x16x32_bf16 v[104:107], v[214:217], v[174:177], v[104:107]
	v_mfma_f32_16x16x32_bf16 v[100:103], v[214:217], v[182:185], v[100:103]
	v_mfma_f32_16x16x32_bf16 v[128:131], v[194:197], v[178:181], v[128:131]
	v_mfma_f32_16x16x32_bf16 v[124:127], v[194:197], v[186:189], v[124:127]
	v_mfma_f32_16x16x32_bf16 v[120:123], v[202:205], v[178:181], v[120:123]
	v_mfma_f32_16x16x32_bf16 v[116:119], v[202:205], v[186:189], v[116:119]
	v_mfma_f32_16x16x32_bf16 v[112:115], v[210:213], v[178:181], v[112:115]
	v_mfma_f32_16x16x32_bf16 v[108:111], v[210:213], v[186:189], v[108:111]
	v_mfma_f32_16x16x32_bf16 v[104:107], v[218:221], v[178:181], v[104:107]
	v_mfma_f32_16x16x32_bf16 v[100:103], v[218:221], v[186:189], v[100:103]
	s_barrier
	v_readfirstlane_b32 s31, v164
	v_lshl_add_u64 v[250:251], v[246:247], 0, s[46:47]
	s_mov_b32 m0, s31
	v_readfirstlane_b32 s31, v165
	ds_read_b128 v[226:229], v158
	ds_read_b128 v[230:233], v158 offset:1024
	ds_read_b128 v[238:241], v158 offset:2048
	ds_read_b128 v[242:245], v158 offset:3072
	global_load_lds_dwordx4 v[250:251], off
	v_lshl_add_u64 v[250:251], v[248:249], 0, s[46:47]
	s_mov_b32 m0, s31
	s_nop 0
	global_load_lds_dwordx4 v[250:251], off
	s_barrier
	s_waitcnt lgkmcnt(0)
	s_waitcnt lgkmcnt(0)
	v_mfma_f32_16x16x32_bf16 v[96:99], v[190:193], v[226:229], v[96:99]
	v_mfma_f32_16x16x32_bf16 v[92:95], v[190:193], v[238:241], v[92:95]
	v_mfma_f32_16x16x32_bf16 v[88:91], v[198:201], v[226:229], v[88:91]
	v_mfma_f32_16x16x32_bf16 v[84:87], v[198:201], v[238:241], v[84:87]
	v_mfma_f32_16x16x32_bf16 v[80:83], v[206:209], v[226:229], v[80:83]
	v_mfma_f32_16x16x32_bf16 v[76:79], v[206:209], v[238:241], v[76:79]
	v_mfma_f32_16x16x32_bf16 v[72:75], v[214:217], v[226:229], v[72:75]
	v_mfma_f32_16x16x32_bf16 v[68:71], v[214:217], v[238:241], v[68:71]
	v_mfma_f32_16x16x32_bf16 v[96:99], v[194:197], v[230:233], v[96:99]
	v_mfma_f32_16x16x32_bf16 v[92:95], v[194:197], v[242:245], v[92:95]
	v_mfma_f32_16x16x32_bf16 v[88:91], v[202:205], v[230:233], v[88:91]
	v_mfma_f32_16x16x32_bf16 v[84:87], v[202:205], v[242:245], v[84:87]
	v_mfma_f32_16x16x32_bf16 v[80:83], v[210:213], v[230:233], v[80:83]
	v_mfma_f32_16x16x32_bf16 v[76:79], v[210:213], v[242:245], v[76:79]
	v_mfma_f32_16x16x32_bf16 v[72:75], v[218:221], v[230:233], v[72:75]
	v_mfma_f32_16x16x32_bf16 v[68:71], v[218:221], v[242:245], v[68:71]
	v_readfirstlane_b32 s31, v166
	v_lshl_add_u64 v[222:223], v[222:223], 0, s[48:49]
	s_mov_b32 m0, s31
	v_readfirstlane_b32 s31, v167
	s_barrier
	ds_read_b128 v[190:193], v156 offset:49152
	ds_read_b128 v[194:197], v156 offset:50176
	ds_read_b128 v[198:201], v155 offset:49152
	ds_read_b128 v[202:205], v155 offset:50176
	ds_read_b128 v[206:209], v154 offset:49152
	ds_read_b128 v[210:213], v154 offset:50176
	ds_read_b128 v[214:217], v153 offset:49152
	ds_read_b128 v[218:221], v153 offset:50176
	global_load_lds_dwordx4 v[222:223], off
	v_lshl_add_u64 v[222:223], v[236:237], 0, s[48:49]
	s_mov_b32 m0, s31
	s_nop 0
	global_load_lds_dwordx4 v[222:223], off
	s_barrier
; #define LDA8(dst, b, h) _Pragma("unroll") for (int m = 0; m < 4; ++m) _Pragma("unroll") for (int k = 0; k < 2; ++k) \
;     dst[m][k] = *(const bf16x8*)((const char*)SA8(b, h) + lds_byte8(wr * 64 + m * 16 + fr, k * 32 + fq * 8))
; #define LDB8(dst, b, h) _Pragma("unroll") for (int n = 0; n < 2; ++n) _Pragma("unroll") for (int k = 0; k < 2; ++k) \
;     dst[n][k] = *(const bf16x8*)((const char*)SB8(b, h) + lds_byte8(wc * 32 + n * 16 + fr, k * 32 + fq * 8))
; #define WAIT_V8(n) asm volatile("s_waitcnt vmcnt(" #n ")" ::: "memory")
; #define WAIT_L8(n) asm volatile("s_waitcnt lgkmcnt(" #n ")" ::: "memory")
; #define BAR8 __builtin_amdgcn_s_barrier()
; #define SCHED8 __builtin_amdgcn_sched_barrier(0)
;     ...
;     BAR8; WAIT_L8(0); MMA8(1, 0, At, B0); BAR8; SCHED8;
;     STAGE8(SB8(1, 1), Bt, K, bcol + 128, tt + 3);
;     WAIT_V8(6); BAR8; MMA8(1, 1, At, B1); BAR8;
;   }
;   { LDB8(B0, 0, 0); LDA8(At, 0, 0); STAGE8(SA8(1, 1), A, lda, brow + 128, nt - 1);
;     BAR8; WAIT_L8(0); MMA8(0, 0, At, B0); BAR8;
;     LDB8(B1, 0, 1); BAR8; WAIT_L8(0); MMA8(0, 1, At, B1); BAR8;
	s_waitcnt lgkmcnt(0)
	s_waitcnt lgkmcnt(0)
	v_mfma_f32_16x16x32_bf16 v[64:67], v[190:193], v[174:177], v[64:67]
	v_mfma_f32_16x16x32_bf16 v[60:63], v[190:193], v[182:185], v[60:63]
	v_mfma_f32_16x16x32_bf16 v[56:59], v[198:201], v[174:177], v[56:59]
	v_mfma_f32_16x16x32_bf16 v[52:55], v[198:201], v[182:185], v[52:55]
	v_mfma_f32_16x16x32_bf16 v[48:51], v[206:209], v[174:177], v[48:51]
	v_mfma_f32_16x16x32_bf16 v[44:47], v[206:209], v[182:185], v[44:47]
	v_mfma_f32_16x16x32_bf16 v[40:43], v[214:217], v[174:177], v[40:43]
	v_mfma_f32_16x16x32_bf16 v[36:39], v[214:217], v[182:185], v[36:39]
	v_mfma_f32_16x16x32_bf16 v[64:67], v[194:197], v[178:181], v[64:67]
	v_mfma_f32_16x16x32_bf16 v[60:63], v[194:197], v[186:189], v[60:63]
	v_mfma_f32_16x16x32_bf16 v[56:59], v[202:205], v[178:181], v[56:59]
	v_mfma_f32_16x16x32_bf16 v[52:55], v[202:205], v[186:189], v[52:55]
	v_mfma_f32_16x16x32_bf16 v[48:51], v[210:213], v[178:181], v[48:51]
	v_mfma_f32_16x16x32_bf16 v[44:47], v[210:213], v[186:189], v[44:47]
	v_mfma_f32_16x16x32_bf16 v[40:43], v[218:221], v[178:181], v[40:43]
	v_mfma_f32_16x16x32_bf16 v[36:39], v[218:221], v[186:189], v[36:39]
	s_barrier
	v_readfirstlane_b32 s31, v168
	v_lshl_add_u64 v[174:175], v[246:247], 0, s[50:51]
	s_mov_b32 m0, s31
	v_readfirstlane_b32 s31, v170
	global_load_lds_dwordx4 v[174:175], off
	v_lshl_add_u64 v[174:175], v[248:249], 0, s[50:51]
	s_mov_b32 m0, s31
	s_nop 0
	global_load_lds_dwordx4 v[174:175], off
	s_waitcnt vmcnt(6)
	s_barrier
	v_mfma_f32_16x16x32_bf16 v[32:35], v[190:193], v[226:229], v[32:35]
	v_mfma_f32_16x16x32_bf16 v[28:31], v[190:193], v[238:241], v[28:31]
	v_mfma_f32_16x16x32_bf16 v[24:27], v[198:201], v[226:229], v[24:27]
	v_mfma_f32_16x16x32_bf16 v[20:23], v[198:201], v[238:241], v[20:23]
	v_mfma_f32_16x16x32_bf16 v[16:19], v[206:209], v[226:229], v[16:19]
	v_mfma_f32_16x16x32_bf16 v[12:15], v[206:209], v[238:241], v[12:15]
	v_mfma_f32_16x16x32_bf16 v[8:11], v[214:217], v[226:229], v[8:11]
	v_mfma_f32_16x16x32_bf16 v[4:7], v[214:217], v[238:241], v[4:7]
	v_mfma_f32_16x16x32_bf16 v[32:35], v[194:197], v[230:233], v[32:35]
	v_mfma_f32_16x16x32_bf16 v[28:31], v[194:197], v[242:245], v[28:31]
	v_mfma_f32_16x16x32_bf16 v[24:27], v[202:205], v[230:233], v[24:27]
	v_mfma_f32_16x16x32_bf16 v[20:23], v[202:205], v[242:245], v[20:23]
	v_mfma_f32_16x16x32_bf16 v[16:19], v[210:213], v[230:233], v[16:19]
	v_mfma_f32_16x16x32_bf16 v[12:15], v[210:213], v[242:245], v[12:15]
	v_mfma_f32_16x16x32_bf16 v[8:11], v[218:221], v[230:233], v[8:11]
	v_mfma_f32_16x16x32_bf16 v[4:7], v[218:221], v[242:245], v[4:7]
	s_add_i32 s29, s29, 2
	s_add_u32 s12, s12, 0x100
	s_addc_u32 s13, s13, 0
	s_cmp_lt_u32 s29, 40
	s_barrier
	s_cbranch_scc1 .LBB0_1325
	s_add_i32 s27, s27, 0xb0000
	s_add_u32 s2, s2, s27
	s_addc_u32 s3, s3, 0
	s_add_u32 s2, s2, 0x2001580
	s_addc_u32 s3, s3, 0
	v_lshl_add_u64 v[132:133], v[132:133], 1, s[2:3]
	v_readfirstlane_b32 s12, v172
	v_lshl_add_u64 v[0:1], v[0:1], 1, v[132:133]
	s_mov_b32 m0, s12
	ds_read_b128 v[138:141], v171
	ds_read_b128 v[142:145], v171 offset:1024
	ds_read_b128 v[160:163], v171 offset:2048
	ds_read_b128 v[164:167], v171 offset:3072
	ds_read_b128 v[174:177], v156
	ds_read_b128 v[178:181], v156 offset:1024
	ds_read_b128 v[182:185], v155
	ds_read_b128 v[186:189], v155 offset:1024
	ds_read_b128 v[190:193], v154
	ds_read_b128 v[194:197], v154 offset:1024
	ds_read_b128 v[198:201], v153
	ds_read_b128 v[202:205], v153 offset:1024
	global_load_lds_dwordx4 v[0:1], off
	v_lshl_add_u64 v[0:1], v[136:137], 1, s[2:3]
	v_readfirstlane_b32 s2, v173
	v_lshl_add_u64 v[0:1], v[134:135], 1, v[0:1]
	s_mov_b32 m0, s2
	s_nop 0
	global_load_lds_dwordx4 v[0:1], off
	s_barrier
	s_waitcnt lgkmcnt(0)
	s_waitcnt lgkmcnt(0)
	v_mfma_f32_16x16x32_bf16 v[128:131], v[174:177], v[138:141], v[128:131]
	v_mfma_f32_16x16x32_bf16 v[124:127], v[174:177], v[160:163], v[124:127]
	v_mfma_f32_16x16x32_bf16 v[120:123], v[182:185], v[138:141], v[120:123]
	v_mfma_f32_16x16x32_bf16 v[112:115], v[190:193], v[138:141], v[112:115]
	v_mfma_f32_16x16x32_bf16 v[128:131], v[178:181], v[142:145], v[128:131]
	v_mfma_f32_16x16x32_bf16 v[124:127], v[178:181], v[164:167], v[124:127]
	v_mfma_f32_16x16x32_bf16 v[120:123], v[186:189], v[142:145], v[120:123]
	v_mfma_f32_16x16x32_bf16 v[116:119], v[182:185], v[160:163], v[116:119]
	v_mfma_f32_16x16x32_bf16 v[112:115], v[194:197], v[142:145], v[112:115]
	v_mfma_f32_16x16x32_bf16 v[108:111], v[190:193], v[160:163], v[108:111]
	v_mfma_f32_16x16x32_bf16 v[104:107], v[198:201], v[138:141], v[104:107]
	v_mfma_f32_16x16x32_bf16 v[100:103], v[198:201], v[160:163], v[100:103]
	v_mfma_f32_16x16x32_bf16 v[132:135], v[186:189], v[164:167], v[116:119]
	v_mfma_f32_16x16x32_bf16 v[170:173], v[194:197], v[164:167], v[108:111]
	v_mfma_f32_16x16x32_bf16 v[206:209], v[202:205], v[142:145], v[104:107]
	v_mfma_f32_16x16x32_bf16 v[210:213], v[202:205], v[164:167], v[100:103]
	s_barrier
	s_nop 1
	ds_read_b128 v[100:103], v169
	ds_read_b128 v[104:107], v169 offset:1024
	ds_read_b128 v[108:111], v169 offset:2048
	ds_read_b128 v[116:119], v169 offset:3072
	s_barrier
; #define LDA8(dst, b, h) _Pragma("unroll") for (int m = 0; m < 4; ++m) _Pragma("unroll") for (int k = 0; k < 2; ++k) \
;     dst[m][k] = *(const bf16x8*)((const char*)SA8(b, h) + lds_byte8(wr * 64 + m * 16 + fr, k * 32 + fq * 8))
; #define LDB8(dst, b, h) _Pragma("unroll") for (int n = 0; n < 2; ++n) _Pragma("unroll") for (int k = 0; k < 2; ++k) \
;     dst[n][k] = *(const bf16x8*)((const char*)SB8(b, h) + lds_byte8(wc * 32 + n * 16 + fr, k * 32 + fq * 8))
; #define WAIT_V8(n) asm volatile("s_waitcnt vmcnt(" #n ")" ::: "memory")
; #define WAIT_L8(n) asm volatile("s_waitcnt lgkmcnt(" #n ")" ::: "memory")
; #define BAR8 __builtin_amdgcn_s_barrier()
;     ...
;     LDB8(B1, 0, 1); BAR8; WAIT_L8(0); MMA8(0, 1, At, B1); BAR8;
;     LDA8(At, 0, 1); WAIT_V8(4); BAR8; WAIT_L8(0); MMA8(1, 0, At, B0); MMA8(1, 1, At, B1); BAR8; }
;   { LDB8(B0, 1, 0); LDA8(At, 1, 0); WAIT_V8(2); BAR8; WAIT_L8(0); MMA8(0, 0, At, B0); BAR8;
	s_waitcnt lgkmcnt(0)
	s_waitcnt lgkmcnt(0)
	v_mfma_f32_16x16x32_bf16 v[80:83], v[190:193], v[100:103], v[80:83]
	v_mfma_f32_16x16x32_bf16 v[76:79], v[190:193], v[108:111], v[76:79]
	v_mfma_f32_16x16x32_bf16 v[72:75], v[198:201], v[100:103], v[72:75]
	v_mfma_f32_16x16x32_bf16 v[68:71], v[198:201], v[108:111], v[68:71]
	v_mfma_f32_16x16x32_bf16 v[96:99], v[174:177], v[100:103], v[96:99]
	v_mfma_f32_16x16x32_bf16 v[92:95], v[174:177], v[108:111], v[92:95]
	v_mfma_f32_16x16x32_bf16 v[88:91], v[182:185], v[100:103], v[88:91]
	v_mfma_f32_16x16x32_bf16 v[84:87], v[182:185], v[108:111], v[84:87]
	v_mfma_f32_16x16x32_bf16 v[80:83], v[194:197], v[104:107], v[80:83]
	v_mfma_f32_16x16x32_bf16 v[76:79], v[194:197], v[116:119], v[76:79]
	v_mfma_f32_16x16x32_bf16 v[72:75], v[202:205], v[104:107], v[72:75]
	v_mfma_f32_16x16x32_bf16 v[68:71], v[202:205], v[116:119], v[68:71]
	v_mfma_f32_16x16x32_bf16 v[214:217], v[178:181], v[104:107], v[96:99]
	v_mfma_f32_16x16x32_bf16 v[174:177], v[178:181], v[116:119], v[92:95]
	v_mfma_f32_16x16x32_bf16 v[178:181], v[186:189], v[104:107], v[88:91]
	v_mfma_f32_16x16x32_bf16 v[182:185], v[186:189], v[116:119], v[84:87]
	s_barrier
	s_nop 0
	ds_read_b128 v[84:87], v156 offset:16384
	ds_read_b128 v[88:91], v156 offset:17408
	ds_read_b128 v[92:95], v155 offset:16384
	ds_read_b128 v[96:99], v155 offset:17408
	ds_read_b128 v[186:189], v154 offset:16384
	ds_read_b128 v[190:193], v154 offset:17408
	ds_read_b128 v[194:197], v153 offset:16384
	ds_read_b128 v[198:201], v153 offset:17408
	s_waitcnt vmcnt(4)
	s_barrier
	s_waitcnt lgkmcnt(0)
	s_waitcnt lgkmcnt(0)
	v_mfma_f32_16x16x32_bf16 v[64:67], v[84:87], v[138:141], v[64:67]
	v_mfma_f32_16x16x32_bf16 v[60:63], v[84:87], v[160:163], v[60:63]
	v_mfma_f32_16x16x32_bf16 v[56:59], v[92:95], v[138:141], v[56:59]
	v_mfma_f32_16x16x32_bf16 v[52:55], v[92:95], v[160:163], v[52:55]
	v_mfma_f32_16x16x32_bf16 v[48:51], v[186:189], v[138:141], v[48:51]
	v_mfma_f32_16x16x32_bf16 v[44:47], v[186:189], v[160:163], v[44:47]
	v_mfma_f32_16x16x32_bf16 v[40:43], v[194:197], v[138:141], v[40:43]
	v_mfma_f32_16x16x32_bf16 v[36:39], v[194:197], v[160:163], v[36:39]
	v_mfma_f32_16x16x32_bf16 v[64:67], v[88:91], v[142:145], v[64:67]
	v_mfma_f32_16x16x32_bf16 v[60:63], v[88:91], v[164:167], v[60:63]
	v_mfma_f32_16x16x32_bf16 v[56:59], v[96:99], v[142:145], v[56:59]
	v_mfma_f32_16x16x32_bf16 v[52:55], v[96:99], v[164:167], v[52:55]
	v_mfma_f32_16x16x32_bf16 v[48:51], v[190:193], v[142:145], v[48:51]
	v_mfma_f32_16x16x32_bf16 v[44:47], v[190:193], v[164:167], v[44:47]
	v_mfma_f32_16x16x32_bf16 v[40:43], v[198:201], v[142:145], v[40:43]
	v_mfma_f32_16x16x32_bf16 v[36:39], v[198:201], v[164:167], v[36:39]
	v_mfma_f32_16x16x32_bf16 v[32:35], v[84:87], v[100:103], v[32:35]
	v_mfma_f32_16x16x32_bf16 v[28:31], v[84:87], v[108:111], v[28:31]
	v_mfma_f32_16x16x32_bf16 v[24:27], v[92:95], v[100:103], v[24:27]
	v_mfma_f32_16x16x32_bf16 v[20:23], v[92:95], v[108:111], v[20:23]
	v_mfma_f32_16x16x32_bf16 v[16:19], v[186:189], v[100:103], v[16:19]
	v_mfma_f32_16x16x32_bf16 v[12:15], v[186:189], v[108:111], v[12:15]
	v_mfma_f32_16x16x32_bf16 v[8:11], v[194:197], v[100:103], v[8:11]
	v_mfma_f32_16x16x32_bf16 v[4:7], v[194:197], v[108:111], v[4:7]
	v_mfma_f32_16x16x32_bf16 v[136:139], v[88:91], v[104:107], v[32:35]
	v_mfma_f32_16x16x32_bf16 v[140:143], v[88:91], v[116:119], v[28:31]
	v_mfma_f32_16x16x32_bf16 v[160:163], v[96:99], v[104:107], v[24:27]
	v_mfma_f32_16x16x32_bf16 v[164:167], v[96:99], v[116:119], v[20:23]
	v_mfma_f32_16x16x32_bf16 v[202:205], v[190:193], v[104:107], v[16:19]
	v_mfma_f32_16x16x32_bf16 v[186:189], v[190:193], v[116:119], v[12:15]
	v_mfma_f32_16x16x32_bf16 v[190:193], v[198:201], v[104:107], v[8:11]
	v_mfma_f32_16x16x32_bf16 v[194:197], v[198:201], v[116:119], v[4:7]
	s_barrier
	ds_read_b128 v[198:201], v159
	ds_read_b128 v[218:221], v159 offset:1024
	ds_read_b128 v[226:229], v159 offset:2048
	ds_read_b128 v[230:233], v159 offset:3072
	ds_read_b128 v[8:11], v156 offset:32768
	ds_read_b128 v[12:15], v156 offset:33792
	ds_read_b128 v[16:19], v155 offset:32768
	ds_read_b128 v[24:27], v155 offset:33792
	ds_read_b128 v[28:31], v154 offset:32768
	ds_read_b128 v[32:35], v154 offset:33792
	ds_read_b128 v[238:241], v153 offset:32768
	ds_read_b128 v[242:245], v153 offset:33792
	s_waitcnt vmcnt(2)
	s_barrier
; DI int tid_opaque() { int t = threadIdx.x; asm volatile("" : "+v"(t)); return t; }
; #define LDA8(dst, b, h) _Pragma("unroll") for (int m = 0; m < 4; ++m) _Pragma("unroll") for (int k = 0; k < 2; ++k) \
;     dst[m][k] = *(const bf16x8*)((const char*)SA8(b, h) + lds_byte8(wr * 64 + m * 16 + fr, k * 32 + fq * 8))
; #define LDB8(dst, b, h) _Pragma("unroll") for (int n = 0; n < 2; ++n) _Pragma("unroll") for (int k = 0; k < 2; ++k) \
;     dst[n][k] = *(const bf16x8*)((const char*)SB8(b, h) + lds_byte8(wc * 32 + n * 16 + fr, k * 32 + fq * 8))
; #define WAIT_V8(n) asm volatile("s_waitcnt vmcnt(" #n ")" ::: "memory")
; #define WAIT_L8(n) asm volatile("s_waitcnt lgkmcnt(" #n ")" ::: "memory")
; #define BAR8 __builtin_amdgcn_s_barrier()
;     ...
;   { LDB8(B0, 1, 0); LDA8(At, 1, 0); WAIT_V8(2); BAR8; WAIT_L8(0); MMA8(0, 0, At, B0); BAR8;
;     LDB8(B1, 1, 1); WAIT_V8(0); BAR8; WAIT_L8(0); MMA8(0, 1, At, B1); BAR8;
;     LDA8(At, 1, 1); BAR8; WAIT_L8(0); MMA8(1, 0, At, B0); MMA8(1, 1, At, B1); BAR8; }
;   if (wr == 0) BAR8;
;   __syncthreads();
;   if (EPI == EPI_GU && nm0 >= 0) {
;     const int t = tid_opaque();
;     STAGE8(SB8(0, 0), Bt, K, nn0, 0); STAGE8(SA8(0, 0), A, lda, nm0, 0);
;     STAGE8(SB8(0, 1), Bt, K, nn0 + 128, 0); STAGE8(SA8(0, 1), A, lda, nm0 + 128, 0);
;   }
;     ...
;   if (t < 256) {
	s_waitcnt lgkmcnt(0)
	s_waitcnt lgkmcnt(0)
	v_mfma_f32_16x16x32_bf16 v[4:7], v[8:11], v[198:201], v[128:131]
	v_mfma_f32_16x16x32_bf16 v[104:107], v[12:15], v[218:221], v[4:7]
	v_mfma_f32_16x16x32_bf16 v[4:7], v[8:11], v[226:229], v[124:127]
	v_mfma_f32_16x16x32_bf16 v[116:119], v[12:15], v[230:233], v[4:7]
	v_mfma_f32_16x16x32_bf16 v[4:7], v[16:19], v[198:201], v[120:123]
	v_mfma_f32_16x16x32_bf16 v[100:103], v[24:27], v[218:221], v[4:7]
	v_mfma_f32_16x16x32_bf16 v[4:7], v[16:19], v[226:229], v[132:135]
	v_mfma_f32_16x16x32_bf16 v[108:111], v[24:27], v[230:233], v[4:7]
	v_mfma_f32_16x16x32_bf16 v[4:7], v[28:31], v[198:201], v[112:115]
	v_mfma_f32_16x16x32_bf16 v[92:95], v[32:35], v[218:221], v[4:7]
	v_mfma_f32_16x16x32_bf16 v[4:7], v[28:31], v[226:229], v[170:173]
	v_mfma_f32_16x16x32_bf16 v[96:99], v[32:35], v[230:233], v[4:7]
	v_mfma_f32_16x16x32_bf16 v[4:7], v[238:241], v[198:201], v[206:209]
	v_mfma_f32_16x16x32_bf16 v[84:87], v[242:245], v[218:221], v[4:7]
	v_mfma_f32_16x16x32_bf16 v[4:7], v[238:241], v[226:229], v[210:213]
	v_mfma_f32_16x16x32_bf16 v[88:91], v[242:245], v[230:233], v[4:7]
	s_barrier
	ds_read_b128 v[132:135], v158
	ds_read_b128 v[168:171], v158 offset:1024
	ds_read_b128 v[206:209], v158 offset:2048
	ds_read_b128 v[210:213], v158 offset:3072
	s_waitcnt vmcnt(0)
	s_barrier
	s_waitcnt lgkmcnt(0)
	s_waitcnt lgkmcnt(0)
	v_mfma_f32_16x16x32_bf16 v[4:7], v[8:11], v[132:135], v[214:217]
	v_mfma_f32_16x16x32_bf16 v[8:11], v[8:11], v[206:209], v[174:177]
	v_mfma_f32_16x16x32_bf16 v[4:7], v[12:15], v[168:171], v[4:7]
	v_mfma_f32_16x16x32_bf16 v[20:23], v[12:15], v[210:213], v[8:11]
	v_mfma_f32_16x16x32_bf16 v[8:11], v[16:19], v[132:135], v[178:181]
	v_mfma_f32_16x16x32_bf16 v[12:15], v[16:19], v[206:209], v[182:185]
	v_mfma_f32_16x16x32_bf16 v[8:11], v[24:27], v[168:171], v[8:11]
	v_mfma_f32_16x16x32_bf16 v[24:27], v[24:27], v[210:213], v[12:15]
	v_mfma_f32_16x16x32_bf16 v[12:15], v[28:31], v[132:135], v[80:83]
	v_mfma_f32_16x16x32_bf16 v[16:19], v[28:31], v[206:209], v[76:79]
	v_mfma_f32_16x16x32_bf16 v[12:15], v[32:35], v[168:171], v[12:15]
	v_mfma_f32_16x16x32_bf16 v[28:31], v[32:35], v[210:213], v[16:19]
	v_mfma_f32_16x16x32_bf16 v[16:19], v[238:241], v[132:135], v[72:75]
	v_mfma_f32_16x16x32_bf16 v[32:35], v[238:241], v[206:209], v[68:71]
	v_mfma_f32_16x16x32_bf16 v[16:19], v[242:245], v[168:171], v[16:19]
	v_mfma_f32_16x16x32_bf16 v[32:35], v[242:245], v[210:213], v[32:35]
	s_barrier
	ds_read_b128 v[172:175], v156 offset:49152
	ds_read_b128 v[156:159], v156 offset:50176
	ds_read_b128 v[176:179], v155 offset:49152
	ds_read_b128 v[180:183], v155 offset:50176
	ds_read_b128 v[214:217], v154 offset:49152
	ds_read_b128 v[238:241], v154 offset:50176
	ds_read_b128 v[242:245], v153 offset:49152
	ds_read_b128 v[150:153], v153 offset:50176
	s_barrier
	s_waitcnt lgkmcnt(0)
	s_waitcnt lgkmcnt(0)
	v_mfma_f32_16x16x32_bf16 v[64:67], v[172:175], v[198:201], v[64:67]
	v_mfma_f32_16x16x32_bf16 v[60:63], v[172:175], v[226:229], v[60:63]
	v_mfma_f32_16x16x32_bf16 v[56:59], v[176:179], v[198:201], v[56:59]
	v_mfma_f32_16x16x32_bf16 v[52:55], v[176:179], v[226:229], v[52:55]
	v_mfma_f32_16x16x32_bf16 v[48:51], v[214:217], v[198:201], v[48:51]
	v_mfma_f32_16x16x32_bf16 v[44:47], v[214:217], v[226:229], v[44:47]
	v_mfma_f32_16x16x32_bf16 v[40:43], v[242:245], v[198:201], v[40:43]
	v_mfma_f32_16x16x32_bf16 v[36:39], v[242:245], v[226:229], v[36:39]
	v_mfma_f32_16x16x32_bf16 v[128:131], v[156:159], v[218:221], v[64:67]
	v_mfma_f32_16x16x32_bf16 v[124:127], v[156:159], v[230:233], v[60:63]
	v_mfma_f32_16x16x32_bf16 v[120:123], v[180:183], v[218:221], v[56:59]
	v_mfma_f32_16x16x32_bf16 v[112:115], v[180:183], v[230:233], v[52:55]
	v_mfma_f32_16x16x32_bf16 v[80:83], v[238:241], v[218:221], v[48:51]
	v_mfma_f32_16x16x32_bf16 v[76:79], v[238:241], v[230:233], v[44:47]
	v_mfma_f32_16x16x32_bf16 v[72:75], v[150:153], v[218:221], v[40:43]
	v_mfma_f32_16x16x32_bf16 v[68:71], v[150:153], v[230:233], v[36:39]
	v_mfma_f32_16x16x32_bf16 v[40:43], v[172:175], v[206:209], v[140:143]
	v_mfma_f32_16x16x32_bf16 v[44:47], v[176:179], v[206:209], v[164:167]
	v_mfma_f32_16x16x32_bf16 v[48:51], v[214:217], v[206:209], v[186:189]
	v_mfma_f32_16x16x32_bf16 v[36:39], v[172:175], v[132:135], v[136:139]
	v_mfma_f32_16x16x32_bf16 v[52:55], v[156:159], v[210:213], v[40:43]
	v_mfma_f32_16x16x32_bf16 v[40:43], v[176:179], v[132:135], v[160:163]
	v_mfma_f32_16x16x32_bf16 v[56:59], v[180:183], v[210:213], v[44:47]
	v_mfma_f32_16x16x32_bf16 v[44:47], v[214:217], v[132:135], v[202:205]
	v_mfma_f32_16x16x32_bf16 v[60:63], v[238:241], v[210:213], v[48:51]
	v_mfma_f32_16x16x32_bf16 v[48:51], v[242:245], v[132:135], v[190:193]
	v_mfma_f32_16x16x32_bf16 v[64:67], v[242:245], v[206:209], v[194:197]
	v_mfma_f32_16x16x32_bf16 v[36:39], v[156:159], v[168:171], v[36:39]
	v_mfma_f32_16x16x32_bf16 v[40:43], v[180:183], v[168:171], v[40:43]
	v_mfma_f32_16x16x32_bf16 v[44:47], v[238:241], v[168:171], v[44:47]
	v_mfma_f32_16x16x32_bf16 v[48:51], v[150:153], v[168:171], v[48:51]
	v_mfma_f32_16x16x32_bf16 v[64:67], v[150:153], v[210:213], v[64:67]
	s_movk_i32 s2, 0x100
	v_cmp_gt_u32_e32 vcc, s2, v3
	s_barrier
	s_and_saveexec_b64 s[2:3], vcc
	s_cbranch_execz .LBB0_1328
	s_barrier
